# write-through (sc1) on all 16-byte global stores: less dirty L2 for the barrier's write-back, on top of the early acquire
# speedup vs baseline: 1.0606x; 1.0036x over previous
.LBB0_25:
	s_cmpk_gt_i32 s60, 0x17f
	s_mov_b64 s[4:5], -1
	s_cbranch_scc0 .LBB0_47
	s_cmpk_lg_i32 s60, 0x180
	s_cbranch_scc0 .LBB0_36
	s_cmpk_gt_u32 s60, 0x2c0
	s_cbranch_scc0 .LBB0_33
	s_cmpk_gt_u32 s60, 0x2d0
	s_cbranch_scc0 .LBB0_30
	s_add_i32 s2, s60, 0xfffffd2f
	s_lshl_b32 s4, s2, 2
	s_and_b32 s4, s4, 0x7fffffc0
	s_lshl_b32 s2, s2, 6
	s_and_b32 s5, s2, 0x3c0
	v_or_b32_e32 v0, s4, v3
	s_lshl_b32 s2, s5, 2
	v_lshlrev_b64 v[40:41], 12, v[0:1]
	v_add_u32_e32 v0, s4, v89
	v_lshl_add_u64 v[52:53], v[6:7], 0, s[2:3]
	v_lshlrev_b64 v[42:43], 12, v[0:1]
	v_lshl_add_u64 v[40:41], v[52:53], 0, v[40:41]
	v_lshl_add_u64 v[44:45], v[52:53], 0, v[42:43]
	s_barrier
	global_load_dwordx4 v[40:43], v[40:41], off nt
	s_nop 0
	global_load_dwordx4 v[44:47], v[44:45], off nt
	v_add_u32_e32 v0, s4, v90
	v_lshlrev_b64 v[48:49], 12, v[0:1]
	v_lshl_add_u64 v[48:49], v[52:53], 0, v[48:49]
	v_add_u32_e32 v0, s4, v91
	global_load_dwordx4 v[48:51], v[48:49], off nt
	v_lshlrev_b64 v[54:55], 12, v[0:1]
	v_lshl_add_u64 v[52:53], v[52:53], 0, v[54:55]
	global_load_dwordx4 v[52:55], v[52:53], off nt
	v_add_u32_e32 v13, v5, v88
	v_add_u32_e32 v31, v94, v92
	v_add_u32_e32 v33, v96, v92
	v_add_u32_e32 v60, 0x1040, v13
	v_add_u32_e32 v61, 0x1048, v13
	v_add_u32_e32 v62, 0x2080, v13
	v_add_u32_e32 v63, 0x2088, v13
	v_add_u32_e32 v64, 0x30c0, v13
	v_add_u32_e32 v65, 0x30c8, v13
	v_add_u32_e32 v66, 0x400, v31
	v_add_u32_e32 v67, 0x400, v33
	s_lshl_b32 s2, s4, 1
	v_lshl_add_u64 v[56:57], v[34:35], 0, s[2:3]
	v_add_lshl_u32 v0, s5, v93, 11
	v_lshl_add_u64 v[58:59], v[56:57], 0, v[0:1]
	v_add_lshl_u32 v0, s5, v95, 11
	v_lshl_add_u64 v[56:57], v[56:57], 0, v[0:1]
	s_mov_b64 s[4:5], 0
	s_waitcnt vmcnt(3)
	ds_write2_b32 v13, v40, v41 offset1:1
	ds_write2_b32 v13, v42, v43 offset0:2 offset1:3
	s_waitcnt vmcnt(2)
	ds_write2_b32 v60, v44, v45 offset1:1
	ds_write2_b32 v61, v46, v47 offset1:1
	s_waitcnt vmcnt(1)
	ds_write2_b32 v62, v48, v49 offset1:1
	ds_write2_b32 v63, v50, v51 offset1:1
	s_waitcnt vmcnt(0)
	ds_write2_b32 v64, v52, v53 offset1:1
	ds_write2_b32 v65, v54, v55 offset1:1
	s_waitcnt lgkmcnt(0)
	s_barrier
	ds_read2_b32 v[40:41], v31 offset1:65
	ds_read2_b32 v[42:43], v31 offset0:130 offset1:195
	ds_read2_b32 v[44:45], v66 offset0:4 offset1:69
	ds_read2_b32 v[46:47], v66 offset0:134 offset1:199
	ds_read2_b32 v[48:49], v33 offset1:65
	ds_read2_b32 v[50:51], v33 offset0:130 offset1:195
	ds_read2_b32 v[52:53], v67 offset0:4 offset1:69
	ds_read2_b32 v[54:55], v67 offset0:134 offset1:199
	s_waitcnt lgkmcnt(7)
	v_cvt_pk_bf16_f32 v40, v40, v41
	s_waitcnt lgkmcnt(6)
	v_cvt_pk_bf16_f32 v41, v42, v43
	s_waitcnt lgkmcnt(5)
	v_cvt_pk_bf16_f32 v42, v44, v45
	s_waitcnt lgkmcnt(4)
	v_cvt_pk_bf16_f32 v43, v46, v47
	s_waitcnt lgkmcnt(3)
	v_cvt_pk_bf16_f32 v44, v48, v49
	s_waitcnt lgkmcnt(2)
	v_cvt_pk_bf16_f32 v45, v50, v51
	s_waitcnt lgkmcnt(1)
	v_cvt_pk_bf16_f32 v46, v52, v53
	s_waitcnt lgkmcnt(0)
	v_cvt_pk_bf16_f32 v47, v54, v55
	global_store_dwordx4 v[58:59], v[40:43], off sc1
	global_store_dwordx4 v[56:57], v[44:47], off sc1
.LBB0_30:
	s_andn2_b64 vcc, exec, s[4:5]
	s_cbranch_vccnz .LBB0_32
	s_add_i32 s16, s60, 0xfffffd3f
	s_lshl_b32 s2, s16, 12
	s_and_b32 s2, s2, 0x7fffc000
	s_lshl_b64 s[4:5], s[2:3], 2
	s_add_u32 s4, s22, s4
	s_addc_u32 s5, s23, s5
	s_lshl_b32 s2, s2, 1
	s_add_u32 s2, s40, s2
	s_addc_u32 s17, s41, 0
	s_lshl_b32 s18, s16, 5
	s_lshl_b32 s16, s16, 6
	s_and_b32 s16, s16, 64
	s_and_b32 s18, s18, 64
	s_lshl_b32 s19, s16, 2
	s_add_u32 s4, s4, s19
	s_addc_u32 s5, s5, 0
	v_mov_b32_e32 v31, v1
	v_or_b32_e32 v0, s18, v3
	v_lshl_add_u64 v[52:53], s[4:5], 0, v[30:31]
	v_lshlrev_b32_e32 v0, 7, v0
	v_lshl_add_u64 v[40:41], v[0:1], 2, v[52:53]
	v_add_lshl_u32 v0, s18, v89, 7
	v_lshl_add_u64 v[44:45], v[0:1], 2, v[52:53]
	s_barrier
	global_load_dwordx4 v[40:43], v[40:41], off nt
	s_nop 0
	global_load_dwordx4 v[44:47], v[44:45], off nt
	v_add_lshl_u32 v0, s18, v90, 7
	v_lshl_add_u64 v[48:49], v[0:1], 2, v[52:53]
	global_load_dwordx4 v[48:51], v[48:49], off nt
	v_add_lshl_u32 v0, s18, v91, 7
	v_lshl_add_u64 v[52:53], v[0:1], 2, v[52:53]
	global_load_dwordx4 v[52:55], v[52:53], off nt
	v_add_u32_e32 v13, v5, v88
	v_add_u32_e32 v31, v94, v92
	v_add_u32_e32 v60, v96, v92
	v_add_u32_e32 v61, 0x1040, v13
	v_add_u32_e32 v62, 0x1048, v13
	v_add_u32_e32 v63, 0x2080, v13
	v_add_u32_e32 v64, 0x2088, v13
	v_add_u32_e32 v65, 0x30c0, v13
	v_add_u32_e32 v66, 0x30c8, v13
	v_add_u32_e32 v67, 0x400, v31
	v_add_u32_e32 v68, 0x400, v60
	s_lshl_b32 s4, s18, 1
	s_add_u32 s4, s2, s4
	v_mov_b32_e32 v33, v1
	s_addc_u32 s5, s17, 0
	v_lshl_add_u64 v[56:57], s[4:5], 0, v[32:33]
	v_add_lshl_u32 v0, s16, v93, 8
	v_lshl_add_u64 v[58:59], v[56:57], 0, v[0:1]
	v_add_lshl_u32 v0, s16, v95, 8
	v_lshl_add_u64 v[56:57], v[56:57], 0, v[0:1]
	s_waitcnt vmcnt(3)
	ds_write2_b32 v13, v40, v41 offset1:1
	ds_write2_b32 v13, v42, v43 offset0:2 offset1:3
	s_waitcnt vmcnt(2)
	ds_write2_b32 v61, v44, v45 offset1:1
	ds_write2_b32 v62, v46, v47 offset1:1
	s_waitcnt vmcnt(1)
	ds_write2_b32 v63, v48, v49 offset1:1
	ds_write2_b32 v64, v50, v51 offset1:1
	s_waitcnt vmcnt(0)
	ds_write2_b32 v65, v52, v53 offset1:1
	ds_write2_b32 v66, v54, v55 offset1:1
	s_waitcnt lgkmcnt(0)
	s_barrier
	ds_read2_b32 v[40:41], v31 offset1:65
	ds_read2_b32 v[42:43], v31 offset0:130 offset1:195
	ds_read2_b32 v[44:45], v67 offset0:4 offset1:69
	ds_read2_b32 v[46:47], v67 offset0:134 offset1:199
	ds_read2_b32 v[48:49], v60 offset1:65
	ds_read2_b32 v[50:51], v60 offset0:130 offset1:195
	ds_read2_b32 v[52:53], v68 offset0:4 offset1:69
	ds_read2_b32 v[54:55], v68 offset0:134 offset1:199
	s_waitcnt lgkmcnt(7)
	v_cvt_pk_bf16_f32 v40, v40, v41
	s_waitcnt lgkmcnt(6)
	v_cvt_pk_bf16_f32 v41, v42, v43
	s_waitcnt lgkmcnt(5)
	v_cvt_pk_bf16_f32 v42, v44, v45
	s_waitcnt lgkmcnt(4)
	v_cvt_pk_bf16_f32 v43, v46, v47
	s_waitcnt lgkmcnt(3)
	v_cvt_pk_bf16_f32 v44, v48, v49
	s_waitcnt lgkmcnt(2)
	v_cvt_pk_bf16_f32 v45, v50, v51
	s_waitcnt lgkmcnt(1)
	v_cvt_pk_bf16_f32 v46, v52, v53
	s_waitcnt lgkmcnt(0)
	v_cvt_pk_bf16_f32 v47, v54, v55
	global_store_dwordx4 v[58:59], v[40:43], off sc1
	global_store_dwordx4 v[56:57], v[44:47], off sc1

.LBB0_33:
	s_andn2_b64 vcc, exec, s[4:5]
	s_cbranch_vccnz .LBB0_35
	s_add_i32 s2, s60, 0xfe7f
	s_and_b32 s4, s2, 0xffff
	s_mul_i32 s4, s4, 0xcccd
	s_lshr_b32 s4, s4, 20
	s_mul_i32 s5, s4, 20
	s_sub_i32 s2, s2, s5
	s_lshl_b32 s2, s2, 6
	s_lshl_b32 s5, s4, 6
	s_and_b32 s16, s2, 0xffc0
	s_lshl_b32 s2, s16, 2
	v_or_b32_e32 v0, s5, v3
	v_lshl_add_u64 v[52:53], v[10:11], 0, s[2:3]
	v_mul_u32_u24_e32 v0, 0x500, v0
	v_lshl_add_u64 v[40:41], v[0:1], 2, v[52:53]
	v_add_u32_e32 v0, s5, v89
	v_mul_u32_u24_e32 v0, 0x500, v0
	v_lshl_add_u64 v[44:45], v[0:1], 2, v[52:53]
	s_barrier
	global_load_dwordx4 v[40:43], v[40:41], off nt
	s_nop 0
	global_load_dwordx4 v[44:47], v[44:45], off nt
	v_add_u32_e32 v0, s5, v90
	v_mul_u32_u24_e32 v0, 0x500, v0
	v_lshl_add_u64 v[48:49], v[0:1], 2, v[52:53]
	v_add_u32_e32 v0, s5, v91
	global_load_dwordx4 v[48:51], v[48:49], off nt
	v_mul_u32_u24_e32 v0, 0x500, v0
	v_lshl_add_u64 v[52:53], v[0:1], 2, v[52:53]
	global_load_dwordx4 v[52:55], v[52:53], off nt
	v_add_u32_e32 v13, v5, v88
	v_add_u32_e32 v31, v94, v92
	v_add_u32_e32 v33, v96, v92
	v_add_u32_e32 v60, 0x1040, v13
	v_add_u32_e32 v61, 0x1048, v13
	v_add_u32_e32 v62, 0x2080, v13
	v_add_u32_e32 v63, 0x2088, v13
	v_add_u32_e32 v64, 0x30c0, v13
	v_add_u32_e32 v65, 0x30c8, v13
	v_add_u32_e32 v66, 0x400, v31
	v_add_u32_e32 v67, 0x400, v33
	s_lshl_b32 s2, s4, 7
	v_lshl_add_u64 v[56:57], v[8:9], 0, s[2:3]
	v_add_lshl_u32 v0, v93, s16, 11
	v_lshl_add_u64 v[58:59], v[56:57], 0, v[0:1]
	v_add_lshl_u32 v0, v95, s16, 11
	v_lshl_add_u64 v[56:57], v[56:57], 0, v[0:1]
	s_waitcnt vmcnt(3)
	ds_write2_b32 v13, v40, v41 offset1:1
	ds_write2_b32 v13, v42, v43 offset0:2 offset1:3
	s_waitcnt vmcnt(2)
	ds_write2_b32 v60, v44, v45 offset1:1
	ds_write2_b32 v61, v46, v47 offset1:1
	s_waitcnt vmcnt(1)
	ds_write2_b32 v62, v48, v49 offset1:1
	ds_write2_b32 v63, v50, v51 offset1:1
	s_waitcnt vmcnt(0)
	ds_write2_b32 v64, v52, v53 offset1:1
	ds_write2_b32 v65, v54, v55 offset1:1
	s_waitcnt lgkmcnt(0)
	s_barrier
	ds_read2_b32 v[40:41], v31 offset1:65
	ds_read2_b32 v[42:43], v31 offset0:130 offset1:195
	ds_read2_b32 v[44:45], v66 offset0:4 offset1:69
	ds_read2_b32 v[46:47], v66 offset0:134 offset1:199
	ds_read2_b32 v[48:49], v33 offset1:65
	ds_read2_b32 v[50:51], v33 offset0:130 offset1:195
	ds_read2_b32 v[52:53], v67 offset0:4 offset1:69
	ds_read2_b32 v[54:55], v67 offset0:134 offset1:199
	s_waitcnt lgkmcnt(7)
	v_cvt_pk_bf16_f32 v40, v40, v41
	s_waitcnt lgkmcnt(6)
	v_cvt_pk_bf16_f32 v41, v42, v43
	s_waitcnt lgkmcnt(5)
	v_cvt_pk_bf16_f32 v42, v44, v45
	s_waitcnt lgkmcnt(4)
	v_cvt_pk_bf16_f32 v43, v46, v47
	s_waitcnt lgkmcnt(3)
	v_cvt_pk_bf16_f32 v44, v48, v49
	s_waitcnt lgkmcnt(2)
	v_cvt_pk_bf16_f32 v45, v50, v51
	s_waitcnt lgkmcnt(1)
	v_cvt_pk_bf16_f32 v46, v52, v53
	s_waitcnt lgkmcnt(0)
	v_cvt_pk_bf16_f32 v47, v54, v55
	global_store_dwordx4 v[58:59], v[40:43], off sc1
	global_store_dwordx4 v[56:57], v[44:47], off sc1

.LBB0_124:
	s_or_b64 exec, exec, s[18:19]
	v_lshl_add_u64 v[8:9], v[10:11], 2, s[4:5]
	v_lshlrev_b32_e32 v0, 2, v6
	v_lshl_add_u64 v[34:35], v[8:9], 0, v[0:1]
	v_add_co_u32_e32 v8, vcc, s23, v34
	v_lshl_add_u64 v[36:37], v[34:35], 0, s[16:17]
	s_nop 0
	v_addc_co_u32_e32 v9, vcc, 0, v35, vcc
	global_load_dwordx4 v[8:11], v[8:9], off
	s_nop 0
	global_load_dwordx4 v[14:17], v[36:37], off offset:16
	global_load_dwordx4 v[18:21], v[34:35], off
	global_load_dwordx4 v[22:25], v[4:5], off
	global_load_dwordx4 v[26:29], v[4:5], off offset:16
	global_load_dwordx4 v[30:33], v[34:35], off offset:16
	v_add_u32_e32 v7, s20, v7
	v_cmp_lt_i32_e32 vcc, s24, v7
	s_or_b64 s[14:15], vcc, s[14:15]
	v_add_u32_e32 v12, s21, v12
	s_waitcnt vmcnt(5)
	v_pk_add_f32 v[4:5], v[8:9], 1.0 op_sel_hi:[1,0]
	v_pk_add_f32 v[8:9], v[10:11], 1.0 op_sel_hi:[1,0]
	s_waitcnt vmcnt(4)
	v_pk_add_f32 v[10:11], v[14:15], 1.0 op_sel_hi:[1,0]
	v_pk_add_f32 v[14:15], v[16:17], 1.0 op_sel_hi:[1,0]
	s_waitcnt vmcnt(2)
	v_pk_fma_f32 v[4:5], v[22:23], v[4:5], v[18:19]
	v_pk_fma_f32 v[16:17], v[24:25], v[8:9], v[20:21]
	s_waitcnt vmcnt(0)
	v_pk_fma_f32 v[10:11], v[26:27], v[10:11], v[30:31]
	v_pk_fma_f32 v[14:15], v[28:29], v[14:15], v[32:33]
	v_cvt_pk_bf16_f32 v8, v4, v5
	v_cvt_pk_bf16_f32 v9, v16, v17
	v_cvt_pk_bf16_f32 v10, v10, v11
	v_cvt_pk_bf16_f32 v11, v14, v15
	global_store_dwordx4 v[2:3], v[8:11], off sc1
	s_andn2_b64 exec, exec, s[14:15]
	s_cbranch_execz .LBB0_130

.LBB0_232:
	s_waitcnt lgkmcnt(1)
	v_lshlrev_b32_e32 v132, 3, v190
	v_and_b32_e32 v195, 56, v132
	v_mul_u32_u24_e32 v132, 0x84, v195
	v_ashrrev_i32_e32 v193, 3, v190
	v_lshl_add_u32 v132, v132, 2, 0
	v_ashrrev_i32_e32 v192, 3, v191
	v_ashrrev_i32_e32 v191, 3, v203
	v_ashrrev_i32_e32 v190, 3, v226
	v_lshl_add_u32 v241, v193, 2, v132
	v_lshl_add_u32 v237, v192, 2, v132
	v_lshl_add_u32 v233, v191, 2, v132
	v_lshl_add_u32 v203, v190, 2, v132
	s_and_b64 vcc, exec, s[4:5]
	v_add_u32_e32 v244, 0x400, v241
	v_add_u32_e32 v245, 0x800, v241
	v_add_u32_e32 v246, 0xc00, v241
	v_add_u32_e32 v238, 0x400, v237
	v_add_u32_e32 v239, 0x800, v237
	v_add_u32_e32 v240, 0xc00, v237
	v_add_u32_e32 v234, 0x400, v233
	v_add_u32_e32 v235, 0x800, v233
	v_add_u32_e32 v236, 0xc00, v233
	v_add_u32_e32 v232, 0x400, v203
	v_add_u32_e32 v229, 0x800, v203
	v_add_u32_e32 v226, 0xc00, v203
	s_cbranch_vccz .LBB0_234
	s_waitcnt lgkmcnt(0)
	ds_read2_b32 v[128:129], v241 offset1:132
	ds_read2_b32 v[130:131], v244 offset0:8 offset1:140
	ds_read2_b32 v[132:133], v245 offset0:16 offset1:148
	ds_read2_b32 v[134:135], v246 offset0:24 offset1:156
	v_mov_b32_e32 v144, s59
	s_and_b64 s[4:5], exec, s[10:11]
	v_bitop3_b32 v144, v195, s54, v144 bitop3:0xc8
	v_or_b32_e32 v138, s59, v195
	s_cselect_b32 s0, 8, 12
	v_add_u32_e32 v144, 0x100, v144
	v_lshrrev_b32_e32 v138, s0, v138
	v_cndmask_b32_e64 v144, v144, v195, s[10:11]
	v_lshlrev_b32_e32 v152, 7, v138
	v_lshlrev_b32_e32 v138, 1, v144
	ds_read2_b32 v[144:145], v237 offset1:132
	ds_read2_b32 v[146:147], v238 offset0:8 offset1:140
	ds_read2_b32 v[148:149], v239 offset0:16 offset1:148
	ds_read2_b32 v[150:151], v240 offset0:24 offset1:156
	s_waitcnt lgkmcnt(7)
	v_cvt_pk_bf16_f32 v128, v128, v129
	s_waitcnt lgkmcnt(6)
	v_cvt_pk_bf16_f32 v129, v130, v131
	s_waitcnt lgkmcnt(5)
	v_cvt_pk_bf16_f32 v130, v132, v133
	s_waitcnt lgkmcnt(4)
	v_cvt_pk_bf16_f32 v131, v134, v135
	v_add_u32_e32 v134, v152, v193
	v_mov_b64_e32 v[132:133], s[28:29]
	v_mad_i64_i32 v[134:135], s[4:5], v134, s55, v[132:133]
	v_lshl_add_u64 v[134:135], v[134:135], 0, v[138:139]
	global_store_dwordx4 v[134:135], v[128:131], off sc1
	v_add_u32_e32 v134, v152, v192
	v_mad_i64_i32 v[134:135], s[4:5], v134, s55, v[132:133]
	s_waitcnt lgkmcnt(3)
	v_cvt_pk_bf16_f32 v128, v144, v145
	s_waitcnt lgkmcnt(2)
	v_cvt_pk_bf16_f32 v129, v146, v147
	s_waitcnt lgkmcnt(1)
	v_cvt_pk_bf16_f32 v130, v148, v149
	s_waitcnt lgkmcnt(0)
	v_cvt_pk_bf16_f32 v131, v150, v151
	ds_read2_b32 v[144:145], v233 offset1:132
	ds_read2_b32 v[146:147], v234 offset0:8 offset1:140
	ds_read2_b32 v[148:149], v235 offset0:16 offset1:148
	ds_read2_b32 v[150:151], v236 offset0:24 offset1:156
	v_lshl_add_u64 v[134:135], v[134:135], 0, v[138:139]
	global_store_dwordx4 v[134:135], v[128:131], off sc1
	v_add_u32_e32 v134, v152, v191
	v_mad_i64_i32 v[134:135], s[4:5], v134, s55, v[132:133]
	s_waitcnt lgkmcnt(3)
	v_cvt_pk_bf16_f32 v128, v144, v145
	s_waitcnt lgkmcnt(2)
	v_cvt_pk_bf16_f32 v129, v146, v147
	s_waitcnt lgkmcnt(1)
	v_cvt_pk_bf16_f32 v130, v148, v149
	s_waitcnt lgkmcnt(0)
	v_cvt_pk_bf16_f32 v131, v150, v151
	v_lshl_add_u64 v[134:135], v[134:135], 0, v[138:139]
	ds_read2_b32 v[144:145], v203 offset1:132
	global_store_dwordx4 v[134:135], v[128:131], off sc1
	ds_read2_b32 v[134:135], v232 offset0:8 offset1:140
	ds_read2_b32 v[128:129], v229 offset0:16 offset1:148
	ds_read2_b32 v[130:131], v226 offset0:24 offset1:156
	s_waitcnt lgkmcnt(3)
	v_cvt_pk_bf16_f32 v144, v144, v145
	v_add_u32_e32 v145, v152, v190
	v_mad_i64_i32 v[132:133], s[4:5], v145, s55, v[132:133]
	v_lshl_add_u64 v[146:147], v[132:133], 0, v[138:139]
	global_store_dword v[146:147], v144, off

.LBB0_272:
	s_and_b64 vcc, exec, s[4:5]
	v_add_u32_e32 v247, 0x8400, v241
	v_add_u32_e32 v248, 0x8800, v241
	v_add_u32_e32 v249, 0x8c00, v241
	v_add_u32_e32 v250, 0x9000, v241
	v_add_u32_e32 v152, 0x8400, v237
	v_add_u32_e32 v153, 0x8800, v237
	v_add_u32_e32 v242, 0x8c00, v237
	v_add_u32_e32 v243, 0x9000, v237
	v_add_u32_e32 v148, 0x8400, v233
	v_add_u32_e32 v149, 0x8800, v233
	v_add_u32_e32 v150, 0x8c00, v233
	v_add_u32_e32 v151, 0x9000, v233
	v_add_u32_e32 v145, 0x8400, v203
	v_add_u32_e32 v144, 0x8800, v203
	s_waitcnt lgkmcnt(1)
	v_add_u32_e32 v133, 0x8c00, v203
	v_add_u32_e32 v132, 0x9000, v203
	s_cbranch_vccz .LBB0_274
	s_waitcnt lgkmcnt(0)
	ds_read2_b32 v[128:129], v247 offset1:132
	ds_read2_b32 v[130:131], v248 offset0:8 offset1:140
	ds_read2_b32 v[134:135], v249 offset0:16 offset1:148
	ds_read2_b32 v[146:147], v250 offset0:24 offset1:156
	v_or_b32_e32 v138, 64, v195
	s_and_b64 s[4:5], exec, s[10:11]
	v_or_b32_e32 v160, s59, v138
	s_cselect_b32 s0, 8, 12
	v_mov_b32_e32 v161, s59
	v_lshrrev_b32_e32 v160, s0, v160
	v_bitop3_b32 v161, v138, s56, v161 bitop3:0xc8
	v_add_u32_e32 v161, 0x100, v161
	v_lshlrev_b32_e32 v160, 7, v160
	v_cndmask_b32_e64 v138, v161, v138, s[10:11]
	s_waitcnt lgkmcnt(3)
	v_cvt_pk_bf16_f32 v128, v128, v129
	s_waitcnt lgkmcnt(2)
	v_cvt_pk_bf16_f32 v129, v130, v131
	s_waitcnt lgkmcnt(1)
	v_cvt_pk_bf16_f32 v130, v134, v135
	s_waitcnt lgkmcnt(0)
	v_cvt_pk_bf16_f32 v131, v146, v147
	v_add_u32_e32 v134, v160, v193
	v_mov_b64_e32 v[146:147], s[28:29]
	v_mad_i64_i32 v[134:135], s[4:5], v134, s55, v[146:147]
	v_lshlrev_b32_e32 v138, 1, v138
	v_lshl_add_u64 v[134:135], v[134:135], 0, v[138:139]
	global_store_dwordx4 v[134:135], v[128:131], off sc1
	ds_read2_b32 v[128:129], v152 offset1:132
	ds_read2_b32 v[130:131], v153 offset0:8 offset1:140
	ds_read2_b32 v[134:135], v242 offset0:16 offset1:148
	ds_read2_b32 v[252:253], v243 offset0:24 offset1:156
	s_waitcnt lgkmcnt(3)
	v_cvt_pk_bf16_f32 v128, v128, v129
	s_waitcnt lgkmcnt(2)
	v_cvt_pk_bf16_f32 v129, v130, v131
	s_waitcnt lgkmcnt(1)
	v_cvt_pk_bf16_f32 v130, v134, v135
	v_add_u32_e32 v134, v160, v192
	v_mad_i64_i32 v[134:135], s[4:5], v134, s55, v[146:147]
	s_waitcnt lgkmcnt(0)
	v_cvt_pk_bf16_f32 v131, v252, v253
	v_lshl_add_u64 v[134:135], v[134:135], 0, v[138:139]
	global_store_dwordx4 v[134:135], v[128:131], off sc1
	ds_read2_b32 v[128:129], v148 offset1:132
	ds_read2_b32 v[130:131], v149 offset0:8 offset1:140
	ds_read2_b32 v[134:135], v150 offset0:16 offset1:148
	ds_read2_b32 v[252:253], v151 offset0:24 offset1:156
	s_waitcnt lgkmcnt(3)
	v_cvt_pk_bf16_f32 v128, v128, v129
	s_waitcnt lgkmcnt(2)
	v_cvt_pk_bf16_f32 v129, v130, v131
	s_waitcnt lgkmcnt(1)
	v_cvt_pk_bf16_f32 v130, v134, v135
	v_add_u32_e32 v134, v160, v191
	v_mad_i64_i32 v[134:135], s[4:5], v134, s55, v[146:147]
	s_waitcnt lgkmcnt(0)
	v_cvt_pk_bf16_f32 v131, v252, v253
	v_lshl_add_u64 v[134:135], v[134:135], 0, v[138:139]
	global_store_dwordx4 v[134:135], v[128:131], off sc1
	ds_read2_b32 v[252:253], v145 offset1:132
	ds_read2_b32 v[134:135], v144 offset0:8 offset1:140
	ds_read2_b32 v[128:129], v133 offset0:16 offset1:148
	ds_read2_b32 v[130:131], v132 offset0:24 offset1:156
	v_add_u32_e32 v160, v160, v190
	v_mad_i64_i32 v[146:147], s[4:5], v160, s55, v[146:147]
	s_waitcnt lgkmcnt(3)
	v_cvt_pk_bf16_f32 v161, v252, v253
	v_lshl_add_u64 v[146:147], v[146:147], 0, v[138:139]
	global_store_dword v[146:147], v161, off

.LBB0_314:
	s_and_b64 vcc, exec, s[4:5]
	s_cbranch_vccz .LBB0_316
	v_or_b32_e32 v8, 0x80, v195
	s_waitcnt lgkmcnt(0)
	ds_read2_b32 v[0:1], v241 offset1:132
	ds_read2_b32 v[2:3], v244 offset0:8 offset1:140
	ds_read2_b32 v[4:5], v245 offset0:16 offset1:148
	ds_read2_b32 v[6:7], v246 offset0:24 offset1:156
	v_mov_b32_e32 v10, s59
	s_and_b64 s[4:5], exec, s[10:11]
	v_bitop3_b32 v10, v8, s57, v10 bitop3:0xc8
	v_or_b32_e32 v9, s59, v8
	s_cselect_b32 s0, 8, 12
	v_add_u32_e32 v10, 0x100, v10
	v_lshrrev_b32_e32 v9, s0, v9
	v_cndmask_b32_e64 v8, v10, v8, s[10:11]
	v_lshlrev_b32_e32 v16, 7, v9
	v_lshlrev_b32_e32 v138, 1, v8
	ds_read2_b32 v[8:9], v237 offset1:132
	ds_read2_b32 v[10:11], v238 offset0:8 offset1:140
	ds_read2_b32 v[12:13], v239 offset0:16 offset1:148
	ds_read2_b32 v[14:15], v240 offset0:24 offset1:156
	s_waitcnt lgkmcnt(7)
	v_cvt_pk_bf16_f32 v0, v0, v1
	s_waitcnt lgkmcnt(6)
	v_cvt_pk_bf16_f32 v1, v2, v3
	s_waitcnt lgkmcnt(5)
	v_cvt_pk_bf16_f32 v2, v4, v5
	s_waitcnt lgkmcnt(4)
	v_cvt_pk_bf16_f32 v3, v6, v7
	v_add_u32_e32 v6, v16, v193
	v_mov_b64_e32 v[4:5], s[28:29]
	v_mad_i64_i32 v[6:7], s[4:5], v6, s55, v[4:5]
	v_lshl_add_u64 v[6:7], v[6:7], 0, v[138:139]
	global_store_dwordx4 v[6:7], v[0:3], off sc1
	v_add_u32_e32 v6, v16, v192
	v_mad_i64_i32 v[6:7], s[4:5], v6, s55, v[4:5]
	s_waitcnt lgkmcnt(3)
	v_cvt_pk_bf16_f32 v0, v8, v9
	s_waitcnt lgkmcnt(2)
	v_cvt_pk_bf16_f32 v1, v10, v11
	s_waitcnt lgkmcnt(1)
	v_cvt_pk_bf16_f32 v2, v12, v13
	s_waitcnt lgkmcnt(0)
	v_cvt_pk_bf16_f32 v3, v14, v15
	ds_read2_b32 v[8:9], v233 offset1:132
	ds_read2_b32 v[10:11], v234 offset0:8 offset1:140
	ds_read2_b32 v[12:13], v235 offset0:16 offset1:148
	ds_read2_b32 v[14:15], v236 offset0:24 offset1:156
	v_lshl_add_u64 v[6:7], v[6:7], 0, v[138:139]
	global_store_dwordx4 v[6:7], v[0:3], off sc1
	v_add_u32_e32 v6, v16, v191
	v_mad_i64_i32 v[6:7], s[4:5], v6, s55, v[4:5]
	s_waitcnt lgkmcnt(3)
	v_cvt_pk_bf16_f32 v0, v8, v9
	s_waitcnt lgkmcnt(2)
	v_cvt_pk_bf16_f32 v1, v10, v11
	s_waitcnt lgkmcnt(1)
	v_cvt_pk_bf16_f32 v2, v12, v13
	s_waitcnt lgkmcnt(0)
	v_cvt_pk_bf16_f32 v3, v14, v15
	v_lshl_add_u64 v[6:7], v[6:7], 0, v[138:139]
	ds_read2_b32 v[8:9], v203 offset1:132
	global_store_dwordx4 v[6:7], v[0:3], off sc1
	ds_read2_b32 v[6:7], v232 offset0:8 offset1:140
	ds_read2_b32 v[0:1], v229 offset0:16 offset1:148
	ds_read2_b32 v[2:3], v226 offset0:24 offset1:156
	s_waitcnt lgkmcnt(3)
	v_cvt_pk_bf16_f32 v8, v8, v9
	v_add_u32_e32 v9, v16, v190
	v_mad_i64_i32 v[4:5], s[4:5], v9, s55, v[4:5]
	v_lshl_add_u64 v[12:13], v[4:5], 0, v[138:139]
	global_store_dword v[12:13], v8, off

.LBB0_354:
	s_and_b64 vcc, exec, s[4:5]
	s_cbranch_vccz .LBB0_187
	v_or_b32_e32 v8, 0xc0, v195
	s_waitcnt lgkmcnt(0)
	ds_read2_b32 v[0:1], v247 offset1:132
	ds_read2_b32 v[2:3], v248 offset0:8 offset1:140
	ds_read2_b32 v[4:5], v249 offset0:16 offset1:148
	ds_read2_b32 v[6:7], v250 offset0:24 offset1:156
	v_mov_b32_e32 v10, s59
	s_and_b64 s[4:5], exec, s[10:11]
	v_bitop3_b32 v10, v8, s58, v10 bitop3:0xc8
	v_or_b32_e32 v9, s59, v8
	s_cselect_b32 s0, 8, 12
	v_add_u32_e32 v10, 0x100, v10
	v_lshrrev_b32_e32 v9, s0, v9
	v_cndmask_b32_e64 v8, v10, v8, s[10:11]
	v_lshlrev_b32_e32 v16, 7, v9
	v_lshlrev_b32_e32 v138, 1, v8
	ds_read2_b32 v[8:9], v152 offset1:132
	ds_read2_b32 v[10:11], v153 offset0:8 offset1:140
	ds_read2_b32 v[12:13], v242 offset0:16 offset1:148
	ds_read2_b32 v[14:15], v243 offset0:24 offset1:156
	s_waitcnt lgkmcnt(7)
	v_cvt_pk_bf16_f32 v0, v0, v1
	s_waitcnt lgkmcnt(6)
	v_cvt_pk_bf16_f32 v1, v2, v3
	s_waitcnt lgkmcnt(5)
	v_cvt_pk_bf16_f32 v2, v4, v5
	s_waitcnt lgkmcnt(4)
	v_cvt_pk_bf16_f32 v3, v6, v7
	v_add_u32_e32 v6, v16, v193
	v_mov_b64_e32 v[4:5], s[28:29]
	v_mad_i64_i32 v[6:7], s[4:5], v6, s55, v[4:5]
	v_lshl_add_u64 v[6:7], v[6:7], 0, v[138:139]
	global_store_dwordx4 v[6:7], v[0:3], off sc1
	v_add_u32_e32 v6, v16, v192
	v_mad_i64_i32 v[6:7], s[4:5], v6, s55, v[4:5]
	s_waitcnt lgkmcnt(3)
	v_cvt_pk_bf16_f32 v0, v8, v9
	s_waitcnt lgkmcnt(2)
	v_cvt_pk_bf16_f32 v1, v10, v11
	s_waitcnt lgkmcnt(1)
	v_cvt_pk_bf16_f32 v2, v12, v13
	s_waitcnt lgkmcnt(0)
	v_cvt_pk_bf16_f32 v3, v14, v15
	ds_read2_b32 v[8:9], v148 offset1:132
	ds_read2_b32 v[10:11], v149 offset0:8 offset1:140
	ds_read2_b32 v[12:13], v150 offset0:16 offset1:148
	ds_read2_b32 v[14:15], v151 offset0:24 offset1:156
	v_lshl_add_u64 v[6:7], v[6:7], 0, v[138:139]
	global_store_dwordx4 v[6:7], v[0:3], off sc1
	v_add_u32_e32 v6, v16, v191
	v_mad_i64_i32 v[6:7], s[4:5], v6, s55, v[4:5]
	s_waitcnt lgkmcnt(3)
	v_cvt_pk_bf16_f32 v0, v8, v9
	s_waitcnt lgkmcnt(2)
	v_cvt_pk_bf16_f32 v1, v10, v11
	s_waitcnt lgkmcnt(1)
	v_cvt_pk_bf16_f32 v2, v12, v13
	s_waitcnt lgkmcnt(0)
	v_cvt_pk_bf16_f32 v3, v14, v15
	v_lshl_add_u64 v[6:7], v[6:7], 0, v[138:139]
	ds_read2_b32 v[8:9], v145 offset1:132
	global_store_dwordx4 v[6:7], v[0:3], off sc1
	ds_read2_b32 v[6:7], v144 offset0:8 offset1:140
	ds_read2_b32 v[0:1], v133 offset0:16 offset1:148
	ds_read2_b32 v[2:3], v132 offset0:24 offset1:156
	s_waitcnt lgkmcnt(3)
	v_cvt_pk_bf16_f32 v8, v8, v9
	v_add_u32_e32 v9, v16, v190
	v_mad_i64_i32 v[4:5], s[4:5], v9, s55, v[4:5]
	v_lshl_add_u64 v[12:13], v[4:5], 0, v[138:139]
	global_store_dword v[12:13], v8, off
	s_branch .LBB0_187

.LBB0_451:
	s_andn2_b32 s26, 0x4000, s52
	v_and_b32_e32 v76, 7, v64
	v_ashrrev_i32_e32 v77, 3, v64
	v_lshrrev_b32_e32 v66, 5, v64
	s_add_i32 s56, s26, 0
	v_bitop3_b32 v66, v66, v76, 15 bitop3:0x6c
	v_lshlrev_b32_e32 v67, 2, v77
	v_lshl_add_u32 v66, v66, 4, s56
	v_and_b32_e32 v67, 12, v67
	v_lshlrev_b32_e32 v78, 11, v76
	v_add3_u32 v72, v66, v67, v78
	ds_read2st64_b32 v[66:67], v72 offset0:144 offset1:145
	ds_read2st64_b32 v[68:69], v72 offset0:146 offset1:147
	ds_read2st64_b32 v[70:71], v72 offset0:148 offset1:149
	ds_read2st64_b32 v[72:73], v72 offset0:150 offset1:151
	v_add_u32_e32 v64, 0x100, v64
	v_ashrrev_i32_e32 v82, 3, v64
	v_lshrrev_b32_e32 v64, 5, v64
	s_lshl_b64 s[26:27], s[0:1], 1
	s_waitcnt lgkmcnt(0)
	v_cvt_pk_bf16_f32 v66, v66, v67
	v_cvt_pk_bf16_f32 v67, v68, v69
	v_cvt_pk_bf16_f32 v69, v72, v73
	v_bitop3_b32 v64, v64, v76, 15 bitop3:0x6c
	v_lshlrev_b32_e32 v72, 2, v82
	s_add_u32 s4, s4, s26
	v_cvt_pk_bf16_f32 v68, v70, v71
	v_add_u32_e32 v70, s55, v77
	v_lshl_add_u32 v64, v64, 4, s56
	v_and_b32_e32 v72, 12, v72
	s_addc_u32 s5, s5, s27
	v_lshlrev_b32_e32 v182, 4, v76
	v_ashrrev_i32_e32 v71, 31, v70
	v_add3_u32 v64, v64, v72, v78
	v_lshl_add_u64 v[74:75], s[4:5], 0, v[182:183]
	v_lshlrev_b64 v[70:71], 11, v[70:71]
	ds_read2st64_b32 v[72:73], v64 offset0:144 offset1:145
	ds_read2st64_b32 v[76:77], v64 offset0:146 offset1:147
	ds_read2st64_b32 v[78:79], v64 offset0:148 offset1:149
	ds_read2st64_b32 v[80:81], v64 offset0:150 offset1:151
	v_lshl_add_u64 v[70:71], v[74:75], 0, v[70:71]
	global_store_dwordx4 v[70:71], v[66:69], off sc1 nt
	v_add_u32_e32 v70, s55, v82
	v_ashrrev_i32_e32 v71, 31, v70
	v_lshlrev_b64 v[70:71], 11, v[70:71]
	s_waitcnt lgkmcnt(0)
	v_cvt_pk_bf16_f32 v66, v72, v73
	v_cvt_pk_bf16_f32 v67, v76, v77
	v_cvt_pk_bf16_f32 v68, v78, v79
	v_cvt_pk_bf16_f32 v69, v80, v81
	v_lshl_add_u64 v[70:71], v[74:75], 0, v[70:71]
	global_store_dwordx4 v[70:71], v[66:69], off sc1 nt

.LBB0_470:
	v_and_b32_e32 v67, 7, v189
	v_ashrrev_i32_e32 v78, 3, v189
	v_lshrrev_b32_e32 v68, 5, v189
	v_bitop3_b32 v68, v68, v67, 15 bitop3:0x6c
	v_lshlrev_b32_e32 v69, 2, v78
	v_lshl_add_u32 v68, v68, 4, 0
	v_and_b32_e32 v69, 12, v69
	v_lshlrev_b32_e32 v79, 11, v67
	v_add3_u32 v74, v68, v69, v79
	ds_read2st64_b32 v[68:69], v74 offset0:144 offset1:145
	ds_read2st64_b32 v[70:71], v74 offset0:146 offset1:147
	ds_read2st64_b32 v[72:73], v74 offset0:148 offset1:149
	ds_read2st64_b32 v[74:75], v74 offset0:150 offset1:151
	s_lshl_b64 s[26:27], s[0:1], 1
	s_waitcnt lgkmcnt(3)
	v_cvt_pk_bf16_f32 v68, v68, v69
	s_waitcnt lgkmcnt(2)
	v_cvt_pk_bf16_f32 v69, v70, v71
	v_lshlrev_b32_e32 v182, 4, v67
	s_waitcnt lgkmcnt(0)
	v_cvt_pk_bf16_f32 v71, v74, v75
	v_add_u32_e32 v74, 0x100, v189
	v_ashrrev_i32_e32 v84, 3, v74
	v_lshrrev_b32_e32 v74, 5, v74
	v_bitop3_b32 v67, v74, v67, 15 bitop3:0x6c
	v_lshlrev_b32_e32 v74, 2, v84
	s_add_u32 s4, s4, s26
	v_cvt_pk_bf16_f32 v70, v72, v73
	v_add_u32_e32 v72, s25, v78
	v_lshl_add_u32 v67, v67, 4, 0
	v_and_b32_e32 v74, 12, v74
	s_addc_u32 s5, s5, s27
	v_ashrrev_i32_e32 v73, 31, v72
	v_add3_u32 v67, v67, v74, v79
	v_lshl_add_u64 v[76:77], s[4:5], 0, v[182:183]
	v_lshlrev_b64 v[72:73], 11, v[72:73]
	ds_read2st64_b32 v[74:75], v67 offset0:144 offset1:145
	ds_read2st64_b32 v[78:79], v67 offset0:146 offset1:147
	ds_read2st64_b32 v[80:81], v67 offset0:148 offset1:149
	ds_read2st64_b32 v[82:83], v67 offset0:150 offset1:151
	v_lshl_add_u64 v[72:73], v[76:77], 0, v[72:73]
	global_store_dwordx4 v[72:73], v[68:71], off sc1 nt
	v_add_u32_e32 v72, s25, v84
	v_ashrrev_i32_e32 v73, 31, v72
	v_lshlrev_b64 v[72:73], 11, v[72:73]
	s_waitcnt lgkmcnt(3)
	v_cvt_pk_bf16_f32 v68, v74, v75
	s_waitcnt lgkmcnt(2)
	v_cvt_pk_bf16_f32 v69, v78, v79
	s_waitcnt lgkmcnt(1)
	v_cvt_pk_bf16_f32 v70, v80, v81
	s_waitcnt lgkmcnt(0)
	v_cvt_pk_bf16_f32 v71, v82, v83
	v_lshl_add_u64 v[72:73], v[76:77], 0, v[72:73]
	global_store_dwordx4 v[72:73], v[68:71], off sc1 nt

.LBB0_480:
	s_cmpk_gt_i32 s4, 0x63ff
	s_cbranch_scc1 .LBB0_479
	s_cmpk_gt_i32 s4, 0x2ff
	s_mov_b64 s[2:3], -1
	s_cbranch_scc0 .LBB0_487
	s_cmpk_gt_u32 s4, 0x3ff
	s_cbranch_scc0 .LBB0_484
	s_add_i32 s0, s4, 0xfffffc00
	s_and_b32 s2, s0, 0xffffe000
	s_cmpk_eq_i32 s2, 0x2000
	s_cselect_b32 s2, s11, 0xb0
	s_cselect_b32 s3, s12, 0x8ca0000
	s_cmpk_lt_u32 s0, 0x2000
	s_cselect_b32 s0, 0xa0, s2
	s_cselect_b32 s14, 0xca0000, s3
	v_readlane_b32 s2, v255, 2
	v_readlane_b32 s3, v255, 3
	s_add_u32 s2, s2, s0
	s_addc_u32 s3, s3, 0
	s_load_dwordx2 s[2:3], s[2:3], 0x0
	s_and_b32 s0, s5, 0x1f00000
	s_lshl_b32 s15, s0, 2
	v_mov_b32_e32 v11, v1
	s_waitcnt lgkmcnt(0)
	s_add_u32 s2, s2, s15
	s_addc_u32 s3, s3, 0
	s_add_u32 s14, s94, s14
	s_addc_u32 s15, s95, 0
	s_lshl_b32 s0, s0, 1
	s_add_u32 s0, s14, s0
	s_addc_u32 s14, s15, 0
	s_and_b32 s16, s9, 0x3c0
	s_and_b32 s15, s7, 0x3c0
	s_lshl_b32 s17, s16, 2
	s_add_u32 s2, s2, s17
	s_addc_u32 s3, s3, 0
	v_or_b32_e32 v0, s15, v22
	v_lshl_add_u64 v[14:15], s[2:3], 0, v[10:11]
	v_lshlrev_b32_e32 v0, 10, v0
	v_lshl_add_u64 v[20:21], v[0:1], 2, v[14:15]
	v_add_lshl_u32 v0, s15, v23, 10
	s_barrier
	v_lshl_add_u64 v[44:45], v[0:1], 2, v[14:15]
	global_load_dwordx4 v[16:19], v[20:21], off nt
	global_load_dwordx4 v[40:43], v[44:45], off nt
	v_add_lshl_u32 v0, s15, v24, 10
	v_lshl_add_u64 v[20:21], v[0:1], 2, v[14:15]
	global_load_dwordx4 v[44:47], v[20:21], off nt
	v_add_lshl_u32 v0, s15, v25, 10
	v_lshl_add_u64 v[14:15], v[0:1], 2, v[14:15]
	global_load_dwordx4 v[48:51], v[14:15], off nt
	s_lshl_b32 s2, s15, 1
	s_add_u32 s2, s0, s2
	v_mov_b32_e32 v13, v1
	s_addc_u32 s3, s14, 0
	v_lshl_add_u64 v[14:15], s[2:3], 0, v[12:13]
	v_add_lshl_u32 v0, s16, v26, 11
	v_lshl_add_u64 v[52:53], v[14:15], 0, v[0:1]
	v_add_lshl_u32 v0, s16, v27, 11
	v_lshl_add_u64 v[14:15], v[14:15], 0, v[0:1]
	s_mov_b64 s[2:3], 0
	s_waitcnt vmcnt(3)
	ds_write2_b32 v28, v16, v17 offset1:1
	ds_write2_b32 v28, v18, v19 offset0:2 offset1:3
	s_waitcnt vmcnt(2)
	ds_write2_b32 v29, v40, v41 offset1:1
	ds_write2_b32 v30, v42, v43 offset1:1
	s_waitcnt vmcnt(1)
	ds_write2_b32 v31, v44, v45 offset1:1
	ds_write2_b32 v32, v46, v47 offset1:1
	s_waitcnt vmcnt(0)
	ds_write2_b32 v33, v48, v49 offset1:1
	ds_write2_b32 v34, v50, v51 offset1:1
	s_waitcnt lgkmcnt(0)
	s_barrier
	ds_read2_b32 v[40:41], v35 offset1:65
	ds_read2_b32 v[42:43], v35 offset0:130 offset1:195
	ds_read2_b32 v[44:45], v37 offset0:4 offset1:69
	ds_read2_b32 v[46:47], v37 offset0:134 offset1:199
	ds_read2_b32 v[48:49], v36 offset1:65
	ds_read2_b32 v[16:17], v36 offset0:130 offset1:195
	ds_read2_b32 v[18:19], v38 offset0:4 offset1:69
	ds_read2_b32 v[20:21], v38 offset0:134 offset1:199
	s_waitcnt lgkmcnt(7)
	v_cvt_pk_bf16_f32 v40, v40, v41
	s_waitcnt lgkmcnt(6)
	v_cvt_pk_bf16_f32 v41, v42, v43
	s_waitcnt lgkmcnt(5)
	v_cvt_pk_bf16_f32 v42, v44, v45
	s_waitcnt lgkmcnt(4)
	v_cvt_pk_bf16_f32 v43, v46, v47
	s_waitcnt lgkmcnt(3)
	v_cvt_pk_bf16_f32 v0, v48, v49
	global_store_dwordx4 v[52:53], v[40:43], off sc1
	global_store_dword v[14:15], v0, off
.LBB0_484:
	s_andn2_b64 vcc, exec, s[2:3]
	s_cbranch_vccnz .LBB0_486
	s_and_b32 s0, s7, 0xfc0
	s_add_i32 s2, s0, 0xfffff400
	s_and_b32 s14, s9, 0x3c0
	s_lshl_b32 s0, s14, 2
	v_or_b32_e32 v0, s2, v22
	v_lshl_add_u64 v[14:15], v[2:3], 0, s[0:1]
	s_waitcnt lgkmcnt(2)
	v_lshlrev_b64 v[16:17], 12, v[0:1]
	v_add_u32_e32 v0, s2, v23
	s_waitcnt lgkmcnt(0)
	v_lshl_add_u64 v[20:21], v[14:15], 0, v[16:17]
	v_lshlrev_b64 v[16:17], 12, v[0:1]
	s_barrier
	v_lshl_add_u64 v[44:45], v[14:15], 0, v[16:17]
	global_load_dwordx4 v[16:19], v[20:21], off nt
	global_load_dwordx4 v[40:43], v[44:45], off nt
	v_add_u32_e32 v0, s2, v24
	v_lshlrev_b64 v[20:21], 12, v[0:1]
	v_lshl_add_u64 v[20:21], v[14:15], 0, v[20:21]
	v_add_u32_e32 v0, s2, v25
	global_load_dwordx4 v[44:47], v[20:21], off nt
	v_lshlrev_b64 v[20:21], 12, v[0:1]
	v_lshl_add_u64 v[14:15], v[14:15], 0, v[20:21]
	global_load_dwordx4 v[48:51], v[14:15], off nt
	s_mov_b32 s3, s1
	v_lshl_add_u64 v[14:15], s[2:3], 1, v[4:5]
	v_add_lshl_u32 v0, s14, v26, 11
	v_lshl_add_u64 v[52:53], v[14:15], 0, v[0:1]
	v_add_lshl_u32 v0, s14, v27, 11
	v_lshl_add_u64 v[14:15], v[14:15], 0, v[0:1]
	s_waitcnt vmcnt(3)
	ds_write2_b32 v28, v16, v17 offset1:1
	ds_write2_b32 v28, v18, v19 offset0:2 offset1:3
	s_waitcnt vmcnt(2)
	ds_write2_b32 v29, v40, v41 offset1:1
	ds_write2_b32 v30, v42, v43 offset1:1
	s_waitcnt vmcnt(1)
	ds_write2_b32 v31, v44, v45 offset1:1
	ds_write2_b32 v32, v46, v47 offset1:1
	s_waitcnt vmcnt(0)
	ds_write2_b32 v33, v48, v49 offset1:1
	ds_write2_b32 v34, v50, v51 offset1:1
	s_waitcnt lgkmcnt(0)
	s_barrier
	ds_read2_b32 v[40:41], v35 offset1:65
	ds_read2_b32 v[42:43], v35 offset0:130 offset1:195
	ds_read2_b32 v[44:45], v37 offset0:4 offset1:69
	ds_read2_b32 v[46:47], v37 offset0:134 offset1:199
	ds_read2_b32 v[48:49], v36 offset1:65
	ds_read2_b32 v[16:17], v36 offset0:130 offset1:195
	ds_read2_b32 v[18:19], v38 offset0:4 offset1:69
	ds_read2_b32 v[20:21], v38 offset0:134 offset1:199
	s_waitcnt lgkmcnt(7)
	v_cvt_pk_bf16_f32 v40, v40, v41
	s_waitcnt lgkmcnt(6)
	v_cvt_pk_bf16_f32 v41, v42, v43
	s_waitcnt lgkmcnt(5)
	v_cvt_pk_bf16_f32 v42, v44, v45
	s_waitcnt lgkmcnt(4)
	v_cvt_pk_bf16_f32 v43, v46, v47
	s_waitcnt lgkmcnt(3)
	v_cvt_pk_bf16_f32 v0, v48, v49
	global_store_dwordx4 v[52:53], v[40:43], off sc1
	global_store_dword v[14:15], v0, off

.LBB0_487:
	s_andn2_b64 vcc, exec, s[2:3]
	s_cbranch_vccnz .LBB0_478
	s_mul_hi_i32 s0, s4, 0x2aaaaaab
	s_lshr_b32 s2, s0, 31
	s_ashr_i32 s0, s0, 3
	s_add_i32 s0, s0, s2
	s_mul_i32 s2, s0, 48
	s_sub_i32 s3, s4, s2
	s_lshl_b32 s14, s3, 6
	s_lshl_b32 s2, s0, 6
	s_ashr_i32 s15, s14, 31
	v_lshl_add_u64 v[14:15], s[14:15], 2, v[6:7]
	v_or_b32_e32 v0, s2, v22
	s_waitcnt lgkmcnt(0)
	v_mad_i64_i32 v[20:21], s[16:17], v0, s13, v[14:15]
	v_add_u32_e32 v0, s2, v23
	s_barrier
	v_mad_i64_i32 v[44:45], s[16:17], v0, s13, v[14:15]
	global_load_dwordx4 v[16:19], v[20:21], off nt
	global_load_dwordx4 v[40:43], v[44:45], off nt
	v_add_u32_e32 v0, s2, v24
	v_mad_i64_i32 v[20:21], s[16:17], v0, s13, v[14:15]
	global_load_dwordx4 v[44:47], v[20:21], off nt
	v_add_u32_e32 v0, s2, v25
	v_mad_i64_i32 v[14:15], s[16:17], v0, s13, v[14:15]
	global_load_dwordx4 v[48:51], v[14:15], off nt
	v_add_u32_e32 v20, s14, v26
	s_ashr_i32 s3, s2, 31
	v_add_u32_e32 v52, s14, v27
	v_ashrrev_i32_e32 v21, 31, v20
	v_lshl_add_u64 v[14:15], s[2:3], 1, v[8:9]
	v_ashrrev_i32_e32 v53, 31, v52
	v_lshlrev_b64 v[20:21], 11, v[20:21]
	v_lshlrev_b64 v[52:53], 11, v[52:53]
	v_lshl_add_u64 v[54:55], v[14:15], 0, v[20:21]
	v_lshl_add_u64 v[14:15], v[14:15], 0, v[52:53]
	s_waitcnt vmcnt(3)
	ds_write2_b32 v28, v16, v17 offset1:1
	ds_write2_b32 v28, v18, v19 offset0:2 offset1:3
	s_waitcnt vmcnt(2)
	ds_write2_b32 v29, v40, v41 offset1:1
	ds_write2_b32 v30, v42, v43 offset1:1
	s_waitcnt vmcnt(1)
	ds_write2_b32 v31, v44, v45 offset1:1
	ds_write2_b32 v32, v46, v47 offset1:1
	s_waitcnt vmcnt(0)
	ds_write2_b32 v33, v48, v49 offset1:1
	ds_write2_b32 v34, v50, v51 offset1:1
	s_waitcnt lgkmcnt(0)
	s_barrier
	ds_read2_b32 v[40:41], v35 offset1:65
	ds_read2_b32 v[42:43], v35 offset0:130 offset1:195
	ds_read2_b32 v[44:45], v37 offset0:4 offset1:69
	ds_read2_b32 v[46:47], v37 offset0:134 offset1:199
	ds_read2_b32 v[48:49], v36 offset1:65
	ds_read2_b32 v[16:17], v36 offset0:130 offset1:195
	ds_read2_b32 v[18:19], v38 offset0:4 offset1:69
	ds_read2_b32 v[20:21], v38 offset0:134 offset1:199
	s_waitcnt lgkmcnt(7)
	v_cvt_pk_bf16_f32 v40, v40, v41
	s_waitcnt lgkmcnt(6)
	v_cvt_pk_bf16_f32 v41, v42, v43
	s_waitcnt lgkmcnt(5)
	v_cvt_pk_bf16_f32 v42, v44, v45
	s_waitcnt lgkmcnt(4)
	v_cvt_pk_bf16_f32 v43, v46, v47
	s_waitcnt lgkmcnt(3)
	v_cvt_pk_bf16_f32 v0, v48, v49
	global_store_dwordx4 v[54:55], v[40:43], off sc1
	global_store_dword v[14:15], v0, off
	s_branch .LBB0_478

.LBB0_491:
	s_waitcnt lgkmcnt(0)
	v_cvt_pk_bf16_f32 v7, v6, v7
	v_cvt_pk_bf16_f32 v6, v4, v5
	v_cvt_pk_bf16_f32 v4, v0, v1
	v_lshlrev_b64 v[0:1], 11, v[152:153]
	v_lshl_add_u64 v[0:1], s[4:5], 0, v[0:1]
	v_lshl_add_u64 v[0:1], v[0:1], 0, v[136:137]
	v_add_co_u32_e32 v0, vcc, 0x60000, v0
	s_add_i32 s28, s28, s29
	v_cvt_pk_bf16_f32 v5, v2, v3
	v_addc_co_u32_e32 v1, vcc, 0, v1, vcc
	s_cmp_lt_u32 s28, 32
	global_store_dwordx4 v[0:1], v[4:7], off sc1
	s_barrier
	s_cbranch_scc0 .LBB0_543

.LBB0_493:
	v_cvt_f32_i32_e32 v6, v6
	s_addk_i32 s42, 0x100
	s_cmpk_eq_i32 s42, 0x1000
	v_div_scale_f32 v7, s[4:5], v6, v6, 1.0
	v_rcp_f32_e32 v14, v7
	v_div_scale_f32 v15, vcc, 1.0, v6, 1.0
	v_fma_f32 v16, -v7, v14, 1.0
	v_fmac_f32_e32 v14, v16, v14
	v_mul_f32_e32 v16, v15, v14
	v_fma_f32 v17, -v7, v16, v15
	v_fmac_f32_e32 v16, v17, v14
	v_fma_f32 v7, -v7, v16, v15
	v_div_fmas_f32 v7, v7, v14, v16
	v_div_fixup_f32 v6, v7, v6, 1.0
	v_pk_fma_f32 v[14:15], v[42:43], v[6:7], v[36:37] op_sel_hi:[1,0,1] neg_lo:[0,0,1] neg_hi:[0,0,1]
	v_pk_fma_f32 v[4:5], v[6:7], v[4:5], v[8:9] op_sel_hi:[0,1,1] neg_lo:[0,0,1] neg_hi:[0,0,1]
	v_pk_fma_f32 v[8:9], v[6:7], v[12:13], v[0:1] op_sel_hi:[0,1,1] neg_lo:[0,0,1] neg_hi:[0,0,1]
	v_pk_fma_f32 v[6:7], v[6:7], v[2:3], v[10:11] op_sel_hi:[0,1,1] neg_lo:[0,0,1] neg_hi:[0,0,1]
	v_cvt_pk_bf16_f32 v0, v14, v15
	v_cvt_pk_bf16_f32 v1, v4, v5
	v_cvt_pk_bf16_f32 v2, v8, v9
	v_cvt_pk_bf16_f32 v3, v6, v7
	v_lshl_add_u64 v[4:5], v[140:141], 0, v[32:33]
	global_store_dwordx4 v[4:5], v[0:3], off sc1
	s_cbranch_scc1 .LBB0_505

.LBB0_511:
	s_lshl_b32 s0, s41, 17
	s_add_u32 s0, s94, s0
	s_addc_u32 s4, s95, 0
	s_add_u32 s0, s0, s37
	v_add_u32_e32 v150, 0x100, v152
	s_addc_u32 s5, s4, 0
	v_ashrrev_i32_e32 v150, 4, v150
	s_add_u32 s4, s0, 0x108de400
	v_mul_lo_u32 v151, v150, s24
	v_ashrrev_i32_e32 v157, 31, v156
	s_addc_u32 s5, s5, 0
	s_waitcnt lgkmcnt(0)
	v_cvt_pk_bf16_f32 v210, v128, v129
	v_lshlrev_b64 v[128:129], 11, v[156:157]
	v_add_u32_e32 v172, v153, v151
	v_cvt_pk_bf16_f32 v208, v132, v133
	v_cvt_pk_bf16_f32 v209, v134, v135
	v_cvt_pk_bf16_f32 v211, v130, v131
	v_lshl_add_u64 v[154:155], s[4:5], 0, v[128:129]
	ds_read_b128 v[132:135], v172
	ds_read_b128 v[128:131], v172 offset:16
	v_lshlrev_b32_e32 v136, 1, v136
	v_lshl_add_u64 v[154:155], v[154:155], 0, v[136:137]
	s_and_b64 vcc, exec, s[10:11]
	global_store_dwordx4 v[154:155], v[208:211], off sc1
	s_cbranch_vccnz .LBB0_513
	global_load_dwordx4 v[208:211], v170, s[16:17]
	global_load_dwordx4 v[214:217], v170, s[16:17] offset:16
	s_waitcnt vmcnt(1) lgkmcnt(1)
	v_pk_mul_f32 v[132:133], v[132:133], v[208:209]
	v_pk_mul_f32 v[134:135], v[134:135], v[210:211]
	s_waitcnt vmcnt(0) lgkmcnt(0)
	v_pk_mul_f32 v[128:129], v[128:129], v[214:215]
	v_pk_mul_f32 v[130:131], v[130:131], v[216:217]
.LBB0_513:
	v_add_u32_e32 v151, 0x200, v152
	v_ashrrev_i32_e32 v154, 4, v151
	v_mul_lo_u32 v155, v154, s24
	v_add_u32_e32 v173, v153, v155
	s_waitcnt lgkmcnt(1)
	v_cvt_pk_bf16_f32 v208, v132, v133
	v_cvt_pk_bf16_f32 v209, v134, v135
	s_waitcnt lgkmcnt(0)
	v_cvt_pk_bf16_f32 v210, v128, v129
	v_cvt_pk_bf16_f32 v211, v130, v131
	ds_read_b128 v[132:135], v173
	ds_read_b128 v[128:131], v173 offset:16
	v_ashrrev_i32_e32 v151, 31, v150
	v_lshlrev_b64 v[214:215], 11, v[150:151]
	v_lshl_add_u64 v[214:215], s[4:5], 0, v[214:215]
	v_lshl_add_u64 v[214:215], v[214:215], 0, v[136:137]
	s_and_b64 vcc, exec, s[10:11]
	global_store_dwordx4 v[214:215], v[208:211], off sc1
	s_cbranch_vccnz .LBB0_515
	global_load_dwordx4 v[208:211], v170, s[16:17]
	global_load_dwordx4 v[214:217], v170, s[16:17] offset:16
	s_waitcnt vmcnt(1) lgkmcnt(1)
	v_pk_mul_f32 v[132:133], v[132:133], v[208:209]
	v_pk_mul_f32 v[134:135], v[134:135], v[210:211]
	s_waitcnt vmcnt(0) lgkmcnt(0)
	v_pk_mul_f32 v[128:129], v[128:129], v[214:215]
	v_pk_mul_f32 v[130:131], v[130:131], v[216:217]
.LBB0_515:
	v_add_u32_e32 v152, 0x300, v152
	v_ashrrev_i32_e32 v152, 4, v152
	v_mul_lo_u32 v174, v152, s24
	v_add_u32_e32 v174, v153, v174
	s_waitcnt lgkmcnt(1)
	v_cvt_pk_bf16_f32 v208, v132, v133
	v_cvt_pk_bf16_f32 v209, v134, v135
	s_waitcnt lgkmcnt(0)
	v_cvt_pk_bf16_f32 v210, v128, v129
	v_cvt_pk_bf16_f32 v211, v130, v131
	ds_read_b128 v[128:131], v174
	ds_read_b128 v[132:135], v174 offset:16
	v_ashrrev_i32_e32 v155, 31, v154
	v_lshlrev_b64 v[214:215], 11, v[154:155]
	v_lshl_add_u64 v[214:215], s[4:5], 0, v[214:215]
	v_lshl_add_u64 v[214:215], v[214:215], 0, v[136:137]
	s_and_b64 vcc, exec, s[10:11]
	global_store_dwordx4 v[214:215], v[208:211], off sc1
	s_cbranch_vccnz .LBB0_517
	global_load_dwordx4 v[208:211], v170, s[16:17]
	global_load_dwordx4 v[214:217], v170, s[16:17] offset:16
	s_waitcnt vmcnt(1) lgkmcnt(1)
	v_pk_mul_f32 v[128:129], v[128:129], v[208:209]
	v_pk_mul_f32 v[130:131], v[130:131], v[210:211]
	s_waitcnt vmcnt(0) lgkmcnt(0)
	v_pk_mul_f32 v[132:133], v[132:133], v[214:215]
	v_pk_mul_f32 v[134:135], v[134:135], v[216:217]
.LBB0_517:
	s_waitcnt lgkmcnt(0)
	v_cvt_pk_bf16_f32 v211, v134, v135
	v_cvt_pk_bf16_f32 v210, v132, v133
	v_cvt_pk_bf16_f32 v209, v130, v131
	v_cvt_pk_bf16_f32 v208, v128, v129
	ds_read_b128 v[132:135], v171 offset:33792
	ds_read_b128 v[128:131], v171 offset:33808
	v_ashrrev_i32_e32 v153, 31, v152
	v_lshlrev_b64 v[214:215], 11, v[152:153]
	v_lshl_add_u64 v[214:215], s[4:5], 0, v[214:215]
	v_lshl_add_u64 v[214:215], v[214:215], 0, v[136:137]
	s_and_b64 vcc, exec, s[10:11]
	global_store_dwordx4 v[214:215], v[208:211], off sc1
	s_cbranch_vccnz .LBB0_519
	global_load_dwordx4 v[208:211], v170, s[16:17]
	global_load_dwordx4 v[214:217], v170, s[16:17] offset:16
	s_waitcnt vmcnt(1) lgkmcnt(1)
	v_pk_mul_f32 v[132:133], v[132:133], v[208:209]
	v_pk_mul_f32 v[134:135], v[134:135], v[210:211]
	s_waitcnt vmcnt(0) lgkmcnt(0)
	v_pk_mul_f32 v[128:129], v[128:129], v[214:215]
	v_pk_mul_f32 v[130:131], v[130:131], v[216:217]
.LBB0_519:
	s_waitcnt lgkmcnt(0)
	v_cvt_pk_bf16_f32 v210, v128, v129
	v_lshlrev_b64 v[128:129], 11, v[156:157]
	v_lshl_add_u64 v[128:129], s[4:5], 0, v[128:129]
	v_cvt_pk_bf16_f32 v208, v132, v133
	v_cvt_pk_bf16_f32 v209, v134, v135
	v_cvt_pk_bf16_f32 v211, v130, v131
	v_lshl_add_u64 v[214:215], v[128:129], 0, v[136:137]
	ds_read_b128 v[132:135], v172 offset:33792
	ds_read_b128 v[128:131], v172 offset:33808
	v_add_co_u32_e32 v214, vcc, s38, v214
	s_nop 1
	v_addc_co_u32_e32 v215, vcc, 0, v215, vcc
	s_and_b64 vcc, exec, s[10:11]
	global_store_dwordx4 v[214:215], v[208:211], off sc1
	s_cbranch_vccnz .LBB0_521
	global_load_dwordx4 v[208:211], v170, s[16:17]
	global_load_dwordx4 v[214:217], v170, s[16:17] offset:16
	s_waitcnt vmcnt(1) lgkmcnt(1)
	v_pk_mul_f32 v[132:133], v[132:133], v[208:209]
	v_pk_mul_f32 v[134:135], v[134:135], v[210:211]
	s_waitcnt vmcnt(0) lgkmcnt(0)
	v_pk_mul_f32 v[128:129], v[128:129], v[214:215]
	v_pk_mul_f32 v[130:131], v[130:131], v[216:217]
.LBB0_521:
	s_waitcnt lgkmcnt(0)
	v_cvt_pk_bf16_f32 v210, v128, v129
	v_lshlrev_b64 v[128:129], 11, v[150:151]
	v_lshl_add_u64 v[128:129], s[4:5], 0, v[128:129]
	v_cvt_pk_bf16_f32 v208, v132, v133
	v_cvt_pk_bf16_f32 v209, v134, v135
	v_cvt_pk_bf16_f32 v211, v130, v131
	v_lshl_add_u64 v[214:215], v[128:129], 0, v[136:137]
	ds_read_b128 v[132:135], v173 offset:33792
	ds_read_b128 v[128:131], v173 offset:33808
	v_add_co_u32_e32 v214, vcc, s38, v214
	s_nop 1
	v_addc_co_u32_e32 v215, vcc, 0, v215, vcc
	s_and_b64 vcc, exec, s[10:11]
	global_store_dwordx4 v[214:215], v[208:211], off sc1
	s_cbranch_vccnz .LBB0_523
	global_load_dwordx4 v[208:211], v170, s[16:17]
	global_load_dwordx4 v[214:217], v170, s[16:17] offset:16
	s_waitcnt vmcnt(1) lgkmcnt(1)
	v_pk_mul_f32 v[132:133], v[132:133], v[208:209]
	v_pk_mul_f32 v[134:135], v[134:135], v[210:211]
	s_waitcnt vmcnt(0) lgkmcnt(0)
	v_pk_mul_f32 v[128:129], v[128:129], v[214:215]
	v_pk_mul_f32 v[130:131], v[130:131], v[216:217]
.LBB0_523:
	s_waitcnt lgkmcnt(0)
	v_cvt_pk_bf16_f32 v210, v128, v129
	v_lshlrev_b64 v[128:129], 11, v[154:155]
	v_lshl_add_u64 v[128:129], s[4:5], 0, v[128:129]
	v_cvt_pk_bf16_f32 v208, v132, v133
	v_cvt_pk_bf16_f32 v209, v134, v135
	v_cvt_pk_bf16_f32 v211, v130, v131
	v_lshl_add_u64 v[214:215], v[128:129], 0, v[136:137]
	ds_read_b128 v[128:131], v174 offset:33792
	ds_read_b128 v[132:135], v174 offset:33808
	v_add_co_u32_e32 v214, vcc, s38, v214
	s_nop 1
	v_addc_co_u32_e32 v215, vcc, 0, v215, vcc
	s_and_b64 vcc, exec, s[10:11]
	global_store_dwordx4 v[214:215], v[208:211], off sc1
	s_cbranch_vccnz .LBB0_525
	global_load_dwordx4 v[208:211], v170, s[16:17]
	global_load_dwordx4 v[214:217], v170, s[16:17] offset:16
	s_waitcnt vmcnt(1) lgkmcnt(1)
	v_pk_mul_f32 v[128:129], v[128:129], v[208:209]
	v_pk_mul_f32 v[130:131], v[130:131], v[210:211]
	s_waitcnt vmcnt(0) lgkmcnt(0)
	v_pk_mul_f32 v[132:133], v[132:133], v[214:215]
	v_pk_mul_f32 v[134:135], v[134:135], v[216:217]
.LBB0_525:
	s_waitcnt lgkmcnt(0)
	v_cvt_pk_bf16_f32 v135, v134, v135
	v_cvt_pk_bf16_f32 v134, v132, v133
	v_cvt_pk_bf16_f32 v132, v128, v129
	v_lshlrev_b64 v[128:129], 11, v[152:153]
	v_lshl_add_u64 v[128:129], s[4:5], 0, v[128:129]
	v_lshl_add_u64 v[128:129], v[128:129], 0, v[136:137]
	v_add_co_u32_e32 v128, vcc, 0x20000, v128
	v_cvt_pk_bf16_f32 v133, v130, v131
	s_nop 0
	v_addc_co_u32_e32 v129, vcc, 0, v129, vcc
	global_store_dwordx4 v[128:129], v[132:135], off sc1
	s_barrier
	s_and_saveexec_b64 s[12:13], s[8:9]
	s_cbranch_execz .LBB0_527
	ds_write2_b32 v164, v0, v16 offset1:32
	ds_write2_b32 v164, v1, v17 offset0:132 offset1:164
	ds_write2_b32 v207, v2, v18 offset0:8 offset1:40
	ds_write2_b32 v207, v3, v19 offset0:140 offset1:172
	ds_write2_b32 v206, v4, v20 offset0:32 offset1:64
	ds_write2_b32 v206, v5, v21 offset0:164 offset1:196
	ds_write2_b32 v205, v6, v22 offset0:40 offset1:72
	ds_write2_b32 v205, v7, v23 offset0:172 offset1:204
	ds_write2_b32 v204, v8, v24 offset0:64 offset1:96
	ds_write2_b32 v204, v9, v25 offset0:196 offset1:228
	ds_write2_b32 v198, v10, v26 offset0:72 offset1:104
	ds_write2_b32 v198, v11, v27 offset0:204 offset1:236
	ds_write2_b32 v199, v12, v28 offset0:96 offset1:128
	ds_write2_b32 v200, v13, v29 offset0:100 offset1:132
	ds_write2_b32 v201, v14, v30 offset0:104 offset1:136
	ds_write2_b32 v202, v15, v31 offset0:108 offset1:140
	ds_write2_b32 v203, v32, v48 offset0:128 offset1:160
	ds_write2_b32 v195, v33, v49 offset0:4 offset1:36
	ds_write2_b32 v195, v34, v50 offset0:136 offset1:168
	ds_write2_b32 v196, v35, v51 offset0:12 offset1:44
	ds_write2_b32 v197, v36, v52 offset0:160 offset1:192
	ds_write2_b32 v192, v37, v53 offset0:36 offset1:68
	ds_write2_b32 v192, v38, v54 offset0:168 offset1:200
	ds_write2_b32 v193, v39, v55 offset0:44 offset1:76
	ds_write2_b32 v194, v40, v56 offset0:192 offset1:224
	ds_write2_b32 v186, v41, v57 offset0:68 offset1:100
	ds_write2_b32 v186, v42, v58 offset0:200 offset1:232
	ds_write2_b32 v187, v43, v59 offset0:76 offset1:108
	ds_write2_b32 v188, v44, v60 offset0:96 offset1:128
	ds_write2_b32 v189, v45, v61 offset0:100 offset1:132
	ds_write2_b32 v190, v46, v62 offset0:104 offset1:136
	ds_write2_b32 v191, v47, v63 offset0:108 offset1:140
	ds_write2_b32 v185, v64, v80 offset1:32
	ds_write2_b32 v185, v65, v81 offset0:132 offset1:164
	ds_write2_b32 v184, v66, v82 offset0:8 offset1:40
	ds_write2_b32 v184, v67, v83 offset0:140 offset1:172
	ds_write2_b32 v183, v68, v84 offset0:32 offset1:64
	ds_write2_b32 v183, v69, v85 offset0:164 offset1:196
	ds_write2_b32 v182, v70, v86 offset0:40 offset1:72
	ds_write2_b32 v182, v71, v87 offset0:172 offset1:204
	ds_write2_b32 v181, v72, v88 offset0:64 offset1:96
	ds_write2_b32 v181, v73, v89 offset0:196 offset1:228
	ds_write2_b32 v175, v74, v90 offset0:72 offset1:104
	ds_write2_b32 v175, v75, v91 offset0:204 offset1:236
	ds_write2_b32 v176, v76, v92 offset0:96 offset1:128
	ds_write2_b32 v177, v77, v93 offset0:100 offset1:132
	ds_write2_b32 v178, v78, v94 offset0:104 offset1:136
	ds_write2_b32 v179, v79, v95 offset0:108 offset1:140
	ds_write_b32 v164, v96 offset:50688
	ds_write_b32 v164, v97 offset:51216
	ds_write_b32 v164, v98 offset:51744
	ds_write_b32 v164, v99 offset:52272
	ds_write_b32 v164, v100 offset:54912
	ds_write_b32 v164, v101 offset:55440
	ds_write_b32 v164, v102 offset:55968
	ds_write_b32 v164, v103 offset:56496
	ds_write_b32 v164, v104 offset:59136
	ds_write_b32 v164, v105 offset:59664
	ds_write_b32 v164, v106 offset:60192
	ds_write_b32 v164, v107 offset:60720
	ds_write_b32 v164, v108 offset:63360
	ds_write_b32 v164, v109 offset:63888
	ds_write_b32 v164, v110 offset:64416
	ds_write_b32 v169, v111
	ds_write_b32 v164, v112 offset:50816
	ds_write_b32 v164, v113 offset:51344
	ds_write_b32 v164, v114 offset:51872
	ds_write_b32 v164, v115 offset:52400
	ds_write_b32 v164, v116 offset:55040
	ds_write_b32 v164, v117 offset:55568
	ds_write_b32 v164, v118 offset:56096
	ds_write_b32 v164, v119 offset:56624
	ds_write_b32 v164, v120 offset:59264
	ds_write_b32 v164, v121 offset:59792
	ds_write_b32 v164, v122 offset:60320
	ds_write_b32 v164, v123 offset:60848
	ds_write_b32 v164, v124 offset:63488
	ds_write_b32 v164, v125 offset:64016
	ds_write_b32 v164, v126 offset:64544
	ds_write_b32 v169, v127 offset:128

.LBB0_529:
	s_waitcnt lgkmcnt(0)
	v_cvt_pk_bf16_f32 v10, v0, v1
	v_lshlrev_b64 v[0:1], 11, v[156:157]
	v_lshl_add_u64 v[0:1], s[4:5], 0, v[0:1]
	v_cvt_pk_bf16_f32 v8, v4, v5
	v_cvt_pk_bf16_f32 v9, v6, v7
	v_cvt_pk_bf16_f32 v11, v2, v3
	v_lshl_add_u64 v[12:13], v[0:1], 0, v[136:137]
	ds_read_b128 v[4:7], v172
	ds_read_b128 v[0:3], v172 offset:16
	v_add_co_u32_e32 v12, vcc, s39, v12
	s_nop 1
	v_addc_co_u32_e32 v13, vcc, 0, v13, vcc
	s_and_b64 vcc, exec, s[10:11]
	global_store_dwordx4 v[12:13], v[8:11], off sc1
	s_cbranch_vccnz .LBB0_531
	global_load_dwordx4 v[8:11], v170, s[16:17]
	global_load_dwordx4 v[12:15], v170, s[16:17] offset:16
	s_waitcnt vmcnt(1) lgkmcnt(1)
	v_pk_mul_f32 v[4:5], v[4:5], v[8:9]
	v_pk_mul_f32 v[6:7], v[6:7], v[10:11]
	s_waitcnt vmcnt(0) lgkmcnt(0)
	v_pk_mul_f32 v[0:1], v[0:1], v[12:13]
	v_pk_mul_f32 v[2:3], v[2:3], v[14:15]
.LBB0_531:
	s_waitcnt lgkmcnt(0)
	v_cvt_pk_bf16_f32 v10, v0, v1
	v_lshlrev_b64 v[0:1], 11, v[150:151]
	v_lshl_add_u64 v[0:1], s[4:5], 0, v[0:1]
	v_cvt_pk_bf16_f32 v8, v4, v5
	v_cvt_pk_bf16_f32 v9, v6, v7
	v_cvt_pk_bf16_f32 v11, v2, v3
	v_lshl_add_u64 v[12:13], v[0:1], 0, v[136:137]
	ds_read_b128 v[4:7], v173
	ds_read_b128 v[0:3], v173 offset:16
	v_add_co_u32_e32 v12, vcc, s39, v12
	s_nop 1
	v_addc_co_u32_e32 v13, vcc, 0, v13, vcc
	s_and_b64 vcc, exec, s[10:11]
	global_store_dwordx4 v[12:13], v[8:11], off sc1
	s_cbranch_vccnz .LBB0_533
	global_load_dwordx4 v[8:11], v170, s[16:17]
	global_load_dwordx4 v[12:15], v170, s[16:17] offset:16
	s_waitcnt vmcnt(1) lgkmcnt(1)
	v_pk_mul_f32 v[4:5], v[4:5], v[8:9]
	v_pk_mul_f32 v[6:7], v[6:7], v[10:11]
	s_waitcnt vmcnt(0) lgkmcnt(0)
	v_pk_mul_f32 v[0:1], v[0:1], v[12:13]
	v_pk_mul_f32 v[2:3], v[2:3], v[14:15]
.LBB0_533:
	s_waitcnt lgkmcnt(0)
	v_cvt_pk_bf16_f32 v10, v0, v1
	v_lshlrev_b64 v[0:1], 11, v[154:155]
	v_lshl_add_u64 v[0:1], s[4:5], 0, v[0:1]
	v_cvt_pk_bf16_f32 v8, v4, v5
	v_cvt_pk_bf16_f32 v9, v6, v7
	v_cvt_pk_bf16_f32 v11, v2, v3
	v_lshl_add_u64 v[12:13], v[0:1], 0, v[136:137]
	ds_read_b128 v[0:3], v174
	ds_read_b128 v[4:7], v174 offset:16
	v_add_co_u32_e32 v12, vcc, s39, v12
	s_nop 1
	v_addc_co_u32_e32 v13, vcc, 0, v13, vcc
	s_and_b64 vcc, exec, s[10:11]
	global_store_dwordx4 v[12:13], v[8:11], off sc1
	s_cbranch_vccnz .LBB0_535
	global_load_dwordx4 v[8:11], v170, s[16:17]
	global_load_dwordx4 v[12:15], v170, s[16:17] offset:16
	s_waitcnt vmcnt(1) lgkmcnt(1)
	v_pk_mul_f32 v[0:1], v[0:1], v[8:9]
	v_pk_mul_f32 v[2:3], v[2:3], v[10:11]
	s_waitcnt vmcnt(0) lgkmcnt(0)
	v_pk_mul_f32 v[4:5], v[4:5], v[12:13]
	v_pk_mul_f32 v[6:7], v[6:7], v[14:15]
.LBB0_535:
	s_waitcnt lgkmcnt(1)
	v_cvt_pk_bf16_f32 v8, v0, v1
	v_lshlrev_b64 v[0:1], 11, v[152:153]
	v_lshl_add_u64 v[0:1], s[4:5], 0, v[0:1]
	s_waitcnt lgkmcnt(0)
	v_cvt_pk_bf16_f32 v11, v6, v7
	v_cvt_pk_bf16_f32 v10, v4, v5
	v_cvt_pk_bf16_f32 v9, v2, v3
	v_lshl_add_u64 v[12:13], v[0:1], 0, v[136:137]
	ds_read_b128 v[4:7], v171 offset:33792
	ds_read_b128 v[0:3], v171 offset:33808
	v_add_co_u32_e32 v12, vcc, s39, v12
	s_nop 1
	v_addc_co_u32_e32 v13, vcc, 0, v13, vcc
	s_and_b64 vcc, exec, s[10:11]
	global_store_dwordx4 v[12:13], v[8:11], off sc1
	s_cbranch_vccnz .LBB0_537
	global_load_dwordx4 v[8:11], v170, s[16:17]
	global_load_dwordx4 v[12:15], v170, s[16:17] offset:16
	s_waitcnt vmcnt(1) lgkmcnt(1)
	v_pk_mul_f32 v[4:5], v[4:5], v[8:9]
	v_pk_mul_f32 v[6:7], v[6:7], v[10:11]
	s_waitcnt vmcnt(0) lgkmcnt(0)
	v_pk_mul_f32 v[0:1], v[0:1], v[12:13]
	v_pk_mul_f32 v[2:3], v[2:3], v[14:15]
.LBB0_537:
	s_waitcnt lgkmcnt(0)
	v_cvt_pk_bf16_f32 v10, v0, v1
	v_lshlrev_b64 v[0:1], 11, v[156:157]
	v_lshl_add_u64 v[0:1], s[4:5], 0, v[0:1]
	v_cvt_pk_bf16_f32 v8, v4, v5
	v_cvt_pk_bf16_f32 v9, v6, v7
	v_cvt_pk_bf16_f32 v11, v2, v3
	v_lshl_add_u64 v[12:13], v[0:1], 0, v[136:137]
	ds_read_b128 v[4:7], v172 offset:33792
	ds_read_b128 v[0:3], v172 offset:33808
	v_add_co_u32_e32 v12, vcc, s40, v12
	s_nop 1
	v_addc_co_u32_e32 v13, vcc, 0, v13, vcc
	s_and_b64 vcc, exec, s[10:11]
	global_store_dwordx4 v[12:13], v[8:11], off sc1
	s_cbranch_vccnz .LBB0_539
	global_load_dwordx4 v[8:11], v170, s[16:17]
	global_load_dwordx4 v[12:15], v170, s[16:17] offset:16
	s_waitcnt vmcnt(1) lgkmcnt(1)
	v_pk_mul_f32 v[4:5], v[4:5], v[8:9]
	v_pk_mul_f32 v[6:7], v[6:7], v[10:11]
	s_waitcnt vmcnt(0) lgkmcnt(0)
	v_pk_mul_f32 v[0:1], v[0:1], v[12:13]
	v_pk_mul_f32 v[2:3], v[2:3], v[14:15]
.LBB0_539:
	s_waitcnt lgkmcnt(0)
	v_cvt_pk_bf16_f32 v10, v0, v1
	v_lshlrev_b64 v[0:1], 11, v[150:151]
	v_lshl_add_u64 v[0:1], s[4:5], 0, v[0:1]
	v_cvt_pk_bf16_f32 v8, v4, v5
	v_cvt_pk_bf16_f32 v9, v6, v7
	v_cvt_pk_bf16_f32 v11, v2, v3
	v_lshl_add_u64 v[12:13], v[0:1], 0, v[136:137]
	ds_read_b128 v[4:7], v173 offset:33792
	ds_read_b128 v[0:3], v173 offset:33808
	v_add_co_u32_e32 v12, vcc, s40, v12
	s_nop 1
	v_addc_co_u32_e32 v13, vcc, 0, v13, vcc
	s_and_b64 vcc, exec, s[10:11]
	global_store_dwordx4 v[12:13], v[8:11], off sc1
	s_cbranch_vccnz .LBB0_541
	global_load_dwordx4 v[8:11], v170, s[16:17]
	global_load_dwordx4 v[12:15], v170, s[16:17] offset:16
	s_waitcnt vmcnt(1) lgkmcnt(1)
	v_pk_mul_f32 v[4:5], v[4:5], v[8:9]
	v_pk_mul_f32 v[6:7], v[6:7], v[10:11]
	s_waitcnt vmcnt(0) lgkmcnt(0)
	v_pk_mul_f32 v[0:1], v[0:1], v[12:13]
	v_pk_mul_f32 v[2:3], v[2:3], v[14:15]
.LBB0_541:
	s_waitcnt lgkmcnt(0)
	v_cvt_pk_bf16_f32 v10, v0, v1
	v_lshlrev_b64 v[0:1], 11, v[154:155]
	v_lshl_add_u64 v[0:1], s[4:5], 0, v[0:1]
	v_cvt_pk_bf16_f32 v8, v4, v5
	v_cvt_pk_bf16_f32 v9, v6, v7
	v_cvt_pk_bf16_f32 v11, v2, v3
	v_lshl_add_u64 v[12:13], v[0:1], 0, v[136:137]
	ds_read_b128 v[0:3], v174 offset:33792
	ds_read_b128 v[4:7], v174 offset:33808
	v_add_co_u32_e32 v12, vcc, s40, v12
	s_nop 1
	v_addc_co_u32_e32 v13, vcc, 0, v13, vcc
	s_and_b64 vcc, exec, s[10:11]
	global_store_dwordx4 v[12:13], v[8:11], off sc1
	s_cbranch_vccnz .LBB0_491
	global_load_dwordx4 v[8:11], v170, s[16:17]
	global_load_dwordx4 v[12:15], v170, s[16:17] offset:16
	s_waitcnt vmcnt(1) lgkmcnt(1)
	v_pk_mul_f32 v[0:1], v[0:1], v[8:9]
	v_pk_mul_f32 v[2:3], v[2:3], v[10:11]
	s_waitcnt vmcnt(0) lgkmcnt(0)
	v_pk_mul_f32 v[4:5], v[4:5], v[12:13]
	v_pk_mul_f32 v[6:7], v[6:7], v[14:15]
	s_branch .LBB0_491

.LBB0_600:
	s_or_b64 exec, exec, s[14:15]
	s_waitcnt lgkmcnt(0)
	s_barrier
	ds_read_b128 v[0:3], v144
	ds_read_b128 v[4:7], v144 offset:16
	v_add_co_u32_e32 v12, vcc, s25, v136
	s_add_i32 s21, s21, s20
	s_waitcnt lgkmcnt(1)
	v_cvt_pk_bf16_f32 v0, v0, v1
	v_cvt_pk_bf16_f32 v1, v2, v3
	s_waitcnt lgkmcnt(0)
	v_cvt_pk_bf16_f32 v2, v4, v5
	v_cvt_pk_bf16_f32 v3, v6, v7
	ds_read_b128 v[4:7], v145
	ds_read_b128 v[8:11], v145 offset:16
	v_addc_co_u32_e32 v13, vcc, 0, v137, vcc
	global_store_dwordx4 v[12:13], v[0:3], off sc1
	v_add_co_u32_e32 v12, vcc, s25, v138
	s_waitcnt lgkmcnt(1)
	v_cvt_pk_bf16_f32 v0, v4, v5
	v_cvt_pk_bf16_f32 v1, v6, v7
	s_waitcnt lgkmcnt(0)
	v_cvt_pk_bf16_f32 v2, v8, v9
	v_cvt_pk_bf16_f32 v3, v10, v11
	ds_read_b128 v[4:7], v146
	ds_read_b128 v[8:11], v146 offset:16
	v_addc_co_u32_e32 v13, vcc, 0, v139, vcc
	global_store_dwordx4 v[12:13], v[0:3], off sc1
	v_add_co_u32_e32 v12, vcc, s25, v140
	s_waitcnt lgkmcnt(1)
	v_cvt_pk_bf16_f32 v0, v4, v5
	v_cvt_pk_bf16_f32 v1, v6, v7
	s_waitcnt lgkmcnt(0)
	v_cvt_pk_bf16_f32 v2, v8, v9
	v_cvt_pk_bf16_f32 v3, v10, v11
	ds_read_b128 v[4:7], v173
	ds_read_b128 v[8:11], v173 offset:16
	v_addc_co_u32_e32 v13, vcc, 0, v141, vcc
	global_store_dwordx4 v[12:13], v[0:3], off sc1
	v_add_co_u32_e32 v12, vcc, s25, v142
	s_waitcnt lgkmcnt(0)
	v_cvt_pk_bf16_f32 v3, v10, v11
	v_cvt_pk_bf16_f32 v2, v8, v9
	v_cvt_pk_bf16_f32 v1, v6, v7
	v_cvt_pk_bf16_f32 v0, v4, v5
	ds_read_b128 v[4:7], v144 offset:33792
	ds_read_b128 v[8:11], v144 offset:33808
	v_addc_co_u32_e32 v13, vcc, 0, v143, vcc
	global_store_dwordx4 v[12:13], v[0:3], off sc1
	v_add_co_u32_e32 v12, vcc, s26, v136
	s_waitcnt lgkmcnt(1)
	v_cvt_pk_bf16_f32 v0, v4, v5
	v_cvt_pk_bf16_f32 v1, v6, v7
	s_waitcnt lgkmcnt(0)
	v_cvt_pk_bf16_f32 v2, v8, v9
	v_cvt_pk_bf16_f32 v3, v10, v11
	ds_read_b128 v[4:7], v145 offset:33792
	ds_read_b128 v[8:11], v145 offset:33808
	v_addc_co_u32_e32 v13, vcc, 0, v137, vcc
	global_store_dwordx4 v[12:13], v[0:3], off sc1
	v_add_co_u32_e32 v12, vcc, s26, v138
	s_waitcnt lgkmcnt(1)
	v_cvt_pk_bf16_f32 v0, v4, v5
	v_cvt_pk_bf16_f32 v1, v6, v7
	s_waitcnt lgkmcnt(0)
	v_cvt_pk_bf16_f32 v2, v8, v9
	v_cvt_pk_bf16_f32 v3, v10, v11
	ds_read_b128 v[4:7], v146 offset:33792
	ds_read_b128 v[8:11], v146 offset:33808
	v_addc_co_u32_e32 v13, vcc, 0, v139, vcc
	global_store_dwordx4 v[12:13], v[0:3], off sc1
	v_add_co_u32_e32 v12, vcc, s26, v140
	s_waitcnt lgkmcnt(1)
	v_cvt_pk_bf16_f32 v0, v4, v5
	v_cvt_pk_bf16_f32 v1, v6, v7
	s_waitcnt lgkmcnt(0)
	v_cvt_pk_bf16_f32 v2, v8, v9
	v_cvt_pk_bf16_f32 v3, v10, v11
	ds_read_b128 v[4:7], v173 offset:33792
	ds_read_b128 v[8:11], v173 offset:33808
	v_addc_co_u32_e32 v13, vcc, 0, v141, vcc
	global_store_dwordx4 v[12:13], v[0:3], off sc1
	s_cmp_lt_u32 s21, 64
	s_waitcnt lgkmcnt(1)
	v_cvt_pk_bf16_f32 v0, v4, v5
	v_add_co_u32_e32 v4, vcc, 0x60000, v142
	s_waitcnt lgkmcnt(0)
	v_cvt_pk_bf16_f32 v3, v10, v11
	v_cvt_pk_bf16_f32 v2, v8, v9
	v_cvt_pk_bf16_f32 v1, v6, v7
	v_addc_co_u32_e32 v5, vcc, 0, v143, vcc
	global_store_dwordx4 v[4:5], v[0:3], off sc1
	s_barrier
	s_cbranch_scc0 .LBB0_607

.LBB0_605:
	s_or_b64 exec, exec, s[14:15]
	v_lshlrev_b32_e32 v136, 3, v130
	v_and_b32_e32 v146, 0x78, v136
	v_ashrrev_i32_e32 v206, 4, v130
	v_add_u32_e32 v137, 0x100, v130
	v_lshl_add_u32 v173, v146, 2, 0
	v_mul_lo_u32 v136, v206, s23
	v_ashrrev_i32_e32 v210, 4, v137
	v_add_u32_e32 v137, 0x200, v130
	v_add_u32_e32 v144, v173, v136
	v_ashrrev_i32_e32 v218, 4, v137
	s_waitcnt lgkmcnt(0)
	s_barrier
	ds_read_b128 v[136:139], v144
	ds_read_b128 v[140:143], v144 offset:16
	s_lshl_b32 s2, s28, 1
	v_mul_lo_u32 v145, v210, s23
	s_add_u32 s2, s18, s2
	v_ashrrev_i32_e32 v207, 31, v206
	v_add_u32_e32 v145, v173, v145
	s_addc_u32 s15, s19, 0
	s_lshl_b32 s14, s27, 8
	s_waitcnt lgkmcnt(1)
	v_cvt_pk_bf16_f32 v202, v136, v137
	v_lshlrev_b64 v[136:137], 11, v[206:207]
	ds_read_b128 v[206:209], v145 offset:16
	s_add_u32 s14, s2, s14
	v_cvt_pk_bf16_f32 v203, v138, v139
	s_waitcnt lgkmcnt(1)
	v_cvt_pk_bf16_f32 v204, v140, v141
	ds_read_b128 v[138:141], v145
	s_addc_u32 s15, s15, 0
	v_add_u32_e32 v130, 0x300, v130
	v_mul_lo_u32 v214, v218, s23
	v_ashrrev_i32_e32 v220, 4, v130
	v_lshl_add_u64 v[136:137], s[14:15], 0, v[136:137]
	v_lshlrev_b32_e32 v130, 1, v146
	v_cvt_pk_bf16_f32 v205, v142, v143
	v_lshl_add_u64 v[136:137], v[136:137], 0, v[130:131]
	v_add_u32_e32 v146, v173, v214
	global_store_dwordx4 v[136:137], v[202:205], off sc1
	v_ashrrev_i32_e32 v211, 31, v210
	v_mul_lo_u32 v215, v220, s23
	s_waitcnt lgkmcnt(1)
	v_cvt_pk_bf16_f32 v204, v206, v207
	v_cvt_pk_bf16_f32 v205, v208, v209
	ds_read_b128 v[206:209], v146 offset:16
	s_waitcnt lgkmcnt(1)
	v_cvt_pk_bf16_f32 v202, v138, v139
	v_lshlrev_b64 v[138:139], 11, v[210:211]
	v_cvt_pk_bf16_f32 v203, v140, v141
	ds_read_b128 v[140:143], v146
	v_lshl_add_u64 v[138:139], s[14:15], 0, v[138:139]
	v_lshl_add_u64 v[138:139], v[138:139], 0, v[130:131]
	global_store_dwordx4 v[138:139], v[202:205], off sc1
	v_add_u32_e32 v173, v173, v215
	v_ashrrev_i32_e32 v219, 31, v218
	s_waitcnt lgkmcnt(1)
	v_cvt_pk_bf16_f32 v204, v206, v207
	v_cvt_pk_bf16_f32 v205, v208, v209
	ds_read_b128 v[206:209], v173
	ds_read_b128 v[214:217], v173 offset:16
	s_waitcnt lgkmcnt(2)
	v_cvt_pk_bf16_f32 v202, v140, v141
	v_lshlrev_b64 v[140:141], 11, v[218:219]
	v_lshl_add_u64 v[140:141], s[14:15], 0, v[140:141]
	v_cvt_pk_bf16_f32 v203, v142, v143
	v_lshl_add_u64 v[140:141], v[140:141], 0, v[130:131]
	global_store_dwordx4 v[140:141], v[202:205], off sc1
	v_ashrrev_i32_e32 v221, 31, v220
	v_lshlrev_b64 v[142:143], 11, v[220:221]
	s_waitcnt lgkmcnt(0)
	v_cvt_pk_bf16_f32 v205, v216, v217
	v_cvt_pk_bf16_f32 v204, v214, v215
	v_cvt_pk_bf16_f32 v203, v208, v209
	v_cvt_pk_bf16_f32 v202, v206, v207
	ds_read_b128 v[206:209], v144 offset:33792
	ds_read_b128 v[214:217], v144 offset:33808
	v_lshl_add_u64 v[142:143], s[14:15], 0, v[142:143]
	v_lshl_add_u64 v[142:143], v[142:143], 0, v[130:131]
	global_store_dwordx4 v[142:143], v[202:205], off sc1
	v_add_co_u32_e32 v210, vcc, s24, v136
	s_waitcnt lgkmcnt(1)
	v_cvt_pk_bf16_f32 v202, v206, v207
	v_cvt_pk_bf16_f32 v203, v208, v209
	s_waitcnt lgkmcnt(0)
	v_cvt_pk_bf16_f32 v204, v214, v215
	v_cvt_pk_bf16_f32 v205, v216, v217
	ds_read_b128 v[206:209], v145 offset:33792
	ds_read_b128 v[214:217], v145 offset:33808
	v_addc_co_u32_e32 v211, vcc, 0, v137, vcc
	global_store_dwordx4 v[210:211], v[202:205], off sc1
	v_add_co_u32_e32 v210, vcc, s24, v138
	s_waitcnt lgkmcnt(1)
	v_cvt_pk_bf16_f32 v202, v206, v207
	v_cvt_pk_bf16_f32 v203, v208, v209
	s_waitcnt lgkmcnt(0)
	v_cvt_pk_bf16_f32 v204, v214, v215
	v_cvt_pk_bf16_f32 v205, v216, v217
	ds_read_b128 v[206:209], v146 offset:33792
	ds_read_b128 v[214:217], v146 offset:33808
	v_addc_co_u32_e32 v211, vcc, 0, v139, vcc
	global_store_dwordx4 v[210:211], v[202:205], off sc1
	v_add_co_u32_e32 v210, vcc, s24, v140
	s_waitcnt lgkmcnt(1)
	v_cvt_pk_bf16_f32 v202, v206, v207
	v_cvt_pk_bf16_f32 v203, v208, v209
	s_waitcnt lgkmcnt(0)
	v_cvt_pk_bf16_f32 v204, v214, v215
	v_cvt_pk_bf16_f32 v205, v216, v217
	ds_read_b128 v[206:209], v173 offset:33792
	ds_read_b128 v[214:217], v173 offset:33808
	v_addc_co_u32_e32 v211, vcc, 0, v141, vcc
	global_store_dwordx4 v[210:211], v[202:205], off sc1
	s_waitcnt lgkmcnt(1)
	s_nop 0
	v_cvt_pk_bf16_f32 v202, v206, v207
	v_add_co_u32_e32 v206, vcc, 0x20000, v142
	s_waitcnt lgkmcnt(0)
	v_cvt_pk_bf16_f32 v205, v216, v217
	v_cvt_pk_bf16_f32 v204, v214, v215
	v_cvt_pk_bf16_f32 v203, v208, v209
	v_addc_co_u32_e32 v207, vcc, 0, v143, vcc
	global_store_dwordx4 v[206:207], v[202:205], off sc1
	s_barrier
	s_and_saveexec_b64 s[14:15], s[8:9]
	s_cbranch_execz .LBB0_600
	v_and_b32_e32 v254, 63, v180
	v_lshrrev_b32_e32 v253, 4, v254
	v_mul_u32_u24_e32 v253, 0x840, v253
	v_and_b32_e32 v254, 15, v254
	v_lshl_add_u32 v253, v254, 2, v253
	v_and_b32_e32 v254, 64, v180
	v_lshl_add_u32 v253, v254, 2, v253
	ds_write_b32 v253, v0 offset:0
	ds_write_b32 v253, v1 offset:528
	ds_write_b32 v253, v2 offset:1056
	ds_write_b32 v253, v3 offset:1584
	ds_write_b32 v253, v4 offset:64
	ds_write_b32 v253, v5 offset:592
	ds_write_b32 v253, v6 offset:1120
	ds_write_b32 v253, v7 offset:1648
	ds_write_b32 v253, v8 offset:128
	ds_write_b32 v253, v9 offset:656
	ds_write_b32 v253, v10 offset:1184
	ds_write_b32 v253, v11 offset:1712
	ds_write_b32 v253, v12 offset:192
	ds_write_b32 v253, v13 offset:720
	ds_write_b32 v253, v14 offset:1248
	ds_write_b32 v253, v15 offset:1776
	ds_write_b32 v253, v16 offset:8448
	ds_write_b32 v253, v17 offset:8976
	ds_write_b32 v253, v18 offset:9504
	ds_write_b32 v253, v19 offset:10032
	ds_write_b32 v253, v20 offset:8512
	ds_write_b32 v253, v21 offset:9040
	ds_write_b32 v253, v22 offset:9568
	ds_write_b32 v253, v23 offset:10096
	ds_write_b32 v253, v24 offset:8576
	ds_write_b32 v253, v25 offset:9104
	ds_write_b32 v253, v26 offset:9632
	ds_write_b32 v253, v27 offset:10160
	ds_write_b32 v253, v28 offset:8640
	ds_write_b32 v253, v29 offset:9168
	ds_write_b32 v253, v30 offset:9696
	ds_write_b32 v253, v31 offset:10224
	ds_write_b32 v253, v32 offset:16896
	ds_write_b32 v253, v33 offset:17424
	ds_write_b32 v253, v34 offset:17952
	ds_write_b32 v253, v35 offset:18480
	ds_write_b32 v253, v36 offset:16960
	ds_write_b32 v253, v37 offset:17488
	ds_write_b32 v253, v38 offset:18016
	ds_write_b32 v253, v39 offset:18544
	ds_write_b32 v253, v40 offset:17024
	ds_write_b32 v253, v41 offset:17552
	ds_write_b32 v253, v42 offset:18080
	ds_write_b32 v253, v43 offset:18608
	ds_write_b32 v253, v44 offset:17088
	ds_write_b32 v253, v45 offset:17616
	ds_write_b32 v253, v46 offset:18144
	ds_write_b32 v253, v47 offset:18672
	ds_write_b32 v253, v48 offset:25344
	ds_write_b32 v253, v49 offset:25872
	ds_write_b32 v253, v50 offset:26400
	ds_write_b32 v253, v51 offset:26928
	ds_write_b32 v253, v52 offset:25408
	ds_write_b32 v253, v53 offset:25936
	ds_write_b32 v253, v54 offset:26464
	ds_write_b32 v253, v55 offset:26992
	ds_write_b32 v253, v56 offset:25472
	ds_write_b32 v253, v57 offset:26000
	ds_write_b32 v253, v58 offset:26528
	ds_write_b32 v253, v59 offset:27056
	ds_write_b32 v253, v60 offset:25536
	ds_write_b32 v253, v61 offset:26064
	ds_write_b32 v253, v62 offset:26592
	ds_write_b32 v253, v63 offset:27120
	ds_write_b32 v253, v64 offset:33792
	ds_write_b32 v253, v65 offset:34320
	ds_write_b32 v253, v66 offset:34848
	ds_write_b32 v253, v67 offset:35376
	ds_write_b32 v253, v68 offset:33856
	ds_write_b32 v253, v69 offset:34384
	ds_write_b32 v253, v70 offset:34912
	ds_write_b32 v253, v71 offset:35440
	ds_write_b32 v253, v72 offset:33920
	ds_write_b32 v253, v73 offset:34448
	ds_write_b32 v253, v74 offset:34976
	ds_write_b32 v253, v75 offset:35504
	ds_write_b32 v253, v76 offset:33984
	ds_write_b32 v253, v77 offset:34512
	ds_write_b32 v253, v78 offset:35040
	ds_write_b32 v253, v79 offset:35568
	ds_write_b32 v253, v80 offset:42240
	ds_write_b32 v253, v81 offset:42768
	ds_write_b32 v253, v82 offset:43296
	ds_write_b32 v253, v83 offset:43824
	ds_write_b32 v253, v84 offset:42304
	ds_write_b32 v253, v85 offset:42832
	ds_write_b32 v253, v86 offset:43360
	ds_write_b32 v253, v87 offset:43888
	ds_write_b32 v253, v88 offset:42368
	ds_write_b32 v253, v89 offset:42896
	ds_write_b32 v253, v90 offset:43424
	ds_write_b32 v253, v91 offset:43952
	ds_write_b32 v253, v92 offset:42432
	ds_write_b32 v253, v93 offset:42960
	ds_write_b32 v253, v94 offset:43488
	ds_write_b32 v253, v95 offset:44016
	ds_write_b32 v253, v96 offset:50688
	ds_write_b32 v253, v97 offset:51216
	ds_write_b32 v253, v98 offset:51744
	ds_write_b32 v253, v99 offset:52272
	ds_write_b32 v253, v100 offset:50752
	ds_write_b32 v253, v101 offset:51280
	ds_write_b32 v253, v102 offset:51808
	ds_write_b32 v253, v103 offset:52336
	ds_write_b32 v253, v104 offset:50816
	ds_write_b32 v253, v105 offset:51344
	ds_write_b32 v253, v106 offset:51872
	ds_write_b32 v253, v107 offset:52400
	ds_write_b32 v253, v108 offset:50880
	ds_write_b32 v253, v109 offset:51408
	ds_write_b32 v253, v110 offset:51936
	ds_write_b32 v253, v111 offset:52464
	ds_write_b32 v253, v112 offset:59136
	ds_write_b32 v253, v113 offset:59664
	ds_write_b32 v253, v114 offset:60192
	ds_write_b32 v253, v115 offset:60720
	ds_write_b32 v253, v116 offset:59200
	ds_write_b32 v253, v117 offset:59728
	ds_write_b32 v253, v118 offset:60256
	ds_write_b32 v253, v119 offset:60784
	ds_write_b32 v253, v120 offset:59264
	ds_write_b32 v253, v121 offset:59792
	ds_write_b32 v253, v122 offset:60320
	ds_write_b32 v253, v123 offset:60848
	ds_write_b32 v253, v124 offset:59328
	ds_write_b32 v253, v125 offset:59856
	ds_write_b32 v253, v126 offset:60384
	ds_write_b32 v253, v127 offset:60912
	s_branch .LBB0_600

.LBB0_684:
	s_or_b64 exec, exec, s[24:25]
	v_lshlrev_b32_e32 v164, 16, v142
	v_and_b32_e32 v165, 0xffff0000, v142
	v_lshlrev_b32_e32 v162, 16, v144
	v_and_b32_e32 v163, 0xffff0000, v144
	v_pk_mul_f32 v[164:165], v[36:37], v[164:165]
	v_lshlrev_b32_e32 v142, 16, v143
	v_and_b32_e32 v143, 0xffff0000, v143
	v_pk_mul_f32 v[162:163], v[52:53], v[162:163]
	v_pk_fma_f32 v[104:105], v[104:105], s[22:23], v[164:165] op_sel_hi:[1,0,1]
	v_pk_mul_f32 v[142:143], v[38:39], v[142:143]
	v_pk_fma_f32 v[108:109], v[108:109], s[22:23], v[162:163] op_sel_hi:[1,0,1]
	v_and_b32_e32 v163, 0xffff0000, v145
	v_lshlrev_b32_e32 v162, 16, v145
	v_lshlrev_b32_e32 v127, 16, v138
	v_mov_b32_e32 v101, v64
	v_and_b32_e32 v96, 0xffff0000, v140
	v_pk_add_f32 v[164:165], v[104:105], v[104:105] op_sel:[0,1] op_sel_hi:[1,0]
	v_pk_fma_f32 v[106:107], v[106:107], s[22:23], v[142:143] op_sel_hi:[1,0,1]
	v_pk_mul_f32 v[144:145], v[54:55], v[162:163]
	v_pk_mul_f32 v[100:101], v[100:101], v[126:127]
	v_and_b32_e32 v127, 0xffff0000, v138
	v_mul_f32_e32 v163, v77, v96
	v_and_b32_e32 v96, 0xffff0000, v141
	v_pk_add_f32 v[142:143], v[106:107], v[164:165]
	v_lshlrev_b32_e32 v165, 16, v140
	v_lshlrev_b32_e32 v164, 16, v139
	v_and_b32_e32 v138, 0xffff0000, v139
	v_lshlrev_b32_e32 v139, 16, v141
	v_pk_mov_b32 v[140:141], v[66:67], v[78:79] op_sel:[1,0]
	v_pk_fma_f32 v[110:111], v[110:111], s[22:23], v[144:145] op_sel_hi:[1,0,1]
	v_pk_mul_f32 v[138:139], v[140:141], v[138:139]
	v_pk_add_f32 v[140:141], v[106:107], v[142:143] op_sel:[1,0] op_sel_hi:[0,1]
	v_pk_add_f32 v[144:145], v[108:109], v[108:109] op_sel:[0,1] op_sel_hi:[1,0]
	s_waitcnt lgkmcnt(0)
	v_mov_b32_e32 v98, v140
	v_pk_add_f32 v[144:145], v[110:111], v[144:145]
	v_pk_add_f32 v[140:141], v[140:141], s[18:19]
	v_pk_mul_f32 v[98:99], v[98:99], s[0:1]
	v_mov_b32_e32 v149, v65
	v_mul_f32_e32 v96, v79, v96
	v_mov_b32_e32 v141, v99
	v_pk_add_f32 v[98:99], v[110:111], v[144:145] op_sel:[1,0] op_sel_hi:[0,1]
	v_pk_mul_f32 v[148:149], v[148:149], v[126:127]
	v_mov_b32_e32 v99, v96
	v_pk_add_f32 v[98:99], v[140:141], v[98:99]
	v_mov_b32_e32 v140, v100
	v_mov_b32_e32 v141, v148
	v_mov_b32_e32 v148, v101
	v_mov_b32_e32 v166, v66
	v_mov_b32_e32 v167, v76
	v_pk_add_f32 v[100:101], v[140:141], v[148:149]
	v_mul_f32_e32 v97, 0x3fb504f3, v97
	v_pk_mul_f32 v[164:165], v[166:167], v[164:165]
	v_mov_b32_e32 v96, v100
	v_mov_b32_e32 v162, v101
	v_pk_fma_f32 v[102:103], v[102:103], s[22:23], v[164:165] op_sel_hi:[1,0,1]
	v_pk_add_f32 v[96:97], v[96:97], v[162:163]
	v_pk_fma_f32 v[138:139], v[146:147], s[22:23], v[138:139] op_sel_hi:[1,0,1]
	v_pk_add_f32 v[140:141], v[102:103], v[96:97]
	v_mov_b32_e32 v164, v102
	v_pk_add_f32 v[140:141], v[138:139], v[140:141]
	v_mov_b32_e32 v165, v138
	v_pk_add_f32 v[140:141], v[98:99], v[140:141]
	v_ashrrev_i32_e32 v115, 31, v114
	v_add_f32_e32 v96, v140, v141
	ds_bpermute_b32 v98, v150, v96
	s_waitcnt lgkmcnt(0)
	v_add_f32_e32 v96, v96, v98
	ds_bpermute_b32 v98, v151, v96
	s_waitcnt lgkmcnt(0)
	v_add_f32_e32 v96, v96, v98
	ds_bpermute_b32 v98, v152, v96
	s_waitcnt lgkmcnt(0)
	v_add_f32_e32 v96, v96, v98
	ds_bpermute_b32 v98, v153, v96
	s_waitcnt lgkmcnt(0)
	v_add_f32_e32 v96, v96, v98
	ds_bpermute_b32 v98, v154, v96
	s_waitcnt lgkmcnt(0)
	v_add_f32_e32 v96, v96, v98
	ds_bpermute_b32 v98, v155, v96
	s_waitcnt lgkmcnt(0)
	v_add_f32_e32 v96, v96, v98
	v_mul_f32_e32 v140, 0x3a800000, v96
	v_pk_add_f32 v[104:105], v[104:105], v[140:141] op_sel_hi:[1,0] neg_lo:[0,1] neg_hi:[0,1]
	v_pk_add_f32 v[106:107], v[106:107], v[140:141] op_sel_hi:[1,0] neg_lo:[0,1] neg_hi:[0,1]
	v_pk_mul_f32 v[142:143], v[104:105], v[104:105]
	v_pk_mul_f32 v[144:145], v[106:107], v[106:107]
	v_add_f32_e32 v102, v142, v143
	v_pk_add_f32 v[108:109], v[108:109], v[140:141] op_sel_hi:[1,0] neg_lo:[0,1] neg_hi:[0,1]
	v_add_f32_e32 v102, v144, v102
	v_pk_mul_f32 v[148:149], v[108:109], v[108:109]
	v_add_f32_e32 v102, v145, v102
	v_pk_add_f32 v[110:111], v[110:111], v[140:141] op_sel_hi:[1,0] neg_lo:[0,1] neg_hi:[0,1]
	v_add_f32_e32 v102, v148, v102
	v_pk_mul_f32 v[162:163], v[110:111], v[110:111]
	v_add_f32_e32 v102, v149, v102
	v_pk_add_f32 v[146:147], v[100:101], v[140:141] op_sel_hi:[1,0] neg_lo:[0,1] neg_hi:[0,1]
	v_add_f32_e32 v102, v162, v102
	v_pk_mul_f32 v[100:101], v[146:147], v[146:147]
	v_add_f32_e32 v102, v163, v102
	v_pk_add_f32 v[164:165], v[164:165], v[140:141] op_sel_hi:[1,0] neg_lo:[0,1] neg_hi:[0,1]
	v_add_f32_e32 v100, v100, v102
	v_pk_mul_f32 v[166:167], v[164:165], v[164:165]
	v_mov_b32_e32 v96, v103
	v_add_f32_e32 v100, v101, v100
	v_pk_add_f32 v[168:169], v[96:97], v[140:141] op_sel_hi:[1,0] neg_lo:[0,1] neg_hi:[0,1]
	v_add_f32_e32 v100, v166, v100
	v_pk_mul_f32 v[96:97], v[168:169], v[168:169]
	v_mov_b32_e32 v98, v139
	v_add_f32_e32 v100, v167, v100
	v_pk_add_f32 v[138:139], v[98:99], v[140:141] op_sel_hi:[1,0] neg_lo:[0,1] neg_hi:[0,1]
	v_add_f32_e32 v96, v96, v100
	v_pk_mul_f32 v[98:99], v[138:139], v[138:139]
	v_add_f32_e32 v96, v97, v96
	v_add_f32_e32 v96, v98, v96
	v_add_f32_e32 v96, v99, v96
	ds_bpermute_b32 v97, v150, v96
	v_pk_add_f32 v[102:103], v[34:35], 1.0 op_sel_hi:[1,0]
	v_pk_add_f32 v[144:145], v[40:41], 1.0 op_sel_hi:[1,0]
	v_pk_add_f32 v[148:149], v[42:43], 1.0 op_sel_hi:[1,0]
	v_pk_add_f32 v[162:163], v[56:57], 1.0 op_sel_hi:[1,0]
	s_waitcnt lgkmcnt(0)
	v_add_f32_e32 v96, v96, v97
	ds_bpermute_b32 v97, v151, v96
	v_pk_add_f32 v[166:167], v[58:59], 1.0 op_sel_hi:[1,0]
	s_waitcnt lgkmcnt(0)
	v_add_f32_e32 v96, v96, v97
	ds_bpermute_b32 v97, v152, v96
	s_waitcnt lgkmcnt(0)
	v_add_f32_e32 v96, v96, v97
	ds_bpermute_b32 v97, v153, v96
	s_waitcnt lgkmcnt(0)
	v_add_f32_e32 v98, v96, v97
	ds_bpermute_b32 v99, v154, v98
	v_lshlrev_b64 v[96:97], 12, v[114:115]
	v_lshl_add_u64 v[140:141], v[122:123], 0, v[96:97]
	v_pk_add_f32 v[96:97], v[32:33], 1.0 op_sel_hi:[1,0]
	s_waitcnt lgkmcnt(0)
	v_add_f32_e32 v100, v98, v99
	ds_bpermute_b32 v101, v155, v100
	v_lshlrev_b64 v[98:99], 11, v[114:115]
	v_lshl_add_u64 v[142:143], v[124:125], 0, v[98:99]
	s_waitcnt lgkmcnt(0)
	v_add_f32_e32 v98, v100, v101
	v_fmamk_f32 v98, v98, 0x3a800000, v159
	v_mul_f32_e32 v99, 0x4b800000, v98
	v_cmp_gt_f32_e32 vcc, s19, v98
	s_nop 1
	v_cndmask_b32_e32 v98, v98, v99, vcc
	v_rsq_f32_e32 v98, v98
	s_nop 0
	v_mul_f32_e32 v99, 0x45800000, v98
	v_cndmask_b32_e32 v170, v98, v99, vcc
	v_pk_mul_f32 v[98:99], v[104:105], v[170:171] op_sel_hi:[1,0]
	v_pk_mul_f32 v[100:101], v[106:107], v[170:171] op_sel_hi:[1,0]
	v_pk_fma_f32 v[98:99], v[28:29], v[98:99], v[24:25]
	v_pk_fma_f32 v[100:101], v[30:31], v[100:101], v[26:27]
	global_store_dwordx4 v[140:141], v[98:101], off sc1 nt
	s_nop 1
	v_pk_fma_f32 v[98:99], v[96:97], v[98:99], v[44:45]
	v_pk_fma_f32 v[96:97], v[102:103], v[100:101], v[46:47]
	v_cvt_pk_bf16_f32 v100, v98, v99
	v_cvt_pk_bf16_f32 v101, v96, v97
	global_store_dwordx2 v[142:143], v[100:101], off
	v_pk_mul_f32 v[100:101], v[108:109], v[170:171] op_sel_hi:[1,0]
	s_nop 0
	v_pk_fma_f32 v[102:103], v[20:21], v[100:101], v[16:17]
	v_pk_mul_f32 v[100:101], v[110:111], v[170:171] op_sel_hi:[1,0]
	v_pk_mul_f32 v[110:111], v[138:139], v[170:171] op_sel_hi:[1,0]
	v_pk_fma_f32 v[104:105], v[22:23], v[100:101], v[18:19]
	global_store_dwordx4 v[140:141], v[102:105], off offset:1024 sc1 nt
	v_pk_fma_f32 v[100:101], v[148:149], v[104:105], v[50:51]
	v_pk_fma_f32 v[110:111], v[6:7], v[110:111], v[2:3]
	v_pk_fma_f32 v[102:103], v[144:145], v[102:103], v[48:49]
	v_cvt_pk_bf16_f32 v105, v100, v101
	v_cvt_pk_bf16_f32 v104, v102, v103
	global_store_dwordx2 v[142:143], v[104:105], off offset:512
	v_pk_mul_f32 v[104:105], v[146:147], v[170:171] op_sel_hi:[1,0]
	v_pk_add_f32 v[138:139], v[68:69], 1.0 op_sel_hi:[1,0]
	v_pk_fma_f32 v[106:107], v[12:13], v[104:105], v[8:9]
	v_pk_mul_f32 v[104:105], v[164:165], v[170:171] op_sel_hi:[1,0]
	s_nop 0
	v_pk_fma_f32 v[108:109], v[14:15], v[104:105], v[10:11]
	global_store_dwordx4 v[140:141], v[106:109], off offset:2048 sc1 nt
	v_pk_fma_f32 v[104:105], v[166:167], v[108:109], v[62:63]
	s_nop 0
	v_pk_fma_f32 v[106:107], v[162:163], v[106:107], v[60:61]
	v_cvt_pk_bf16_f32 v109, v104, v105
	v_cvt_pk_bf16_f32 v108, v106, v107
	global_store_dwordx2 v[142:143], v[108:109], off offset:1024
	v_pk_mul_f32 v[108:109], v[168:169], v[170:171] op_sel_hi:[1,0]
	s_nop 0
	v_pk_fma_f32 v[108:109], v[4:5], v[108:109], v[0:1]
	global_store_dwordx4 v[140:141], v[108:111], off offset:3072 sc1 nt
	s_nop 1
	v_pk_fma_f32 v[108:109], v[138:139], v[108:109], v[72:73]
	v_pk_add_f32 v[138:139], v[70:71], 1.0 op_sel_hi:[1,0]
	v_cvt_pk_bf16_f32 v144, v108, v109
	v_pk_fma_f32 v[110:111], v[138:139], v[110:111], v[74:75]
	ds_read_b128 v[138:141], v156
	v_cvt_pk_bf16_f32 v145, v110, v111
	global_store_dwordx2 v[142:143], v[144:145], off offset:1536
	ds_read_b128 v[142:145], v156 offset:1024
	s_waitcnt lgkmcnt(1)
	v_mul_f32_e32 v115, v139, v99
	v_fmac_f32_e32 v115, v138, v98
	v_fmac_f32_e32 v115, v140, v96
	v_fmac_f32_e32 v115, v141, v97
	ds_read_b128 v[138:141], v156 offset:2048
	s_waitcnt lgkmcnt(1)
	v_mul_f32_e32 v127, v143, v103
	v_fmac_f32_e32 v127, v142, v102
	v_fmac_f32_e32 v127, v144, v100
	v_add_f32_e32 v115, 0, v115
	v_fmac_f32_e32 v127, v145, v101
	ds_read_b128 v[142:145], v156 offset:3072
	v_add_f32_e32 v115, v127, v115
	s_waitcnt lgkmcnt(1)
	v_mul_f32_e32 v127, v139, v107
	v_fmac_f32_e32 v127, v138, v106
	v_fmac_f32_e32 v127, v140, v104
	v_fmac_f32_e32 v127, v141, v105
	ds_read_b128 v[138:141], v156 offset:5120
	ds_read_b128 v[146:149], v156 offset:4096
	v_add_f32_e32 v115, v127, v115
	s_waitcnt lgkmcnt(2)
	v_mul_f32_e32 v127, v143, v109
	v_fmac_f32_e32 v127, v142, v108
	v_fmac_f32_e32 v127, v144, v110
	v_fmac_f32_e32 v127, v145, v111
	v_add_f32_e32 v115, v127, v115
	ds_read_b128 v[142:145], v156 offset:7168
	ds_read_b128 v[162:165], v156 offset:6144
	s_waitcnt lgkmcnt(2)
	v_mul_f32_e32 v127, v98, v146
	v_fmac_f32_e32 v127, v99, v147
	v_mul_f32_e32 v129, v102, v138
	v_fmac_f32_e32 v127, v96, v148
	v_fmac_f32_e32 v129, v103, v139
	v_fmac_f32_e32 v127, v97, v149
	v_fmac_f32_e32 v129, v100, v140
	v_add_f32_e32 v127, 0, v127
	v_fmac_f32_e32 v129, v101, v141
	v_add_f32_e32 v127, v129, v127
	s_waitcnt lgkmcnt(0)
	v_mul_f32_e32 v129, v106, v162
	v_fmac_f32_e32 v129, v107, v163
	v_fmac_f32_e32 v129, v104, v164
	v_fmac_f32_e32 v129, v105, v165
	ds_read_b128 v[138:141], v156 offset:9216
	ds_read_b128 v[146:149], v156 offset:8192
	v_add_f32_e32 v127, v129, v127
	v_mul_f32_e32 v129, v143, v109
	v_fmac_f32_e32 v129, v108, v142
	v_fmac_f32_e32 v129, v144, v110
	v_fmac_f32_e32 v129, v145, v111
	v_add_f32_e32 v127, v129, v127
	ds_read_b128 v[142:145], v156 offset:11264
	ds_read_b128 v[162:165], v156 offset:10240
	s_waitcnt lgkmcnt(2)
	v_mul_f32_e32 v129, v98, v146
	v_fmac_f32_e32 v129, v99, v147
	v_mul_f32_e32 v138, v102, v138
	v_fmac_f32_e32 v129, v96, v148
	v_fmac_f32_e32 v138, v103, v139
	v_fmac_f32_e32 v129, v97, v149
	v_fmac_f32_e32 v138, v100, v140
	v_add_f32_e32 v129, 0, v129
	v_fmac_f32_e32 v138, v101, v141
	v_add_f32_e32 v129, v138, v129
	s_waitcnt lgkmcnt(0)
	v_mul_f32_e32 v138, v106, v162
	v_fmac_f32_e32 v138, v107, v163
	v_fmac_f32_e32 v138, v104, v164
	v_mul_f32_e32 v142, v108, v142
	v_fmac_f32_e32 v138, v105, v165
	v_fmac_f32_e32 v142, v109, v143
	v_add_f32_e32 v129, v138, v129
	v_fmac_f32_e32 v142, v110, v144
	ds_read_b128 v[138:141], v156 offset:13312
	ds_read_b128 v[146:149], v156 offset:12288
	v_fmac_f32_e32 v142, v111, v145
	v_add_f32_e32 v129, v142, v129
	ds_read_b128 v[142:145], v156 offset:15360
	ds_read_b128 v[162:165], v156 offset:14336
	s_waitcnt lgkmcnt(3)
	v_mul_f32_e32 v138, v102, v138
	s_waitcnt lgkmcnt(2)
	v_mul_f32_e32 v146, v98, v146
	v_fmac_f32_e32 v146, v99, v147
	v_fmac_f32_e32 v146, v96, v148
	v_fmac_f32_e32 v138, v103, v139
	s_waitcnt lgkmcnt(0)
	v_mul_f32_e32 v139, v106, v162
	v_fmac_f32_e32 v146, v97, v149
	v_fmac_f32_e32 v138, v100, v140
	v_fmac_f32_e32 v139, v107, v163
	v_add_f32_e32 v146, 0, v146
	v_fmac_f32_e32 v138, v101, v141
	v_fmac_f32_e32 v139, v104, v164
	v_add_f32_e32 v138, v138, v146
	v_fmac_f32_e32 v139, v105, v165
	v_add_f32_e32 v138, v139, v138
	v_mul_f32_e32 v139, v108, v142
	v_fmac_f32_e32 v139, v109, v143
	ds_read_b128 v[140:143], v156 offset:16384
	v_fmac_f32_e32 v139, v110, v144
	v_fmac_f32_e32 v139, v111, v145
	ds_read_b128 v[144:147], v156 offset:17408
	v_add_f32_e32 v138, v139, v138
	s_waitcnt lgkmcnt(1)
	v_mul_f32_e32 v139, v99, v141
	v_fmac_f32_e32 v139, v98, v140
	v_fmac_f32_e32 v139, v96, v142
	s_waitcnt lgkmcnt(0)
	v_mul_f32_e32 v145, v103, v145
	v_fmac_f32_e32 v145, v102, v144
	v_fmac_f32_e32 v139, v97, v143
	ds_read_b128 v[140:143], v156 offset:18432
	v_fmac_f32_e32 v145, v100, v146
	v_add_f32_e32 v139, 0, v139
	v_fmac_f32_e32 v145, v101, v147
	v_add_f32_e32 v139, v139, v145
	ds_read_b128 v[144:147], v156 offset:19456
	s_waitcnt lgkmcnt(1)
	v_mul_f32_e32 v141, v107, v141
	v_fmac_f32_e32 v141, v106, v140
	v_fmac_f32_e32 v141, v104, v142
	v_fmac_f32_e32 v141, v105, v143
	s_waitcnt lgkmcnt(0)
	v_mul_f32_e32 v145, v109, v145
	v_fmac_f32_e32 v145, v108, v144
	v_add_f32_e32 v139, v139, v141
	v_fmac_f32_e32 v145, v110, v146
	ds_read_b128 v[140:143], v156 offset:21504
	ds_read_b128 v[162:165], v156 offset:20480
	v_fmac_f32_e32 v145, v111, v147
	v_add_f32_e32 v139, v139, v145
	ds_read_b128 v[144:147], v156 offset:23552
	ds_read_b128 v[166:169], v156 offset:22528
	s_waitcnt lgkmcnt(3)
	v_mul_f32_e32 v140, v102, v140
	s_waitcnt lgkmcnt(2)
	v_mul_f32_e32 v148, v98, v162
	v_fmac_f32_e32 v148, v99, v163
	v_fmac_f32_e32 v148, v96, v164
	v_fmac_f32_e32 v140, v103, v141
	s_waitcnt lgkmcnt(0)
	v_mul_f32_e32 v141, v106, v166
	v_fmac_f32_e32 v148, v97, v165
	v_fmac_f32_e32 v140, v100, v142
	v_fmac_f32_e32 v141, v107, v167
	v_add_f32_e32 v148, 0, v148
	v_fmac_f32_e32 v140, v101, v143
	v_fmac_f32_e32 v141, v104, v168
	v_mul_f32_e32 v144, v108, v144
	v_add_f32_e32 v140, v140, v148
	v_fmac_f32_e32 v141, v105, v169
	v_fmac_f32_e32 v144, v109, v145
	v_add_f32_e32 v148, v141, v140
	v_fmac_f32_e32 v144, v110, v146
	ds_read_b128 v[140:143], v156 offset:25600
	ds_read_b128 v[162:165], v156 offset:24576
	v_fmac_f32_e32 v144, v111, v147
	v_add_f32_e32 v148, v144, v148
	ds_read_b128 v[144:147], v156 offset:27648
	ds_read_b128 v[166:169], v156 offset:26624
	s_waitcnt lgkmcnt(3)
	v_mul_f32_e32 v140, v102, v140
	s_waitcnt lgkmcnt(2)
	v_mul_f32_e32 v149, v98, v162
	v_fmac_f32_e32 v149, v99, v163
	v_fmac_f32_e32 v149, v96, v164
	v_fmac_f32_e32 v140, v103, v141
	s_waitcnt lgkmcnt(0)
	v_mul_f32_e32 v141, v106, v166
	v_fmac_f32_e32 v149, v97, v165
	v_fmac_f32_e32 v140, v100, v142
	v_fmac_f32_e32 v141, v107, v167
	v_add_f32_e32 v149, 0, v149
	v_fmac_f32_e32 v140, v101, v143
	v_fmac_f32_e32 v141, v104, v168
	v_mul_f32_e32 v144, v108, v144
	v_add_f32_e32 v140, v140, v149
	v_fmac_f32_e32 v141, v105, v169
	v_fmac_f32_e32 v144, v109, v145
	v_add_f32_e32 v149, v141, v140
	v_fmac_f32_e32 v144, v110, v146
	ds_read_b128 v[140:143], v156 offset:29696
	ds_read_b128 v[162:165], v156 offset:28672
	v_fmac_f32_e32 v144, v111, v147
	v_add_f32_e32 v149, v144, v149
	ds_read_b128 v[144:147], v156 offset:31744
	ds_read_b128 v[166:169], v156 offset:30720
	s_waitcnt lgkmcnt(3)
	v_mul_f32_e32 v140, v102, v140
	s_waitcnt lgkmcnt(2)
	v_mul_f32_e32 v161, v98, v162
	v_fmac_f32_e32 v161, v99, v163
	v_fmac_f32_e32 v161, v96, v164
	v_fmac_f32_e32 v140, v103, v141
	s_waitcnt lgkmcnt(0)
	v_mul_f32_e32 v141, v106, v166
	v_fmac_f32_e32 v161, v97, v165
	v_fmac_f32_e32 v140, v100, v142
	v_fmac_f32_e32 v141, v107, v167
	v_add_f32_e32 v161, 0, v161
	v_fmac_f32_e32 v140, v101, v143
	v_fmac_f32_e32 v141, v104, v168
	v_mul_f32_e32 v144, v108, v144
	v_add_f32_e32 v140, v140, v161
	v_fmac_f32_e32 v141, v105, v169
	v_fmac_f32_e32 v144, v109, v145
	v_add_f32_e32 v161, v141, v140
	ds_read_b128 v[140:143], v156 offset:32768
	v_fmac_f32_e32 v144, v110, v146
	v_fmac_f32_e32 v144, v111, v147
	v_add_f32_e32 v161, v144, v161
	ds_read_b128 v[144:147], v156 offset:33792
	s_waitcnt lgkmcnt(1)
	v_mul_f32_e32 v141, v99, v141
	v_fmac_f32_e32 v141, v98, v140
	v_fmac_f32_e32 v141, v96, v142
	v_fmac_f32_e32 v141, v97, v143
	s_waitcnt lgkmcnt(0)
	v_mul_f32_e32 v145, v103, v145
	v_fmac_f32_e32 v145, v102, v144
	v_add_f32_e32 v162, 0, v141
	ds_read_b128 v[140:143], v156 offset:34816
	v_fmac_f32_e32 v145, v100, v146
	v_fmac_f32_e32 v145, v101, v147
	v_add_f32_e32 v162, v162, v145
	ds_read_b128 v[144:147], v156 offset:35840
	s_waitcnt lgkmcnt(1)
	v_mul_f32_e32 v141, v107, v141
	v_fmac_f32_e32 v141, v106, v140
	v_fmac_f32_e32 v141, v104, v142
	v_fmac_f32_e32 v141, v105, v143
	s_waitcnt lgkmcnt(0)
	v_mul_f32_e32 v145, v109, v145
	v_fmac_f32_e32 v145, v108, v144
	v_add_f32_e32 v166, v162, v141
	v_fmac_f32_e32 v145, v110, v146
	ds_read_b128 v[140:143], v156 offset:37888
	ds_read_b128 v[162:165], v156 offset:36864
	v_fmac_f32_e32 v145, v111, v147
	v_add_f32_e32 v170, v166, v145
	ds_read_b128 v[144:147], v156 offset:39936
	ds_read_b128 v[166:169], v156 offset:38912
	s_waitcnt lgkmcnt(3)
	v_mul_f32_e32 v140, v102, v140
	s_waitcnt lgkmcnt(2)
	v_mul_f32_e32 v162, v98, v162
	v_fmac_f32_e32 v162, v99, v163
	v_fmac_f32_e32 v162, v96, v164
	v_fmac_f32_e32 v140, v103, v141
	s_waitcnt lgkmcnt(0)
	v_mul_f32_e32 v141, v106, v166
	v_fmac_f32_e32 v162, v97, v165
	v_fmac_f32_e32 v140, v100, v142
	v_fmac_f32_e32 v141, v107, v167
	v_add_f32_e32 v162, 0, v162
	v_fmac_f32_e32 v140, v101, v143
	v_fmac_f32_e32 v141, v104, v168
	v_mul_f32_e32 v144, v108, v144
	v_add_f32_e32 v140, v140, v162
	v_fmac_f32_e32 v141, v105, v169
	v_fmac_f32_e32 v144, v109, v145
	v_add_f32_e32 v166, v141, v140
	v_fmac_f32_e32 v144, v110, v146
	ds_read_b128 v[140:143], v156 offset:41984
	ds_read_b128 v[162:165], v156 offset:40960
	v_fmac_f32_e32 v144, v111, v147
	v_add_f32_e32 v171, v144, v166
	ds_read_b128 v[144:147], v156 offset:44032
	ds_read_b128 v[166:169], v156 offset:43008
	s_waitcnt lgkmcnt(3)
	v_mul_f32_e32 v140, v102, v140
	s_waitcnt lgkmcnt(2)
	v_mul_f32_e32 v162, v98, v162
	v_fmac_f32_e32 v162, v99, v163
	v_fmac_f32_e32 v162, v96, v164
	v_fmac_f32_e32 v140, v103, v141
	s_waitcnt lgkmcnt(0)
	v_mul_f32_e32 v141, v106, v166
	v_fmac_f32_e32 v162, v97, v165
	v_fmac_f32_e32 v140, v100, v142
	v_fmac_f32_e32 v141, v107, v167
	v_add_f32_e32 v162, 0, v162
	v_fmac_f32_e32 v140, v101, v143
	v_fmac_f32_e32 v141, v104, v168
	v_mul_f32_e32 v144, v108, v144
	v_add_f32_e32 v140, v140, v162
	v_fmac_f32_e32 v141, v105, v169
	v_fmac_f32_e32 v144, v109, v145
	v_add_f32_e32 v166, v141, v140
	v_fmac_f32_e32 v144, v110, v146
	ds_read_b128 v[140:143], v156 offset:46080
	ds_read_b128 v[162:165], v156 offset:45056
	v_fmac_f32_e32 v144, v111, v147
	v_add_f32_e32 v172, v144, v166
	ds_read_b128 v[144:147], v156 offset:48128
	ds_read_b128 v[166:169], v156 offset:47104
	s_waitcnt lgkmcnt(3)
	v_mul_f32_e32 v140, v102, v140
	s_waitcnt lgkmcnt(2)
	v_mul_f32_e32 v162, v98, v162
	v_fmac_f32_e32 v162, v99, v163
	v_fmac_f32_e32 v162, v96, v164
	v_fmac_f32_e32 v140, v103, v141
	s_waitcnt lgkmcnt(0)
	v_mul_f32_e32 v141, v106, v166
	v_fmac_f32_e32 v162, v97, v165
	v_fmac_f32_e32 v140, v100, v142
	v_fmac_f32_e32 v141, v107, v167
	v_add_f32_e32 v162, 0, v162
	v_fmac_f32_e32 v140, v101, v143
	v_fmac_f32_e32 v141, v104, v168
	v_mul_f32_e32 v144, v108, v144
	v_add_f32_e32 v140, v140, v162
	v_fmac_f32_e32 v141, v105, v169
	v_fmac_f32_e32 v144, v109, v145
	v_add_f32_e32 v162, v141, v140
	ds_read_b128 v[140:143], v156 offset:49152
	v_fmac_f32_e32 v144, v110, v146
	v_fmac_f32_e32 v144, v111, v147
	v_add_f32_e32 v173, v144, v162
	ds_read_b128 v[144:147], v156 offset:50176
	s_waitcnt lgkmcnt(1)
	v_mul_f32_e32 v141, v99, v141
	v_fmac_f32_e32 v141, v98, v140
	v_fmac_f32_e32 v141, v96, v142
	v_fmac_f32_e32 v141, v97, v143
	s_waitcnt lgkmcnt(0)
	v_mul_f32_e32 v145, v103, v145
	v_fmac_f32_e32 v145, v102, v144
	v_add_f32_e32 v162, 0, v141
	ds_read_b128 v[140:143], v156 offset:51200
	v_fmac_f32_e32 v145, v100, v146
	v_fmac_f32_e32 v145, v101, v147
	v_add_f32_e32 v162, v162, v145
	ds_read_b128 v[144:147], v156 offset:52224
	s_waitcnt lgkmcnt(1)
	v_mul_f32_e32 v141, v107, v141
	v_fmac_f32_e32 v141, v106, v140
	v_fmac_f32_e32 v141, v104, v142
	v_fmac_f32_e32 v141, v105, v143
	s_waitcnt lgkmcnt(0)
	v_mul_f32_e32 v145, v109, v145
	v_fmac_f32_e32 v145, v108, v144
	v_add_f32_e32 v166, v162, v141
	v_fmac_f32_e32 v145, v110, v146
	ds_read_b128 v[140:143], v156 offset:54272
	ds_read_b128 v[162:165], v156 offset:53248
	v_fmac_f32_e32 v145, v111, v147
	v_add_f32_e32 v174, v166, v145
	ds_read_b128 v[144:147], v156 offset:56320
	ds_read_b128 v[166:169], v156 offset:55296
	s_waitcnt lgkmcnt(3)
	v_mul_f32_e32 v140, v102, v140
	s_waitcnt lgkmcnt(2)
	v_mul_f32_e32 v162, v98, v162
	v_fmac_f32_e32 v162, v99, v163
	v_fmac_f32_e32 v162, v96, v164
	v_fmac_f32_e32 v140, v103, v141
	s_waitcnt lgkmcnt(0)
	v_mul_f32_e32 v141, v106, v166
	v_fmac_f32_e32 v162, v97, v165
	v_fmac_f32_e32 v140, v100, v142
	v_fmac_f32_e32 v141, v107, v167
	v_add_f32_e32 v162, 0, v162
	v_fmac_f32_e32 v140, v101, v143
	v_fmac_f32_e32 v141, v104, v168
	v_mul_f32_e32 v144, v108, v144
	v_add_f32_e32 v140, v140, v162
	v_fmac_f32_e32 v141, v105, v169
	v_fmac_f32_e32 v144, v109, v145
	v_add_f32_e32 v166, v141, v140
	v_fmac_f32_e32 v144, v110, v146
	ds_read_b128 v[140:143], v156 offset:58368
	ds_read_b128 v[162:165], v156 offset:57344
	v_fmac_f32_e32 v144, v111, v147
	v_add_f32_e32 v175, v144, v166
	ds_read_b128 v[144:147], v156 offset:60416
	ds_read_b128 v[166:169], v156 offset:59392
	s_waitcnt lgkmcnt(3)
	v_mul_f32_e32 v140, v102, v140
	s_waitcnt lgkmcnt(2)
	v_mul_f32_e32 v162, v98, v162
	v_fmac_f32_e32 v162, v99, v163
	v_fmac_f32_e32 v162, v96, v164
	v_fmac_f32_e32 v140, v103, v141
	s_waitcnt lgkmcnt(0)
	v_mul_f32_e32 v141, v106, v166
	v_fmac_f32_e32 v162, v97, v165
	v_fmac_f32_e32 v140, v100, v142
	v_fmac_f32_e32 v141, v107, v167
	v_add_f32_e32 v162, 0, v162
	v_fmac_f32_e32 v140, v101, v143
	v_fmac_f32_e32 v141, v104, v168
	v_add_f32_e32 v140, v140, v162
	v_fmac_f32_e32 v141, v105, v169
	v_add_f32_e32 v166, v141, v140
	ds_read_b128 v[140:143], v156 offset:62464
	ds_read_b128 v[162:165], v156 offset:61440
	v_mul_f32_e32 v144, v108, v144
	v_fmac_f32_e32 v144, v109, v145
	v_fmac_f32_e32 v144, v110, v146
	v_fmac_f32_e32 v144, v111, v147
	s_waitcnt lgkmcnt(0)
	v_mul_f32_e32 v98, v98, v162
	v_fmac_f32_e32 v98, v99, v163
	v_add_f32_e32 v176, v144, v166
	ds_read_b128 v[144:147], v156 offset:64512
	ds_read_b128 v[166:169], v156 offset:63488
	v_fmac_f32_e32 v98, v96, v164
	v_fmac_f32_e32 v98, v97, v165
	v_mul_f32_e32 v97, v102, v140
	v_fmac_f32_e32 v97, v103, v141
	v_fmac_f32_e32 v97, v100, v142
	v_add_f32_e32 v96, 0, v98
	v_fmac_f32_e32 v97, v101, v143
	v_add_f32_e32 v96, v97, v96
	s_waitcnt lgkmcnt(0)
	v_mul_f32_e32 v97, v106, v166
	v_fmac_f32_e32 v97, v107, v167
	v_fmac_f32_e32 v97, v104, v168
	v_fmac_f32_e32 v97, v105, v169
	v_add_f32_e32 v96, v97, v96
	v_mul_f32_e32 v97, v108, v144
	v_fmac_f32_e32 v97, v109, v145
	v_fmac_f32_e32 v97, v110, v146
	v_fmac_f32_e32 v97, v111, v147
	v_add_f32_e32 v96, v97, v96
	v_cndmask_b32_e64 v97, v115, v170, s[6:7]
	ds_bpermute_b32 v97, v150, v97
	v_cndmask_b32_e64 v99, v127, v171, s[6:7]
	ds_bpermute_b32 v99, v150, v99
	v_cndmask_b32_e64 v100, v129, v172, s[6:7]
	ds_bpermute_b32 v100, v150, v100
	v_cndmask_b32_e64 v98, v170, v115, s[6:7]
	s_waitcnt lgkmcnt(2)
	v_add_f32_e32 v97, v98, v97
	v_cndmask_b32_e64 v98, v171, v127, s[6:7]
	s_waitcnt lgkmcnt(1)
	v_add_f32_e32 v98, v98, v99
	v_cndmask_b32_e64 v99, v172, v129, s[6:7]
	s_waitcnt lgkmcnt(0)
	v_add_f32_e32 v99, v99, v100
	v_cndmask_b32_e64 v100, v138, v173, s[6:7]
	ds_bpermute_b32 v100, v150, v100
	v_cndmask_b32_e64 v102, v139, v174, s[6:7]
	ds_bpermute_b32 v102, v150, v102
	v_cndmask_b32_e64 v103, v148, v175, s[6:7]
	ds_bpermute_b32 v103, v150, v103
	v_cndmask_b32_e64 v101, v173, v138, s[6:7]
	s_waitcnt lgkmcnt(2)
	v_add_f32_e32 v100, v101, v100
	v_cndmask_b32_e64 v101, v174, v139, s[6:7]
	s_waitcnt lgkmcnt(1)
	v_add_f32_e32 v101, v101, v102
	v_cndmask_b32_e64 v102, v175, v148, s[6:7]
	s_waitcnt lgkmcnt(0)
	v_add_f32_e32 v102, v102, v103
	v_cndmask_b32_e64 v103, v149, v176, s[6:7]
	v_cndmask_b32_e64 v105, v161, v96, s[6:7]
	ds_bpermute_b32 v103, v150, v103
	ds_bpermute_b32 v105, v150, v105
	v_cndmask_b32_e64 v104, v176, v149, s[6:7]
	v_cndmask_b32_e64 v96, v96, v161, s[6:7]
	v_cndmask_b32_e64 v106, v97, v101, s[8:9]
	s_waitcnt lgkmcnt(1)
	v_add_f32_e32 v103, v104, v103
	s_waitcnt lgkmcnt(0)
	v_add_f32_e32 v96, v96, v105
	v_cndmask_b32_e64 v97, v101, v97, s[8:9]
	v_cndmask_b32_e64 v101, v98, v102, s[8:9]
	v_cndmask_b32_e64 v98, v102, v98, s[8:9]
	v_cndmask_b32_e64 v102, v99, v103, s[8:9]
	v_cndmask_b32_e64 v104, v100, v96, s[8:9]
	ds_bpermute_b32 v106, v151, v106
	ds_bpermute_b32 v101, v151, v101
	ds_bpermute_b32 v102, v151, v102
	ds_bpermute_b32 v104, v151, v104
	v_cndmask_b32_e64 v99, v103, v99, s[8:9]
	v_cndmask_b32_e64 v96, v96, v100, s[8:9]
	s_waitcnt lgkmcnt(3)
	v_add_f32_e32 v97, v97, v106
	s_waitcnt lgkmcnt(2)
	v_add_f32_e32 v98, v98, v101
	s_waitcnt lgkmcnt(1)
	v_add_f32_e32 v99, v99, v102
	s_waitcnt lgkmcnt(0)
	v_add_f32_e32 v96, v96, v104
	v_cndmask_b32_e64 v100, v97, v99, s[10:11]
	v_cndmask_b32_e64 v101, v98, v96, s[10:11]
	ds_bpermute_b32 v100, v152, v100
	ds_bpermute_b32 v101, v152, v101
	v_cndmask_b32_e64 v97, v99, v97, s[10:11]
	v_cndmask_b32_e64 v96, v96, v98, s[10:11]
	s_waitcnt lgkmcnt(1)
	v_add_f32_e32 v97, v97, v100
	s_waitcnt lgkmcnt(0)
	v_add_f32_e32 v96, v96, v101
	v_cndmask_b32_e64 v98, v97, v96, s[12:13]
	ds_bpermute_b32 v98, v153, v98
	v_cndmask_b32_e64 v96, v96, v97, s[12:13]
	s_waitcnt lgkmcnt(0)
	v_add_f32_e32 v96, v96, v98
	ds_bpermute_b32 v97, v154, v96
	s_waitcnt lgkmcnt(0)
	v_add_f32_e32 v96, v96, v97
	ds_bpermute_b32 v97, v155, v96
	s_waitcnt lgkmcnt(0)
	v_add_f32_e32 v96, v96, v97
	ds_bpermute_b32 v97, v153, v96
	s_waitcnt lgkmcnt(0)
	v_max_f32_e32 v97, v97, v97
	v_max_f32_e32 v97, v96, v97
	ds_bpermute_b32 v98, v152, v97
	s_waitcnt lgkmcnt(0)
	v_max_f32_e32 v98, v98, v98
	v_max_f32_e32 v97, v97, v98
	ds_bpermute_b32 v98, v151, v97
	s_waitcnt lgkmcnt(0)
	v_max_f32_e32 v98, v98, v98
	v_max_f32_e32 v97, v97, v98
	ds_bpermute_b32 v98, v150, v97
	s_waitcnt lgkmcnt(0)
	v_max_f32_e32 v98, v98, v98
	v_max_f32_e32 v97, v97, v98
	v_sub_f32_e32 v96, v96, v97
	v_mul_f32_e32 v97, 0x3fb8aa3b, v96
	v_fma_f32 v98, v96, s23, -v97
	v_rndne_f32_e32 v99, v97
	v_fmac_f32_e32 v98, 0x32a5705f, v96
	v_sub_f32_e32 v97, v97, v99
	v_add_f32_e32 v97, v97, v98
	v_exp_f32_e32 v97, v97
	v_cvt_i32_f32_e32 v98, v99
	v_cmp_ngt_f32_e32 vcc, s26, v96
	v_ldexp_f32 v97, v97, v98
	s_nop 0
	v_cndmask_b32_e32 v97, 0, v97, vcc
	v_cmp_nlt_f32_e32 vcc, s27, v96
	s_nop 1
	v_cndmask_b32_e32 v96, v160, v97, vcc
	ds_bpermute_b32 v97, v153, v96
	s_waitcnt lgkmcnt(0)
	v_add_f32_e32 v97, v96, v97
	ds_bpermute_b32 v98, v152, v97
	s_waitcnt lgkmcnt(0)
	v_add_f32_e32 v97, v97, v98
	ds_bpermute_b32 v98, v151, v97
	s_waitcnt lgkmcnt(0)
	v_add_f32_e32 v97, v97, v98
	ds_bpermute_b32 v98, v150, v97
	s_and_saveexec_b64 s[24:25], s[14:15]
	s_cbranch_execz .LBB0_679
	s_waitcnt lgkmcnt(0)
	v_add_f32_e32 v97, v97, v98
	v_div_scale_f32 v98, s[28:29], v97, v97, v96
	v_rcp_f32_e32 v99, v98
	v_and_b32_e32 v100, 0xfff, v114
	v_fma_f32 v101, -v98, v99, 1.0
	v_fmac_f32_e32 v99, v101, v99
	v_div_scale_f32 v101, vcc, v96, v97, v96
	v_mul_f32_e32 v102, v101, v99
	v_fma_f32 v103, -v98, v102, v101
	v_fmac_f32_e32 v102, v103, v99
	v_fma_f32 v98, -v98, v102, v101
	v_div_fmas_f32 v98, v98, v99, v102
	v_div_fixup_f32 v98, v98, v97, v96
	v_lshl_or_b32 v96, v112, 4, v157
	v_ashrrev_i32_e32 v97, 31, v96
	v_lshlrev_b64 v[96:97], 14, v[96:97]
	v_lshl_add_u64 v[96:97], s[4:5], 0, v[96:97]
	v_lshlrev_b32_e32 v112, 2, v100
	v_lshl_add_u64 v[96:97], v[96:97], 0, v[112:113]
	global_store_dword v[96:97], v98, off
	s_branch .LBB0_679

.LBB0_954:
	s_or_b64 exec, exec, s[14:15]
	s_waitcnt lgkmcnt(0)
	s_barrier
	ds_read_b128 v[0:3], v139
	ds_read_b128 v[4:7], v139 offset:16
	s_add_i32 s19, s19, s18
	s_cmpk_lt_u32 s19, 0x100
	s_waitcnt lgkmcnt(1)
	v_mul_f32_e32 v8, 0xbfb8aa3b, v0
	v_mul_f32_e32 v9, 0xbfb8aa3b, v1
	v_exp_f32_e32 v8, v8
	v_exp_f32_e32 v9, v9
	s_nop 0
	v_pk_add_f32 v[12:13], v[8:9], 1.0 op_sel_hi:[1,0]
	s_nop 0
	v_div_scale_f32 v14, s[14:15], v13, v13, v1
	v_rcp_f32_e32 v15, v14
	v_div_scale_f32 v16, vcc, v1, v13, v1
	ds_read_b128 v[8:11], v139 offset:256
	v_fma_f32 v17, -v14, v15, 1.0
	v_fmac_f32_e32 v15, v17, v15
	v_mul_f32_e32 v17, v16, v15
	v_fma_f32 v18, -v14, v17, v16
	v_fmac_f32_e32 v17, v18, v15
	v_fma_f32 v14, -v14, v17, v16
	v_div_scale_f32 v16, s[14:15], v12, v12, v0
	v_rcp_f32_e32 v18, v16
	v_div_fmas_f32 v14, v14, v15, v17
	v_div_fixup_f32 v1, v14, v13, v1
	v_mul_f32_e32 v15, 0xbfb8aa3b, v3
	v_fma_f32 v13, -v16, v18, 1.0
	v_fmac_f32_e32 v18, v13, v18
	v_div_scale_f32 v13, vcc, v0, v12, v0
	v_mul_f32_e32 v17, v13, v18
	v_fma_f32 v14, -v16, v17, v13
	v_fmac_f32_e32 v17, v14, v18
	v_mul_f32_e32 v14, 0xbfb8aa3b, v2
	v_exp_f32_e32 v14, v14
	v_exp_f32_e32 v15, v15
	v_fma_f32 v13, -v16, v17, v13
	v_div_fmas_f32 v13, v13, v18, v17
	v_div_fixup_f32 v0, v13, v12, v0
	v_pk_add_f32 v[16:17], v[14:15], 1.0 op_sel_hi:[1,0]
	s_waitcnt lgkmcnt(0)
	v_pk_mul_f32 v[8:9], v[0:1], v[8:9]
	v_div_scale_f32 v18, s[14:15], v17, v17, v3
	v_rcp_f32_e32 v19, v18
	ds_read_b128 v[12:15], v139 offset:272
	v_fma_f32 v0, -v18, v19, 1.0
	v_fmac_f32_e32 v19, v0, v19
	v_div_scale_f32 v0, vcc, v3, v17, v3
	v_mul_f32_e32 v1, v0, v19
	v_fma_f32 v20, -v18, v1, v0
	v_fmac_f32_e32 v1, v20, v19
	v_div_scale_f32 v20, s[14:15], v16, v16, v2
	v_fma_f32 v0, -v18, v1, v0
	v_rcp_f32_e32 v21, v20
	v_div_fmas_f32 v0, v0, v19, v1
	v_div_fixup_f32 v1, v0, v17, v3
	v_mul_f32_e32 v17, 0xbfb8aa3b, v4
	v_exp_f32_e32 v18, v17
	v_mul_f32_e32 v17, 0xbfb8aa3b, v5
	v_fma_f32 v0, -v20, v21, 1.0
	v_exp_f32_e32 v19, v17
	v_fmac_f32_e32 v21, v0, v21
	v_div_scale_f32 v0, vcc, v2, v16, v2
	v_mul_f32_e32 v3, v0, v21
	v_fma_f32 v17, -v20, v3, v0
	v_fmac_f32_e32 v3, v17, v21
	v_pk_add_f32 v[18:19], v[18:19], 1.0 op_sel_hi:[1,0]
	v_fma_f32 v0, -v20, v3, v0
	v_div_scale_f32 v20, s[14:15], v19, v19, v5
	v_rcp_f32_e32 v22, v20
	v_div_fmas_f32 v0, v0, v21, v3
	v_div_fixup_f32 v0, v0, v16, v2
	v_pk_mul_f32 v[16:17], v[0:1], v[10:11]
	v_fma_f32 v0, -v20, v22, 1.0
	v_fmac_f32_e32 v22, v0, v22
	v_div_scale_f32 v0, vcc, v5, v19, v5
	v_mul_f32_e32 v1, v0, v22
	v_fma_f32 v2, -v20, v1, v0
	v_fmac_f32_e32 v1, v2, v22
	v_div_scale_f32 v10, s[14:15], v18, v18, v4
	v_fma_f32 v0, -v20, v1, v0
	v_rcp_f32_e32 v20, v10
	v_div_fmas_f32 v0, v0, v22, v1
	v_div_fixup_f32 v1, v0, v19, v5
	v_mul_f32_e32 v2, 0xbfb8aa3b, v6
	v_fma_f32 v0, -v10, v20, 1.0
	v_mul_f32_e32 v3, 0xbfb8aa3b, v7
	v_fmac_f32_e32 v20, v0, v20
	v_div_scale_f32 v0, vcc, v4, v18, v4
	v_exp_f32_e32 v2, v2
	v_exp_f32_e32 v3, v3
	v_mul_f32_e32 v5, v0, v20
	v_fma_f32 v11, -v10, v5, v0
	v_fmac_f32_e32 v5, v11, v20
	v_fma_f32 v0, -v10, v5, v0
	v_pk_add_f32 v[10:11], v[2:3], 1.0 op_sel_hi:[1,0]
	v_div_fmas_f32 v0, v0, v20, v5
	v_div_scale_f32 v2, s[14:15], v11, v11, v7
	v_rcp_f32_e32 v3, v2
	v_div_fixup_f32 v0, v0, v18, v4
	s_waitcnt lgkmcnt(0)
	v_pk_mul_f32 v[12:13], v[0:1], v[12:13]
	v_fma_f32 v0, -v2, v3, 1.0
	v_fmac_f32_e32 v3, v0, v3
	v_div_scale_f32 v0, vcc, v7, v11, v7
	v_mul_f32_e32 v1, v0, v3
	v_fma_f32 v4, -v2, v1, v0
	v_fmac_f32_e32 v1, v4, v3
	v_fma_f32 v0, -v2, v1, v0
	v_div_scale_f32 v2, s[14:15], v10, v10, v6
	v_rcp_f32_e32 v4, v2
	v_div_fmas_f32 v0, v0, v3, v1
	v_div_fixup_f32 v5, v0, v11, v7
	v_fma_f32 v0, -v2, v4, 1.0
	v_fmac_f32_e32 v4, v0, v4
	v_div_scale_f32 v0, vcc, v6, v10, v6
	v_mul_f32_e32 v1, v0, v4
	v_fma_f32 v3, -v2, v1, v0
	v_fmac_f32_e32 v1, v3, v4
	v_fma_f32 v0, -v2, v1, v0
	v_div_fmas_f32 v4, v0, v4, v1
	ds_read_b128 v[0:3], v138
	v_div_fixup_f32 v4, v4, v10, v6
	v_pk_mul_f32 v[14:15], v[4:5], v[14:15]
	v_cvt_pk_bf16_f32 v6, v12, v13
	v_cvt_pk_bf16_f32 v7, v14, v15
	s_waitcnt lgkmcnt(0)
	v_mul_f32_e32 v5, 0xbfb8aa3b, v0
	v_exp_f32_e32 v18, v5
	v_mul_f32_e32 v5, 0xbfb8aa3b, v1
	v_exp_f32_e32 v19, v5
	v_cvt_pk_bf16_f32 v5, v16, v17
	v_add_co_u32_e32 v14, vcc, s24, v134
	v_pk_add_f32 v[12:13], v[18:19], 1.0 op_sel_hi:[1,0]
	v_cvt_pk_bf16_f32 v4, v8, v9
	v_div_scale_f32 v16, s[14:15], v13, v13, v1
	v_rcp_f32_e32 v17, v16
	v_addc_co_u32_e32 v15, vcc, 0, v135, vcc
	global_store_dwordx4 v[14:15], v[4:7], off sc1
	v_fma_f32 v14, -v16, v17, 1.0
	v_fmac_f32_e32 v17, v14, v17
	v_div_scale_f32 v14, vcc, v1, v13, v1
	v_mul_f32_e32 v15, v14, v17
	v_fma_f32 v18, -v16, v15, v14
	v_fmac_f32_e32 v15, v18, v17
	v_fma_f32 v14, -v16, v15, v14
	v_div_scale_f32 v16, s[14:15], v12, v12, v0
	v_rcp_f32_e32 v18, v16
	v_div_fmas_f32 v14, v14, v17, v15
	v_div_fixup_f32 v1, v14, v13, v1
	v_mul_f32_e32 v15, 0xbfb8aa3b, v3
	v_fma_f32 v13, -v16, v18, 1.0
	v_fmac_f32_e32 v18, v13, v18
	v_div_scale_f32 v13, vcc, v0, v12, v0
	v_mul_f32_e32 v17, v13, v18
	v_fma_f32 v14, -v16, v17, v13
	v_fmac_f32_e32 v17, v14, v18
	v_mul_f32_e32 v14, 0xbfb8aa3b, v2
	v_exp_f32_e32 v14, v14
	v_exp_f32_e32 v15, v15
	v_fma_f32 v13, -v16, v17, v13
	v_div_fmas_f32 v13, v13, v18, v17
	ds_read_b128 v[4:7], v138 offset:256
	v_pk_add_f32 v[16:17], v[14:15], 1.0 op_sel_hi:[1,0]
	v_div_fixup_f32 v0, v13, v12, v0
	v_div_scale_f32 v20, s[14:15], v17, v17, v3
	v_rcp_f32_e32 v21, v20
	s_waitcnt lgkmcnt(0)
	v_pk_mul_f32 v[18:19], v[0:1], v[4:5]
	ds_read_b128 v[8:11], v138 offset:16
	ds_read_b128 v[12:15], v138 offset:272
	v_fma_f32 v0, -v20, v21, 1.0
	v_fmac_f32_e32 v21, v0, v21
	v_div_scale_f32 v0, vcc, v3, v17, v3
	v_mul_f32_e32 v1, v0, v21
	v_fma_f32 v4, -v20, v1, v0
	v_fmac_f32_e32 v1, v4, v21
	v_fma_f32 v0, -v20, v1, v0
	v_div_scale_f32 v20, s[14:15], v16, v16, v2
	v_rcp_f32_e32 v22, v20
	v_div_fmas_f32 v0, v0, v21, v1
	s_waitcnt lgkmcnt(1)
	v_mul_f32_e32 v4, 0xbfb8aa3b, v8
	v_mul_f32_e32 v5, 0xbfb8aa3b, v9
	v_div_fixup_f32 v1, v0, v17, v3
	v_fma_f32 v0, -v20, v22, 1.0
	v_exp_f32_e32 v4, v4
	v_exp_f32_e32 v5, v5
	v_fmac_f32_e32 v22, v0, v22
	v_div_scale_f32 v0, vcc, v2, v16, v2
	v_mul_f32_e32 v3, v0, v22
	v_fma_f32 v17, -v20, v3, v0
	v_fmac_f32_e32 v3, v17, v22
	v_pk_add_f32 v[4:5], v[4:5], 1.0 op_sel_hi:[1,0]
	v_fma_f32 v0, -v20, v3, v0
	v_div_scale_f32 v20, s[14:15], v5, v5, v9
	v_rcp_f32_e32 v21, v20
	v_div_fmas_f32 v0, v0, v22, v3
	v_div_fixup_f32 v0, v0, v16, v2
	v_pk_mul_f32 v[16:17], v[0:1], v[6:7]
	v_fma_f32 v0, -v20, v21, 1.0
	v_fmac_f32_e32 v21, v0, v21
	v_div_scale_f32 v0, vcc, v9, v5, v9
	v_mul_f32_e32 v1, v0, v21
	v_fma_f32 v2, -v20, v1, v0
	v_fmac_f32_e32 v1, v2, v21
	v_div_scale_f32 v6, s[14:15], v4, v4, v8
	v_fma_f32 v0, -v20, v1, v0
	v_rcp_f32_e32 v20, v6
	v_div_fmas_f32 v0, v0, v21, v1
	v_div_fixup_f32 v1, v0, v5, v9
	v_mul_f32_e32 v2, 0xbfb8aa3b, v10
	v_fma_f32 v0, -v6, v20, 1.0
	v_mul_f32_e32 v3, 0xbfb8aa3b, v11
	v_fmac_f32_e32 v20, v0, v20
	v_div_scale_f32 v0, vcc, v8, v4, v8
	v_exp_f32_e32 v2, v2
	v_exp_f32_e32 v3, v3
	v_mul_f32_e32 v5, v0, v20
	v_fma_f32 v7, -v6, v5, v0
	v_fmac_f32_e32 v5, v7, v20
	v_fma_f32 v0, -v6, v5, v0
	v_pk_add_f32 v[6:7], v[2:3], 1.0 op_sel_hi:[1,0]
	v_div_fmas_f32 v0, v0, v20, v5
	v_div_scale_f32 v2, s[14:15], v7, v7, v11
	v_rcp_f32_e32 v3, v2
	v_div_fixup_f32 v0, v0, v4, v8
	s_waitcnt lgkmcnt(0)
	v_pk_mul_f32 v[4:5], v[0:1], v[12:13]
	v_fma_f32 v0, -v2, v3, 1.0
	v_fmac_f32_e32 v3, v0, v3
	v_div_scale_f32 v0, vcc, v11, v7, v11
	v_mul_f32_e32 v1, v0, v3
	v_fma_f32 v8, -v2, v1, v0
	v_fmac_f32_e32 v1, v8, v3
	v_fma_f32 v0, -v2, v1, v0
	v_div_scale_f32 v2, s[14:15], v6, v6, v10
	v_rcp_f32_e32 v8, v2
	v_div_fmas_f32 v0, v0, v3, v1
	v_div_fixup_f32 v7, v0, v7, v11
	v_fma_f32 v0, -v2, v8, 1.0
	v_fmac_f32_e32 v8, v0, v8
	v_div_scale_f32 v0, vcc, v10, v6, v10
	v_mul_f32_e32 v1, v0, v8
	v_fma_f32 v3, -v2, v1, v0
	v_fmac_f32_e32 v1, v3, v8
	v_fma_f32 v0, -v2, v1, v0
	v_div_fmas_f32 v8, v0, v8, v1
	ds_read_b128 v[0:3], v139 offset:33792
	v_div_fixup_f32 v6, v8, v6, v10
	v_pk_mul_f32 v[6:7], v[6:7], v[14:15]
	v_add_co_u32_e32 v14, vcc, s24, v136
	v_cvt_pk_bf16_f32 v7, v6, v7
	s_waitcnt lgkmcnt(0)
	v_mul_f32_e32 v6, 0xbfb8aa3b, v0
	v_exp_f32_e32 v12, v6
	v_mul_f32_e32 v6, 0xbfb8aa3b, v1
	v_exp_f32_e32 v13, v6
	v_cvt_pk_bf16_f32 v6, v4, v5
	v_cvt_pk_bf16_f32 v5, v16, v17
	v_cvt_pk_bf16_f32 v4, v18, v19
	v_pk_add_f32 v[12:13], v[12:13], 1.0 op_sel_hi:[1,0]
	v_addc_co_u32_e32 v15, vcc, 0, v137, vcc
	v_div_scale_f32 v16, s[14:15], v13, v13, v1
	v_rcp_f32_e32 v17, v16
	global_store_dwordx4 v[14:15], v[4:7], off sc1
	ds_read_b128 v[4:7], v139 offset:34048
	ds_read_b128 v[8:11], v139 offset:33808
	v_fma_f32 v14, -v16, v17, 1.0
	v_fmac_f32_e32 v17, v14, v17
	v_div_scale_f32 v14, vcc, v1, v13, v1
	v_mul_f32_e32 v15, v14, v17
	v_fma_f32 v18, -v16, v15, v14
	v_fmac_f32_e32 v15, v18, v17
	v_fma_f32 v14, -v16, v15, v14
	v_div_scale_f32 v16, s[14:15], v12, v12, v0
	v_rcp_f32_e32 v18, v16
	v_div_fmas_f32 v14, v14, v17, v15
	v_div_fixup_f32 v1, v14, v13, v1
	v_mul_f32_e32 v15, 0xbfb8aa3b, v3
	v_fma_f32 v13, -v16, v18, 1.0
	v_fmac_f32_e32 v18, v13, v18
	v_div_scale_f32 v13, vcc, v0, v12, v0
	v_mul_f32_e32 v17, v13, v18
	v_fma_f32 v14, -v16, v17, v13
	v_fmac_f32_e32 v17, v14, v18
	v_mul_f32_e32 v14, 0xbfb8aa3b, v2
	v_exp_f32_e32 v14, v14
	v_exp_f32_e32 v15, v15
	v_fma_f32 v13, -v16, v17, v13
	v_div_fmas_f32 v13, v13, v18, v17
	v_div_fixup_f32 v0, v13, v12, v0
	v_pk_add_f32 v[16:17], v[14:15], 1.0 op_sel_hi:[1,0]
	s_waitcnt lgkmcnt(1)
	v_pk_mul_f32 v[4:5], v[0:1], v[4:5]
	v_div_scale_f32 v18, s[14:15], v17, v17, v3
	v_rcp_f32_e32 v19, v18
	ds_read_b128 v[12:15], v139 offset:34064
	v_cvt_pk_bf16_f32 v4, v4, v5
	v_fma_f32 v0, -v18, v19, 1.0
	v_fmac_f32_e32 v19, v0, v19
	v_div_scale_f32 v0, vcc, v3, v17, v3
	v_mul_f32_e32 v1, v0, v19
	v_fma_f32 v20, -v18, v1, v0
	v_fmac_f32_e32 v1, v20, v19
	v_fma_f32 v0, -v18, v1, v0
	v_div_scale_f32 v20, s[14:15], v16, v16, v2
	v_rcp_f32_e32 v21, v20
	v_div_fmas_f32 v0, v0, v19, v1
	v_div_fixup_f32 v1, v0, v17, v3
	s_waitcnt lgkmcnt(1)
	v_mul_f32_e32 v17, 0xbfb8aa3b, v8
	v_exp_f32_e32 v18, v17
	v_mul_f32_e32 v17, 0xbfb8aa3b, v9
	v_exp_f32_e32 v19, v17
	v_fma_f32 v0, -v20, v21, 1.0
	v_fmac_f32_e32 v21, v0, v21
	v_div_scale_f32 v0, vcc, v2, v16, v2
	v_mul_f32_e32 v3, v0, v21
	v_fma_f32 v17, -v20, v3, v0
	v_pk_add_f32 v[18:19], v[18:19], 1.0 op_sel_hi:[1,0]
	v_fmac_f32_e32 v3, v17, v21
	v_div_scale_f32 v17, s[14:15], v19, v19, v9
	v_fma_f32 v0, -v20, v3, v0
	v_rcp_f32_e32 v20, v17
	v_div_fmas_f32 v0, v0, v21, v3
	v_div_fixup_f32 v0, v0, v16, v2
	v_pk_mul_f32 v[6:7], v[0:1], v[6:7]
	v_fma_f32 v0, -v17, v20, 1.0
	v_fmac_f32_e32 v20, v0, v20
	v_div_scale_f32 v0, vcc, v9, v19, v9
	v_mul_f32_e32 v1, v0, v20
	v_div_scale_f32 v16, s[14:15], v18, v18, v8
	v_fma_f32 v2, -v17, v1, v0
	v_rcp_f32_e32 v21, v16
	v_fmac_f32_e32 v1, v2, v20
	v_fma_f32 v0, -v17, v1, v0
	v_div_fmas_f32 v0, v0, v20, v1
	v_div_fixup_f32 v1, v0, v19, v9
	v_fma_f32 v0, -v16, v21, 1.0
	v_mul_f32_e32 v2, 0xbfb8aa3b, v10
	v_mul_f32_e32 v3, 0xbfb8aa3b, v11
	v_fmac_f32_e32 v21, v0, v21
	v_div_scale_f32 v0, vcc, v8, v18, v8
	v_exp_f32_e32 v2, v2
	v_exp_f32_e32 v3, v3
	v_mul_f32_e32 v9, v0, v21
	v_fma_f32 v17, -v16, v9, v0
	v_fmac_f32_e32 v9, v17, v21
	v_fma_f32 v0, -v16, v9, v0
	v_pk_add_f32 v[16:17], v[2:3], 1.0 op_sel_hi:[1,0]
	v_div_fmas_f32 v0, v0, v21, v9
	v_div_scale_f32 v2, s[14:15], v17, v17, v11
	v_rcp_f32_e32 v3, v2
	v_div_fixup_f32 v0, v0, v18, v8
	s_waitcnt lgkmcnt(0)
	v_pk_mul_f32 v[12:13], v[0:1], v[12:13]
	v_fma_f32 v0, -v2, v3, 1.0
	v_fmac_f32_e32 v3, v0, v3
	v_div_scale_f32 v0, vcc, v11, v17, v11
	v_mul_f32_e32 v1, v0, v3
	v_fma_f32 v8, -v2, v1, v0
	v_fmac_f32_e32 v1, v8, v3
	v_fma_f32 v0, -v2, v1, v0
	v_div_scale_f32 v2, s[14:15], v16, v16, v10
	v_rcp_f32_e32 v8, v2
	v_div_fmas_f32 v0, v0, v3, v1
	v_div_fixup_f32 v9, v0, v17, v11
	v_fma_f32 v0, -v2, v8, 1.0
	v_fmac_f32_e32 v8, v0, v8
	v_div_scale_f32 v0, vcc, v10, v16, v10
	v_mul_f32_e32 v1, v0, v8
	v_fma_f32 v3, -v2, v1, v0
	v_fmac_f32_e32 v1, v3, v8
	v_fma_f32 v0, -v2, v1, v0
	v_div_fmas_f32 v8, v0, v8, v1
	ds_read_b128 v[0:3], v138 offset:33792
	v_div_fixup_f32 v8, v8, v16, v10
	v_pk_mul_f32 v[14:15], v[8:9], v[14:15]
	ds_read_b128 v[8:11], v138 offset:33808
	s_waitcnt lgkmcnt(1)
	v_mul_f32_e32 v5, 0xbfb8aa3b, v0
	v_exp_f32_e32 v16, v5
	v_mul_f32_e32 v5, 0xbfb8aa3b, v1
	v_exp_f32_e32 v17, v5
	v_cvt_pk_bf16_f32 v5, v6, v7
	v_cvt_pk_bf16_f32 v6, v12, v13
	v_cvt_pk_bf16_f32 v7, v14, v15
	v_pk_add_f32 v[12:13], v[16:17], 1.0 op_sel_hi:[1,0]
	v_add_co_u32_e32 v14, vcc, s25, v134
	v_div_scale_f32 v16, s[14:15], v13, v13, v1
	v_rcp_f32_e32 v17, v16
	v_addc_co_u32_e32 v15, vcc, 0, v135, vcc
	global_store_dwordx4 v[14:15], v[4:7], off sc1
	v_fma_f32 v14, -v16, v17, 1.0
	v_fmac_f32_e32 v17, v14, v17
	v_div_scale_f32 v14, vcc, v1, v13, v1
	v_mul_f32_e32 v15, v14, v17
	v_fma_f32 v18, -v16, v15, v14
	v_fmac_f32_e32 v15, v18, v17
	v_fma_f32 v14, -v16, v15, v14
	v_div_scale_f32 v16, s[14:15], v12, v12, v0
	v_rcp_f32_e32 v18, v16
	v_div_fmas_f32 v14, v14, v17, v15
	v_div_fixup_f32 v1, v14, v13, v1
	v_mul_f32_e32 v15, 0xbfb8aa3b, v3
	v_fma_f32 v13, -v16, v18, 1.0
	v_fmac_f32_e32 v18, v13, v18
	v_div_scale_f32 v13, vcc, v0, v12, v0
	v_mul_f32_e32 v17, v13, v18
	v_fma_f32 v14, -v16, v17, v13
	v_fmac_f32_e32 v17, v14, v18
	v_mul_f32_e32 v14, 0xbfb8aa3b, v2
	v_exp_f32_e32 v14, v14
	v_exp_f32_e32 v15, v15
	v_fma_f32 v13, -v16, v17, v13
	v_div_fmas_f32 v13, v13, v18, v17
	ds_read_b128 v[4:7], v138 offset:34048
	v_pk_add_f32 v[16:17], v[14:15], 1.0 op_sel_hi:[1,0]
	v_div_fixup_f32 v0, v13, v12, v0
	v_div_scale_f32 v18, s[14:15], v17, v17, v3
	v_rcp_f32_e32 v19, v18
	s_waitcnt lgkmcnt(0)
	v_pk_mul_f32 v[4:5], v[0:1], v[4:5]
	ds_read_b128 v[12:15], v138 offset:34064
	v_fma_f32 v0, -v18, v19, 1.0
	v_fmac_f32_e32 v19, v0, v19
	v_div_scale_f32 v0, vcc, v3, v17, v3
	v_mul_f32_e32 v1, v0, v19
	v_fma_f32 v20, -v18, v1, v0
	v_fmac_f32_e32 v1, v20, v19
	v_fma_f32 v0, -v18, v1, v0
	v_div_scale_f32 v20, s[14:15], v16, v16, v2
	v_rcp_f32_e32 v21, v20
	v_div_fmas_f32 v0, v0, v19, v1
	v_div_fixup_f32 v1, v0, v17, v3
	v_mul_f32_e32 v17, 0xbfb8aa3b, v8
	v_exp_f32_e32 v18, v17
	v_mul_f32_e32 v17, 0xbfb8aa3b, v9
	v_exp_f32_e32 v19, v17
	v_fma_f32 v0, -v20, v21, 1.0
	v_fmac_f32_e32 v21, v0, v21
	v_div_scale_f32 v0, vcc, v2, v16, v2
	v_mul_f32_e32 v3, v0, v21
	v_fma_f32 v17, -v20, v3, v0
	v_pk_add_f32 v[18:19], v[18:19], 1.0 op_sel_hi:[1,0]
	v_fmac_f32_e32 v3, v17, v21
	v_div_scale_f32 v17, s[14:15], v19, v19, v9
	v_fma_f32 v0, -v20, v3, v0
	v_rcp_f32_e32 v20, v17
	v_div_fmas_f32 v0, v0, v21, v3
	v_div_fixup_f32 v0, v0, v16, v2
	v_pk_mul_f32 v[0:1], v[0:1], v[6:7]
	v_fma_f32 v2, -v17, v20, 1.0
	v_fmac_f32_e32 v20, v2, v20
	v_div_scale_f32 v2, vcc, v9, v19, v9
	v_mul_f32_e32 v3, v2, v20
	v_fma_f32 v6, -v17, v3, v2
	v_fmac_f32_e32 v3, v6, v20
	v_div_scale_f32 v16, s[14:15], v18, v18, v8
	v_fma_f32 v2, -v17, v3, v2
	v_rcp_f32_e32 v17, v16
	v_div_fmas_f32 v2, v2, v20, v3
	v_mul_f32_e32 v6, 0xbfb8aa3b, v10
	v_mul_f32_e32 v7, 0xbfb8aa3b, v11
	v_div_fixup_f32 v3, v2, v19, v9
	v_fma_f32 v2, -v16, v17, 1.0
	v_exp_f32_e32 v6, v6
	v_exp_f32_e32 v7, v7
	v_fmac_f32_e32 v17, v2, v17
	v_div_scale_f32 v2, vcc, v8, v18, v8
	v_mul_f32_e32 v9, v2, v17
	v_fma_f32 v19, -v16, v9, v2
	v_fmac_f32_e32 v9, v19, v17
	v_pk_add_f32 v[6:7], v[6:7], 1.0 op_sel_hi:[1,0]
	v_fma_f32 v2, -v16, v9, v2
	v_div_scale_f32 v16, s[14:15], v7, v7, v11
	v_rcp_f32_e32 v19, v16
	v_div_fmas_f32 v2, v2, v17, v9
	v_div_fixup_f32 v2, v2, v18, v8
	s_waitcnt lgkmcnt(0)
	v_pk_mul_f32 v[8:9], v[2:3], v[12:13]
	v_fma_f32 v2, -v16, v19, 1.0
	v_fmac_f32_e32 v19, v2, v19
	v_div_scale_f32 v2, vcc, v11, v7, v11
	v_mul_f32_e32 v3, v2, v19
	v_fma_f32 v12, -v16, v3, v2
	v_fmac_f32_e32 v3, v12, v19
	v_div_scale_f32 v12, s[14:15], v6, v6, v10
	v_rcp_f32_e32 v13, v12
	v_fma_f32 v2, -v16, v3, v2
	v_div_fmas_f32 v2, v2, v19, v3
	v_div_fixup_f32 v3, v2, v7, v11
	v_fma_f32 v2, -v12, v13, 1.0
	v_fmac_f32_e32 v13, v2, v13
	v_div_scale_f32 v2, vcc, v10, v6, v10
	v_mul_f32_e32 v7, v2, v13
	v_fma_f32 v11, -v12, v7, v2
	v_fmac_f32_e32 v7, v11, v13
	v_fma_f32 v2, -v12, v7, v2
	v_div_fmas_f32 v2, v2, v13, v7
	v_div_fixup_f32 v2, v2, v6, v10
	v_pk_mul_f32 v[2:3], v[2:3], v[14:15]
	v_cvt_pk_bf16_f32 v1, v0, v1
	v_cvt_pk_bf16_f32 v0, v4, v5
	v_add_co_u32_e32 v4, vcc, 0x60000, v136
	v_cvt_pk_bf16_f32 v3, v2, v3
	v_cvt_pk_bf16_f32 v2, v8, v9
	v_addc_co_u32_e32 v5, vcc, 0, v137, vcc
	global_store_dwordx4 v[4:5], v[0:3], off sc1
	s_barrier
	s_cbranch_scc0 .LBB0_961

.LBB0_959:
	s_or_b64 exec, exec, s[14:15]
	v_lshlrev_b32_e32 v134, 3, v128
	v_and_b32_e32 v137, 56, v134
	v_ashrrev_i32_e32 v134, 3, v128
	v_mul_lo_u32 v135, v134, s22
	v_lshlrev_b32_e32 v138, 2, v137
	v_add3_u32 v139, 0, v135, v138
	s_waitcnt lgkmcnt(0)
	s_barrier
	ds_read_b128 v[194:197], v139
	v_add_u32_e32 v128, 0x100, v128
	s_lshl_b32 s10, s26, 19
	s_lshl_b32 s14, s27, 20
	v_ashrrev_i32_e32 v136, 3, v128
	s_waitcnt lgkmcnt(0)
	v_mul_f32_e32 v135, 0xbfb8aa3b, v194
	v_exp_f32_e32 v202, v135
	v_mul_f32_e32 v135, 0xbfb8aa3b, v195
	v_exp_f32_e32 v203, v135
	ds_read_b128 v[198:201], v139 offset:16
	s_or_b32 s10, s14, s10
	s_add_u32 s10, s16, s10
	v_pk_add_f32 v[206:207], v[202:203], 1.0 op_sel_hi:[1,0]
	v_mul_lo_u32 v202, v136, s22
	v_div_scale_f32 v128, s[26:27], v207, v207, v195
	v_rcp_f32_e32 v135, v128
	v_add3_u32 v138, 0, v202, v138
	ds_read_b128 v[202:205], v139 offset:256
	s_addc_u32 s15, s17, 0
	v_fma_f32 v208, -v128, v135, 1.0
	v_fmac_f32_e32 v135, v208, v135
	v_div_scale_f32 v208, vcc, v195, v207, v195
	v_mul_f32_e32 v209, v208, v135
	v_fma_f32 v210, -v128, v209, v208
	v_fmac_f32_e32 v209, v210, v135
	v_div_scale_f32 v210, s[26:27], v206, v206, v194
	v_rcp_f32_e32 v211, v210
	v_fma_f32 v128, -v128, v209, v208
	v_div_fmas_f32 v128, v128, v135, v209
	v_div_fixup_f32 v195, v128, v207, v195
	v_fma_f32 v128, -v210, v211, 1.0
	v_fmac_f32_e32 v211, v128, v211
	v_div_scale_f32 v128, vcc, v194, v206, v194
	v_mul_f32_e32 v135, v128, v211
	v_fma_f32 v207, -v210, v135, v128
	v_fmac_f32_e32 v135, v207, v211
	v_mul_f32_e32 v207, 0xbfb8aa3b, v196
	v_exp_f32_e32 v208, v207
	v_mul_f32_e32 v207, 0xbfb8aa3b, v197
	v_exp_f32_e32 v209, v207
	v_fma_f32 v128, -v210, v135, v128
	v_div_fmas_f32 v128, v128, v211, v135
	v_div_fixup_f32 v194, v128, v206, v194
	v_pk_add_f32 v[210:211], v[208:209], 1.0 op_sel_hi:[1,0]
	s_waitcnt lgkmcnt(0)
	v_pk_mul_f32 v[194:195], v[194:195], v[202:203]
	v_div_scale_f32 v135, s[26:27], v211, v211, v197
	v_rcp_f32_e32 v214, v135
	ds_read_b128 v[206:209], v139 offset:272
	s_lshl_b32 s14, s28, 7
	s_add_u32 s14, s10, s14
	v_fma_f32 v128, -v135, v214, 1.0
	v_fmac_f32_e32 v214, v128, v214
	v_div_scale_f32 v128, vcc, v197, v211, v197
	v_mul_f32_e32 v202, v128, v214
	v_fma_f32 v203, -v135, v202, v128
	v_fmac_f32_e32 v202, v203, v214
	v_fma_f32 v128, -v135, v202, v128
	v_div_scale_f32 v135, s[26:27], v210, v210, v196
	v_rcp_f32_e32 v215, v135
	v_div_fmas_f32 v128, v128, v214, v202
	v_mul_f32_e32 v202, 0xbfb8aa3b, v198
	v_mul_f32_e32 v203, 0xbfb8aa3b, v199
	v_div_fixup_f32 v197, v128, v211, v197
	v_fma_f32 v128, -v135, v215, 1.0
	v_exp_f32_e32 v202, v202
	v_exp_f32_e32 v203, v203
	v_fmac_f32_e32 v215, v128, v215
	v_div_scale_f32 v128, vcc, v196, v210, v196
	v_mul_f32_e32 v211, v128, v215
	v_fma_f32 v214, -v135, v211, v128
	v_fmac_f32_e32 v211, v214, v215
	v_pk_add_f32 v[202:203], v[202:203], 1.0 op_sel_hi:[1,0]
	v_fma_f32 v128, -v135, v211, v128
	v_div_scale_f32 v135, s[26:27], v203, v203, v199
	v_rcp_f32_e32 v214, v135
	v_div_fmas_f32 v128, v128, v215, v211
	v_div_fixup_f32 v196, v128, v210, v196
	v_pk_mul_f32 v[196:197], v[196:197], v[204:205]
	v_fma_f32 v128, -v135, v214, 1.0
	v_fmac_f32_e32 v214, v128, v214
	v_div_scale_f32 v128, vcc, v199, v203, v199
	v_mul_f32_e32 v204, v128, v214
	v_fma_f32 v205, -v135, v204, v128
	v_fmac_f32_e32 v204, v205, v214
	v_fma_f32 v128, -v135, v204, v128
	v_div_scale_f32 v135, s[26:27], v202, v202, v198
	v_rcp_f32_e32 v210, v135
	v_div_fmas_f32 v128, v128, v214, v204
	v_mul_f32_e32 v204, 0xbfb8aa3b, v200
	v_mul_f32_e32 v205, 0xbfb8aa3b, v201
	v_div_fixup_f32 v199, v128, v203, v199
	v_fma_f32 v128, -v135, v210, 1.0
	v_exp_f32_e32 v204, v204
	v_exp_f32_e32 v205, v205
	v_fmac_f32_e32 v210, v128, v210
	v_div_scale_f32 v128, vcc, v198, v202, v198
	v_mul_f32_e32 v203, v128, v210
	v_fma_f32 v211, -v135, v203, v128
	v_fmac_f32_e32 v203, v211, v210
	v_pk_add_f32 v[204:205], v[204:205], 1.0 op_sel_hi:[1,0]
	v_fma_f32 v128, -v135, v203, v128
	v_div_scale_f32 v135, s[26:27], v205, v205, v201
	v_rcp_f32_e32 v211, v135
	v_div_fmas_f32 v128, v128, v210, v203
	v_div_fixup_f32 v198, v128, v202, v198
	s_waitcnt lgkmcnt(0)
	v_pk_mul_f32 v[202:203], v[198:199], v[206:207]
	v_fma_f32 v128, -v135, v211, 1.0
	v_fmac_f32_e32 v211, v128, v211
	v_div_scale_f32 v128, vcc, v201, v205, v201
	v_mul_f32_e32 v198, v128, v211
	v_fma_f32 v199, -v135, v198, v128
	v_fmac_f32_e32 v198, v199, v211
	v_fma_f32 v128, -v135, v198, v128
	v_div_scale_f32 v135, s[26:27], v204, v204, v200
	v_rcp_f32_e32 v206, v135
	v_div_fmas_f32 v128, v128, v211, v198
	v_div_fixup_f32 v199, v128, v205, v201
	s_addc_u32 s15, s15, 0
	v_fma_f32 v128, -v135, v206, 1.0
	v_fmac_f32_e32 v206, v128, v206
	v_div_scale_f32 v128, vcc, v200, v204, v200
	v_mul_f32_e32 v198, v128, v206
	v_fma_f32 v201, -v135, v198, v128
	v_fmac_f32_e32 v198, v201, v206
	v_fma_f32 v128, -v135, v198, v128
	v_div_fmas_f32 v128, v128, v206, v198
	v_div_fixup_f32 v198, v128, v204, v200
	v_pk_mul_f32 v[204:205], v[198:199], v[208:209]
	ds_read_b128 v[198:201], v138
	v_ashrrev_i32_e32 v135, 31, v134
	v_lshlrev_b64 v[134:135], 11, v[134:135]
	v_lshl_add_u64 v[134:135], s[14:15], 0, v[134:135]
	v_cvt_pk_bf16_f32 v194, v194, v195
	s_waitcnt lgkmcnt(0)
	v_mul_f32_e32 v128, 0xbfb8aa3b, v198
	v_exp_f32_e32 v206, v128
	v_mul_f32_e32 v128, 0xbfb8aa3b, v199
	v_exp_f32_e32 v207, v128
	v_lshlrev_b32_e32 v128, 1, v137
	v_cvt_pk_bf16_f32 v195, v196, v197
	v_cvt_pk_bf16_f32 v196, v202, v203
	v_pk_add_f32 v[206:207], v[206:207], 1.0 op_sel_hi:[1,0]
	v_cvt_pk_bf16_f32 v197, v204, v205
	v_div_scale_f32 v137, s[26:27], v207, v207, v199
	v_rcp_f32_e32 v208, v137
	v_lshl_add_u64 v[134:135], v[134:135], 0, v[128:129]
	global_store_dwordx4 v[134:135], v[194:197], off sc1
	ds_read_b128 v[194:197], v138 offset:256
	v_fma_f32 v209, -v137, v208, 1.0
	v_fmac_f32_e32 v208, v209, v208
	v_div_scale_f32 v209, vcc, v199, v207, v199
	v_mul_f32_e32 v210, v209, v208
	v_fma_f32 v211, -v137, v210, v209
	v_fmac_f32_e32 v210, v211, v208
	v_div_scale_f32 v211, s[26:27], v206, v206, v198
	v_rcp_f32_e32 v214, v211
	v_fma_f32 v137, -v137, v210, v209
	v_div_fmas_f32 v137, v137, v208, v210
	v_div_fixup_f32 v199, v137, v207, v199
	v_fma_f32 v137, -v211, v214, 1.0
	v_fmac_f32_e32 v214, v137, v214
	v_div_scale_f32 v137, vcc, v198, v206, v198
	v_mul_f32_e32 v207, v137, v214
	v_fma_f32 v208, -v211, v207, v137
	v_fmac_f32_e32 v207, v208, v214
	v_mul_f32_e32 v208, 0xbfb8aa3b, v200
	v_mul_f32_e32 v209, 0xbfb8aa3b, v201
	v_exp_f32_e32 v208, v208
	v_exp_f32_e32 v209, v209
	v_fma_f32 v137, -v211, v207, v137
	v_div_fmas_f32 v137, v137, v214, v207
	v_div_fixup_f32 v198, v137, v206, v198
	v_pk_add_f32 v[210:211], v[208:209], 1.0 op_sel_hi:[1,0]
	s_waitcnt lgkmcnt(0)
	v_pk_mul_f32 v[214:215], v[198:199], v[194:195]
	v_div_scale_f32 v216, s[26:27], v211, v211, v201
	v_rcp_f32_e32 v217, v216
	ds_read_b128 v[202:205], v138 offset:16
	ds_read_b128 v[206:209], v138 offset:272
	v_fma_f32 v137, -v216, v217, 1.0
	v_fmac_f32_e32 v217, v137, v217
	v_div_scale_f32 v137, vcc, v201, v211, v201
	v_mul_f32_e32 v194, v137, v217
	v_fma_f32 v195, -v216, v194, v137
	v_fmac_f32_e32 v194, v195, v217
	v_fma_f32 v137, -v216, v194, v137
	v_div_scale_f32 v216, s[26:27], v210, v210, v200
	v_rcp_f32_e32 v218, v216
	s_waitcnt lgkmcnt(1)
	v_mul_f32_e32 v198, 0xbfb8aa3b, v202
	v_mul_f32_e32 v199, 0xbfb8aa3b, v203
	v_div_fmas_f32 v137, v137, v217, v194
	v_exp_f32_e32 v198, v198
	v_exp_f32_e32 v199, v199
	v_div_fixup_f32 v195, v137, v211, v201
	v_fma_f32 v137, -v216, v218, 1.0
	v_fmac_f32_e32 v218, v137, v218
	v_div_scale_f32 v137, vcc, v200, v210, v200
	v_mul_f32_e32 v194, v137, v218
	v_fma_f32 v201, -v216, v194, v137
	v_pk_add_f32 v[198:199], v[198:199], 1.0 op_sel_hi:[1,0]
	v_fmac_f32_e32 v194, v201, v218
	v_div_scale_f32 v201, s[26:27], v199, v199, v203
	v_rcp_f32_e32 v211, v201
	v_fma_f32 v137, -v216, v194, v137
	v_div_fmas_f32 v137, v137, v218, v194
	v_div_fixup_f32 v194, v137, v210, v200
	v_fma_f32 v137, -v201, v211, 1.0
	v_fmac_f32_e32 v211, v137, v211
	v_div_scale_f32 v137, vcc, v203, v199, v203
	v_pk_mul_f32 v[194:195], v[194:195], v[196:197]
	v_mul_f32_e32 v196, v137, v211
	v_fma_f32 v197, -v201, v196, v137
	v_fmac_f32_e32 v196, v197, v211
	v_fma_f32 v137, -v201, v196, v137
	v_div_scale_f32 v210, s[26:27], v198, v198, v202
	v_rcp_f32_e32 v216, v210
	v_div_fmas_f32 v137, v137, v211, v196
	v_div_fixup_f32 v197, v137, v199, v203
	v_mul_f32_e32 v199, 0xbfb8aa3b, v204
	v_exp_f32_e32 v200, v199
	v_mul_f32_e32 v199, 0xbfb8aa3b, v205
	v_exp_f32_e32 v201, v199
	v_fma_f32 v137, -v210, v216, 1.0
	v_fmac_f32_e32 v216, v137, v216
	v_div_scale_f32 v137, vcc, v202, v198, v202
	v_mul_f32_e32 v196, v137, v216
	v_fma_f32 v199, -v210, v196, v137
	v_pk_add_f32 v[200:201], v[200:201], 1.0 op_sel_hi:[1,0]
	v_fmac_f32_e32 v196, v199, v216
	v_div_scale_f32 v199, s[26:27], v201, v201, v205
	v_fma_f32 v137, -v210, v196, v137
	v_rcp_f32_e32 v210, v199
	v_div_fmas_f32 v137, v137, v216, v196
	v_div_fixup_f32 v196, v137, v198, v202
	s_waitcnt lgkmcnt(0)
	v_pk_mul_f32 v[202:203], v[196:197], v[206:207]
	v_fma_f32 v137, -v199, v210, 1.0
	v_fmac_f32_e32 v210, v137, v210
	v_div_scale_f32 v137, vcc, v205, v201, v205
	v_mul_f32_e32 v196, v137, v210
	v_fma_f32 v197, -v199, v196, v137
	v_fmac_f32_e32 v196, v197, v210
	v_div_scale_f32 v198, s[26:27], v200, v200, v204
	v_fma_f32 v137, -v199, v196, v137
	v_rcp_f32_e32 v199, v198
	v_div_fmas_f32 v137, v137, v210, v196
	v_div_fixup_f32 v197, v137, v201, v205
	v_cvt_pk_bf16_f32 v195, v194, v195
	v_fma_f32 v137, -v198, v199, 1.0
	v_fmac_f32_e32 v199, v137, v199
	v_div_scale_f32 v137, vcc, v204, v200, v204
	v_mul_f32_e32 v196, v137, v199
	v_fma_f32 v201, -v198, v196, v137
	v_fmac_f32_e32 v196, v201, v199
	v_fma_f32 v137, -v198, v196, v137
	v_div_fmas_f32 v137, v137, v199, v196
	v_div_fixup_f32 v196, v137, v200, v204
	ds_read_b128 v[198:201], v139 offset:33792
	v_pk_mul_f32 v[196:197], v[196:197], v[208:209]
	v_cvt_pk_bf16_f32 v194, v214, v215
	v_cvt_pk_bf16_f32 v197, v196, v197
	v_cvt_pk_bf16_f32 v196, v202, v203
	s_waitcnt lgkmcnt(0)
	v_mul_f32_e32 v137, 0xbfb8aa3b, v198
	v_exp_f32_e32 v206, v137
	v_mul_f32_e32 v137, 0xbfb8aa3b, v199
	v_exp_f32_e32 v207, v137
	v_ashrrev_i32_e32 v137, 31, v136
	v_lshlrev_b64 v[136:137], 11, v[136:137]
	v_lshl_add_u64 v[136:137], s[14:15], 0, v[136:137]
	v_pk_add_f32 v[206:207], v[206:207], 1.0 op_sel_hi:[1,0]
	v_lshl_add_u64 v[136:137], v[136:137], 0, v[128:129]
	v_div_scale_f32 v208, s[14:15], v207, v207, v199
	v_rcp_f32_e32 v209, v208
	global_store_dwordx4 v[136:137], v[194:197], off sc1
	ds_read_b128 v[194:197], v139 offset:34048
	ds_read_b128 v[202:205], v139 offset:33808
	v_fma_f32 v128, -v208, v209, 1.0
	v_fmac_f32_e32 v209, v128, v209
	v_div_scale_f32 v128, vcc, v199, v207, v199
	v_mul_f32_e32 v210, v128, v209
	v_fma_f32 v211, -v208, v210, v128
	v_fmac_f32_e32 v210, v211, v209
	v_div_scale_f32 v211, s[14:15], v206, v206, v198
	v_rcp_f32_e32 v214, v211
	v_fma_f32 v128, -v208, v210, v128
	v_div_fmas_f32 v128, v128, v209, v210
	v_div_fixup_f32 v199, v128, v207, v199
	v_fma_f32 v128, -v211, v214, 1.0
	v_fmac_f32_e32 v214, v128, v214
	v_div_scale_f32 v128, vcc, v198, v206, v198
	v_mul_f32_e32 v207, v128, v214
	v_fma_f32 v208, -v211, v207, v128
	v_fmac_f32_e32 v207, v208, v214
	v_mul_f32_e32 v208, 0xbfb8aa3b, v200
	v_mul_f32_e32 v209, 0xbfb8aa3b, v201
	v_exp_f32_e32 v208, v208
	v_exp_f32_e32 v209, v209
	v_fma_f32 v128, -v211, v207, v128
	v_div_fmas_f32 v128, v128, v214, v207
	v_div_fixup_f32 v198, v128, v206, v198
	v_pk_add_f32 v[210:211], v[208:209], 1.0 op_sel_hi:[1,0]
	s_waitcnt lgkmcnt(1)
	v_pk_mul_f32 v[198:199], v[198:199], v[194:195]
	v_div_scale_f32 v214, s[14:15], v211, v211, v201
	v_rcp_f32_e32 v215, v214
	v_div_scale_f32 v216, s[14:15], v210, v210, v200
	v_rcp_f32_e32 v217, v216
	v_fma_f32 v128, -v214, v215, 1.0
	v_fmac_f32_e32 v215, v128, v215
	v_div_scale_f32 v128, vcc, v201, v211, v201
	v_mul_f32_e32 v194, v128, v215
	v_fma_f32 v195, -v214, v194, v128
	v_fmac_f32_e32 v194, v195, v215
	v_fma_f32 v128, -v214, v194, v128
	v_div_fmas_f32 v128, v128, v215, v194
	v_div_fixup_f32 v195, v128, v211, v201
	s_waitcnt lgkmcnt(0)
	v_mul_f32_e32 v201, 0xbfb8aa3b, v202
	v_exp_f32_e32 v214, v201
	v_mul_f32_e32 v201, 0xbfb8aa3b, v203
	v_exp_f32_e32 v215, v201
	v_fma_f32 v128, -v216, v217, 1.0
	v_fmac_f32_e32 v217, v128, v217
	v_div_scale_f32 v128, vcc, v200, v210, v200
	v_mul_f32_e32 v194, v128, v217
	v_fma_f32 v201, -v216, v194, v128
	v_pk_add_f32 v[214:215], v[214:215], 1.0 op_sel_hi:[1,0]
	v_fmac_f32_e32 v194, v201, v217
	v_div_scale_f32 v211, s[14:15], v215, v215, v203
	v_fma_f32 v128, -v216, v194, v128
	v_rcp_f32_e32 v216, v211
	v_div_fmas_f32 v128, v128, v217, v194
	v_div_fixup_f32 v194, v128, v210, v200
	v_pk_mul_f32 v[200:201], v[194:195], v[196:197]
	v_fma_f32 v128, -v211, v216, 1.0
	v_fmac_f32_e32 v216, v128, v216
	v_div_scale_f32 v128, vcc, v203, v215, v203
	v_mul_f32_e32 v194, v128, v216
	v_div_scale_f32 v210, s[14:15], v214, v214, v202
	v_fma_f32 v195, -v211, v194, v128
	v_rcp_f32_e32 v217, v210
	v_fmac_f32_e32 v194, v195, v216
	v_fma_f32 v128, -v211, v194, v128
	v_div_fmas_f32 v128, v128, v216, v194
	v_div_fixup_f32 v195, v128, v215, v203
	v_fma_f32 v128, -v210, v217, 1.0
	v_mul_f32_e32 v196, 0xbfb8aa3b, v204
	v_mul_f32_e32 v197, 0xbfb8aa3b, v205
	v_fmac_f32_e32 v217, v128, v217
	v_div_scale_f32 v128, vcc, v202, v214, v202
	v_exp_f32_e32 v196, v196
	v_exp_f32_e32 v197, v197
	v_mul_f32_e32 v194, v128, v217
	v_fma_f32 v203, -v210, v194, v128
	v_fmac_f32_e32 v194, v203, v217
	v_fma_f32 v128, -v210, v194, v128
	v_pk_add_f32 v[210:211], v[196:197], 1.0 op_sel_hi:[1,0]
	ds_read_b128 v[206:209], v139 offset:34064
	v_div_scale_f32 v196, s[14:15], v211, v211, v205
	v_rcp_f32_e32 v197, v196
	v_div_fmas_f32 v128, v128, v217, v194
	v_div_fixup_f32 v194, v128, v214, v202
	s_waitcnt lgkmcnt(0)
	v_pk_mul_f32 v[206:207], v[194:195], v[206:207]
	v_fma_f32 v128, -v196, v197, 1.0
	v_fmac_f32_e32 v197, v128, v197
	v_div_scale_f32 v128, vcc, v205, v211, v205
	v_mul_f32_e32 v194, v128, v197
	v_fma_f32 v195, -v196, v194, v128
	v_fmac_f32_e32 v194, v195, v197
	v_div_scale_f32 v195, s[14:15], v210, v210, v204
	v_fma_f32 v128, -v196, v194, v128
	v_rcp_f32_e32 v196, v195
	v_div_fmas_f32 v128, v128, v197, v194
	v_div_fixup_f32 v203, v128, v211, v205
	v_cvt_pk_bf16_f32 v198, v198, v199
	v_fma_f32 v128, -v195, v196, 1.0
	v_fmac_f32_e32 v196, v128, v196
	v_div_scale_f32 v128, vcc, v204, v210, v204
	v_mul_f32_e32 v194, v128, v196
	v_fma_f32 v197, -v195, v194, v128
	v_fmac_f32_e32 v194, v197, v196
	v_fma_f32 v128, -v195, v194, v128
	v_div_fmas_f32 v128, v128, v196, v194
	ds_read_b128 v[194:197], v138 offset:33792
	v_div_fixup_f32 v202, v128, v210, v204
	v_cvt_pk_bf16_f32 v199, v200, v201
	v_cvt_pk_bf16_f32 v200, v206, v207
	v_pk_mul_f32 v[208:209], v[202:203], v[208:209]
	s_waitcnt lgkmcnt(0)
	v_mul_f32_e32 v128, 0xbfb8aa3b, v194
	v_exp_f32_e32 v210, v128
	v_mul_f32_e32 v128, 0xbfb8aa3b, v195
	v_exp_f32_e32 v211, v128
	v_cvt_pk_bf16_f32 v201, v208, v209
	v_add_co_u32_e32 v208, vcc, s23, v134
	v_pk_add_f32 v[206:207], v[210:211], 1.0 op_sel_hi:[1,0]
	s_nop 0
	v_addc_co_u32_e32 v209, vcc, 0, v135, vcc
	v_div_scale_f32 v128, s[14:15], v207, v207, v195
	v_rcp_f32_e32 v210, v128
	global_store_dwordx4 v[208:209], v[198:201], off sc1
	ds_read_b128 v[198:201], v138 offset:34048
	ds_read_b128 v[202:205], v138 offset:33808
	v_fma_f32 v208, -v128, v210, 1.0
	v_fmac_f32_e32 v210, v208, v210
	v_div_scale_f32 v208, vcc, v195, v207, v195
	v_mul_f32_e32 v209, v208, v210
	v_fma_f32 v211, -v128, v209, v208
	v_fmac_f32_e32 v209, v211, v210
	v_div_scale_f32 v211, s[14:15], v206, v206, v194
	v_rcp_f32_e32 v214, v211
	v_fma_f32 v128, -v128, v209, v208
	v_div_fmas_f32 v128, v128, v210, v209
	v_div_fixup_f32 v195, v128, v207, v195
	v_fma_f32 v128, -v211, v214, 1.0
	v_fmac_f32_e32 v214, v128, v214
	v_div_scale_f32 v128, vcc, v194, v206, v194
	v_mul_f32_e32 v207, v128, v214
	v_fma_f32 v208, -v211, v207, v128
	v_fmac_f32_e32 v207, v208, v214
	v_mul_f32_e32 v208, 0xbfb8aa3b, v196
	v_mul_f32_e32 v209, 0xbfb8aa3b, v197
	v_exp_f32_e32 v208, v208
	v_exp_f32_e32 v209, v209
	v_fma_f32 v128, -v211, v207, v128
	v_div_fmas_f32 v128, v128, v214, v207
	v_div_fixup_f32 v194, v128, v206, v194
	v_pk_add_f32 v[210:211], v[208:209], 1.0 op_sel_hi:[1,0]
	s_waitcnt lgkmcnt(1)
	v_pk_mul_f32 v[198:199], v[194:195], v[198:199]
	v_div_scale_f32 v214, s[14:15], v211, v211, v197
	v_rcp_f32_e32 v215, v214
	v_div_scale_f32 v216, s[14:15], v210, v210, v196
	v_rcp_f32_e32 v217, v216
	v_fma_f32 v128, -v214, v215, 1.0
	v_fmac_f32_e32 v215, v128, v215
	v_div_scale_f32 v128, vcc, v197, v211, v197
	v_mul_f32_e32 v194, v128, v215
	v_fma_f32 v195, -v214, v194, v128
	v_fmac_f32_e32 v194, v195, v215
	v_fma_f32 v128, -v214, v194, v128
	v_div_fmas_f32 v128, v128, v215, v194
	v_div_fixup_f32 v195, v128, v211, v197
	s_waitcnt lgkmcnt(0)
	v_mul_f32_e32 v197, 0xbfb8aa3b, v202
	v_exp_f32_e32 v214, v197
	v_mul_f32_e32 v197, 0xbfb8aa3b, v203
	v_exp_f32_e32 v215, v197
	v_fma_f32 v128, -v216, v217, 1.0
	v_fmac_f32_e32 v217, v128, v217
	v_div_scale_f32 v128, vcc, v196, v210, v196
	v_mul_f32_e32 v194, v128, v217
	v_fma_f32 v197, -v216, v194, v128
	v_pk_add_f32 v[214:215], v[214:215], 1.0 op_sel_hi:[1,0]
	v_fmac_f32_e32 v194, v197, v217
	v_div_scale_f32 v197, s[14:15], v215, v215, v203
	v_rcp_f32_e32 v211, v197
	v_fma_f32 v128, -v216, v194, v128
	v_div_fmas_f32 v128, v128, v217, v194
	v_div_fixup_f32 v194, v128, v210, v196
	v_fma_f32 v128, -v197, v211, 1.0
	v_fmac_f32_e32 v211, v128, v211
	v_div_scale_f32 v128, vcc, v203, v215, v203
	v_mul_f32_e32 v196, v128, v211
	v_div_scale_f32 v210, s[14:15], v214, v214, v202
	v_pk_mul_f32 v[194:195], v[194:195], v[200:201]
	v_fma_f32 v200, -v197, v196, v128
	v_rcp_f32_e32 v216, v210
	v_fmac_f32_e32 v196, v200, v211
	v_fma_f32 v128, -v197, v196, v128
	v_div_fmas_f32 v128, v128, v211, v196
	v_mul_f32_e32 v200, 0xbfb8aa3b, v204
	v_mul_f32_e32 v201, 0xbfb8aa3b, v205
	v_div_fixup_f32 v197, v128, v215, v203
	v_fma_f32 v128, -v210, v216, 1.0
	v_exp_f32_e32 v200, v200
	v_exp_f32_e32 v201, v201
	v_fmac_f32_e32 v216, v128, v216
	v_div_scale_f32 v128, vcc, v202, v214, v202
	v_mul_f32_e32 v196, v128, v216
	v_fma_f32 v203, -v210, v196, v128
	v_fmac_f32_e32 v196, v203, v216
	v_pk_add_f32 v[200:201], v[200:201], 1.0 op_sel_hi:[1,0]
	v_fma_f32 v128, -v210, v196, v128
	v_div_scale_f32 v210, s[14:15], v201, v201, v205
	v_rcp_f32_e32 v211, v210
	ds_read_b128 v[206:209], v138 offset:34064
	v_div_fmas_f32 v128, v128, v216, v196
	v_div_fixup_f32 v196, v128, v214, v202
	v_fma_f32 v128, -v210, v211, 1.0
	v_fmac_f32_e32 v211, v128, v211
	v_div_scale_f32 v128, vcc, v205, v201, v205
	s_waitcnt lgkmcnt(0)
	v_pk_mul_f32 v[202:203], v[196:197], v[206:207]
	v_mul_f32_e32 v196, v128, v211
	v_div_scale_f32 v206, s[14:15], v200, v200, v204
	v_fma_f32 v197, -v210, v196, v128
	v_rcp_f32_e32 v207, v206
	v_fmac_f32_e32 v196, v197, v211
	v_fma_f32 v128, -v210, v196, v128
	v_div_fmas_f32 v128, v128, v211, v196
	v_div_fixup_f32 v197, v128, v201, v205
	v_fma_f32 v128, -v206, v207, 1.0
	v_fmac_f32_e32 v207, v128, v207
	v_div_scale_f32 v128, vcc, v204, v200, v204
	v_mul_f32_e32 v196, v128, v207
	v_fma_f32 v201, -v206, v196, v128
	v_fmac_f32_e32 v196, v201, v207
	v_fma_f32 v128, -v206, v196, v128
	v_div_fmas_f32 v128, v128, v207, v196
	v_div_fixup_f32 v196, v128, v200, v204
	v_pk_mul_f32 v[196:197], v[196:197], v[208:209]
	v_cvt_pk_bf16_f32 v195, v194, v195
	v_cvt_pk_bf16_f32 v194, v198, v199
	v_add_co_u32_e32 v198, vcc, 0x20000, v136
	v_cvt_pk_bf16_f32 v197, v196, v197
	v_cvt_pk_bf16_f32 v196, v202, v203
	v_addc_co_u32_e32 v199, vcc, 0, v137, vcc
	global_store_dwordx4 v[198:199], v[194:197], off sc1
	s_barrier
	s_and_saveexec_b64 s[14:15], s[8:9]
	s_cbranch_execz .LBB0_954
	v_and_b32_e32 v254, 63, v180
	v_lshrrev_b32_e32 v253, 4, v254
	v_mul_u32_u24_e32 v253, 0x840, v253
	v_and_b32_e32 v254, 15, v254
	v_lshl_add_u32 v253, v254, 2, v253
	v_and_b32_e32 v254, 64, v180
	v_lshl_add_u32 v253, v254, 2, v253
	ds_write_b32 v253, v0 offset:0
	ds_write_b32 v253, v1 offset:528
	ds_write_b32 v253, v2 offset:1056
	ds_write_b32 v253, v3 offset:1584
	ds_write_b32 v253, v4 offset:64
	ds_write_b32 v253, v5 offset:592
	ds_write_b32 v253, v6 offset:1120
	ds_write_b32 v253, v7 offset:1648
	ds_write_b32 v253, v8 offset:128
	ds_write_b32 v253, v9 offset:656
	ds_write_b32 v253, v10 offset:1184
	ds_write_b32 v253, v11 offset:1712
	ds_write_b32 v253, v12 offset:192
	ds_write_b32 v253, v13 offset:720
	ds_write_b32 v253, v14 offset:1248
	ds_write_b32 v253, v15 offset:1776
	ds_write_b32 v253, v16 offset:8448
	ds_write_b32 v253, v17 offset:8976
	ds_write_b32 v253, v18 offset:9504
	ds_write_b32 v253, v19 offset:10032
	ds_write_b32 v253, v20 offset:8512
	ds_write_b32 v253, v21 offset:9040
	ds_write_b32 v253, v22 offset:9568
	ds_write_b32 v253, v23 offset:10096
	ds_write_b32 v253, v24 offset:8576
	ds_write_b32 v253, v25 offset:9104
	ds_write_b32 v253, v26 offset:9632
	ds_write_b32 v253, v27 offset:10160
	ds_write_b32 v253, v28 offset:8640
	ds_write_b32 v253, v29 offset:9168
	ds_write_b32 v253, v30 offset:9696
	ds_write_b32 v253, v31 offset:10224
	ds_write_b32 v253, v32 offset:16896
	ds_write_b32 v253, v33 offset:17424
	ds_write_b32 v253, v34 offset:17952
	ds_write_b32 v253, v35 offset:18480
	ds_write_b32 v253, v36 offset:16960
	ds_write_b32 v253, v37 offset:17488
	ds_write_b32 v253, v38 offset:18016
	ds_write_b32 v253, v39 offset:18544
	ds_write_b32 v253, v40 offset:17024
	ds_write_b32 v253, v41 offset:17552
	ds_write_b32 v253, v42 offset:18080
	ds_write_b32 v253, v43 offset:18608
	ds_write_b32 v253, v44 offset:17088
	ds_write_b32 v253, v45 offset:17616
	ds_write_b32 v253, v46 offset:18144
	ds_write_b32 v253, v47 offset:18672
	ds_write_b32 v253, v48 offset:25344
	ds_write_b32 v253, v49 offset:25872
	ds_write_b32 v253, v50 offset:26400
	ds_write_b32 v253, v51 offset:26928
	ds_write_b32 v253, v52 offset:25408
	ds_write_b32 v253, v53 offset:25936
	ds_write_b32 v253, v54 offset:26464
	ds_write_b32 v253, v55 offset:26992
	ds_write_b32 v253, v56 offset:25472
	ds_write_b32 v253, v57 offset:26000
	ds_write_b32 v253, v58 offset:26528
	ds_write_b32 v253, v59 offset:27056
	ds_write_b32 v253, v60 offset:25536
	ds_write_b32 v253, v61 offset:26064
	ds_write_b32 v253, v62 offset:26592
	ds_write_b32 v253, v63 offset:27120
	ds_write_b32 v253, v64 offset:33792
	ds_write_b32 v253, v65 offset:34320
	ds_write_b32 v253, v66 offset:34848
	ds_write_b32 v253, v67 offset:35376
	ds_write_b32 v253, v68 offset:33856
	ds_write_b32 v253, v69 offset:34384
	ds_write_b32 v253, v70 offset:34912
	ds_write_b32 v253, v71 offset:35440
	ds_write_b32 v253, v72 offset:33920
	ds_write_b32 v253, v73 offset:34448
	ds_write_b32 v253, v74 offset:34976
	ds_write_b32 v253, v75 offset:35504
	ds_write_b32 v253, v76 offset:33984
	ds_write_b32 v253, v77 offset:34512
	ds_write_b32 v253, v78 offset:35040
	ds_write_b32 v253, v79 offset:35568
	ds_write_b32 v253, v80 offset:42240
	ds_write_b32 v253, v81 offset:42768
	ds_write_b32 v253, v82 offset:43296
	ds_write_b32 v253, v83 offset:43824
	ds_write_b32 v253, v84 offset:42304
	ds_write_b32 v253, v85 offset:42832
	ds_write_b32 v253, v86 offset:43360
	ds_write_b32 v253, v87 offset:43888
	ds_write_b32 v253, v88 offset:42368
	ds_write_b32 v253, v89 offset:42896
	ds_write_b32 v253, v90 offset:43424
	ds_write_b32 v253, v91 offset:43952
	ds_write_b32 v253, v92 offset:42432
	ds_write_b32 v253, v93 offset:42960
	ds_write_b32 v253, v94 offset:43488
	ds_write_b32 v253, v95 offset:44016
	ds_write_b32 v253, v96 offset:50688
	ds_write_b32 v253, v97 offset:51216
	ds_write_b32 v253, v98 offset:51744
	ds_write_b32 v253, v99 offset:52272
	ds_write_b32 v253, v100 offset:50752
	ds_write_b32 v253, v101 offset:51280
	ds_write_b32 v253, v102 offset:51808
	ds_write_b32 v253, v103 offset:52336
	ds_write_b32 v253, v104 offset:50816
	ds_write_b32 v253, v105 offset:51344
	ds_write_b32 v253, v106 offset:51872
	ds_write_b32 v253, v107 offset:52400
	ds_write_b32 v253, v108 offset:50880
	ds_write_b32 v253, v109 offset:51408
	ds_write_b32 v253, v110 offset:51936
	ds_write_b32 v253, v111 offset:52464
	ds_write_b32 v253, v112 offset:59136
	ds_write_b32 v253, v113 offset:59664
	ds_write_b32 v253, v114 offset:60192
	ds_write_b32 v253, v115 offset:60720
	ds_write_b32 v253, v116 offset:59200
	ds_write_b32 v253, v117 offset:59728
	ds_write_b32 v253, v118 offset:60256
	ds_write_b32 v253, v119 offset:60784
	ds_write_b32 v253, v120 offset:59264
	ds_write_b32 v253, v121 offset:59792
	ds_write_b32 v253, v122 offset:60320
	ds_write_b32 v253, v123 offset:60848
	ds_write_b32 v253, v124 offset:59328
	ds_write_b32 v253, v125 offset:59856
	ds_write_b32 v253, v126 offset:60384
	ds_write_b32 v253, v127 offset:60912
	s_branch .LBB0_954

.LBB0_1020:
	s_or_b64 exec, exec, s[16:17]
	s_waitcnt lgkmcnt(0)
	s_barrier
	global_load_dword v8, v[136:137], off offset:512
	ds_read_b128 v[0:3], v173
	ds_read_b128 v[4:7], v173 offset:16
	v_add_co_u32_e32 v10, vcc, s31, v140
	s_add_i32 s26, s26, s25
	s_nop 0
	v_addc_co_u32_e32 v11, vcc, 0, v141, vcc
	s_cmpk_lt_u32 s26, 0x80
	s_waitcnt vmcnt(0) lgkmcnt(1)
	v_pk_mul_f32 v[0:1], v[0:1], v[8:9] op_sel_hi:[1,0]
	v_pk_mul_f32 v[2:3], v[2:3], v[8:9] op_sel_hi:[1,0]
	s_waitcnt lgkmcnt(0)
	v_pk_mul_f32 v[4:5], v[4:5], v[8:9] op_sel_hi:[1,0]
	v_pk_mul_f32 v[6:7], v[6:7], v[8:9] op_sel_hi:[1,0]
	v_cvt_pk_bf16_f32 v0, v0, v1
	v_cvt_pk_bf16_f32 v1, v2, v3
	v_cvt_pk_bf16_f32 v2, v4, v5
	v_cvt_pk_bf16_f32 v3, v6, v7
	global_store_dwordx4 v[10:11], v[0:3], off sc1
	global_load_dword v8, v[138:139], off offset:512
	ds_read_b128 v[0:3], v179
	ds_read_b128 v[4:7], v179 offset:16
	v_add_co_u32_e32 v10, vcc, s31, v144
	s_waitcnt vmcnt(0) lgkmcnt(1)
	v_pk_mul_f32 v[0:1], v[0:1], v[8:9] op_sel_hi:[1,0]
	v_pk_mul_f32 v[2:3], v[2:3], v[8:9] op_sel_hi:[1,0]
	s_waitcnt lgkmcnt(0)
	v_pk_mul_f32 v[4:5], v[4:5], v[8:9] op_sel_hi:[1,0]
	v_pk_mul_f32 v[6:7], v[6:7], v[8:9] op_sel_hi:[1,0]
	v_addc_co_u32_e32 v11, vcc, 0, v145, vcc
	v_cvt_pk_bf16_f32 v0, v0, v1
	v_cvt_pk_bf16_f32 v1, v2, v3
	v_cvt_pk_bf16_f32 v2, v4, v5
	v_cvt_pk_bf16_f32 v3, v6, v7
	global_store_dwordx4 v[10:11], v[0:3], off sc1
	global_load_dword v8, v[142:143], off offset:512
	ds_read_b128 v[0:3], v210
	ds_read_b128 v[4:7], v210 offset:16
	v_add_co_u32_e32 v10, vcc, s31, v150
	s_waitcnt vmcnt(0) lgkmcnt(1)
	v_pk_mul_f32 v[0:1], v[0:1], v[8:9] op_sel_hi:[1,0]
	v_pk_mul_f32 v[2:3], v[2:3], v[8:9] op_sel_hi:[1,0]
	s_waitcnt lgkmcnt(0)
	v_pk_mul_f32 v[4:5], v[4:5], v[8:9] op_sel_hi:[1,0]
	v_pk_mul_f32 v[6:7], v[6:7], v[8:9] op_sel_hi:[1,0]
	v_addc_co_u32_e32 v11, vcc, 0, v151, vcc
	v_cvt_pk_bf16_f32 v0, v0, v1
	v_cvt_pk_bf16_f32 v1, v2, v3
	v_cvt_pk_bf16_f32 v2, v4, v5
	v_cvt_pk_bf16_f32 v3, v6, v7
	global_store_dwordx4 v[10:11], v[0:3], off sc1
	global_load_dword v8, v[148:149], off offset:512
	ds_read_b128 v[0:3], v182
	ds_read_b128 v[4:7], v182 offset:16
	v_add_co_u32_e32 v10, vcc, s31, v146
	s_waitcnt vmcnt(0) lgkmcnt(1)
	v_pk_mul_f32 v[12:13], v[0:1], v[8:9] op_sel_hi:[1,0]
	v_pk_mul_f32 v[0:1], v[2:3], v[8:9] op_sel_hi:[1,0]
	s_waitcnt lgkmcnt(0)
	v_pk_mul_f32 v[4:5], v[4:5], v[8:9] op_sel_hi:[1,0]
	v_pk_mul_f32 v[2:3], v[6:7], v[8:9] op_sel_hi:[1,0]
	v_addc_co_u32_e32 v11, vcc, 0, v147, vcc
	v_cvt_pk_bf16_f32 v3, v2, v3
	v_cvt_pk_bf16_f32 v2, v4, v5
	v_cvt_pk_bf16_f32 v1, v0, v1
	v_cvt_pk_bf16_f32 v0, v12, v13
	global_store_dwordx4 v[10:11], v[0:3], off sc1
	global_load_dword v8, v[136:137], off offset:768
	ds_read_b128 v[0:3], v173 offset:33792
	ds_read_b128 v[4:7], v173 offset:33808
	v_add_co_u32_e32 v10, vcc, s34, v140
	s_waitcnt vmcnt(0) lgkmcnt(1)
	v_pk_mul_f32 v[0:1], v[0:1], v[8:9] op_sel_hi:[1,0]
	v_pk_mul_f32 v[2:3], v[2:3], v[8:9] op_sel_hi:[1,0]
	s_waitcnt lgkmcnt(0)
	v_pk_mul_f32 v[4:5], v[4:5], v[8:9] op_sel_hi:[1,0]
	v_pk_mul_f32 v[6:7], v[6:7], v[8:9] op_sel_hi:[1,0]
	v_addc_co_u32_e32 v11, vcc, 0, v141, vcc
	v_cvt_pk_bf16_f32 v0, v0, v1
	v_cvt_pk_bf16_f32 v1, v2, v3
	v_cvt_pk_bf16_f32 v2, v4, v5
	v_cvt_pk_bf16_f32 v3, v6, v7
	global_store_dwordx4 v[10:11], v[0:3], off sc1
	global_load_dword v8, v[138:139], off offset:768
	ds_read_b128 v[0:3], v179 offset:33792
	ds_read_b128 v[4:7], v179 offset:33808
	v_add_co_u32_e32 v10, vcc, s34, v144
	s_waitcnt vmcnt(0) lgkmcnt(1)
	v_pk_mul_f32 v[0:1], v[0:1], v[8:9] op_sel_hi:[1,0]
	v_pk_mul_f32 v[2:3], v[2:3], v[8:9] op_sel_hi:[1,0]
	s_waitcnt lgkmcnt(0)
	v_pk_mul_f32 v[4:5], v[4:5], v[8:9] op_sel_hi:[1,0]
	v_pk_mul_f32 v[6:7], v[6:7], v[8:9] op_sel_hi:[1,0]
	v_addc_co_u32_e32 v11, vcc, 0, v145, vcc
	v_cvt_pk_bf16_f32 v0, v0, v1
	v_cvt_pk_bf16_f32 v1, v2, v3
	v_cvt_pk_bf16_f32 v2, v4, v5
	v_cvt_pk_bf16_f32 v3, v6, v7
	global_store_dwordx4 v[10:11], v[0:3], off sc1
	global_load_dword v8, v[142:143], off offset:768
	ds_read_b128 v[0:3], v210 offset:33792
	ds_read_b128 v[4:7], v210 offset:33808
	v_add_co_u32_e32 v10, vcc, s34, v150
	s_waitcnt vmcnt(0) lgkmcnt(1)
	v_pk_mul_f32 v[0:1], v[0:1], v[8:9] op_sel_hi:[1,0]
	v_pk_mul_f32 v[2:3], v[2:3], v[8:9] op_sel_hi:[1,0]
	s_waitcnt lgkmcnt(0)
	v_pk_mul_f32 v[4:5], v[4:5], v[8:9] op_sel_hi:[1,0]
	v_pk_mul_f32 v[6:7], v[6:7], v[8:9] op_sel_hi:[1,0]
	v_addc_co_u32_e32 v11, vcc, 0, v151, vcc
	v_cvt_pk_bf16_f32 v0, v0, v1
	v_cvt_pk_bf16_f32 v1, v2, v3
	v_cvt_pk_bf16_f32 v2, v4, v5
	v_cvt_pk_bf16_f32 v3, v6, v7
	global_store_dwordx4 v[10:11], v[0:3], off sc1
	global_load_dword v8, v[148:149], off offset:768
	ds_read_b128 v[0:3], v182 offset:33792
	ds_read_b128 v[4:7], v182 offset:33808
	v_add_co_u32_e32 v10, vcc, 0x60000, v146
	s_waitcnt vmcnt(0) lgkmcnt(1)
	v_pk_mul_f32 v[12:13], v[0:1], v[8:9] op_sel_hi:[1,0]
	v_pk_mul_f32 v[0:1], v[2:3], v[8:9] op_sel_hi:[1,0]
	s_waitcnt lgkmcnt(0)
	v_pk_mul_f32 v[4:5], v[4:5], v[8:9] op_sel_hi:[1,0]
	v_pk_mul_f32 v[2:3], v[6:7], v[8:9] op_sel_hi:[1,0]
	v_addc_co_u32_e32 v11, vcc, 0, v147, vcc
	v_cvt_pk_bf16_f32 v3, v2, v3
	v_cvt_pk_bf16_f32 v2, v4, v5
	v_cvt_pk_bf16_f32 v1, v0, v1
	v_cvt_pk_bf16_f32 v0, v12, v13
	global_store_dwordx4 v[10:11], v[0:3], off sc1
	s_barrier
	s_cbranch_scc0 .LBB0_1027

.LBB0_1025:
	s_or_b64 exec, exec, s[16:17]
	s_lshl_b32 s4, s35, 19
	s_lshl_b32 s16, s36, 20
	s_or_b32 s4, s16, s4
	s_add_u32 s4, s20, s4
	s_addc_u32 s17, s21, 0
	s_lshl_b32 s16, s19, 2
	s_add_u32 s19, s22, s16
	s_addc_u32 s35, s23, 0
	s_lshl_b32 s16, s37, 1
	s_add_u32 s16, s4, s16
	s_addc_u32 s17, s17, 0
	s_lshl_b32 s4, s18, 2
	s_add_u32 s18, s19, s4
	v_ashrrev_i32_e32 v138, 4, v146
	s_addc_u32 s19, s35, 0
	v_ashrrev_i32_e32 v139, 31, v138
	v_lshl_add_u64 v[136:137], v[138:139], 2, s[18:19]
	s_waitcnt lgkmcnt(0)
	s_barrier
	global_load_dword v182, v[136:137], off
	v_lshlrev_b32_e32 v130, 3, v146
	v_and_b32_e32 v130, 0x78, v130
	v_mul_lo_u32 v141, v138, s27
	v_lshl_add_u32 v223, v130, 2, 0
	v_add_u32_e32 v173, v223, v141
	ds_read_b128 v[142:145], v173
	ds_read_b128 v[148:151], v173 offset:16
	v_add_u32_e32 v140, 0x100, v146
	v_lshlrev_b64 v[138:139], 11, v[138:139]
	v_ashrrev_i32_e32 v210, 4, v140
	v_lshlrev_b32_e32 v130, 1, v130
	v_lshl_add_u64 v[138:139], s[16:17], 0, v[138:139]
	v_ashrrev_i32_e32 v211, 31, v210
	v_lshl_add_u64 v[140:141], v[138:139], 0, v[130:131]
	v_lshl_add_u64 v[138:139], v[210:211], 2, s[18:19]
	s_waitcnt vmcnt(0) lgkmcnt(1)
	v_pk_mul_f32 v[142:143], v[142:143], v[182:183] op_sel_hi:[1,0]
	v_pk_mul_f32 v[144:145], v[144:145], v[182:183] op_sel_hi:[1,0]
	s_waitcnt lgkmcnt(0)
	v_pk_mul_f32 v[148:149], v[148:149], v[182:183] op_sel_hi:[1,0]
	v_pk_mul_f32 v[150:151], v[150:151], v[182:183] op_sel_hi:[1,0]
	v_cvt_pk_bf16_f32 v142, v142, v143
	v_cvt_pk_bf16_f32 v143, v144, v145
	v_cvt_pk_bf16_f32 v144, v148, v149
	v_cvt_pk_bf16_f32 v145, v150, v151
	global_store_dwordx4 v[140:141], v[142:145], off sc1
	global_load_dword v182, v[138:139], off
	s_nop 0
	v_add_u32_e32 v142, 0x200, v146
	v_ashrrev_i32_e32 v218, 4, v142
	v_mul_lo_u32 v142, v210, s27
	v_add_u32_e32 v179, v223, v142
	ds_read_b128 v[148:151], v179
	ds_read_b128 v[214:217], v179 offset:16
	v_lshlrev_b64 v[142:143], 11, v[210:211]
	v_lshl_add_u64 v[142:143], s[16:17], 0, v[142:143]
	v_ashrrev_i32_e32 v219, 31, v218
	v_lshl_add_u64 v[144:145], v[142:143], 0, v[130:131]
	v_lshl_add_u64 v[142:143], v[218:219], 2, s[18:19]
	v_add_u32_e32 v146, 0x300, v146
	v_ashrrev_i32_e32 v146, 4, v146
	v_ashrrev_i32_e32 v147, 31, v146
	s_waitcnt vmcnt(0) lgkmcnt(1)
	v_pk_mul_f32 v[148:149], v[148:149], v[182:183] op_sel_hi:[1,0]
	v_pk_mul_f32 v[150:151], v[150:151], v[182:183] op_sel_hi:[1,0]
	s_waitcnt lgkmcnt(0)
	v_pk_mul_f32 v[210:211], v[214:215], v[182:183] op_sel_hi:[1,0]
	v_pk_mul_f32 v[214:215], v[216:217], v[182:183] op_sel_hi:[1,0]
	v_cvt_pk_bf16_f32 v148, v148, v149
	v_cvt_pk_bf16_f32 v149, v150, v151
	v_cvt_pk_bf16_f32 v150, v210, v211
	v_cvt_pk_bf16_f32 v151, v214, v215
	global_store_dwordx4 v[144:145], v[148:151], off sc1
	global_load_dword v182, v[142:143], off
	s_nop 0
	v_mul_lo_u32 v148, v218, s27
	v_add_u32_e32 v210, v223, v148
	v_lshlrev_b64 v[148:149], 11, v[218:219]
	ds_read_b128 v[214:217], v210
	ds_read_b128 v[218:221], v210 offset:16
	v_lshl_add_u64 v[148:149], s[16:17], 0, v[148:149]
	v_lshl_add_u64 v[150:151], v[148:149], 0, v[130:131]
	v_lshl_add_u64 v[148:149], v[146:147], 2, s[18:19]
	s_waitcnt vmcnt(0) lgkmcnt(1)
	v_pk_mul_f32 v[214:215], v[214:215], v[182:183] op_sel_hi:[1,0]
	v_pk_mul_f32 v[216:217], v[216:217], v[182:183] op_sel_hi:[1,0]
	s_waitcnt lgkmcnt(0)
	v_pk_mul_f32 v[218:219], v[218:219], v[182:183] op_sel_hi:[1,0]
	v_pk_mul_f32 v[220:221], v[220:221], v[182:183] op_sel_hi:[1,0]
	v_cvt_pk_bf16_f32 v214, v214, v215
	v_cvt_pk_bf16_f32 v215, v216, v217
	v_cvt_pk_bf16_f32 v216, v218, v219
	v_cvt_pk_bf16_f32 v217, v220, v221
	global_store_dwordx4 v[150:151], v[214:217], off sc1
	global_load_dword v222, v[148:149], off
	v_mul_lo_u32 v182, v146, s27
	v_add_u32_e32 v182, v223, v182
	ds_read_b128 v[214:217], v182
	ds_read_b128 v[218:221], v182 offset:16
	v_lshlrev_b64 v[146:147], 11, v[146:147]
	v_lshl_add_u64 v[146:147], s[16:17], 0, v[146:147]
	v_lshl_add_u64 v[146:147], v[146:147], 0, v[130:131]
	s_waitcnt vmcnt(0) lgkmcnt(1)
	v_pk_mul_f32 v[224:225], v[214:215], v[222:223] op_sel_hi:[1,0]
	v_pk_mul_f32 v[214:215], v[216:217], v[222:223] op_sel_hi:[1,0]
	s_waitcnt lgkmcnt(0)
	v_pk_mul_f32 v[218:219], v[218:219], v[222:223] op_sel_hi:[1,0]
	v_pk_mul_f32 v[216:217], v[220:221], v[222:223] op_sel_hi:[1,0]
	v_cvt_pk_bf16_f32 v215, v214, v215
	v_cvt_pk_bf16_f32 v217, v216, v217
	v_cvt_pk_bf16_f32 v216, v218, v219
	v_cvt_pk_bf16_f32 v214, v224, v225
	global_store_dwordx4 v[146:147], v[214:217], off sc1
	global_load_dword v130, v[136:137], off offset:256
	ds_read_b128 v[214:217], v173 offset:33792
	ds_read_b128 v[218:221], v173 offset:33808
	v_add_co_u32_e32 v222, vcc, s30, v140
	s_waitcnt vmcnt(0) lgkmcnt(1)
	v_pk_mul_f32 v[214:215], v[214:215], v[130:131] op_sel_hi:[1,0]
	v_pk_mul_f32 v[216:217], v[216:217], v[130:131] op_sel_hi:[1,0]
	s_waitcnt lgkmcnt(0)
	v_pk_mul_f32 v[218:219], v[218:219], v[130:131] op_sel_hi:[1,0]
	v_pk_mul_f32 v[220:221], v[220:221], v[130:131] op_sel_hi:[1,0]
	v_addc_co_u32_e32 v223, vcc, 0, v141, vcc
	v_cvt_pk_bf16_f32 v214, v214, v215
	v_cvt_pk_bf16_f32 v215, v216, v217
	v_cvt_pk_bf16_f32 v216, v218, v219
	v_cvt_pk_bf16_f32 v217, v220, v221
	global_store_dwordx4 v[222:223], v[214:217], off sc1
	global_load_dword v130, v[138:139], off offset:256
	ds_read_b128 v[214:217], v179 offset:33792
	ds_read_b128 v[218:221], v179 offset:33808
	v_add_co_u32_e32 v222, vcc, s30, v144
	s_waitcnt vmcnt(0) lgkmcnt(1)
	v_pk_mul_f32 v[214:215], v[214:215], v[130:131] op_sel_hi:[1,0]
	v_pk_mul_f32 v[216:217], v[216:217], v[130:131] op_sel_hi:[1,0]
	s_waitcnt lgkmcnt(0)
	v_pk_mul_f32 v[218:219], v[218:219], v[130:131] op_sel_hi:[1,0]
	v_pk_mul_f32 v[220:221], v[220:221], v[130:131] op_sel_hi:[1,0]
	v_addc_co_u32_e32 v223, vcc, 0, v145, vcc
	v_cvt_pk_bf16_f32 v214, v214, v215
	v_cvt_pk_bf16_f32 v215, v216, v217
	v_cvt_pk_bf16_f32 v216, v218, v219
	v_cvt_pk_bf16_f32 v217, v220, v221
	global_store_dwordx4 v[222:223], v[214:217], off sc1
	global_load_dword v130, v[142:143], off offset:256
	ds_read_b128 v[214:217], v210 offset:33792
	ds_read_b128 v[218:221], v210 offset:33808
	v_add_co_u32_e32 v222, vcc, s30, v150
	s_waitcnt vmcnt(0) lgkmcnt(1)
	v_pk_mul_f32 v[214:215], v[214:215], v[130:131] op_sel_hi:[1,0]
	v_pk_mul_f32 v[216:217], v[216:217], v[130:131] op_sel_hi:[1,0]
	s_waitcnt lgkmcnt(0)
	v_pk_mul_f32 v[218:219], v[218:219], v[130:131] op_sel_hi:[1,0]
	v_pk_mul_f32 v[220:221], v[220:221], v[130:131] op_sel_hi:[1,0]
	v_addc_co_u32_e32 v223, vcc, 0, v151, vcc
	v_cvt_pk_bf16_f32 v214, v214, v215
	v_cvt_pk_bf16_f32 v215, v216, v217
	v_cvt_pk_bf16_f32 v216, v218, v219
	v_cvt_pk_bf16_f32 v217, v220, v221
	global_store_dwordx4 v[222:223], v[214:217], off sc1
	global_load_dword v130, v[148:149], off offset:256
	ds_read_b128 v[214:217], v182 offset:33792
	ds_read_b128 v[218:221], v182 offset:33808
	v_add_co_u32_e32 v222, vcc, 0x20000, v146
	s_waitcnt vmcnt(0) lgkmcnt(1)
	v_pk_mul_f32 v[224:225], v[214:215], v[130:131] op_sel_hi:[1,0]
	v_pk_mul_f32 v[214:215], v[216:217], v[130:131] op_sel_hi:[1,0]
	s_waitcnt lgkmcnt(0)
	v_pk_mul_f32 v[218:219], v[218:219], v[130:131] op_sel_hi:[1,0]
	v_pk_mul_f32 v[216:217], v[220:221], v[130:131] op_sel_hi:[1,0]
	v_addc_co_u32_e32 v223, vcc, 0, v147, vcc
	v_cvt_pk_bf16_f32 v217, v216, v217
	v_cvt_pk_bf16_f32 v216, v218, v219
	v_cvt_pk_bf16_f32 v215, v214, v215
	v_cvt_pk_bf16_f32 v214, v224, v225
	global_store_dwordx4 v[222:223], v[214:217], off sc1
	s_barrier
	s_and_saveexec_b64 s[16:17], s[8:9]
	s_cbranch_execz .LBB0_1020
	v_and_b32_e32 v254, 63, v180
	v_lshrrev_b32_e32 v253, 4, v254
	v_mul_u32_u24_e32 v253, 0x840, v253
	v_and_b32_e32 v254, 15, v254
	v_lshl_add_u32 v253, v254, 2, v253
	v_and_b32_e32 v254, 64, v180
	v_lshl_add_u32 v253, v254, 2, v253
	ds_write_b32 v253, v0 offset:0
	ds_write_b32 v253, v1 offset:528
	ds_write_b32 v253, v2 offset:1056
	ds_write_b32 v253, v3 offset:1584
	ds_write_b32 v253, v4 offset:64
	ds_write_b32 v253, v5 offset:592
	ds_write_b32 v253, v6 offset:1120
	ds_write_b32 v253, v7 offset:1648
	ds_write_b32 v253, v8 offset:128
	ds_write_b32 v253, v9 offset:656
	ds_write_b32 v253, v10 offset:1184
	ds_write_b32 v253, v11 offset:1712
	ds_write_b32 v253, v12 offset:192
	ds_write_b32 v253, v13 offset:720
	ds_write_b32 v253, v14 offset:1248
	ds_write_b32 v253, v15 offset:1776
	ds_write_b32 v253, v16 offset:8448
	ds_write_b32 v253, v17 offset:8976
	ds_write_b32 v253, v18 offset:9504
	ds_write_b32 v253, v19 offset:10032
	ds_write_b32 v253, v20 offset:8512
	ds_write_b32 v253, v21 offset:9040
	ds_write_b32 v253, v22 offset:9568
	ds_write_b32 v253, v23 offset:10096
	ds_write_b32 v253, v24 offset:8576
	ds_write_b32 v253, v25 offset:9104
	ds_write_b32 v253, v26 offset:9632
	ds_write_b32 v253, v27 offset:10160
	ds_write_b32 v253, v28 offset:8640
	ds_write_b32 v253, v29 offset:9168
	ds_write_b32 v253, v30 offset:9696
	ds_write_b32 v253, v31 offset:10224
	ds_write_b32 v253, v32 offset:16896
	ds_write_b32 v253, v33 offset:17424
	ds_write_b32 v253, v34 offset:17952
	ds_write_b32 v253, v35 offset:18480
	ds_write_b32 v253, v36 offset:16960
	ds_write_b32 v253, v37 offset:17488
	ds_write_b32 v253, v38 offset:18016
	ds_write_b32 v253, v39 offset:18544
	ds_write_b32 v253, v40 offset:17024
	ds_write_b32 v253, v41 offset:17552
	ds_write_b32 v253, v42 offset:18080
	ds_write_b32 v253, v43 offset:18608
	ds_write_b32 v253, v44 offset:17088
	ds_write_b32 v253, v45 offset:17616
	ds_write_b32 v253, v46 offset:18144
	ds_write_b32 v253, v47 offset:18672
	ds_write_b32 v253, v48 offset:25344
	ds_write_b32 v253, v49 offset:25872
	ds_write_b32 v253, v50 offset:26400
	ds_write_b32 v253, v51 offset:26928
	ds_write_b32 v253, v52 offset:25408
	ds_write_b32 v253, v53 offset:25936
	ds_write_b32 v253, v54 offset:26464
	ds_write_b32 v253, v55 offset:26992
	ds_write_b32 v253, v56 offset:25472
	ds_write_b32 v253, v57 offset:26000
	ds_write_b32 v253, v58 offset:26528
	ds_write_b32 v253, v59 offset:27056
	ds_write_b32 v253, v60 offset:25536
	ds_write_b32 v253, v61 offset:26064
	ds_write_b32 v253, v62 offset:26592
	ds_write_b32 v253, v63 offset:27120
	ds_write_b32 v253, v64 offset:33792
	ds_write_b32 v253, v65 offset:34320
	ds_write_b32 v253, v66 offset:34848
	ds_write_b32 v253, v67 offset:35376
	ds_write_b32 v253, v68 offset:33856
	ds_write_b32 v253, v69 offset:34384
	ds_write_b32 v253, v70 offset:34912
	ds_write_b32 v253, v71 offset:35440
	ds_write_b32 v253, v72 offset:33920
	ds_write_b32 v253, v73 offset:34448
	ds_write_b32 v253, v74 offset:34976
	ds_write_b32 v253, v75 offset:35504
	ds_write_b32 v253, v76 offset:33984
	ds_write_b32 v253, v77 offset:34512
	ds_write_b32 v253, v78 offset:35040
	ds_write_b32 v253, v79 offset:35568
	ds_write_b32 v253, v80 offset:42240
	ds_write_b32 v253, v81 offset:42768
	ds_write_b32 v253, v82 offset:43296
	ds_write_b32 v253, v83 offset:43824
	ds_write_b32 v253, v84 offset:42304
	ds_write_b32 v253, v85 offset:42832
	ds_write_b32 v253, v86 offset:43360
	ds_write_b32 v253, v87 offset:43888
	ds_write_b32 v253, v88 offset:42368
	ds_write_b32 v253, v89 offset:42896
	ds_write_b32 v253, v90 offset:43424
	ds_write_b32 v253, v91 offset:43952
	ds_write_b32 v253, v92 offset:42432
	ds_write_b32 v253, v93 offset:42960
	ds_write_b32 v253, v94 offset:43488
	ds_write_b32 v253, v95 offset:44016
	ds_write_b32 v253, v96 offset:50688
	ds_write_b32 v253, v97 offset:51216
	ds_write_b32 v253, v98 offset:51744
	ds_write_b32 v253, v99 offset:52272
	ds_write_b32 v253, v100 offset:50752
	ds_write_b32 v253, v101 offset:51280
	ds_write_b32 v253, v102 offset:51808
	ds_write_b32 v253, v103 offset:52336
	ds_write_b32 v253, v104 offset:50816
	ds_write_b32 v253, v105 offset:51344
	ds_write_b32 v253, v106 offset:51872
	ds_write_b32 v253, v107 offset:52400
	ds_write_b32 v253, v108 offset:50880
	ds_write_b32 v253, v109 offset:51408
	ds_write_b32 v253, v110 offset:51936
	ds_write_b32 v253, v111 offset:52464
	ds_write_b32 v253, v112 offset:59136
	ds_write_b32 v253, v113 offset:59664
	ds_write_b32 v253, v114 offset:60192
	ds_write_b32 v253, v115 offset:60720
	ds_write_b32 v253, v116 offset:59200
	ds_write_b32 v253, v117 offset:59728
	ds_write_b32 v253, v118 offset:60256
	ds_write_b32 v253, v119 offset:60784
	ds_write_b32 v253, v120 offset:59264
	ds_write_b32 v253, v121 offset:59792
	ds_write_b32 v253, v122 offset:60320
	ds_write_b32 v253, v123 offset:60848
	ds_write_b32 v253, v124 offset:59328
	ds_write_b32 v253, v125 offset:59856
	ds_write_b32 v253, v126 offset:60384
	ds_write_b32 v253, v127 offset:60912
	s_branch .LBB0_1020

.LBB0_1095:
	s_waitcnt vmcnt(10)
	v_pk_mul_f32 v[148:149], v[52:53], v[148:149]
	v_pk_mul_f32 v[146:147], v[54:55], v[146:147]
	v_pk_fma_f32 v[92:93], v[92:93], s[14:15], v[148:149] op_sel_hi:[1,0,1]
	v_pk_mul_f32 v[142:143], v[36:37], v[142:143]
	v_pk_fma_f32 v[94:95], v[94:95], s[14:15], v[146:147] op_sel_hi:[1,0,1]
	v_add_f32_e32 v87, v92, v93
	v_pk_fma_f32 v[80:81], v[80:81], s[14:15], v[142:143] op_sel_hi:[1,0,1]
	v_pk_mul_f32 v[140:141], v[38:39], v[140:141]
	v_add_f32_e32 v104, v94, v87
	v_mov_b32_e32 v87, v144
	v_mul_f32_e32 v144, 0x3fb504f3, v85
	s_waitcnt vmcnt(4)
	v_mul_f32_e32 v148, v77, v139
	v_pk_fma_f32 v[82:83], v[82:83], s[14:15], v[140:141] op_sel_hi:[1,0,1]
	v_add_f32_e32 v85, v80, v81
	v_mov_b32_e32 v142, v76
	v_mov_b32_e32 v143, v66
	v_mov_b32_e32 v139, v136
	v_pk_add_f32 v[146:147], v[94:95], v[104:105] op_sel_hi:[1,0]
	v_add_f32_e32 v104, v82, v85
	v_pk_mul_f32 v[138:139], v[142:143], v[138:139]
	v_mov_b32_e32 v89, v64
	v_mul_f32_e32 v146, v79, v111
	v_pk_add_f32 v[140:141], v[82:83], v[104:105] op_sel_hi:[1,0]
	v_pk_fma_f32 v[128:129], v[128:129], s[14:15], v[138:139] op_sel_hi:[1,0,1]
	v_mov_b32_e32 v138, v78
	v_mov_b32_e32 v139, v67
	v_mov_b32_e32 v111, v137
	v_pk_mul_f32 v[88:89], v[88:89], v[86:87]
	v_mov_b32_e32 v135, v65
	v_mov_b32_e32 v87, v145
	v_pk_mul_f32 v[110:111], v[138:139], v[110:111]
	v_mov_b32_e32 v85, v141
	v_pk_mul_f32 v[134:135], v[134:135], v[86:87]
	v_pk_fma_f32 v[110:111], v[126:127], s[14:15], v[110:111] op_sel_hi:[1,0,1]
	v_pk_mul_f32 v[84:85], v[84:85], s[14:15]
	v_pk_add_f32 v[126:127], v[140:141], s[10:11]
	v_ashrrev_i32_e32 v113, 31, v112
	v_mov_b32_e32 v85, v127
	v_mov_b32_e32 v126, v88
	v_mov_b32_e32 v127, v134
	v_mov_b32_e32 v134, v89
	v_pk_add_f32 v[88:89], v[126:127], v[134:135]
	v_pk_add_f32 v[84:85], v[84:85], v[146:147]
	v_mov_b32_e32 v145, v88
	v_mov_b32_e32 v149, v89
	v_pk_add_f32 v[126:127], v[144:145], v[148:149]
	v_mov_b32_e32 v144, v129
	v_pk_add_f32 v[134:135], v[128:129], v[126:127]
	v_mov_b32_e32 v145, v111
	v_pk_add_f32 v[134:135], v[110:111], v[134:135]
	v_mov_b32_e32 v129, v126
	v_pk_add_f32 v[134:135], v[134:135], v[84:85]
	v_mov_b32_e32 v111, v84
	v_add_f32_e32 v85, v134, v135
	ds_bpermute_b32 v87, v190, v85
	s_and_b64 s[8:9], exec, s[8:9]
	s_or_b64 s[12:13], s[8:9], s[12:13]
	s_waitcnt lgkmcnt(0)
	v_add_f32_e32 v85, v85, v87
	ds_bpermute_b32 v87, v191, v85
	s_waitcnt lgkmcnt(0)
	v_add_f32_e32 v85, v85, v87
	ds_bpermute_b32 v87, v192, v85
	s_waitcnt lgkmcnt(0)
	v_add_f32_e32 v85, v85, v87
	ds_bpermute_b32 v87, v193, v85
	s_waitcnt lgkmcnt(0)
	v_add_f32_e32 v85, v85, v87
	ds_bpermute_b32 v87, v194, v85
	s_waitcnt lgkmcnt(0)
	v_add_f32_e32 v85, v85, v87
	ds_bpermute_b32 v87, v195, v85
	s_waitcnt lgkmcnt(0)
	v_add_f32_e32 v85, v85, v87
	v_mul_f32_e32 v104, 0x3a800000, v85
	v_pk_add_f32 v[80:81], v[80:81], v[104:105] op_sel_hi:[1,0] neg_lo:[0,1] neg_hi:[0,1]
	v_pk_add_f32 v[82:83], v[82:83], v[104:105] op_sel_hi:[1,0] neg_lo:[0,1] neg_hi:[0,1]
	v_pk_mul_f32 v[134:135], v[80:81], v[80:81]
	v_pk_mul_f32 v[136:137], v[82:83], v[82:83]
	v_add_f32_e32 v87, v134, v135
	v_pk_add_f32 v[92:93], v[92:93], v[104:105] op_sel_hi:[1,0] neg_lo:[0,1] neg_hi:[0,1]
	v_add_f32_e32 v87, v136, v87
	v_pk_mul_f32 v[140:141], v[92:93], v[92:93]
	v_add_f32_e32 v87, v137, v87
	v_pk_add_f32 v[94:95], v[94:95], v[104:105] op_sel_hi:[1,0] neg_lo:[0,1] neg_hi:[0,1]
	v_add_f32_e32 v87, v140, v87
	v_pk_mul_f32 v[142:143], v[94:95], v[94:95]
	v_add_f32_e32 v87, v141, v87
	v_pk_add_f32 v[88:89], v[88:89], v[104:105] op_sel_hi:[1,0] neg_lo:[0,1] neg_hi:[0,1]
	v_add_f32_e32 v87, v142, v87
	v_pk_mul_f32 v[138:139], v[88:89], v[88:89]
	v_add_f32_e32 v87, v143, v87
	v_pk_add_f32 v[144:145], v[144:145], v[104:105] op_sel_hi:[1,0] neg_lo:[0,1] neg_hi:[0,1]
	v_add_f32_e32 v87, v138, v87
	v_pk_mul_f32 v[146:147], v[144:145], v[144:145]
	v_add_f32_e32 v87, v139, v87
	v_pk_add_f32 v[126:127], v[128:129], v[104:105] op_sel_hi:[1,0] neg_lo:[0,1] neg_hi:[0,1]
	v_add_f32_e32 v87, v146, v87
	v_pk_mul_f32 v[128:129], v[126:127], v[126:127]
	v_add_f32_e32 v87, v147, v87
	v_pk_add_f32 v[84:85], v[110:111], v[104:105] op_sel_hi:[1,0] neg_lo:[0,1] neg_hi:[0,1]
	v_add_f32_e32 v87, v128, v87
	v_pk_mul_f32 v[110:111], v[84:85], v[84:85]
	v_add_f32_e32 v87, v129, v87
	v_add_f32_e32 v87, v110, v87
	v_add_f32_e32 v87, v111, v87
	ds_bpermute_b32 v104, v190, v87
	v_lshlrev_b64 v[110:111], 12, v[112:113]
	v_lshl_add_u64 v[110:111], v[90:91], 0, v[110:111]
	v_pk_add_f32 v[128:129], v[32:33], 1.0 op_sel_hi:[1,0]
	v_pk_add_f32 v[134:135], v[34:35], 1.0 op_sel_hi:[1,0]
	s_waitcnt lgkmcnt(0)
	v_add_f32_e32 v87, v87, v104
	ds_bpermute_b32 v104, v191, v87
	v_lshlrev_b64 v[112:113], 11, v[112:113]
	v_lshl_add_u64 v[112:113], v[122:123], 0, v[112:113]
	v_pk_add_f32 v[136:137], v[40:41], 1.0 op_sel_hi:[1,0]
	v_pk_add_f32 v[138:139], v[42:43], 1.0 op_sel_hi:[1,0]
	s_waitcnt lgkmcnt(0)
	v_add_f32_e32 v87, v87, v104
	ds_bpermute_b32 v104, v192, v87
	s_waitcnt vmcnt(1)
	v_pk_add_f32 v[140:141], v[56:57], 1.0 op_sel_hi:[1,0]
	v_pk_add_f32 v[142:143], v[58:59], 1.0 op_sel_hi:[1,0]
	s_waitcnt lgkmcnt(0)
	v_add_f32_e32 v87, v87, v104
	ds_bpermute_b32 v104, v193, v87
	s_waitcnt lgkmcnt(0)
	v_add_f32_e32 v87, v87, v104
	ds_bpermute_b32 v104, v194, v87
	s_waitcnt lgkmcnt(0)
	v_add_f32_e32 v87, v87, v104
	ds_bpermute_b32 v104, v195, v87
	s_waitcnt lgkmcnt(0)
	v_add_f32_e32 v87, v87, v104
	v_fmamk_f32 v87, v87, 0x3a800000, v196
	v_mul_f32_e32 v104, 0x4b800000, v87
	v_cmp_gt_f32_e32 vcc, s3, v87
	s_nop 1
	v_cndmask_b32_e32 v87, v87, v104, vcc
	v_rsq_f32_e32 v87, v87
	s_nop 0
	v_mul_f32_e32 v104, 0x45800000, v87
	v_cndmask_b32_e32 v104, v87, v104, vcc
	v_pk_mul_f32 v[80:81], v[80:81], v[104:105] op_sel_hi:[1,0]
	v_pk_mul_f32 v[82:83], v[82:83], v[104:105] op_sel_hi:[1,0]
	v_pk_fma_f32 v[80:81], v[0:1], v[80:81], v[4:5]
	v_pk_fma_f32 v[82:83], v[2:3], v[82:83], v[6:7]
	global_store_dwordx4 v[110:111], v[80:83], off sc1 nt
	s_nop 1
	v_pk_fma_f32 v[80:81], v[128:129], v[80:81], v[44:45]
	v_pk_fma_f32 v[82:83], v[134:135], v[82:83], v[46:47]
	v_cvt_pk_bf16_f32 v80, v80, v81
	v_cvt_pk_bf16_f32 v81, v82, v83
	global_store_dwordx2 v[112:113], v[80:81], off
	v_pk_mul_f32 v[80:81], v[92:93], v[104:105] op_sel_hi:[1,0]
	v_pk_mul_f32 v[82:83], v[94:95], v[104:105] op_sel_hi:[1,0]
	v_pk_fma_f32 v[80:81], v[8:9], v[80:81], v[12:13]
	v_pk_fma_f32 v[82:83], v[10:11], v[82:83], v[14:15]
	global_store_dwordx4 v[110:111], v[80:83], off offset:1024 sc1 nt
	v_mov_b32_e32 v135, v197
	v_mov_b32_e32 v134, v109
	v_pk_fma_f32 v[80:81], v[136:137], v[80:81], v[48:49]
	v_pk_fma_f32 v[82:83], v[138:139], v[82:83], v[50:51]
	v_cvt_pk_bf16_f32 v80, v80, v81
	v_cvt_pk_bf16_f32 v81, v82, v83
	global_store_dwordx2 v[112:113], v[80:81], off offset:512
	v_pk_mul_f32 v[80:81], v[88:89], v[104:105] op_sel_hi:[1,0]
	v_pk_mul_f32 v[82:83], v[144:145], v[104:105] op_sel_hi:[1,0]
	v_pk_fma_f32 v[80:81], v[16:17], v[80:81], v[20:21]
	v_pk_fma_f32 v[82:83], v[18:19], v[82:83], v[22:23]
	global_store_dwordx4 v[110:111], v[80:83], off offset:2048 sc1 nt
	v_mov_b32_e32 v88, v108
	v_mov_b64_e32 v[128:129], v[132:133]
	v_pk_fma_f32 v[80:81], v[140:141], v[80:81], v[60:61]
	v_pk_fma_f32 v[82:83], v[142:143], v[82:83], v[62:63]
	v_cvt_pk_bf16_f32 v80, v80, v81
	v_cvt_pk_bf16_f32 v81, v82, v83
	global_store_dwordx2 v[112:113], v[80:81], off offset:1024
	v_pk_mul_f32 v[80:81], v[126:127], v[104:105] op_sel_hi:[1,0]
	v_pk_mul_f32 v[82:83], v[84:85], v[104:105] op_sel_hi:[1,0]
	v_pk_fma_f32 v[80:81], v[24:25], v[80:81], v[28:29]
	v_pk_fma_f32 v[82:83], v[26:27], v[82:83], v[30:31]
	s_waitcnt vmcnt(6)
	v_pk_add_f32 v[84:85], v[68:69], 1.0 op_sel_hi:[1,0]
	global_store_dwordx4 v[110:111], v[80:83], off offset:3072 sc1 nt
	v_mov_b64_e32 v[126:127], v[130:131]
	v_mov_b32_e32 v94, v102
	v_pk_fma_f32 v[80:81], v[84:85], v[80:81], v[72:73]
	v_pk_add_f32 v[84:85], v[70:71], 1.0 op_sel_hi:[1,0]
	v_cvt_pk_bf16_f32 v80, v80, v81
	v_pk_fma_f32 v[82:83], v[84:85], v[82:83], v[74:75]
	v_mov_b32_e32 v84, v107
	v_cvt_pk_bf16_f32 v81, v82, v83
	global_store_dwordx2 v[112:113], v[80:81], off offset:1536
	v_mov_b32_e32 v112, v124
	v_mov_b32_e32 v85, v105
	v_mov_b32_e32 v80, v96
	v_mov_b32_e32 v81, v97
	v_mov_b32_e32 v82, v98
	v_mov_b32_e32 v83, v99
	v_mov_b32_e32 v95, v103
	v_mov_b32_e32 v92, v100
	v_mov_b32_e32 v93, v101
	s_andn2_b64 exec, exec, s[12:13]
	s_cbranch_execz .LBB0_1111

.LBB0_1172:
	s_or_b64 exec, exec, s[24:25]
	s_waitcnt lgkmcnt(0)
	s_barrier
	ds_read_b128 v[0:3], v135 offset:256
	ds_read_b128 v[4:7], v135
	ds_read_b128 v[8:11], v135 offset:16
	ds_read_b128 v[12:15], v135 offset:272
	v_add_co_u32_e32 v20, vcc, s41, v136
	s_waitcnt lgkmcnt(2)
	v_pk_mul_f32 v[0:1], v[4:5], v[0:1]
	v_pk_mul_f32 v[2:3], v[6:7], v[2:3]
	s_waitcnt lgkmcnt(0)
	v_pk_mul_f32 v[4:5], v[8:9], v[12:13]
	v_pk_mul_f32 v[6:7], v[10:11], v[14:15]
	v_cvt_pk_bf16_f32 v0, v0, v1
	v_cvt_pk_bf16_f32 v1, v2, v3
	v_cvt_pk_bf16_f32 v2, v4, v5
	v_cvt_pk_bf16_f32 v3, v6, v7
	ds_read_b128 v[4:7], v133
	ds_read_b128 v[8:11], v133 offset:16
	ds_read_b128 v[12:15], v133 offset:256
	ds_read_b128 v[16:19], v133 offset:272
	v_addc_co_u32_e32 v21, vcc, 0, v137, vcc
	global_store_dwordx4 v[20:21], v[0:3], off sc1
	s_waitcnt lgkmcnt(1)
	v_pk_mul_f32 v[4:5], v[4:5], v[12:13]
	v_add_co_u32_e32 v20, vcc, s41, v138
	v_pk_mul_f32 v[0:1], v[6:7], v[14:15]
	s_waitcnt lgkmcnt(0)
	v_pk_mul_f32 v[6:7], v[8:9], v[16:17]
	v_pk_mul_f32 v[2:3], v[10:11], v[18:19]
	v_cvt_pk_bf16_f32 v1, v0, v1
	v_cvt_pk_bf16_f32 v3, v2, v3
	v_cvt_pk_bf16_f32 v2, v6, v7
	v_cvt_pk_bf16_f32 v0, v4, v5
	ds_read_b128 v[4:7], v135 offset:33792
	ds_read_b128 v[8:11], v135 offset:33808
	ds_read_b128 v[12:15], v135 offset:34048
	ds_read_b128 v[16:19], v135 offset:34064
	v_addc_co_u32_e32 v21, vcc, 0, v139, vcc
	global_store_dwordx4 v[20:21], v[0:3], off sc1
	v_add_co_u32_e32 v20, vcc, s42, v136
	s_waitcnt lgkmcnt(1)
	v_pk_mul_f32 v[0:1], v[4:5], v[12:13]
	v_pk_mul_f32 v[2:3], v[6:7], v[14:15]
	s_waitcnt lgkmcnt(0)
	v_pk_mul_f32 v[4:5], v[8:9], v[16:17]
	v_pk_mul_f32 v[6:7], v[10:11], v[18:19]
	v_cvt_pk_bf16_f32 v0, v0, v1
	v_cvt_pk_bf16_f32 v1, v2, v3
	v_cvt_pk_bf16_f32 v2, v4, v5
	v_cvt_pk_bf16_f32 v3, v6, v7
	ds_read_b128 v[4:7], v133 offset:33792
	ds_read_b128 v[8:11], v133 offset:33808
	ds_read_b128 v[12:15], v133 offset:34048
	ds_read_b128 v[16:19], v133 offset:34064
	v_addc_co_u32_e32 v21, vcc, 0, v137, vcc
	global_store_dwordx4 v[20:21], v[0:3], off sc1
	s_waitcnt lgkmcnt(1)
	v_pk_mul_f32 v[4:5], v[4:5], v[12:13]
	v_pk_mul_f32 v[0:1], v[6:7], v[14:15]
	s_waitcnt lgkmcnt(0)
	v_pk_mul_f32 v[6:7], v[8:9], v[16:17]
	v_pk_mul_f32 v[2:3], v[10:11], v[18:19]
	v_cvt_pk_bf16_f32 v1, v0, v1
	v_cvt_pk_bf16_f32 v0, v4, v5
	v_add_co_u32_e32 v4, vcc, 0x60000, v138
	v_cvt_pk_bf16_f32 v3, v2, v3
	v_cvt_pk_bf16_f32 v2, v6, v7
	v_addc_co_u32_e32 v5, vcc, 0, v139, vcc
	global_store_dwordx4 v[4:5], v[0:3], off sc1
	s_barrier

.LBB0_1179:
	s_or_b64 exec, exec, s[26:27]
	v_lshlrev_b32_e32 v133, 3, v130
	v_and_b32_e32 v179, 0x78, v133
	v_ashrrev_i32_e32 v186, 4, v130
	v_lshl_add_u32 v181, v179, 2, 0
	v_mul_lo_u32 v133, v186, s35
	v_add_u32_e32 v152, 0x200, v130
	v_add_u32_e32 v133, v181, v133
	v_add_u32_e32 v135, 0x100, v130
	v_ashrrev_i32_e32 v198, 4, v152
	s_waitcnt lgkmcnt(0)
	s_barrier
	ds_read_b128 v[152:155], v133
	ds_read_b128 v[156:159], v133 offset:16
	v_ashrrev_i32_e32 v194, 4, v135
	s_lshl_b32 s4, s44, 1
	v_mul_lo_u32 v135, v194, s35
	s_add_u32 s4, s36, s4
	v_add_u32_e32 v135, v181, v135
	s_addc_u32 s26, s37, 0
	s_lshl_b64 s[24:25], s[24:25], 1
	ds_read_b128 v[190:193], v135 offset:16
	s_add_u32 s24, s4, s24
	s_waitcnt lgkmcnt(2)
	v_cvt_pk_bf16_f32 v183, v154, v155
	s_waitcnt lgkmcnt(1)
	v_cvt_pk_bf16_f32 v184, v156, v157
	v_ashrrev_i32_e32 v187, 31, v186
	ds_read_b128 v[154:157], v135
	s_addc_u32 s25, s26, s25
	v_add_u32_e32 v130, 0x300, v130
	v_cvt_pk_bf16_f32 v182, v152, v153
	v_lshlrev_b64 v[152:153], 11, v[186:187]
	v_mul_lo_u32 v189, v198, s35
	v_ashrrev_i32_e32 v200, 4, v130
	v_lshl_add_u64 v[152:153], s[24:25], 0, v[152:153]
	v_lshlrev_b32_e32 v130, 1, v179
	v_cvt_pk_bf16_f32 v185, v158, v159
	v_lshl_add_u64 v[152:153], v[152:153], 0, v[130:131]
	v_add_u32_e32 v179, v181, v189
	global_store_dwordx4 v[152:153], v[182:185], off sc1
	v_ashrrev_i32_e32 v195, 31, v194
	v_mul_lo_u32 v196, v200, s35
	s_waitcnt lgkmcnt(1)
	v_cvt_pk_bf16_f32 v184, v190, v191
	v_cvt_pk_bf16_f32 v185, v192, v193
	ds_read_b128 v[190:193], v179 offset:16
	s_waitcnt lgkmcnt(1)
	v_cvt_pk_bf16_f32 v182, v154, v155
	v_lshlrev_b64 v[154:155], 11, v[194:195]
	v_cvt_pk_bf16_f32 v183, v156, v157
	ds_read_b128 v[156:159], v179
	v_lshl_add_u64 v[154:155], s[24:25], 0, v[154:155]
	v_lshl_add_u64 v[154:155], v[154:155], 0, v[130:131]
	global_store_dwordx4 v[154:155], v[182:185], off sc1
	v_add_u32_e32 v181, v181, v196
	v_ashrrev_i32_e32 v199, 31, v198
	s_waitcnt lgkmcnt(1)
	v_cvt_pk_bf16_f32 v184, v190, v191
	v_cvt_pk_bf16_f32 v185, v192, v193
	ds_read_b128 v[190:193], v181
	ds_read_b128 v[194:197], v181 offset:16
	s_waitcnt lgkmcnt(2)
	v_cvt_pk_bf16_f32 v182, v156, v157
	v_lshlrev_b64 v[156:157], 11, v[198:199]
	v_lshl_add_u64 v[156:157], s[24:25], 0, v[156:157]
	v_cvt_pk_bf16_f32 v183, v158, v159
	v_lshl_add_u64 v[156:157], v[156:157], 0, v[130:131]
	global_store_dwordx4 v[156:157], v[182:185], off sc1
	v_ashrrev_i32_e32 v201, 31, v200
	v_lshlrev_b64 v[158:159], 11, v[200:201]
	s_waitcnt lgkmcnt(0)
	v_cvt_pk_bf16_f32 v185, v196, v197
	v_cvt_pk_bf16_f32 v184, v194, v195
	v_cvt_pk_bf16_f32 v183, v192, v193
	v_cvt_pk_bf16_f32 v182, v190, v191
	ds_read_b128 v[190:193], v133 offset:33792
	ds_read_b128 v[194:197], v133 offset:33808
	v_lshl_add_u64 v[158:159], s[24:25], 0, v[158:159]
	v_lshl_add_u64 v[158:159], v[158:159], 0, v[130:131]
	global_store_dwordx4 v[158:159], v[182:185], off sc1
	v_add_co_u32_e32 v186, vcc, s40, v152
	s_waitcnt lgkmcnt(1)
	v_cvt_pk_bf16_f32 v182, v190, v191
	v_cvt_pk_bf16_f32 v183, v192, v193
	s_waitcnt lgkmcnt(0)
	v_cvt_pk_bf16_f32 v184, v194, v195
	v_cvt_pk_bf16_f32 v185, v196, v197
	ds_read_b128 v[190:193], v135 offset:33792
	ds_read_b128 v[194:197], v135 offset:33808
	v_addc_co_u32_e32 v187, vcc, 0, v153, vcc
	global_store_dwordx4 v[186:187], v[182:185], off sc1
	v_add_co_u32_e32 v186, vcc, s40, v154
	s_waitcnt lgkmcnt(1)
	v_cvt_pk_bf16_f32 v182, v190, v191
	v_cvt_pk_bf16_f32 v183, v192, v193
	s_waitcnt lgkmcnt(0)
	v_cvt_pk_bf16_f32 v184, v194, v195
	v_cvt_pk_bf16_f32 v185, v196, v197
	ds_read_b128 v[190:193], v179 offset:33792
	ds_read_b128 v[194:197], v179 offset:33808
	v_addc_co_u32_e32 v187, vcc, 0, v155, vcc
	global_store_dwordx4 v[186:187], v[182:185], off sc1
	v_add_co_u32_e32 v186, vcc, s40, v156
	s_waitcnt lgkmcnt(1)
	v_cvt_pk_bf16_f32 v182, v190, v191
	v_cvt_pk_bf16_f32 v183, v192, v193
	s_waitcnt lgkmcnt(0)
	v_cvt_pk_bf16_f32 v184, v194, v195
	v_cvt_pk_bf16_f32 v185, v196, v197
	ds_read_b128 v[190:193], v181 offset:33792
	ds_read_b128 v[194:197], v181 offset:33808
	v_addc_co_u32_e32 v187, vcc, 0, v157, vcc
	global_store_dwordx4 v[186:187], v[182:185], off sc1
	v_add_co_u32_e32 v186, vcc, 0x20000, v158
	s_waitcnt lgkmcnt(0)
	v_cvt_pk_bf16_f32 v185, v196, v197
	v_cvt_pk_bf16_f32 v184, v194, v195
	v_cvt_pk_bf16_f32 v183, v192, v193
	v_cvt_pk_bf16_f32 v182, v190, v191
	v_addc_co_u32_e32 v187, vcc, 0, v159, vcc
	global_store_dwordx4 v[186:187], v[182:185], off sc1
	s_barrier
	s_and_saveexec_b64 s[24:25], s[8:9]
	s_cbranch_execz .LBB0_1181
	v_and_b32_e32 v254, 63, v180
	v_lshrrev_b32_e32 v253, 4, v254
	v_mul_u32_u24_e32 v253, 0x840, v253
	v_and_b32_e32 v254, 15, v254
	v_lshl_add_u32 v253, v254, 2, v253
	v_and_b32_e32 v254, 64, v180
	v_lshl_add_u32 v253, v254, 2, v253
	ds_write_b32 v253, v0 offset:0
	ds_write_b32 v253, v1 offset:528
	ds_write_b32 v253, v2 offset:1056
	ds_write_b32 v253, v3 offset:1584
	ds_write_b32 v253, v4 offset:64
	ds_write_b32 v253, v5 offset:592
	ds_write_b32 v253, v6 offset:1120
	ds_write_b32 v253, v7 offset:1648
	ds_write_b32 v253, v8 offset:128
	ds_write_b32 v253, v9 offset:656
	ds_write_b32 v253, v10 offset:1184
	ds_write_b32 v253, v11 offset:1712
	ds_write_b32 v253, v12 offset:192
	ds_write_b32 v253, v13 offset:720
	ds_write_b32 v253, v14 offset:1248
	ds_write_b32 v253, v15 offset:1776
	ds_write_b32 v253, v16 offset:8448
	ds_write_b32 v253, v17 offset:8976
	ds_write_b32 v253, v18 offset:9504
	ds_write_b32 v253, v19 offset:10032
	ds_write_b32 v253, v20 offset:8512
	ds_write_b32 v253, v21 offset:9040
	ds_write_b32 v253, v22 offset:9568
	ds_write_b32 v253, v23 offset:10096
	ds_write_b32 v253, v24 offset:8576
	ds_write_b32 v253, v25 offset:9104
	ds_write_b32 v253, v26 offset:9632
	ds_write_b32 v253, v27 offset:10160
	ds_write_b32 v253, v28 offset:8640
	ds_write_b32 v253, v29 offset:9168
	ds_write_b32 v253, v30 offset:9696
	ds_write_b32 v253, v31 offset:10224
	ds_write_b32 v253, v32 offset:16896
	ds_write_b32 v253, v33 offset:17424
	ds_write_b32 v253, v34 offset:17952
	ds_write_b32 v253, v35 offset:18480
	ds_write_b32 v253, v36 offset:16960
	ds_write_b32 v253, v37 offset:17488
	ds_write_b32 v253, v38 offset:18016
	ds_write_b32 v253, v39 offset:18544
	ds_write_b32 v253, v40 offset:17024
	ds_write_b32 v253, v41 offset:17552
	ds_write_b32 v253, v42 offset:18080
	ds_write_b32 v253, v43 offset:18608
	ds_write_b32 v253, v44 offset:17088
	ds_write_b32 v253, v45 offset:17616
	ds_write_b32 v253, v46 offset:18144
	ds_write_b32 v253, v47 offset:18672
	ds_write_b32 v253, v48 offset:25344
	ds_write_b32 v253, v49 offset:25872
	ds_write_b32 v253, v50 offset:26400
	ds_write_b32 v253, v51 offset:26928
	ds_write_b32 v253, v52 offset:25408
	ds_write_b32 v253, v53 offset:25936
	ds_write_b32 v253, v54 offset:26464
	ds_write_b32 v253, v55 offset:26992
	ds_write_b32 v253, v56 offset:25472
	ds_write_b32 v253, v57 offset:26000
	ds_write_b32 v253, v58 offset:26528
	ds_write_b32 v253, v59 offset:27056
	ds_write_b32 v253, v60 offset:25536
	ds_write_b32 v253, v61 offset:26064
	ds_write_b32 v253, v62 offset:26592
	ds_write_b32 v253, v63 offset:27120
	ds_write_b32 v253, v64 offset:33792
	ds_write_b32 v253, v65 offset:34320
	ds_write_b32 v253, v66 offset:34848
	ds_write_b32 v253, v67 offset:35376
	ds_write_b32 v253, v68 offset:33856
	ds_write_b32 v253, v69 offset:34384
	ds_write_b32 v253, v70 offset:34912
	ds_write_b32 v253, v71 offset:35440
	ds_write_b32 v253, v72 offset:33920
	ds_write_b32 v253, v73 offset:34448
	ds_write_b32 v253, v74 offset:34976
	ds_write_b32 v253, v75 offset:35504
	ds_write_b32 v253, v76 offset:33984
	ds_write_b32 v253, v77 offset:34512
	ds_write_b32 v253, v78 offset:35040
	ds_write_b32 v253, v79 offset:35568
	ds_write_b32 v253, v80 offset:42240
	ds_write_b32 v253, v81 offset:42768
	ds_write_b32 v253, v82 offset:43296
	ds_write_b32 v253, v83 offset:43824
	ds_write_b32 v253, v84 offset:42304
	ds_write_b32 v253, v85 offset:42832
	ds_write_b32 v253, v86 offset:43360
	ds_write_b32 v253, v87 offset:43888
	ds_write_b32 v253, v88 offset:42368
	ds_write_b32 v253, v89 offset:42896
	ds_write_b32 v253, v90 offset:43424
	ds_write_b32 v253, v91 offset:43952
	ds_write_b32 v253, v92 offset:42432
	ds_write_b32 v253, v93 offset:42960
	ds_write_b32 v253, v94 offset:43488
	ds_write_b32 v253, v95 offset:44016
	ds_write_b32 v253, v96 offset:50688
	ds_write_b32 v253, v97 offset:51216
	ds_write_b32 v253, v98 offset:51744
	ds_write_b32 v253, v99 offset:52272
	ds_write_b32 v253, v100 offset:50752
	ds_write_b32 v253, v101 offset:51280
	ds_write_b32 v253, v102 offset:51808
	ds_write_b32 v253, v103 offset:52336
	ds_write_b32 v253, v104 offset:50816
	ds_write_b32 v253, v105 offset:51344
	ds_write_b32 v253, v106 offset:51872
	ds_write_b32 v253, v107 offset:52400
	ds_write_b32 v253, v108 offset:50880
	ds_write_b32 v253, v109 offset:51408
	ds_write_b32 v253, v110 offset:51936
	ds_write_b32 v253, v111 offset:52464
	ds_write_b32 v253, v112 offset:59136
	ds_write_b32 v253, v113 offset:59664
	ds_write_b32 v253, v114 offset:60192
	ds_write_b32 v253, v115 offset:60720
	ds_write_b32 v253, v116 offset:59200
	ds_write_b32 v253, v117 offset:59728
	ds_write_b32 v253, v118 offset:60256
	ds_write_b32 v253, v119 offset:60784
	ds_write_b32 v253, v120 offset:59264
	ds_write_b32 v253, v121 offset:59792
	ds_write_b32 v253, v122 offset:60320
	ds_write_b32 v253, v123 offset:60848
	ds_write_b32 v253, v124 offset:59328
	ds_write_b32 v253, v125 offset:59856
	ds_write_b32 v253, v126 offset:60384
	ds_write_b32 v253, v127 offset:60912
.LBB0_1181:
	s_or_b64 exec, exec, s[24:25]
	s_waitcnt lgkmcnt(0)
	s_barrier
	ds_read_b128 v[0:3], v133
	ds_read_b128 v[4:7], v133 offset:16
	v_add_co_u32_e32 v12, vcc, s41, v152
	s_waitcnt lgkmcnt(1)
	v_cvt_pk_bf16_f32 v0, v0, v1
	v_cvt_pk_bf16_f32 v1, v2, v3
	s_waitcnt lgkmcnt(0)
	v_cvt_pk_bf16_f32 v2, v4, v5
	v_cvt_pk_bf16_f32 v3, v6, v7
	ds_read_b128 v[4:7], v135
	ds_read_b128 v[8:11], v135 offset:16
	v_addc_co_u32_e32 v13, vcc, 0, v153, vcc
	global_store_dwordx4 v[12:13], v[0:3], off sc1
	v_add_co_u32_e32 v12, vcc, s41, v154
	s_waitcnt lgkmcnt(1)
	v_cvt_pk_bf16_f32 v0, v4, v5
	v_cvt_pk_bf16_f32 v1, v6, v7
	s_waitcnt lgkmcnt(0)
	v_cvt_pk_bf16_f32 v2, v8, v9
	v_cvt_pk_bf16_f32 v3, v10, v11
	ds_read_b128 v[4:7], v179
	ds_read_b128 v[8:11], v179 offset:16
	v_addc_co_u32_e32 v13, vcc, 0, v155, vcc
	global_store_dwordx4 v[12:13], v[0:3], off sc1
	v_add_co_u32_e32 v12, vcc, s41, v156
	s_waitcnt lgkmcnt(1)
	v_cvt_pk_bf16_f32 v0, v4, v5
	v_cvt_pk_bf16_f32 v1, v6, v7
	s_waitcnt lgkmcnt(0)
	v_cvt_pk_bf16_f32 v2, v8, v9
	v_cvt_pk_bf16_f32 v3, v10, v11
	ds_read_b128 v[4:7], v181
	ds_read_b128 v[8:11], v181 offset:16
	v_addc_co_u32_e32 v13, vcc, 0, v157, vcc
	global_store_dwordx4 v[12:13], v[0:3], off sc1
	v_add_co_u32_e32 v12, vcc, s41, v158
	s_waitcnt lgkmcnt(0)
	v_cvt_pk_bf16_f32 v3, v10, v11
	v_cvt_pk_bf16_f32 v2, v8, v9
	v_cvt_pk_bf16_f32 v1, v6, v7
	v_cvt_pk_bf16_f32 v0, v4, v5
	ds_read_b128 v[4:7], v133 offset:33792
	ds_read_b128 v[8:11], v133 offset:33808
	v_addc_co_u32_e32 v13, vcc, 0, v159, vcc
	global_store_dwordx4 v[12:13], v[0:3], off sc1
	v_add_co_u32_e32 v12, vcc, s42, v152
	s_waitcnt lgkmcnt(1)
	v_cvt_pk_bf16_f32 v0, v4, v5
	v_cvt_pk_bf16_f32 v1, v6, v7
	s_waitcnt lgkmcnt(0)
	v_cvt_pk_bf16_f32 v2, v8, v9
	v_cvt_pk_bf16_f32 v3, v10, v11
	ds_read_b128 v[4:7], v135 offset:33792
	ds_read_b128 v[8:11], v135 offset:33808
	v_addc_co_u32_e32 v13, vcc, 0, v153, vcc
	global_store_dwordx4 v[12:13], v[0:3], off sc1
	v_add_co_u32_e32 v12, vcc, s42, v154
	s_waitcnt lgkmcnt(1)
	v_cvt_pk_bf16_f32 v0, v4, v5
	v_cvt_pk_bf16_f32 v1, v6, v7
	s_waitcnt lgkmcnt(0)
	v_cvt_pk_bf16_f32 v2, v8, v9
	v_cvt_pk_bf16_f32 v3, v10, v11
	ds_read_b128 v[4:7], v179 offset:33792
	ds_read_b128 v[8:11], v179 offset:33808
	v_addc_co_u32_e32 v13, vcc, 0, v155, vcc
	global_store_dwordx4 v[12:13], v[0:3], off sc1
	v_add_co_u32_e32 v12, vcc, s42, v156
	s_waitcnt lgkmcnt(1)
	v_cvt_pk_bf16_f32 v0, v4, v5
	v_cvt_pk_bf16_f32 v1, v6, v7
	s_waitcnt lgkmcnt(0)
	v_cvt_pk_bf16_f32 v2, v8, v9
	v_cvt_pk_bf16_f32 v3, v10, v11
	ds_read_b128 v[4:7], v181 offset:33792
	ds_read_b128 v[8:11], v181 offset:33808
	v_addc_co_u32_e32 v13, vcc, 0, v157, vcc
	global_store_dwordx4 v[12:13], v[0:3], off sc1
	s_waitcnt lgkmcnt(1)
	s_nop 0
	v_cvt_pk_bf16_f32 v0, v4, v5
	v_add_co_u32_e32 v4, vcc, 0x60000, v158
	s_waitcnt lgkmcnt(0)
	v_cvt_pk_bf16_f32 v3, v10, v11
	v_cvt_pk_bf16_f32 v2, v8, v9
	v_cvt_pk_bf16_f32 v1, v6, v7
	v_addc_co_u32_e32 v5, vcc, 0, v159, vcc
	global_store_dwordx4 v[4:5], v[0:3], off sc1
	s_barrier
	s_branch .LBB0_1173

.LBB0_1187:
	s_or_b64 exec, exec, s[24:25]
	v_lshlrev_b32_e32 v133, 3, v130
	v_and_b32_e32 v193, 56, v133
	v_ashrrev_i32_e32 v206, 3, v130
	v_mul_lo_u32 v133, v206, s35
	v_lshlrev_b32_e32 v207, 2, v193
	v_add3_u32 v135, 0, v133, v207
	s_waitcnt lgkmcnt(0)
	s_barrier
	ds_read_b128 v[136:139], v135 offset:256
	ds_read_b128 v[194:197], v135
	ds_read_b128 v[198:201], v135 offset:16
	ds_read_b128 v[202:205], v135 offset:272
	v_add_u32_e32 v130, 0x100, v130
	v_ashrrev_i32_e32 v210, 3, v130
	s_lshl_b32 s4, s44, 1
	v_mul_lo_u32 v130, v210, s35
	s_add_u32 s4, s38, s4
	v_add3_u32 v133, 0, v130, v207
	s_waitcnt lgkmcnt(2)
	v_pk_mul_f32 v[136:137], v[194:195], v[136:137]
	v_pk_mul_f32 v[138:139], v[196:197], v[138:139]
	s_waitcnt lgkmcnt(0)
	v_pk_mul_f32 v[196:197], v[198:199], v[202:203]
	v_pk_mul_f32 v[198:199], v[200:201], v[204:205]
	v_ashrrev_i32_e32 v207, 31, v206
	s_addc_u32 s25, s39, 0
	s_lshl_b32 s24, s43, 7
	v_cvt_pk_bf16_f32 v194, v136, v137
	v_cvt_pk_bf16_f32 v196, v196, v197
	v_cvt_pk_bf16_f32 v197, v198, v199
	v_lshlrev_b64 v[136:137], 11, v[206:207]
	ds_read_b128 v[198:201], v133 offset:256
	ds_read_b128 v[202:205], v133
	ds_read_b128 v[206:209], v133 offset:16
	ds_read_b128 v[214:217], v133 offset:272
	s_add_u32 s24, s4, s24
	s_addc_u32 s25, s25, 0
	v_lshl_add_u64 v[136:137], s[24:25], 0, v[136:137]
	v_lshlrev_b32_e32 v130, 1, v193
	v_cvt_pk_bf16_f32 v195, v138, v139
	v_lshl_add_u64 v[136:137], v[136:137], 0, v[130:131]
	global_store_dwordx4 v[136:137], v[194:197], off sc1
	s_waitcnt lgkmcnt(2)
	v_pk_mul_f32 v[138:139], v[202:203], v[198:199]
	s_waitcnt lgkmcnt(0)
	v_pk_mul_f32 v[198:199], v[206:207], v[214:215]
	v_pk_mul_f32 v[196:197], v[208:209], v[216:217]
	v_pk_mul_f32 v[194:195], v[204:205], v[200:201]
	v_cvt_pk_bf16_f32 v197, v196, v197
	v_cvt_pk_bf16_f32 v196, v198, v199
	ds_read_b128 v[198:201], v135 offset:34048
	ds_read_b128 v[202:205], v135 offset:33792
	ds_read_b128 v[206:209], v135 offset:33808
	ds_read_b128 v[214:217], v135 offset:34064
	v_ashrrev_i32_e32 v211, 31, v210
	v_cvt_pk_bf16_f32 v195, v194, v195
	v_cvt_pk_bf16_f32 v194, v138, v139
	v_lshlrev_b64 v[138:139], 11, v[210:211]
	v_lshl_add_u64 v[138:139], s[24:25], 0, v[138:139]
	v_lshl_add_u64 v[138:139], v[138:139], 0, v[130:131]
	global_store_dwordx4 v[138:139], v[194:197], off sc1
	v_add_co_u32_e32 v210, vcc, s40, v136
	s_waitcnt lgkmcnt(2)
	v_pk_mul_f32 v[194:195], v[202:203], v[198:199]
	v_pk_mul_f32 v[196:197], v[204:205], v[200:201]
	s_waitcnt lgkmcnt(0)
	v_pk_mul_f32 v[198:199], v[206:207], v[214:215]
	v_pk_mul_f32 v[200:201], v[208:209], v[216:217]
	v_cvt_pk_bf16_f32 v194, v194, v195
	v_cvt_pk_bf16_f32 v195, v196, v197
	v_cvt_pk_bf16_f32 v196, v198, v199
	v_cvt_pk_bf16_f32 v197, v200, v201
	ds_read_b128 v[198:201], v133 offset:33792
	ds_read_b128 v[202:205], v133 offset:33808
	ds_read_b128 v[206:209], v133 offset:34048
	ds_read_b128 v[214:217], v133 offset:34064
	v_addc_co_u32_e32 v211, vcc, 0, v137, vcc
	global_store_dwordx4 v[210:211], v[194:197], off sc1
	s_waitcnt lgkmcnt(1)
	v_pk_mul_f32 v[198:199], v[198:199], v[206:207]
	v_pk_mul_f32 v[194:195], v[200:201], v[208:209]
	s_waitcnt lgkmcnt(0)
	v_pk_mul_f32 v[200:201], v[202:203], v[214:215]
	v_pk_mul_f32 v[196:197], v[204:205], v[216:217]
	v_cvt_pk_bf16_f32 v195, v194, v195
	v_cvt_pk_bf16_f32 v194, v198, v199
	v_add_co_u32_e32 v198, vcc, 0x20000, v138
	v_cvt_pk_bf16_f32 v197, v196, v197
	v_cvt_pk_bf16_f32 v196, v200, v201
	v_addc_co_u32_e32 v199, vcc, 0, v139, vcc
	global_store_dwordx4 v[198:199], v[194:197], off sc1
	s_barrier
	s_and_saveexec_b64 s[24:25], s[8:9]
	s_cbranch_execz .LBB0_1172
	v_and_b32_e32 v254, 63, v180
	v_lshrrev_b32_e32 v253, 4, v254
	v_mul_u32_u24_e32 v253, 0x840, v253
	v_and_b32_e32 v254, 15, v254
	v_lshl_add_u32 v253, v254, 2, v253
	v_and_b32_e32 v254, 64, v180
	v_lshl_add_u32 v253, v254, 2, v253
	ds_write_b32 v253, v0 offset:0
	ds_write_b32 v253, v1 offset:528
	ds_write_b32 v253, v2 offset:1056
	ds_write_b32 v253, v3 offset:1584
	ds_write_b32 v253, v4 offset:64
	ds_write_b32 v253, v5 offset:592
	ds_write_b32 v253, v6 offset:1120
	ds_write_b32 v253, v7 offset:1648
	ds_write_b32 v253, v8 offset:128
	ds_write_b32 v253, v9 offset:656
	ds_write_b32 v253, v10 offset:1184
	ds_write_b32 v253, v11 offset:1712
	ds_write_b32 v253, v12 offset:192
	ds_write_b32 v253, v13 offset:720
	ds_write_b32 v253, v14 offset:1248
	ds_write_b32 v253, v15 offset:1776
	ds_write_b32 v253, v16 offset:8448
	ds_write_b32 v253, v17 offset:8976
	ds_write_b32 v253, v18 offset:9504
	ds_write_b32 v253, v19 offset:10032
	ds_write_b32 v253, v20 offset:8512
	ds_write_b32 v253, v21 offset:9040
	ds_write_b32 v253, v22 offset:9568
	ds_write_b32 v253, v23 offset:10096
	ds_write_b32 v253, v24 offset:8576
	ds_write_b32 v253, v25 offset:9104
	ds_write_b32 v253, v26 offset:9632
	ds_write_b32 v253, v27 offset:10160
	ds_write_b32 v253, v28 offset:8640
	ds_write_b32 v253, v29 offset:9168
	ds_write_b32 v253, v30 offset:9696
	ds_write_b32 v253, v31 offset:10224
	ds_write_b32 v253, v32 offset:16896
	ds_write_b32 v253, v33 offset:17424
	ds_write_b32 v253, v34 offset:17952
	ds_write_b32 v253, v35 offset:18480
	ds_write_b32 v253, v36 offset:16960
	ds_write_b32 v253, v37 offset:17488
	ds_write_b32 v253, v38 offset:18016
	ds_write_b32 v253, v39 offset:18544
	ds_write_b32 v253, v40 offset:17024
	ds_write_b32 v253, v41 offset:17552
	ds_write_b32 v253, v42 offset:18080
	ds_write_b32 v253, v43 offset:18608
	ds_write_b32 v253, v44 offset:17088
	ds_write_b32 v253, v45 offset:17616
	ds_write_b32 v253, v46 offset:18144
	ds_write_b32 v253, v47 offset:18672
	ds_write_b32 v253, v48 offset:25344
	ds_write_b32 v253, v49 offset:25872
	ds_write_b32 v253, v50 offset:26400
	ds_write_b32 v253, v51 offset:26928
	ds_write_b32 v253, v52 offset:25408
	ds_write_b32 v253, v53 offset:25936
	ds_write_b32 v253, v54 offset:26464
	ds_write_b32 v253, v55 offset:26992
	ds_write_b32 v253, v56 offset:25472
	ds_write_b32 v253, v57 offset:26000
	ds_write_b32 v253, v58 offset:26528
	ds_write_b32 v253, v59 offset:27056
	ds_write_b32 v253, v60 offset:25536
	ds_write_b32 v253, v61 offset:26064
	ds_write_b32 v253, v62 offset:26592
	ds_write_b32 v253, v63 offset:27120
	ds_write_b32 v253, v64 offset:33792
	ds_write_b32 v253, v65 offset:34320
	ds_write_b32 v253, v66 offset:34848
	ds_write_b32 v253, v67 offset:35376
	ds_write_b32 v253, v68 offset:33856
	ds_write_b32 v253, v69 offset:34384
	ds_write_b32 v253, v70 offset:34912
	ds_write_b32 v253, v71 offset:35440
	ds_write_b32 v253, v72 offset:33920
	ds_write_b32 v253, v73 offset:34448
	ds_write_b32 v253, v74 offset:34976
	ds_write_b32 v253, v75 offset:35504
	ds_write_b32 v253, v76 offset:33984
	ds_write_b32 v253, v77 offset:34512
	ds_write_b32 v253, v78 offset:35040
	ds_write_b32 v253, v79 offset:35568
	ds_write_b32 v253, v80 offset:42240
	ds_write_b32 v253, v81 offset:42768
	ds_write_b32 v253, v82 offset:43296
	ds_write_b32 v253, v83 offset:43824
	ds_write_b32 v253, v84 offset:42304
	ds_write_b32 v253, v85 offset:42832
	ds_write_b32 v253, v86 offset:43360
	ds_write_b32 v253, v87 offset:43888
	ds_write_b32 v253, v88 offset:42368
	ds_write_b32 v253, v89 offset:42896
	ds_write_b32 v253, v90 offset:43424
	ds_write_b32 v253, v91 offset:43952
	ds_write_b32 v253, v92 offset:42432
	ds_write_b32 v253, v93 offset:42960
	ds_write_b32 v253, v94 offset:43488
	ds_write_b32 v253, v95 offset:44016
	ds_write_b32 v253, v96 offset:50688
	ds_write_b32 v253, v97 offset:51216
	ds_write_b32 v253, v98 offset:51744
	ds_write_b32 v253, v99 offset:52272
	ds_write_b32 v253, v100 offset:50752
	ds_write_b32 v253, v101 offset:51280
	ds_write_b32 v253, v102 offset:51808
	ds_write_b32 v253, v103 offset:52336
	ds_write_b32 v253, v104 offset:50816
	ds_write_b32 v253, v105 offset:51344
	ds_write_b32 v253, v106 offset:51872
	ds_write_b32 v253, v107 offset:52400
	ds_write_b32 v253, v108 offset:50880
	ds_write_b32 v253, v109 offset:51408
	ds_write_b32 v253, v110 offset:51936
	ds_write_b32 v253, v111 offset:52464
	ds_write_b32 v253, v112 offset:59136
	ds_write_b32 v253, v113 offset:59664
	ds_write_b32 v253, v114 offset:60192
	ds_write_b32 v253, v115 offset:60720
	ds_write_b32 v253, v116 offset:59200
	ds_write_b32 v253, v117 offset:59728
	ds_write_b32 v253, v118 offset:60256
	ds_write_b32 v253, v119 offset:60784
	ds_write_b32 v253, v120 offset:59264
	ds_write_b32 v253, v121 offset:59792
	ds_write_b32 v253, v122 offset:60320
	ds_write_b32 v253, v123 offset:60848
	ds_write_b32 v253, v124 offset:59328
	ds_write_b32 v253, v125 offset:59856
	ds_write_b32 v253, v126 offset:60384
	ds_write_b32 v253, v127 offset:60912
	s_branch .LBB0_1172

.LBB0_1248:
	s_or_b64 exec, exec, s[18:19]
	v_lshlrev_b64 v[18:19], 10, v[18:19]
	v_lshlrev_b64 v[28:29], 10, v[20:21]
	v_lshlrev_b64 v[20:21], 1, v[18:19]
	v_lshl_add_u64 v[18:19], s[6:7], 0, v[20:21]
	v_lshlrev_b32_e32 v32, 2, v22
	v_mov_b32_e32 v33, v17
	v_lshl_add_u64 v[18:19], v[18:19], 0, v[16:17]
	v_lshl_add_u64 v[40:41], s[4:5], 0, v[32:33]
	global_load_dwordx4 v[24:27], v[18:19], off
	v_lshlrev_b64 v[18:19], 1, v[28:29]
	v_add_co_u32_e32 v38, vcc, s23, v40
	v_lshl_add_u64 v[28:29], s[6:7], 0, v[18:19]
	v_lshl_add_u64 v[36:37], v[40:41], 0, s[14:15]
	v_addc_co_u32_e32 v39, vcc, 0, v41, vcc
	v_lshl_add_u64 v[56:57], v[28:29], 0, v[16:17]
	global_load_dwordx4 v[28:31], v32, s[4:5] offset:4
	global_load_dwordx3 v[44:46], v32, s[4:5] offset:20
	s_nop 0
	global_load_dwordx4 v[32:35], v[38:39], off offset:4
	global_load_dwordx3 v[48:50], v[36:37], off offset:16
	v_add_co_u32_e32 v36, vcc, s24, v40
	v_lshlrev_b32_e32 v58, 2, v22
	s_nop 0
	v_addc_co_u32_e32 v37, vcc, 0, v41, vcc
	v_lshl_add_u64 v[40:41], v[40:41], 0, s[16:17]
	v_mov_b32_e32 v59, v17
	global_load_dwordx3 v[52:54], v[40:41], off offset:16
	v_lshl_add_u64 v[40:41], s[4:5], 0, v[58:59]
	global_load_dwordx4 v[36:39], v[36:37], off offset:4
	v_add_co_u32_e32 v60, vcc, s24, v40
	s_waitcnt vmcnt(8)
	v_and_b32_e32 v59, 0xffff0000, v12
	v_addc_co_u32_e32 v61, vcc, 0, v41, vcc
	global_load_dword v62, v[60:61], off offset:-4096
	global_load_dwordx4 v[40:43], v[56:57], off
	global_load_dword v64, v58, s[4:5]
	global_load_dword v66, v[60:61], off
	v_lshlrev_b32_e32 v58, 16, v12
	s_waitcnt vmcnt(11)
	v_lshlrev_b32_e32 v60, 16, v8
	v_and_b32_e32 v61, 0xffff0000, v8
	v_lshlrev_b32_e32 v56, 16, v0
	v_and_b32_e32 v57, 0xffff0000, v0
	v_lshlrev_b32_e32 v68, 16, v4
	v_and_b32_e32 v69, 0xffff0000, v4
	v_lshlrev_b32_e32 v12, 16, v13
	v_and_b32_e32 v13, 0xffff0000, v13
	v_lshlrev_b32_e32 v0, 16, v1
	v_and_b32_e32 v1, 0xffff0000, v1
	v_lshlrev_b32_e32 v8, 16, v9
	v_and_b32_e32 v9, 0xffff0000, v9
	v_add_u32_e32 v213, s20, v213
	v_cmp_lt_i32_e32 vcc, s25, v213
	s_or_b64 s[12:13], vcc, s[12:13]
	v_add_u32_e32 v23, s21, v23
	s_waitcnt vmcnt(9)
	v_mov_b32_e32 v70, v29
	s_waitcnt vmcnt(7)
	v_mov_b32_e32 v63, v32
	v_mov_b32_e32 v65, v28
	v_mov_b32_e32 v29, v34
	v_mov_b32_e32 v34, v35
	s_waitcnt vmcnt(6)
	v_mov_b32_e32 v35, v48
	v_mov_b32_e32 v71, v30
	v_mov_b32_e32 v30, v31
	v_mov_b32_e32 v31, v44
	v_mov_b32_e32 v44, v45
	s_waitcnt vmcnt(5)
	v_mov_b32_e32 v51, v54
	v_mov_b32_e32 v45, v46
	s_waitcnt vmcnt(4)
	v_mov_b32_e32 v48, v37
	v_mov_b32_e32 v67, v36
	v_mov_b32_e32 v28, v33
	s_waitcnt vmcnt(3)
	v_pk_mul_f32 v[36:37], v[62:63], v[58:59]
	v_pk_mul_f32 v[54:55], v[62:63], v[60:61]
	s_waitcnt vmcnt(1)
	v_pk_fma_f32 v[36:37], v[64:65], v[56:57], v[36:37]
	v_pk_fma_f32 v[54:55], v[64:65], v[58:59], v[54:55]
	v_mov_b32_e32 v46, v49
	v_mov_b32_e32 v47, v50
	v_mov_b32_e32 v49, v38
	v_mov_b32_e32 v38, v39
	v_mov_b32_e32 v39, v52
	v_mov_b32_e32 v50, v53
	v_lshlrev_b32_e32 v32, 16, v24
	v_and_b32_e32 v33, 0xffff0000, v24
	v_lshlrev_b32_e32 v52, 16, v40
	v_and_b32_e32 v53, 0xffff0000, v40
	s_waitcnt vmcnt(0)
	v_pk_fma_f32 v[36:37], v[66:67], v[60:61], v[36:37]
	v_pk_fma_f32 v[54:55], v[66:67], v[68:69], v[54:55]
	v_pk_mul_f32 v[32:33], v[36:37], v[32:33]
	v_pk_mul_f32 v[36:37], v[54:55], v[52:53]
	v_pk_mul_f32 v[52:53], v[28:29], v[12:13]
	v_lshlrev_b32_e32 v24, 16, v25
	v_pk_fma_f32 v[0:1], v[70:71], v[0:1], v[52:53]
	v_and_b32_e32 v25, 0xffff0000, v25
	v_pk_fma_f32 v[0:1], v[48:49], v[8:9], v[0:1]
	v_pk_mul_f32 v[8:9], v[28:29], v[8:9]
	v_pk_mul_f32 v[24:25], v[0:1], v[24:25]
	v_lshlrev_b32_e32 v0, 16, v5
	v_and_b32_e32 v1, 0xffff0000, v5
	v_pk_fma_f32 v[8:9], v[70:71], v[12:13], v[8:9]
	v_lshlrev_b32_e32 v4, 16, v41
	v_and_b32_e32 v5, 0xffff0000, v41
	v_pk_fma_f32 v[0:1], v[48:49], v[0:1], v[8:9]
	v_lshlrev_b32_e32 v8, 16, v14
	v_and_b32_e32 v9, 0xffff0000, v14
	v_pk_mul_f32 v[4:5], v[0:1], v[4:5]
	v_lshlrev_b32_e32 v0, 16, v2
	v_and_b32_e32 v1, 0xffff0000, v2
	v_pk_mul_f32 v[40:41], v[34:35], v[8:9]
	v_lshlrev_b32_e32 v12, 16, v10
	v_and_b32_e32 v13, 0xffff0000, v10
	v_pk_fma_f32 v[0:1], v[30:31], v[0:1], v[40:41]
	v_lshlrev_b32_e32 v28, 16, v26
	v_and_b32_e32 v29, 0xffff0000, v26
	v_pk_fma_f32 v[0:1], v[38:39], v[12:13], v[0:1]
	v_pk_mul_f32 v[12:13], v[34:35], v[12:13]
	v_pk_mul_f32 v[28:29], v[0:1], v[28:29]
	v_lshlrev_b32_e32 v0, 16, v6
	v_and_b32_e32 v1, 0xffff0000, v6
	v_pk_fma_f32 v[8:9], v[30:31], v[8:9], v[12:13]
	v_lshlrev_b32_e32 v40, 16, v42
	v_and_b32_e32 v41, 0xffff0000, v42
	v_pk_fma_f32 v[0:1], v[38:39], v[0:1], v[8:9]
	v_lshlrev_b32_e32 v2, 16, v15
	v_pk_mul_f32 v[8:9], v[0:1], v[40:41]
	v_lshlrev_b32_e32 v0, 16, v3
	v_and_b32_e32 v1, 0xffff0000, v3
	v_and_b32_e32 v3, 0xffff0000, v15
	v_pk_mul_f32 v[14:15], v[46:47], v[2:3]
	v_lshlrev_b32_e32 v10, 16, v11
	v_and_b32_e32 v11, 0xffff0000, v11
	v_pk_fma_f32 v[0:1], v[44:45], v[0:1], v[14:15]
	v_lshlrev_b32_e32 v12, 16, v27
	v_and_b32_e32 v13, 0xffff0000, v27
	v_pk_fma_f32 v[0:1], v[50:51], v[10:11], v[0:1]
	v_pk_mul_f32 v[10:11], v[46:47], v[10:11]
	v_pk_mul_f32 v[12:13], v[0:1], v[12:13]
	v_lshlrev_b32_e32 v0, 16, v7
	v_and_b32_e32 v1, 0xffff0000, v7
	v_pk_fma_f32 v[2:3], v[44:45], v[2:3], v[10:11]
	v_lshlrev_b32_e32 v6, 16, v43
	v_and_b32_e32 v7, 0xffff0000, v43
	v_pk_fma_f32 v[0:1], v[50:51], v[0:1], v[2:3]
	v_lshl_add_u64 v[10:11], s[10:11], 0, v[20:21]
	v_pk_mul_f32 v[6:7], v[0:1], v[6:7]
	v_cvt_pk_bf16_f32 v0, v32, v33
	v_cvt_pk_bf16_f32 v1, v24, v25
	v_cvt_pk_bf16_f32 v2, v28, v29
	v_cvt_pk_bf16_f32 v3, v12, v13
	v_lshl_add_u64 v[10:11], v[10:11], 0, v[16:17]
	global_store_dwordx4 v[10:11], v[0:3], off sc1
	s_nop 1
	v_cvt_pk_bf16_f32 v1, v4, v5
	v_lshl_add_u64 v[4:5], s[10:11], 0, v[18:19]
	v_cvt_pk_bf16_f32 v0, v36, v37
	v_cvt_pk_bf16_f32 v2, v8, v9
	v_cvt_pk_bf16_f32 v3, v6, v7
	v_lshl_add_u64 v[4:5], v[4:5], 0, v[16:17]
	global_store_dwordx4 v[4:5], v[0:3], off sc1
	s_andn2_b64 exec, exec, s[12:13]
	s_cbranch_execz .LBB0_1255

.LBB0_1314:
	s_or_b64 exec, exec, s[16:17]
	s_waitcnt lgkmcnt(0)
	s_barrier
	ds_read_b128 v[0:3], v144
	ds_read_b128 v[4:7], v144 offset:16
	v_add_co_u32_e32 v12, vcc, s27, v136
	s_add_i32 s23, s23, s22
	s_waitcnt lgkmcnt(1)
	v_cvt_pk_bf16_f32 v0, v0, v1
	v_cvt_pk_bf16_f32 v1, v2, v3
	s_waitcnt lgkmcnt(0)
	v_cvt_pk_bf16_f32 v2, v4, v5
	v_cvt_pk_bf16_f32 v3, v6, v7
	ds_read_b128 v[4:7], v145
	ds_read_b128 v[8:11], v145 offset:16
	v_addc_co_u32_e32 v13, vcc, 0, v137, vcc
	global_store_dwordx4 v[12:13], v[0:3], off sc1
	v_add_co_u32_e32 v12, vcc, s27, v138
	s_waitcnt lgkmcnt(1)
	v_cvt_pk_bf16_f32 v0, v4, v5
	v_cvt_pk_bf16_f32 v1, v6, v7
	s_waitcnt lgkmcnt(0)
	v_cvt_pk_bf16_f32 v2, v8, v9
	v_cvt_pk_bf16_f32 v3, v10, v11
	ds_read_b128 v[4:7], v146
	ds_read_b128 v[8:11], v146 offset:16
	v_addc_co_u32_e32 v13, vcc, 0, v139, vcc
	global_store_dwordx4 v[12:13], v[0:3], off sc1
	v_add_co_u32_e32 v12, vcc, s27, v140
	s_waitcnt lgkmcnt(1)
	v_cvt_pk_bf16_f32 v0, v4, v5
	v_cvt_pk_bf16_f32 v1, v6, v7
	s_waitcnt lgkmcnt(0)
	v_cvt_pk_bf16_f32 v2, v8, v9
	v_cvt_pk_bf16_f32 v3, v10, v11
	ds_read_b128 v[4:7], v173
	ds_read_b128 v[8:11], v173 offset:16
	v_addc_co_u32_e32 v13, vcc, 0, v141, vcc
	global_store_dwordx4 v[12:13], v[0:3], off sc1
	v_add_co_u32_e32 v12, vcc, s27, v142
	s_waitcnt lgkmcnt(0)
	v_cvt_pk_bf16_f32 v3, v10, v11
	v_cvt_pk_bf16_f32 v2, v8, v9
	v_cvt_pk_bf16_f32 v1, v6, v7
	v_cvt_pk_bf16_f32 v0, v4, v5
	ds_read_b128 v[4:7], v144 offset:33792
	ds_read_b128 v[8:11], v144 offset:33808
	v_addc_co_u32_e32 v13, vcc, 0, v143, vcc
	global_store_dwordx4 v[12:13], v[0:3], off sc1
	v_add_co_u32_e32 v12, vcc, s28, v136
	s_waitcnt lgkmcnt(1)
	v_cvt_pk_bf16_f32 v0, v4, v5
	v_cvt_pk_bf16_f32 v1, v6, v7
	s_waitcnt lgkmcnt(0)
	v_cvt_pk_bf16_f32 v2, v8, v9
	v_cvt_pk_bf16_f32 v3, v10, v11
	ds_read_b128 v[4:7], v145 offset:33792
	ds_read_b128 v[8:11], v145 offset:33808
	v_addc_co_u32_e32 v13, vcc, 0, v137, vcc
	global_store_dwordx4 v[12:13], v[0:3], off sc1
	v_add_co_u32_e32 v12, vcc, s28, v138
	s_waitcnt lgkmcnt(1)
	v_cvt_pk_bf16_f32 v0, v4, v5
	v_cvt_pk_bf16_f32 v1, v6, v7
	s_waitcnt lgkmcnt(0)
	v_cvt_pk_bf16_f32 v2, v8, v9
	v_cvt_pk_bf16_f32 v3, v10, v11
	ds_read_b128 v[4:7], v146 offset:33792
	ds_read_b128 v[8:11], v146 offset:33808
	v_addc_co_u32_e32 v13, vcc, 0, v139, vcc
	global_store_dwordx4 v[12:13], v[0:3], off sc1
	v_add_co_u32_e32 v12, vcc, s28, v140
	s_waitcnt lgkmcnt(1)
	v_cvt_pk_bf16_f32 v0, v4, v5
	v_cvt_pk_bf16_f32 v1, v6, v7
	s_waitcnt lgkmcnt(0)
	v_cvt_pk_bf16_f32 v2, v8, v9
	v_cvt_pk_bf16_f32 v3, v10, v11
	ds_read_b128 v[4:7], v173 offset:33792
	ds_read_b128 v[8:11], v173 offset:33808
	v_addc_co_u32_e32 v13, vcc, 0, v141, vcc
	global_store_dwordx4 v[12:13], v[0:3], off sc1
	s_cmp_lt_u32 s23, 64
	s_waitcnt lgkmcnt(1)
	v_cvt_pk_bf16_f32 v0, v4, v5
	v_add_co_u32_e32 v4, vcc, 0x60000, v142
	s_waitcnt lgkmcnt(0)
	v_cvt_pk_bf16_f32 v3, v10, v11
	v_cvt_pk_bf16_f32 v2, v8, v9
	v_cvt_pk_bf16_f32 v1, v6, v7
	v_addc_co_u32_e32 v5, vcc, 0, v143, vcc
	global_store_dwordx4 v[4:5], v[0:3], off sc1
	s_barrier
	s_cbranch_scc0 .LBB0_1321

.LBB0_1319:
	s_or_b64 exec, exec, s[16:17]
	v_lshlrev_b32_e32 v136, 3, v130
	v_and_b32_e32 v146, 0x78, v136
	v_ashrrev_i32_e32 v208, 4, v130
	v_add_u32_e32 v137, 0x100, v130
	v_lshl_add_u32 v173, v146, 2, 0
	v_mul_lo_u32 v136, v208, s25
	v_ashrrev_i32_e32 v214, 4, v137
	v_add_u32_e32 v137, 0x200, v130
	v_add_u32_e32 v144, v173, v136
	v_ashrrev_i32_e32 v218, 4, v137
	s_waitcnt lgkmcnt(0)
	s_barrier
	ds_read_b128 v[136:139], v144
	ds_read_b128 v[140:143], v144 offset:16
	s_lshl_b32 s4, s30, 1
	v_mul_lo_u32 v145, v214, s25
	s_add_u32 s4, s20, s4
	v_ashrrev_i32_e32 v209, 31, v208
	v_add_u32_e32 v145, v173, v145
	s_addc_u32 s17, s21, 0
	s_lshl_b32 s16, s29, 8
	s_waitcnt lgkmcnt(1)
	v_cvt_pk_bf16_f32 v204, v136, v137
	v_lshlrev_b64 v[136:137], 11, v[208:209]
	ds_read_b128 v[208:211], v145 offset:16
	s_add_u32 s16, s4, s16
	v_cvt_pk_bf16_f32 v205, v138, v139
	s_waitcnt lgkmcnt(1)
	v_cvt_pk_bf16_f32 v206, v140, v141
	ds_read_b128 v[138:141], v145
	s_addc_u32 s17, s17, 0
	v_add_u32_e32 v130, 0x300, v130
	v_mul_lo_u32 v203, v218, s25
	v_ashrrev_i32_e32 v220, 4, v130
	v_lshl_add_u64 v[136:137], s[16:17], 0, v[136:137]
	v_lshlrev_b32_e32 v130, 1, v146
	v_cvt_pk_bf16_f32 v207, v142, v143
	v_lshl_add_u64 v[136:137], v[136:137], 0, v[130:131]
	v_add_u32_e32 v146, v173, v203
	global_store_dwordx4 v[136:137], v[204:207], off sc1
	v_ashrrev_i32_e32 v215, 31, v214
	v_mul_lo_u32 v213, v220, s25
	s_waitcnt lgkmcnt(1)
	v_cvt_pk_bf16_f32 v206, v208, v209
	v_cvt_pk_bf16_f32 v207, v210, v211
	ds_read_b128 v[208:211], v146 offset:16
	s_waitcnt lgkmcnt(1)
	v_cvt_pk_bf16_f32 v204, v138, v139
	v_lshlrev_b64 v[138:139], 11, v[214:215]
	v_cvt_pk_bf16_f32 v205, v140, v141
	ds_read_b128 v[140:143], v146
	v_lshl_add_u64 v[138:139], s[16:17], 0, v[138:139]
	v_lshl_add_u64 v[138:139], v[138:139], 0, v[130:131]
	global_store_dwordx4 v[138:139], v[204:207], off sc1
	v_add_u32_e32 v173, v173, v213
	v_ashrrev_i32_e32 v219, 31, v218
	s_waitcnt lgkmcnt(1)
	v_cvt_pk_bf16_f32 v206, v208, v209
	v_cvt_pk_bf16_f32 v207, v210, v211
	ds_read_b128 v[208:211], v173
	ds_read_b128 v[214:217], v173 offset:16
	s_waitcnt lgkmcnt(2)
	v_cvt_pk_bf16_f32 v204, v140, v141
	v_lshlrev_b64 v[140:141], 11, v[218:219]
	v_lshl_add_u64 v[140:141], s[16:17], 0, v[140:141]
	v_cvt_pk_bf16_f32 v205, v142, v143
	v_lshl_add_u64 v[140:141], v[140:141], 0, v[130:131]
	global_store_dwordx4 v[140:141], v[204:207], off sc1
	v_ashrrev_i32_e32 v221, 31, v220
	v_lshlrev_b64 v[142:143], 11, v[220:221]
	s_waitcnt lgkmcnt(0)
	v_cvt_pk_bf16_f32 v207, v216, v217
	v_cvt_pk_bf16_f32 v206, v214, v215
	v_cvt_pk_bf16_f32 v205, v210, v211
	v_cvt_pk_bf16_f32 v204, v208, v209
	ds_read_b128 v[208:211], v144 offset:33792
	ds_read_b128 v[214:217], v144 offset:33808
	v_lshl_add_u64 v[142:143], s[16:17], 0, v[142:143]
	v_lshl_add_u64 v[142:143], v[142:143], 0, v[130:131]
	global_store_dwordx4 v[142:143], v[204:207], off sc1
	v_add_co_u32_e32 v218, vcc, s26, v136
	s_waitcnt lgkmcnt(1)
	v_cvt_pk_bf16_f32 v204, v208, v209
	v_cvt_pk_bf16_f32 v205, v210, v211
	s_waitcnt lgkmcnt(0)
	v_cvt_pk_bf16_f32 v206, v214, v215
	v_cvt_pk_bf16_f32 v207, v216, v217
	ds_read_b128 v[208:211], v145 offset:33792
	ds_read_b128 v[214:217], v145 offset:33808
	v_addc_co_u32_e32 v219, vcc, 0, v137, vcc
	global_store_dwordx4 v[218:219], v[204:207], off sc1
	v_add_co_u32_e32 v218, vcc, s26, v138
	s_waitcnt lgkmcnt(1)
	v_cvt_pk_bf16_f32 v204, v208, v209
	v_cvt_pk_bf16_f32 v205, v210, v211
	s_waitcnt lgkmcnt(0)
	v_cvt_pk_bf16_f32 v206, v214, v215
	v_cvt_pk_bf16_f32 v207, v216, v217
	ds_read_b128 v[208:211], v146 offset:33792
	ds_read_b128 v[214:217], v146 offset:33808
	v_addc_co_u32_e32 v219, vcc, 0, v139, vcc
	global_store_dwordx4 v[218:219], v[204:207], off sc1
	v_add_co_u32_e32 v218, vcc, s26, v140
	s_waitcnt lgkmcnt(1)
	v_cvt_pk_bf16_f32 v204, v208, v209
	v_cvt_pk_bf16_f32 v205, v210, v211
	s_waitcnt lgkmcnt(0)
	v_cvt_pk_bf16_f32 v206, v214, v215
	v_cvt_pk_bf16_f32 v207, v216, v217
	ds_read_b128 v[208:211], v173 offset:33792
	ds_read_b128 v[214:217], v173 offset:33808
	v_addc_co_u32_e32 v219, vcc, 0, v141, vcc
	global_store_dwordx4 v[218:219], v[204:207], off sc1
	s_waitcnt lgkmcnt(1)
	s_nop 0
	v_cvt_pk_bf16_f32 v204, v208, v209
	v_add_co_u32_e32 v208, vcc, 0x20000, v142
	s_waitcnt lgkmcnt(0)
	v_cvt_pk_bf16_f32 v207, v216, v217
	v_cvt_pk_bf16_f32 v206, v214, v215
	v_cvt_pk_bf16_f32 v205, v210, v211
	v_addc_co_u32_e32 v209, vcc, 0, v143, vcc
	global_store_dwordx4 v[208:209], v[204:207], off sc1
	s_barrier
	s_and_saveexec_b64 s[16:17], s[8:9]
	s_cbranch_execz .LBB0_1314
	v_and_b32_e32 v254, 63, v180
	v_lshrrev_b32_e32 v253, 4, v254
	v_mul_u32_u24_e32 v253, 0x840, v253
	v_and_b32_e32 v254, 15, v254
	v_lshl_add_u32 v253, v254, 2, v253
	v_and_b32_e32 v254, 64, v180
	v_lshl_add_u32 v253, v254, 2, v253
	ds_write_b32 v253, v0 offset:0
	ds_write_b32 v253, v1 offset:528
	ds_write_b32 v253, v2 offset:1056
	ds_write_b32 v253, v3 offset:1584
	ds_write_b32 v253, v4 offset:64
	ds_write_b32 v253, v5 offset:592
	ds_write_b32 v253, v6 offset:1120
	ds_write_b32 v253, v7 offset:1648
	ds_write_b32 v253, v8 offset:128
	ds_write_b32 v253, v9 offset:656
	ds_write_b32 v253, v10 offset:1184
	ds_write_b32 v253, v11 offset:1712
	ds_write_b32 v253, v12 offset:192
	ds_write_b32 v253, v13 offset:720
	ds_write_b32 v253, v14 offset:1248
	ds_write_b32 v253, v15 offset:1776
	ds_write_b32 v253, v16 offset:8448
	ds_write_b32 v253, v17 offset:8976
	ds_write_b32 v253, v18 offset:9504
	ds_write_b32 v253, v19 offset:10032
	ds_write_b32 v253, v20 offset:8512
	ds_write_b32 v253, v21 offset:9040
	ds_write_b32 v253, v22 offset:9568
	ds_write_b32 v253, v23 offset:10096
	ds_write_b32 v253, v24 offset:8576
	ds_write_b32 v253, v25 offset:9104
	ds_write_b32 v253, v26 offset:9632
	ds_write_b32 v253, v27 offset:10160
	ds_write_b32 v253, v28 offset:8640
	ds_write_b32 v253, v29 offset:9168
	ds_write_b32 v253, v30 offset:9696
	ds_write_b32 v253, v31 offset:10224
	ds_write_b32 v253, v32 offset:16896
	ds_write_b32 v253, v33 offset:17424
	ds_write_b32 v253, v34 offset:17952
	ds_write_b32 v253, v35 offset:18480
	ds_write_b32 v253, v36 offset:16960
	ds_write_b32 v253, v37 offset:17488
	ds_write_b32 v253, v38 offset:18016
	ds_write_b32 v253, v39 offset:18544
	ds_write_b32 v253, v40 offset:17024
	ds_write_b32 v253, v41 offset:17552
	ds_write_b32 v253, v42 offset:18080
	ds_write_b32 v253, v43 offset:18608
	ds_write_b32 v253, v44 offset:17088
	ds_write_b32 v253, v45 offset:17616
	ds_write_b32 v253, v46 offset:18144
	ds_write_b32 v253, v47 offset:18672
	ds_write_b32 v253, v48 offset:25344
	ds_write_b32 v253, v49 offset:25872
	ds_write_b32 v253, v50 offset:26400
	ds_write_b32 v253, v51 offset:26928
	ds_write_b32 v253, v52 offset:25408
	ds_write_b32 v253, v53 offset:25936
	ds_write_b32 v253, v54 offset:26464
	ds_write_b32 v253, v55 offset:26992
	ds_write_b32 v253, v56 offset:25472
	ds_write_b32 v253, v57 offset:26000
	ds_write_b32 v253, v58 offset:26528
	ds_write_b32 v253, v59 offset:27056
	ds_write_b32 v253, v60 offset:25536
	ds_write_b32 v253, v61 offset:26064
	ds_write_b32 v253, v62 offset:26592
	ds_write_b32 v253, v63 offset:27120
	ds_write_b32 v253, v64 offset:33792
	ds_write_b32 v253, v65 offset:34320
	ds_write_b32 v253, v66 offset:34848
	ds_write_b32 v253, v67 offset:35376
	ds_write_b32 v253, v68 offset:33856
	ds_write_b32 v253, v69 offset:34384
	ds_write_b32 v253, v70 offset:34912
	ds_write_b32 v253, v71 offset:35440
	ds_write_b32 v253, v72 offset:33920
	ds_write_b32 v253, v73 offset:34448
	ds_write_b32 v253, v74 offset:34976
	ds_write_b32 v253, v75 offset:35504
	ds_write_b32 v253, v76 offset:33984
	ds_write_b32 v253, v77 offset:34512
	ds_write_b32 v253, v78 offset:35040
	ds_write_b32 v253, v79 offset:35568
	ds_write_b32 v253, v80 offset:42240
	ds_write_b32 v253, v81 offset:42768
	ds_write_b32 v253, v82 offset:43296
	ds_write_b32 v253, v83 offset:43824
	ds_write_b32 v253, v84 offset:42304
	ds_write_b32 v253, v85 offset:42832
	ds_write_b32 v253, v86 offset:43360
	ds_write_b32 v253, v87 offset:43888
	ds_write_b32 v253, v88 offset:42368
	ds_write_b32 v253, v89 offset:42896
	ds_write_b32 v253, v90 offset:43424
	ds_write_b32 v253, v91 offset:43952
	ds_write_b32 v253, v92 offset:42432
	ds_write_b32 v253, v93 offset:42960
	ds_write_b32 v253, v94 offset:43488
	ds_write_b32 v253, v95 offset:44016
	ds_write_b32 v253, v96 offset:50688
	ds_write_b32 v253, v97 offset:51216
	ds_write_b32 v253, v98 offset:51744
	ds_write_b32 v253, v99 offset:52272
	ds_write_b32 v253, v100 offset:50752
	ds_write_b32 v253, v101 offset:51280
	ds_write_b32 v253, v102 offset:51808
	ds_write_b32 v253, v103 offset:52336
	ds_write_b32 v253, v104 offset:50816
	ds_write_b32 v253, v105 offset:51344
	ds_write_b32 v253, v106 offset:51872
	ds_write_b32 v253, v107 offset:52400
	ds_write_b32 v253, v108 offset:50880
	ds_write_b32 v253, v109 offset:51408
	ds_write_b32 v253, v110 offset:51936
	ds_write_b32 v253, v111 offset:52464
	ds_write_b32 v253, v112 offset:59136
	ds_write_b32 v253, v113 offset:59664
	ds_write_b32 v253, v114 offset:60192
	ds_write_b32 v253, v115 offset:60720
	ds_write_b32 v253, v116 offset:59200
	ds_write_b32 v253, v117 offset:59728
	ds_write_b32 v253, v118 offset:60256
	ds_write_b32 v253, v119 offset:60784
	ds_write_b32 v253, v120 offset:59264
	ds_write_b32 v253, v121 offset:59792
	ds_write_b32 v253, v122 offset:60320
	ds_write_b32 v253, v123 offset:60848
	ds_write_b32 v253, v124 offset:59328
	ds_write_b32 v253, v125 offset:59856
	ds_write_b32 v253, v126 offset:60384
	ds_write_b32 v253, v127 offset:60912
	s_branch .LBB0_1314

.LBB0_1399:
	s_or_b64 exec, exec, s[26:27]
	v_lshlrev_b32_e32 v164, 16, v142
	v_and_b32_e32 v165, 0xffff0000, v142
	v_lshlrev_b32_e32 v162, 16, v144
	v_and_b32_e32 v163, 0xffff0000, v144
	v_pk_mul_f32 v[164:165], v[36:37], v[164:165]
	v_lshlrev_b32_e32 v142, 16, v143
	v_and_b32_e32 v143, 0xffff0000, v143
	v_pk_mul_f32 v[162:163], v[52:53], v[162:163]
	v_pk_fma_f32 v[104:105], v[104:105], s[24:25], v[164:165] op_sel_hi:[1,0,1]
	v_pk_mul_f32 v[142:143], v[38:39], v[142:143]
	v_pk_fma_f32 v[108:109], v[108:109], s[24:25], v[162:163] op_sel_hi:[1,0,1]
	v_and_b32_e32 v163, 0xffff0000, v145
	v_lshlrev_b32_e32 v162, 16, v145
	v_lshlrev_b32_e32 v127, 16, v138
	v_mov_b32_e32 v101, v64
	v_and_b32_e32 v96, 0xffff0000, v140
	v_pk_add_f32 v[164:165], v[104:105], v[104:105] op_sel:[0,1] op_sel_hi:[1,0]
	v_pk_fma_f32 v[106:107], v[106:107], s[24:25], v[142:143] op_sel_hi:[1,0,1]
	v_pk_mul_f32 v[144:145], v[54:55], v[162:163]
	v_pk_mul_f32 v[100:101], v[100:101], v[126:127]
	v_and_b32_e32 v127, 0xffff0000, v138
	v_mul_f32_e32 v163, v77, v96
	v_and_b32_e32 v96, 0xffff0000, v141
	v_pk_add_f32 v[142:143], v[106:107], v[164:165]
	v_lshlrev_b32_e32 v165, 16, v140
	v_lshlrev_b32_e32 v164, 16, v139
	v_and_b32_e32 v138, 0xffff0000, v139
	v_lshlrev_b32_e32 v139, 16, v141
	v_pk_mov_b32 v[140:141], v[66:67], v[78:79] op_sel:[1,0]
	v_pk_fma_f32 v[110:111], v[110:111], s[24:25], v[144:145] op_sel_hi:[1,0,1]
	v_pk_mul_f32 v[138:139], v[140:141], v[138:139]
	v_pk_add_f32 v[140:141], v[106:107], v[142:143] op_sel:[1,0] op_sel_hi:[0,1]
	v_pk_add_f32 v[144:145], v[108:109], v[108:109] op_sel:[0,1] op_sel_hi:[1,0]
	s_waitcnt lgkmcnt(0)
	v_mov_b32_e32 v98, v140
	v_pk_add_f32 v[144:145], v[110:111], v[144:145]
	v_pk_add_f32 v[140:141], v[140:141], s[20:21]
	v_pk_mul_f32 v[98:99], v[98:99], s[2:3]
	v_mov_b32_e32 v149, v65
	v_mul_f32_e32 v96, v79, v96
	v_mov_b32_e32 v141, v99
	v_pk_add_f32 v[98:99], v[110:111], v[144:145] op_sel:[1,0] op_sel_hi:[0,1]
	v_pk_mul_f32 v[148:149], v[148:149], v[126:127]
	v_mov_b32_e32 v99, v96
	v_pk_add_f32 v[98:99], v[140:141], v[98:99]
	v_mov_b32_e32 v140, v100
	v_mov_b32_e32 v141, v148
	v_mov_b32_e32 v148, v101
	v_mov_b32_e32 v166, v66
	v_mov_b32_e32 v167, v76
	v_pk_add_f32 v[100:101], v[140:141], v[148:149]
	v_mul_f32_e32 v97, 0x3fb504f3, v97
	v_pk_mul_f32 v[164:165], v[166:167], v[164:165]
	v_mov_b32_e32 v96, v100
	v_mov_b32_e32 v162, v101
	v_pk_fma_f32 v[102:103], v[102:103], s[24:25], v[164:165] op_sel_hi:[1,0,1]
	v_pk_add_f32 v[96:97], v[96:97], v[162:163]
	v_pk_fma_f32 v[138:139], v[146:147], s[24:25], v[138:139] op_sel_hi:[1,0,1]
	v_pk_add_f32 v[140:141], v[102:103], v[96:97]
	v_mov_b32_e32 v164, v102
	v_pk_add_f32 v[140:141], v[138:139], v[140:141]
	v_mov_b32_e32 v165, v138
	v_pk_add_f32 v[140:141], v[98:99], v[140:141]
	v_ashrrev_i32_e32 v115, 31, v114
	v_add_f32_e32 v96, v140, v141
	ds_bpermute_b32 v98, v150, v96
	s_waitcnt lgkmcnt(0)
	v_add_f32_e32 v96, v96, v98
	ds_bpermute_b32 v98, v151, v96
	s_waitcnt lgkmcnt(0)
	v_add_f32_e32 v96, v96, v98
	ds_bpermute_b32 v98, v152, v96
	s_waitcnt lgkmcnt(0)
	v_add_f32_e32 v96, v96, v98
	ds_bpermute_b32 v98, v153, v96
	s_waitcnt lgkmcnt(0)
	v_add_f32_e32 v96, v96, v98
	ds_bpermute_b32 v98, v154, v96
	s_waitcnt lgkmcnt(0)
	v_add_f32_e32 v96, v96, v98
	ds_bpermute_b32 v98, v155, v96
	s_waitcnt lgkmcnt(0)
	v_add_f32_e32 v96, v96, v98
	v_mul_f32_e32 v140, 0x3a800000, v96
	v_pk_add_f32 v[104:105], v[104:105], v[140:141] op_sel_hi:[1,0] neg_lo:[0,1] neg_hi:[0,1]
	v_pk_add_f32 v[106:107], v[106:107], v[140:141] op_sel_hi:[1,0] neg_lo:[0,1] neg_hi:[0,1]
	v_pk_mul_f32 v[142:143], v[104:105], v[104:105]
	v_pk_mul_f32 v[144:145], v[106:107], v[106:107]
	v_add_f32_e32 v102, v142, v143
	v_pk_add_f32 v[108:109], v[108:109], v[140:141] op_sel_hi:[1,0] neg_lo:[0,1] neg_hi:[0,1]
	v_add_f32_e32 v102, v144, v102
	v_pk_mul_f32 v[148:149], v[108:109], v[108:109]
	v_add_f32_e32 v102, v145, v102
	v_pk_add_f32 v[110:111], v[110:111], v[140:141] op_sel_hi:[1,0] neg_lo:[0,1] neg_hi:[0,1]
	v_add_f32_e32 v102, v148, v102
	v_pk_mul_f32 v[162:163], v[110:111], v[110:111]
	v_add_f32_e32 v102, v149, v102
	v_pk_add_f32 v[146:147], v[100:101], v[140:141] op_sel_hi:[1,0] neg_lo:[0,1] neg_hi:[0,1]
	v_add_f32_e32 v102, v162, v102
	v_pk_mul_f32 v[100:101], v[146:147], v[146:147]
	v_add_f32_e32 v102, v163, v102
	v_pk_add_f32 v[164:165], v[164:165], v[140:141] op_sel_hi:[1,0] neg_lo:[0,1] neg_hi:[0,1]
	v_add_f32_e32 v100, v100, v102
	v_pk_mul_f32 v[166:167], v[164:165], v[164:165]
	v_mov_b32_e32 v96, v103
	v_add_f32_e32 v100, v101, v100
	v_pk_add_f32 v[168:169], v[96:97], v[140:141] op_sel_hi:[1,0] neg_lo:[0,1] neg_hi:[0,1]
	v_add_f32_e32 v100, v166, v100
	v_pk_mul_f32 v[96:97], v[168:169], v[168:169]
	v_mov_b32_e32 v98, v139
	v_add_f32_e32 v100, v167, v100
	v_pk_add_f32 v[138:139], v[98:99], v[140:141] op_sel_hi:[1,0] neg_lo:[0,1] neg_hi:[0,1]
	v_add_f32_e32 v96, v96, v100
	v_pk_mul_f32 v[98:99], v[138:139], v[138:139]
	v_add_f32_e32 v96, v97, v96
	v_add_f32_e32 v96, v98, v96
	v_add_f32_e32 v96, v99, v96
	ds_bpermute_b32 v97, v150, v96
	v_pk_add_f32 v[102:103], v[34:35], 1.0 op_sel_hi:[1,0]
	v_pk_add_f32 v[144:145], v[40:41], 1.0 op_sel_hi:[1,0]
	v_pk_add_f32 v[148:149], v[42:43], 1.0 op_sel_hi:[1,0]
	v_pk_add_f32 v[162:163], v[56:57], 1.0 op_sel_hi:[1,0]
	s_waitcnt lgkmcnt(0)
	v_add_f32_e32 v96, v96, v97
	ds_bpermute_b32 v97, v151, v96
	v_pk_add_f32 v[166:167], v[58:59], 1.0 op_sel_hi:[1,0]
	s_waitcnt lgkmcnt(0)
	v_add_f32_e32 v96, v96, v97
	ds_bpermute_b32 v97, v152, v96
	s_waitcnt lgkmcnt(0)
	v_add_f32_e32 v96, v96, v97
	ds_bpermute_b32 v97, v153, v96
	s_waitcnt lgkmcnt(0)
	v_add_f32_e32 v98, v96, v97
	ds_bpermute_b32 v99, v154, v98
	v_lshlrev_b64 v[96:97], 12, v[114:115]
	v_lshl_add_u64 v[140:141], v[122:123], 0, v[96:97]
	v_pk_add_f32 v[96:97], v[32:33], 1.0 op_sel_hi:[1,0]
	s_waitcnt lgkmcnt(0)
	v_add_f32_e32 v100, v98, v99
	ds_bpermute_b32 v101, v155, v100
	v_lshlrev_b64 v[98:99], 11, v[114:115]
	v_lshl_add_u64 v[142:143], v[124:125], 0, v[98:99]
	s_waitcnt lgkmcnt(0)
	v_add_f32_e32 v98, v100, v101
	v_fmamk_f32 v98, v98, 0x3a800000, v159
	v_mul_f32_e32 v99, 0x4b800000, v98
	v_cmp_gt_f32_e32 vcc, s21, v98
	s_nop 1
	v_cndmask_b32_e32 v98, v98, v99, vcc
	v_rsq_f32_e32 v98, v98
	s_nop 0
	v_mul_f32_e32 v99, 0x45800000, v98
	v_cndmask_b32_e32 v170, v98, v99, vcc
	v_pk_mul_f32 v[98:99], v[104:105], v[170:171] op_sel_hi:[1,0]
	v_pk_mul_f32 v[100:101], v[106:107], v[170:171] op_sel_hi:[1,0]
	v_pk_fma_f32 v[98:99], v[28:29], v[98:99], v[24:25]
	v_pk_fma_f32 v[100:101], v[30:31], v[100:101], v[26:27]
	global_store_dwordx4 v[140:141], v[98:101], off sc1 nt
	s_nop 1
	v_pk_fma_f32 v[98:99], v[96:97], v[98:99], v[44:45]
	v_pk_fma_f32 v[96:97], v[102:103], v[100:101], v[46:47]
	v_cvt_pk_bf16_f32 v100, v98, v99
	v_cvt_pk_bf16_f32 v101, v96, v97
	global_store_dwordx2 v[142:143], v[100:101], off
	v_pk_mul_f32 v[100:101], v[108:109], v[170:171] op_sel_hi:[1,0]
	s_nop 0
	v_pk_fma_f32 v[102:103], v[20:21], v[100:101], v[12:13]
	v_pk_mul_f32 v[100:101], v[110:111], v[170:171] op_sel_hi:[1,0]
	v_pk_mul_f32 v[110:111], v[138:139], v[170:171] op_sel_hi:[1,0]
	v_pk_fma_f32 v[104:105], v[22:23], v[100:101], v[14:15]
	global_store_dwordx4 v[140:141], v[102:105], off offset:1024 sc1 nt
	v_pk_fma_f32 v[100:101], v[148:149], v[104:105], v[50:51]
	v_pk_fma_f32 v[110:111], v[6:7], v[110:111], v[2:3]
	v_pk_fma_f32 v[102:103], v[144:145], v[102:103], v[48:49]
	v_cvt_pk_bf16_f32 v105, v100, v101
	v_cvt_pk_bf16_f32 v104, v102, v103
	global_store_dwordx2 v[142:143], v[104:105], off offset:512
	v_pk_mul_f32 v[104:105], v[146:147], v[170:171] op_sel_hi:[1,0]
	v_pk_add_f32 v[138:139], v[68:69], 1.0 op_sel_hi:[1,0]
	v_pk_fma_f32 v[106:107], v[16:17], v[104:105], v[8:9]
	v_pk_mul_f32 v[104:105], v[164:165], v[170:171] op_sel_hi:[1,0]
	s_nop 0
	v_pk_fma_f32 v[108:109], v[18:19], v[104:105], v[10:11]
	global_store_dwordx4 v[140:141], v[106:109], off offset:2048 sc1 nt
	v_pk_fma_f32 v[104:105], v[166:167], v[108:109], v[62:63]
	s_nop 0
	v_pk_fma_f32 v[106:107], v[162:163], v[106:107], v[60:61]
	v_cvt_pk_bf16_f32 v109, v104, v105
	v_cvt_pk_bf16_f32 v108, v106, v107
	global_store_dwordx2 v[142:143], v[108:109], off offset:1024
	v_pk_mul_f32 v[108:109], v[168:169], v[170:171] op_sel_hi:[1,0]
	s_nop 0
	v_pk_fma_f32 v[108:109], v[4:5], v[108:109], v[0:1]
	global_store_dwordx4 v[140:141], v[108:111], off offset:3072 sc1 nt
	s_nop 1
	v_pk_fma_f32 v[108:109], v[138:139], v[108:109], v[72:73]
	v_pk_add_f32 v[138:139], v[70:71], 1.0 op_sel_hi:[1,0]
	v_cvt_pk_bf16_f32 v144, v108, v109
	v_pk_fma_f32 v[110:111], v[138:139], v[110:111], v[74:75]
	ds_read_b128 v[138:141], v156
	v_cvt_pk_bf16_f32 v145, v110, v111
	global_store_dwordx2 v[142:143], v[144:145], off offset:1536
	ds_read_b128 v[142:145], v156 offset:1024
	s_waitcnt lgkmcnt(1)
	v_mul_f32_e32 v115, v139, v99
	v_fmac_f32_e32 v115, v138, v98
	v_fmac_f32_e32 v115, v140, v96
	v_fmac_f32_e32 v115, v141, v97
	ds_read_b128 v[138:141], v156 offset:2048
	s_waitcnt lgkmcnt(1)
	v_mul_f32_e32 v127, v143, v103
	v_fmac_f32_e32 v127, v142, v102
	v_fmac_f32_e32 v127, v144, v100
	v_add_f32_e32 v115, 0, v115
	v_fmac_f32_e32 v127, v145, v101
	ds_read_b128 v[142:145], v156 offset:3072
	v_add_f32_e32 v115, v127, v115
	s_waitcnt lgkmcnt(1)
	v_mul_f32_e32 v127, v139, v107
	v_fmac_f32_e32 v127, v138, v106
	v_fmac_f32_e32 v127, v140, v104
	v_fmac_f32_e32 v127, v141, v105
	ds_read_b128 v[138:141], v156 offset:5120
	ds_read_b128 v[146:149], v156 offset:4096
	v_add_f32_e32 v115, v127, v115
	s_waitcnt lgkmcnt(2)
	v_mul_f32_e32 v127, v143, v109
	v_fmac_f32_e32 v127, v142, v108
	v_fmac_f32_e32 v127, v144, v110
	v_fmac_f32_e32 v127, v145, v111
	v_add_f32_e32 v115, v127, v115
	ds_read_b128 v[142:145], v156 offset:7168
	ds_read_b128 v[162:165], v156 offset:6144
	s_waitcnt lgkmcnt(2)
	v_mul_f32_e32 v127, v98, v146
	v_fmac_f32_e32 v127, v99, v147
	v_mul_f32_e32 v129, v102, v138
	v_fmac_f32_e32 v127, v96, v148
	v_fmac_f32_e32 v129, v103, v139
	v_fmac_f32_e32 v127, v97, v149
	v_fmac_f32_e32 v129, v100, v140
	v_add_f32_e32 v127, 0, v127
	v_fmac_f32_e32 v129, v101, v141
	v_add_f32_e32 v127, v129, v127
	s_waitcnt lgkmcnt(0)
	v_mul_f32_e32 v129, v106, v162
	v_fmac_f32_e32 v129, v107, v163
	v_fmac_f32_e32 v129, v104, v164
	v_fmac_f32_e32 v129, v105, v165
	ds_read_b128 v[138:141], v156 offset:9216
	ds_read_b128 v[146:149], v156 offset:8192
	v_add_f32_e32 v127, v129, v127
	v_mul_f32_e32 v129, v143, v109
	v_fmac_f32_e32 v129, v108, v142
	v_fmac_f32_e32 v129, v144, v110
	v_fmac_f32_e32 v129, v145, v111
	v_add_f32_e32 v127, v129, v127
	ds_read_b128 v[142:145], v156 offset:11264
	ds_read_b128 v[162:165], v156 offset:10240
	s_waitcnt lgkmcnt(2)
	v_mul_f32_e32 v129, v98, v146
	v_fmac_f32_e32 v129, v99, v147
	v_mul_f32_e32 v138, v102, v138
	v_fmac_f32_e32 v129, v96, v148
	v_fmac_f32_e32 v138, v103, v139
	v_fmac_f32_e32 v129, v97, v149
	v_fmac_f32_e32 v138, v100, v140
	v_add_f32_e32 v129, 0, v129
	v_fmac_f32_e32 v138, v101, v141
	v_add_f32_e32 v129, v138, v129
	s_waitcnt lgkmcnt(0)
	v_mul_f32_e32 v138, v106, v162
	v_fmac_f32_e32 v138, v107, v163
	v_fmac_f32_e32 v138, v104, v164
	v_mul_f32_e32 v142, v108, v142
	v_fmac_f32_e32 v138, v105, v165
	v_fmac_f32_e32 v142, v109, v143
	v_add_f32_e32 v129, v138, v129
	v_fmac_f32_e32 v142, v110, v144
	ds_read_b128 v[138:141], v156 offset:13312
	ds_read_b128 v[146:149], v156 offset:12288
	v_fmac_f32_e32 v142, v111, v145
	v_add_f32_e32 v129, v142, v129
	ds_read_b128 v[142:145], v156 offset:15360
	ds_read_b128 v[162:165], v156 offset:14336
	s_waitcnt lgkmcnt(3)
	v_mul_f32_e32 v138, v102, v138
	s_waitcnt lgkmcnt(2)
	v_mul_f32_e32 v146, v98, v146
	v_fmac_f32_e32 v146, v99, v147
	v_fmac_f32_e32 v146, v96, v148
	v_fmac_f32_e32 v138, v103, v139
	s_waitcnt lgkmcnt(0)
	v_mul_f32_e32 v139, v106, v162
	v_fmac_f32_e32 v146, v97, v149
	v_fmac_f32_e32 v138, v100, v140
	v_fmac_f32_e32 v139, v107, v163
	v_add_f32_e32 v146, 0, v146
	v_fmac_f32_e32 v138, v101, v141
	v_fmac_f32_e32 v139, v104, v164
	v_add_f32_e32 v138, v138, v146
	v_fmac_f32_e32 v139, v105, v165
	v_add_f32_e32 v138, v139, v138
	v_mul_f32_e32 v139, v108, v142
	v_fmac_f32_e32 v139, v109, v143
	ds_read_b128 v[140:143], v156 offset:16384
	v_fmac_f32_e32 v139, v110, v144
	v_fmac_f32_e32 v139, v111, v145
	ds_read_b128 v[144:147], v156 offset:17408
	v_add_f32_e32 v138, v139, v138
	s_waitcnt lgkmcnt(1)
	v_mul_f32_e32 v139, v99, v141
	v_fmac_f32_e32 v139, v98, v140
	v_fmac_f32_e32 v139, v96, v142
	s_waitcnt lgkmcnt(0)
	v_mul_f32_e32 v145, v103, v145
	v_fmac_f32_e32 v145, v102, v144
	v_fmac_f32_e32 v139, v97, v143
	ds_read_b128 v[140:143], v156 offset:18432
	v_fmac_f32_e32 v145, v100, v146
	v_add_f32_e32 v139, 0, v139
	v_fmac_f32_e32 v145, v101, v147
	v_add_f32_e32 v139, v139, v145
	ds_read_b128 v[144:147], v156 offset:19456
	s_waitcnt lgkmcnt(1)
	v_mul_f32_e32 v141, v107, v141
	v_fmac_f32_e32 v141, v106, v140
	v_fmac_f32_e32 v141, v104, v142
	v_fmac_f32_e32 v141, v105, v143
	s_waitcnt lgkmcnt(0)
	v_mul_f32_e32 v145, v109, v145
	v_fmac_f32_e32 v145, v108, v144
	v_add_f32_e32 v139, v139, v141
	v_fmac_f32_e32 v145, v110, v146
	ds_read_b128 v[140:143], v156 offset:21504
	ds_read_b128 v[162:165], v156 offset:20480
	v_fmac_f32_e32 v145, v111, v147
	v_add_f32_e32 v139, v139, v145
	ds_read_b128 v[144:147], v156 offset:23552
	ds_read_b128 v[166:169], v156 offset:22528
	s_waitcnt lgkmcnt(3)
	v_mul_f32_e32 v140, v102, v140
	s_waitcnt lgkmcnt(2)
	v_mul_f32_e32 v148, v98, v162
	v_fmac_f32_e32 v148, v99, v163
	v_fmac_f32_e32 v148, v96, v164
	v_fmac_f32_e32 v140, v103, v141
	s_waitcnt lgkmcnt(0)
	v_mul_f32_e32 v141, v106, v166
	v_fmac_f32_e32 v148, v97, v165
	v_fmac_f32_e32 v140, v100, v142
	v_fmac_f32_e32 v141, v107, v167
	v_add_f32_e32 v148, 0, v148
	v_fmac_f32_e32 v140, v101, v143
	v_fmac_f32_e32 v141, v104, v168
	v_mul_f32_e32 v144, v108, v144
	v_add_f32_e32 v140, v140, v148
	v_fmac_f32_e32 v141, v105, v169
	v_fmac_f32_e32 v144, v109, v145
	v_add_f32_e32 v148, v141, v140
	v_fmac_f32_e32 v144, v110, v146
	ds_read_b128 v[140:143], v156 offset:25600
	ds_read_b128 v[162:165], v156 offset:24576
	v_fmac_f32_e32 v144, v111, v147
	v_add_f32_e32 v148, v144, v148
	ds_read_b128 v[144:147], v156 offset:27648
	ds_read_b128 v[166:169], v156 offset:26624
	s_waitcnt lgkmcnt(3)
	v_mul_f32_e32 v140, v102, v140
	s_waitcnt lgkmcnt(2)
	v_mul_f32_e32 v149, v98, v162
	v_fmac_f32_e32 v149, v99, v163
	v_fmac_f32_e32 v149, v96, v164
	v_fmac_f32_e32 v140, v103, v141
	s_waitcnt lgkmcnt(0)
	v_mul_f32_e32 v141, v106, v166
	v_fmac_f32_e32 v149, v97, v165
	v_fmac_f32_e32 v140, v100, v142
	v_fmac_f32_e32 v141, v107, v167
	v_add_f32_e32 v149, 0, v149
	v_fmac_f32_e32 v140, v101, v143
	v_fmac_f32_e32 v141, v104, v168
	v_mul_f32_e32 v144, v108, v144
	v_add_f32_e32 v140, v140, v149
	v_fmac_f32_e32 v141, v105, v169
	v_fmac_f32_e32 v144, v109, v145
	v_add_f32_e32 v149, v141, v140
	v_fmac_f32_e32 v144, v110, v146
	ds_read_b128 v[140:143], v156 offset:29696
	ds_read_b128 v[162:165], v156 offset:28672
	v_fmac_f32_e32 v144, v111, v147
	v_add_f32_e32 v149, v144, v149
	ds_read_b128 v[144:147], v156 offset:31744
	ds_read_b128 v[166:169], v156 offset:30720
	s_waitcnt lgkmcnt(3)
	v_mul_f32_e32 v140, v102, v140
	s_waitcnt lgkmcnt(2)
	v_mul_f32_e32 v161, v98, v162
	v_fmac_f32_e32 v161, v99, v163
	v_fmac_f32_e32 v161, v96, v164
	v_fmac_f32_e32 v140, v103, v141
	s_waitcnt lgkmcnt(0)
	v_mul_f32_e32 v141, v106, v166
	v_fmac_f32_e32 v161, v97, v165
	v_fmac_f32_e32 v140, v100, v142
	v_fmac_f32_e32 v141, v107, v167
	v_add_f32_e32 v161, 0, v161
	v_fmac_f32_e32 v140, v101, v143
	v_fmac_f32_e32 v141, v104, v168
	v_mul_f32_e32 v144, v108, v144
	v_add_f32_e32 v140, v140, v161
	v_fmac_f32_e32 v141, v105, v169
	v_fmac_f32_e32 v144, v109, v145
	v_add_f32_e32 v161, v141, v140
	ds_read_b128 v[140:143], v156 offset:32768
	v_fmac_f32_e32 v144, v110, v146
	v_fmac_f32_e32 v144, v111, v147
	v_add_f32_e32 v161, v144, v161
	ds_read_b128 v[144:147], v156 offset:33792
	s_waitcnt lgkmcnt(1)
	v_mul_f32_e32 v141, v99, v141
	v_fmac_f32_e32 v141, v98, v140
	v_fmac_f32_e32 v141, v96, v142
	v_fmac_f32_e32 v141, v97, v143
	s_waitcnt lgkmcnt(0)
	v_mul_f32_e32 v145, v103, v145
	v_fmac_f32_e32 v145, v102, v144
	v_add_f32_e32 v162, 0, v141
	ds_read_b128 v[140:143], v156 offset:34816
	v_fmac_f32_e32 v145, v100, v146
	v_fmac_f32_e32 v145, v101, v147
	v_add_f32_e32 v162, v162, v145
	ds_read_b128 v[144:147], v156 offset:35840
	s_waitcnt lgkmcnt(1)
	v_mul_f32_e32 v141, v107, v141
	v_fmac_f32_e32 v141, v106, v140
	v_fmac_f32_e32 v141, v104, v142
	v_fmac_f32_e32 v141, v105, v143
	s_waitcnt lgkmcnt(0)
	v_mul_f32_e32 v145, v109, v145
	v_fmac_f32_e32 v145, v108, v144
	v_add_f32_e32 v166, v162, v141
	v_fmac_f32_e32 v145, v110, v146
	ds_read_b128 v[140:143], v156 offset:37888
	ds_read_b128 v[162:165], v156 offset:36864
	v_fmac_f32_e32 v145, v111, v147
	v_add_f32_e32 v170, v166, v145
	ds_read_b128 v[144:147], v156 offset:39936
	ds_read_b128 v[166:169], v156 offset:38912
	s_waitcnt lgkmcnt(3)
	v_mul_f32_e32 v140, v102, v140
	s_waitcnt lgkmcnt(2)
	v_mul_f32_e32 v162, v98, v162
	v_fmac_f32_e32 v162, v99, v163
	v_fmac_f32_e32 v162, v96, v164
	v_fmac_f32_e32 v140, v103, v141
	s_waitcnt lgkmcnt(0)
	v_mul_f32_e32 v141, v106, v166
	v_fmac_f32_e32 v162, v97, v165
	v_fmac_f32_e32 v140, v100, v142
	v_fmac_f32_e32 v141, v107, v167
	v_add_f32_e32 v162, 0, v162
	v_fmac_f32_e32 v140, v101, v143
	v_fmac_f32_e32 v141, v104, v168
	v_mul_f32_e32 v144, v108, v144
	v_add_f32_e32 v140, v140, v162
	v_fmac_f32_e32 v141, v105, v169
	v_fmac_f32_e32 v144, v109, v145
	v_add_f32_e32 v166, v141, v140
	v_fmac_f32_e32 v144, v110, v146
	ds_read_b128 v[140:143], v156 offset:41984
	ds_read_b128 v[162:165], v156 offset:40960
	v_fmac_f32_e32 v144, v111, v147
	v_add_f32_e32 v171, v144, v166
	ds_read_b128 v[144:147], v156 offset:44032
	ds_read_b128 v[166:169], v156 offset:43008
	s_waitcnt lgkmcnt(3)
	v_mul_f32_e32 v140, v102, v140
	s_waitcnt lgkmcnt(2)
	v_mul_f32_e32 v162, v98, v162
	v_fmac_f32_e32 v162, v99, v163
	v_fmac_f32_e32 v162, v96, v164
	v_fmac_f32_e32 v140, v103, v141
	s_waitcnt lgkmcnt(0)
	v_mul_f32_e32 v141, v106, v166
	v_fmac_f32_e32 v162, v97, v165
	v_fmac_f32_e32 v140, v100, v142
	v_fmac_f32_e32 v141, v107, v167
	v_add_f32_e32 v162, 0, v162
	v_fmac_f32_e32 v140, v101, v143
	v_fmac_f32_e32 v141, v104, v168
	v_mul_f32_e32 v144, v108, v144
	v_add_f32_e32 v140, v140, v162
	v_fmac_f32_e32 v141, v105, v169
	v_fmac_f32_e32 v144, v109, v145
	v_add_f32_e32 v166, v141, v140
	v_fmac_f32_e32 v144, v110, v146
	ds_read_b128 v[140:143], v156 offset:46080
	ds_read_b128 v[162:165], v156 offset:45056
	v_fmac_f32_e32 v144, v111, v147
	v_add_f32_e32 v172, v144, v166
	ds_read_b128 v[144:147], v156 offset:48128
	ds_read_b128 v[166:169], v156 offset:47104
	s_waitcnt lgkmcnt(3)
	v_mul_f32_e32 v140, v102, v140
	s_waitcnt lgkmcnt(2)
	v_mul_f32_e32 v162, v98, v162
	v_fmac_f32_e32 v162, v99, v163
	v_fmac_f32_e32 v162, v96, v164
	v_fmac_f32_e32 v140, v103, v141
	s_waitcnt lgkmcnt(0)
	v_mul_f32_e32 v141, v106, v166
	v_fmac_f32_e32 v162, v97, v165
	v_fmac_f32_e32 v140, v100, v142
	v_fmac_f32_e32 v141, v107, v167
	v_add_f32_e32 v162, 0, v162
	v_fmac_f32_e32 v140, v101, v143
	v_fmac_f32_e32 v141, v104, v168
	v_mul_f32_e32 v144, v108, v144
	v_add_f32_e32 v140, v140, v162
	v_fmac_f32_e32 v141, v105, v169
	v_fmac_f32_e32 v144, v109, v145
	v_add_f32_e32 v162, v141, v140
	ds_read_b128 v[140:143], v156 offset:49152
	v_fmac_f32_e32 v144, v110, v146
	v_fmac_f32_e32 v144, v111, v147
	v_add_f32_e32 v173, v144, v162
	ds_read_b128 v[144:147], v156 offset:50176
	s_waitcnt lgkmcnt(1)
	v_mul_f32_e32 v141, v99, v141
	v_fmac_f32_e32 v141, v98, v140
	v_fmac_f32_e32 v141, v96, v142
	v_fmac_f32_e32 v141, v97, v143
	s_waitcnt lgkmcnt(0)
	v_mul_f32_e32 v145, v103, v145
	v_fmac_f32_e32 v145, v102, v144
	v_add_f32_e32 v162, 0, v141
	ds_read_b128 v[140:143], v156 offset:51200
	v_fmac_f32_e32 v145, v100, v146
	v_fmac_f32_e32 v145, v101, v147
	v_add_f32_e32 v162, v162, v145
	ds_read_b128 v[144:147], v156 offset:52224
	s_waitcnt lgkmcnt(1)
	v_mul_f32_e32 v141, v107, v141
	v_fmac_f32_e32 v141, v106, v140
	v_fmac_f32_e32 v141, v104, v142
	v_fmac_f32_e32 v141, v105, v143
	s_waitcnt lgkmcnt(0)
	v_mul_f32_e32 v145, v109, v145
	v_fmac_f32_e32 v145, v108, v144
	v_add_f32_e32 v166, v162, v141
	v_fmac_f32_e32 v145, v110, v146
	ds_read_b128 v[140:143], v156 offset:54272
	ds_read_b128 v[162:165], v156 offset:53248
	v_fmac_f32_e32 v145, v111, v147
	v_add_f32_e32 v174, v166, v145
	ds_read_b128 v[144:147], v156 offset:56320
	ds_read_b128 v[166:169], v156 offset:55296
	s_waitcnt lgkmcnt(3)
	v_mul_f32_e32 v140, v102, v140
	s_waitcnt lgkmcnt(2)
	v_mul_f32_e32 v162, v98, v162
	v_fmac_f32_e32 v162, v99, v163
	v_fmac_f32_e32 v162, v96, v164
	v_fmac_f32_e32 v140, v103, v141
	s_waitcnt lgkmcnt(0)
	v_mul_f32_e32 v141, v106, v166
	v_fmac_f32_e32 v162, v97, v165
	v_fmac_f32_e32 v140, v100, v142
	v_fmac_f32_e32 v141, v107, v167
	v_add_f32_e32 v162, 0, v162
	v_fmac_f32_e32 v140, v101, v143
	v_fmac_f32_e32 v141, v104, v168
	v_mul_f32_e32 v144, v108, v144
	v_add_f32_e32 v140, v140, v162
	v_fmac_f32_e32 v141, v105, v169
	v_fmac_f32_e32 v144, v109, v145
	v_add_f32_e32 v166, v141, v140
	v_fmac_f32_e32 v144, v110, v146
	ds_read_b128 v[140:143], v156 offset:58368
	ds_read_b128 v[162:165], v156 offset:57344
	v_fmac_f32_e32 v144, v111, v147
	v_add_f32_e32 v175, v144, v166
	ds_read_b128 v[144:147], v156 offset:60416
	ds_read_b128 v[166:169], v156 offset:59392
	s_waitcnt lgkmcnt(3)
	v_mul_f32_e32 v140, v102, v140
	s_waitcnt lgkmcnt(2)
	v_mul_f32_e32 v162, v98, v162
	v_fmac_f32_e32 v162, v99, v163
	v_fmac_f32_e32 v162, v96, v164
	v_fmac_f32_e32 v140, v103, v141
	s_waitcnt lgkmcnt(0)
	v_mul_f32_e32 v141, v106, v166
	v_fmac_f32_e32 v162, v97, v165
	v_fmac_f32_e32 v140, v100, v142
	v_fmac_f32_e32 v141, v107, v167
	v_add_f32_e32 v162, 0, v162
	v_fmac_f32_e32 v140, v101, v143
	v_fmac_f32_e32 v141, v104, v168
	v_add_f32_e32 v140, v140, v162
	v_fmac_f32_e32 v141, v105, v169
	v_add_f32_e32 v166, v141, v140
	ds_read_b128 v[140:143], v156 offset:62464
	ds_read_b128 v[162:165], v156 offset:61440
	v_mul_f32_e32 v144, v108, v144
	v_fmac_f32_e32 v144, v109, v145
	v_fmac_f32_e32 v144, v110, v146
	v_fmac_f32_e32 v144, v111, v147
	s_waitcnt lgkmcnt(0)
	v_mul_f32_e32 v98, v98, v162
	v_fmac_f32_e32 v98, v99, v163
	v_add_f32_e32 v176, v144, v166
	ds_read_b128 v[144:147], v156 offset:64512
	ds_read_b128 v[166:169], v156 offset:63488
	v_fmac_f32_e32 v98, v96, v164
	v_fmac_f32_e32 v98, v97, v165
	v_mul_f32_e32 v97, v102, v140
	v_fmac_f32_e32 v97, v103, v141
	v_fmac_f32_e32 v97, v100, v142
	v_add_f32_e32 v96, 0, v98
	v_fmac_f32_e32 v97, v101, v143
	v_add_f32_e32 v96, v97, v96
	s_waitcnt lgkmcnt(0)
	v_mul_f32_e32 v97, v106, v166
	v_fmac_f32_e32 v97, v107, v167
	v_fmac_f32_e32 v97, v104, v168
	v_fmac_f32_e32 v97, v105, v169
	v_add_f32_e32 v96, v97, v96
	v_mul_f32_e32 v97, v108, v144
	v_fmac_f32_e32 v97, v109, v145
	v_fmac_f32_e32 v97, v110, v146
	v_fmac_f32_e32 v97, v111, v147
	v_add_f32_e32 v96, v97, v96
	v_cndmask_b32_e64 v97, v115, v170, s[6:7]
	ds_bpermute_b32 v97, v150, v97
	v_cndmask_b32_e64 v99, v127, v171, s[6:7]
	ds_bpermute_b32 v99, v150, v99
	v_cndmask_b32_e64 v100, v129, v172, s[6:7]
	ds_bpermute_b32 v100, v150, v100
	v_cndmask_b32_e64 v98, v170, v115, s[6:7]
	s_waitcnt lgkmcnt(2)
	v_add_f32_e32 v97, v98, v97
	v_cndmask_b32_e64 v98, v171, v127, s[6:7]
	s_waitcnt lgkmcnt(1)
	v_add_f32_e32 v98, v98, v99
	v_cndmask_b32_e64 v99, v172, v129, s[6:7]
	s_waitcnt lgkmcnt(0)
	v_add_f32_e32 v99, v99, v100
	v_cndmask_b32_e64 v100, v138, v173, s[6:7]
	ds_bpermute_b32 v100, v150, v100
	v_cndmask_b32_e64 v102, v139, v174, s[6:7]
	ds_bpermute_b32 v102, v150, v102
	v_cndmask_b32_e64 v103, v148, v175, s[6:7]
	ds_bpermute_b32 v103, v150, v103
	v_cndmask_b32_e64 v101, v173, v138, s[6:7]
	s_waitcnt lgkmcnt(2)
	v_add_f32_e32 v100, v101, v100
	v_cndmask_b32_e64 v101, v174, v139, s[6:7]
	s_waitcnt lgkmcnt(1)
	v_add_f32_e32 v101, v101, v102
	v_cndmask_b32_e64 v102, v175, v148, s[6:7]
	s_waitcnt lgkmcnt(0)
	v_add_f32_e32 v102, v102, v103
	v_cndmask_b32_e64 v103, v149, v176, s[6:7]
	v_cndmask_b32_e64 v105, v161, v96, s[6:7]
	ds_bpermute_b32 v103, v150, v103
	ds_bpermute_b32 v105, v150, v105
	v_cndmask_b32_e64 v104, v176, v149, s[6:7]
	v_cndmask_b32_e64 v96, v96, v161, s[6:7]
	v_cndmask_b32_e64 v106, v97, v101, s[8:9]
	s_waitcnt lgkmcnt(1)
	v_add_f32_e32 v103, v104, v103
	s_waitcnt lgkmcnt(0)
	v_add_f32_e32 v96, v96, v105
	v_cndmask_b32_e64 v97, v101, v97, s[8:9]
	v_cndmask_b32_e64 v101, v98, v102, s[8:9]
	v_cndmask_b32_e64 v98, v102, v98, s[8:9]
	v_cndmask_b32_e64 v102, v99, v103, s[8:9]
	v_cndmask_b32_e64 v104, v100, v96, s[8:9]
	ds_bpermute_b32 v106, v151, v106
	ds_bpermute_b32 v101, v151, v101
	ds_bpermute_b32 v102, v151, v102
	ds_bpermute_b32 v104, v151, v104
	v_cndmask_b32_e64 v99, v103, v99, s[8:9]
	v_cndmask_b32_e64 v96, v96, v100, s[8:9]
	s_waitcnt lgkmcnt(3)
	v_add_f32_e32 v97, v97, v106
	s_waitcnt lgkmcnt(2)
	v_add_f32_e32 v98, v98, v101
	s_waitcnt lgkmcnt(1)
	v_add_f32_e32 v99, v99, v102
	s_waitcnt lgkmcnt(0)
	v_add_f32_e32 v96, v96, v104
	v_cndmask_b32_e64 v100, v97, v99, s[10:11]
	v_cndmask_b32_e64 v101, v98, v96, s[10:11]
	ds_bpermute_b32 v100, v152, v100
	ds_bpermute_b32 v101, v152, v101
	v_cndmask_b32_e64 v97, v99, v97, s[10:11]
	v_cndmask_b32_e64 v96, v96, v98, s[10:11]
	s_waitcnt lgkmcnt(1)
	v_add_f32_e32 v97, v97, v100
	s_waitcnt lgkmcnt(0)
	v_add_f32_e32 v96, v96, v101
	v_cndmask_b32_e64 v98, v97, v96, s[12:13]
	ds_bpermute_b32 v98, v153, v98
	v_cndmask_b32_e64 v96, v96, v97, s[12:13]
	s_waitcnt lgkmcnt(0)
	v_add_f32_e32 v96, v96, v98
	ds_bpermute_b32 v97, v154, v96
	s_waitcnt lgkmcnt(0)
	v_add_f32_e32 v96, v96, v97
	ds_bpermute_b32 v97, v155, v96
	s_waitcnt lgkmcnt(0)
	v_add_f32_e32 v96, v96, v97
	ds_bpermute_b32 v97, v153, v96
	s_waitcnt lgkmcnt(0)
	v_max_f32_e32 v97, v97, v97
	v_max_f32_e32 v97, v96, v97
	ds_bpermute_b32 v98, v152, v97
	s_waitcnt lgkmcnt(0)
	v_max_f32_e32 v98, v98, v98
	v_max_f32_e32 v97, v97, v98
	ds_bpermute_b32 v98, v151, v97
	s_waitcnt lgkmcnt(0)
	v_max_f32_e32 v98, v98, v98
	v_max_f32_e32 v97, v97, v98
	ds_bpermute_b32 v98, v150, v97
	s_waitcnt lgkmcnt(0)
	v_max_f32_e32 v98, v98, v98
	v_max_f32_e32 v97, v97, v98
	v_sub_f32_e32 v96, v96, v97
	v_mul_f32_e32 v97, 0x3fb8aa3b, v96
	v_fma_f32 v98, v96, s25, -v97
	v_rndne_f32_e32 v99, v97
	v_fmac_f32_e32 v98, 0x32a5705f, v96
	v_sub_f32_e32 v97, v97, v99
	v_add_f32_e32 v97, v97, v98
	v_exp_f32_e32 v97, v97
	v_cvt_i32_f32_e32 v98, v99
	v_cmp_ngt_f32_e32 vcc, s28, v96
	v_ldexp_f32 v97, v97, v98
	s_nop 0
	v_cndmask_b32_e32 v97, 0, v97, vcc
	v_cmp_nlt_f32_e32 vcc, s29, v96
	s_nop 1
	v_cndmask_b32_e32 v96, v160, v97, vcc
	ds_bpermute_b32 v97, v153, v96
	s_waitcnt lgkmcnt(0)
	v_add_f32_e32 v97, v96, v97
	ds_bpermute_b32 v98, v152, v97
	s_waitcnt lgkmcnt(0)
	v_add_f32_e32 v97, v97, v98
	ds_bpermute_b32 v98, v151, v97
	s_waitcnt lgkmcnt(0)
	v_add_f32_e32 v97, v97, v98
	ds_bpermute_b32 v98, v150, v97
	s_and_saveexec_b64 s[26:27], s[14:15]
	s_cbranch_execz .LBB0_1394
	s_waitcnt lgkmcnt(0)
	v_add_f32_e32 v97, v97, v98
	v_div_scale_f32 v98, s[30:31], v97, v97, v96
	v_rcp_f32_e32 v99, v98
	v_and_b32_e32 v100, 0xfff, v114
	v_fma_f32 v101, -v98, v99, 1.0
	v_fmac_f32_e32 v99, v101, v99
	v_div_scale_f32 v101, vcc, v96, v97, v96
	v_mul_f32_e32 v102, v101, v99
	v_fma_f32 v103, -v98, v102, v101
	v_fmac_f32_e32 v102, v103, v99
	v_fma_f32 v98, -v98, v102, v101
	v_div_fmas_f32 v98, v98, v99, v102
	v_div_fixup_f32 v98, v98, v97, v96
	v_lshl_or_b32 v96, v112, 4, v157
	v_ashrrev_i32_e32 v97, 31, v96
	v_lshlrev_b64 v[96:97], 14, v[96:97]
	v_lshl_add_u64 v[96:97], s[18:19], 0, v[96:97]
	v_lshlrev_b32_e32 v112, 2, v100
	v_lshl_add_u64 v[96:97], v[96:97], 0, v[112:113]
	global_store_dword v[96:97], v98, off
	s_branch .LBB0_1394

.LBB0_1674:
	s_or_b64 exec, exec, s[14:15]
	v_lshlrev_b32_e32 v134, 3, v128
	v_and_b32_e32 v137, 56, v134
	v_ashrrev_i32_e32 v134, 3, v128
	v_mul_lo_u32 v135, v134, s22
	v_lshlrev_b32_e32 v138, 2, v137
	v_add3_u32 v139, 0, v135, v138
	s_waitcnt lgkmcnt(0)
	s_barrier
	ds_read_b128 v[194:197], v139
	v_add_u32_e32 v128, 0x100, v128
	s_lshl_b32 s10, s26, 19
	s_lshl_b32 s14, s27, 20
	v_ashrrev_i32_e32 v136, 3, v128
	s_waitcnt lgkmcnt(0)
	v_mul_f32_e32 v135, 0xbfb8aa3b, v194
	v_exp_f32_e32 v202, v135
	v_mul_f32_e32 v135, 0xbfb8aa3b, v195
	v_exp_f32_e32 v203, v135
	v_mul_lo_u32 v193, v136, s22
	v_add3_u32 v138, 0, v193, v138
	ds_read_b128 v[198:201], v139 offset:16
	v_pk_add_f32 v[206:207], v[202:203], 1.0 op_sel_hi:[1,0]
	ds_read_b128 v[202:205], v139 offset:256
	v_div_scale_f32 v128, s[26:27], v207, v207, v195
	v_rcp_f32_e32 v135, v128
	s_or_b32 s10, s14, s10
	s_add_u32 s10, s16, s10
	s_addc_u32 s15, s17, 0
	v_fma_f32 v193, -v128, v135, 1.0
	v_fmac_f32_e32 v135, v193, v135
	v_div_scale_f32 v193, vcc, v195, v207, v195
	v_mul_f32_e32 v208, v193, v135
	v_fma_f32 v209, -v128, v208, v193
	v_fmac_f32_e32 v208, v209, v135
	v_fma_f32 v128, -v128, v208, v193
	v_div_scale_f32 v193, s[26:27], v206, v206, v194
	v_rcp_f32_e32 v210, v193
	v_div_fmas_f32 v128, v128, v135, v208
	v_div_fixup_f32 v195, v128, v207, v195
	s_lshl_b32 s14, s28, 7
	v_fma_f32 v128, -v193, v210, 1.0
	v_fmac_f32_e32 v210, v128, v210
	v_div_scale_f32 v128, vcc, v194, v206, v194
	v_mul_f32_e32 v135, v128, v210
	v_fma_f32 v207, -v193, v135, v128
	v_fmac_f32_e32 v135, v207, v210
	v_mul_f32_e32 v207, 0xbfb8aa3b, v196
	v_exp_f32_e32 v208, v207
	v_mul_f32_e32 v207, 0xbfb8aa3b, v197
	v_exp_f32_e32 v209, v207
	v_fma_f32 v128, -v193, v135, v128
	v_div_fmas_f32 v128, v128, v210, v135
	v_div_fixup_f32 v194, v128, v206, v194
	v_pk_add_f32 v[210:211], v[208:209], 1.0 op_sel_hi:[1,0]
	s_waitcnt lgkmcnt(0)
	v_pk_mul_f32 v[194:195], v[194:195], v[202:203]
	v_div_scale_f32 v135, s[26:27], v211, v211, v197
	v_rcp_f32_e32 v193, v135
	ds_read_b128 v[206:209], v139 offset:272
	s_add_u32 s14, s10, s14
	s_addc_u32 s15, s15, 0
	v_fma_f32 v128, -v135, v193, 1.0
	v_fmac_f32_e32 v193, v128, v193
	v_div_scale_f32 v128, vcc, v197, v211, v197
	v_mul_f32_e32 v202, v128, v193
	v_fma_f32 v203, -v135, v202, v128
	v_fmac_f32_e32 v202, v203, v193
	v_fma_f32 v128, -v135, v202, v128
	v_div_scale_f32 v135, s[26:27], v210, v210, v196
	v_rcp_f32_e32 v213, v135
	v_div_fmas_f32 v128, v128, v193, v202
	v_mul_f32_e32 v202, 0xbfb8aa3b, v198
	v_mul_f32_e32 v203, 0xbfb8aa3b, v199
	v_div_fixup_f32 v197, v128, v211, v197
	v_fma_f32 v128, -v135, v213, 1.0
	v_exp_f32_e32 v202, v202
	v_exp_f32_e32 v203, v203
	v_fmac_f32_e32 v213, v128, v213
	v_div_scale_f32 v128, vcc, v196, v210, v196
	v_mul_f32_e32 v193, v128, v213
	v_fma_f32 v211, -v135, v193, v128
	v_fmac_f32_e32 v193, v211, v213
	v_pk_add_f32 v[202:203], v[202:203], 1.0 op_sel_hi:[1,0]
	v_fma_f32 v128, -v135, v193, v128
	v_div_scale_f32 v135, s[26:27], v203, v203, v199
	v_rcp_f32_e32 v211, v135
	v_div_fmas_f32 v128, v128, v213, v193
	v_div_fixup_f32 v196, v128, v210, v196
	v_pk_mul_f32 v[196:197], v[196:197], v[204:205]
	v_fma_f32 v128, -v135, v211, 1.0
	v_fmac_f32_e32 v211, v128, v211
	v_div_scale_f32 v128, vcc, v199, v203, v199
	v_mul_f32_e32 v193, v128, v211
	v_fma_f32 v204, -v135, v193, v128
	v_fmac_f32_e32 v193, v204, v211
	v_fma_f32 v128, -v135, v193, v128
	v_div_scale_f32 v135, s[26:27], v202, v202, v198
	v_rcp_f32_e32 v210, v135
	v_div_fmas_f32 v128, v128, v211, v193
	v_div_fixup_f32 v199, v128, v203, v199
	v_mul_f32_e32 v203, 0xbfb8aa3b, v200
	v_exp_f32_e32 v204, v203
	v_mul_f32_e32 v203, 0xbfb8aa3b, v201
	v_fma_f32 v128, -v135, v210, 1.0
	v_exp_f32_e32 v205, v203
	v_fmac_f32_e32 v210, v128, v210
	v_div_scale_f32 v128, vcc, v198, v202, v198
	v_mul_f32_e32 v193, v128, v210
	v_fma_f32 v203, -v135, v193, v128
	v_fmac_f32_e32 v193, v203, v210
	v_pk_add_f32 v[204:205], v[204:205], 1.0 op_sel_hi:[1,0]
	v_fma_f32 v128, -v135, v193, v128
	v_div_scale_f32 v135, s[26:27], v205, v205, v201
	v_rcp_f32_e32 v211, v135
	v_div_fmas_f32 v128, v128, v210, v193
	v_div_fixup_f32 v198, v128, v202, v198
	s_waitcnt lgkmcnt(0)
	v_pk_mul_f32 v[202:203], v[198:199], v[206:207]
	v_fma_f32 v128, -v135, v211, 1.0
	v_fmac_f32_e32 v211, v128, v211
	v_div_scale_f32 v128, vcc, v201, v205, v201
	v_mul_f32_e32 v193, v128, v211
	v_fma_f32 v198, -v135, v193, v128
	v_fmac_f32_e32 v193, v198, v211
	v_fma_f32 v128, -v135, v193, v128
	v_div_scale_f32 v135, s[26:27], v204, v204, v200
	v_rcp_f32_e32 v198, v135
	v_div_fmas_f32 v128, v128, v211, v193
	v_div_fixup_f32 v199, v128, v205, v201
	v_cvt_pk_bf16_f32 v194, v194, v195
	v_fma_f32 v128, -v135, v198, 1.0
	v_fmac_f32_e32 v198, v128, v198
	v_div_scale_f32 v128, vcc, v200, v204, v200
	v_mul_f32_e32 v193, v128, v198
	v_fma_f32 v201, -v135, v193, v128
	v_fmac_f32_e32 v193, v201, v198
	v_fma_f32 v128, -v135, v193, v128
	v_div_fmas_f32 v128, v128, v198, v193
	v_div_fixup_f32 v198, v128, v204, v200
	v_pk_mul_f32 v[204:205], v[198:199], v[208:209]
	ds_read_b128 v[198:201], v138
	v_ashrrev_i32_e32 v135, 31, v134
	v_lshlrev_b64 v[134:135], 11, v[134:135]
	v_lshl_add_u64 v[134:135], s[14:15], 0, v[134:135]
	v_cvt_pk_bf16_f32 v195, v196, v197
	s_waitcnt lgkmcnt(0)
	v_mul_f32_e32 v128, 0xbfb8aa3b, v198
	v_exp_f32_e32 v206, v128
	v_mul_f32_e32 v128, 0xbfb8aa3b, v199
	v_exp_f32_e32 v207, v128
	v_lshlrev_b32_e32 v128, 1, v137
	v_cvt_pk_bf16_f32 v196, v202, v203
	v_cvt_pk_bf16_f32 v197, v204, v205
	v_pk_add_f32 v[206:207], v[206:207], 1.0 op_sel_hi:[1,0]
	v_lshl_add_u64 v[134:135], v[134:135], 0, v[128:129]
	v_div_scale_f32 v137, s[26:27], v207, v207, v199
	v_rcp_f32_e32 v193, v137
	global_store_dwordx4 v[134:135], v[194:197], off sc1
	ds_read_b128 v[194:197], v138 offset:256
	ds_read_b128 v[202:205], v138 offset:16
	v_fma_f32 v208, -v137, v193, 1.0
	v_fmac_f32_e32 v193, v208, v193
	v_div_scale_f32 v208, vcc, v199, v207, v199
	v_mul_f32_e32 v209, v208, v193
	v_fma_f32 v210, -v137, v209, v208
	v_fmac_f32_e32 v209, v210, v193
	v_div_scale_f32 v210, s[26:27], v206, v206, v198
	v_rcp_f32_e32 v211, v210
	v_fma_f32 v137, -v137, v209, v208
	v_div_fmas_f32 v137, v137, v193, v209
	v_div_fixup_f32 v199, v137, v207, v199
	v_fma_f32 v137, -v210, v211, 1.0
	v_fmac_f32_e32 v211, v137, v211
	v_div_scale_f32 v137, vcc, v198, v206, v198
	v_mul_f32_e32 v193, v137, v211
	v_fma_f32 v207, -v210, v193, v137
	v_fmac_f32_e32 v193, v207, v211
	v_mul_f32_e32 v207, 0xbfb8aa3b, v200
	v_exp_f32_e32 v208, v207
	v_mul_f32_e32 v207, 0xbfb8aa3b, v201
	v_exp_f32_e32 v209, v207
	v_fma_f32 v137, -v210, v193, v137
	v_div_fmas_f32 v137, v137, v211, v193
	v_div_fixup_f32 v198, v137, v206, v198
	v_pk_add_f32 v[210:211], v[208:209], 1.0 op_sel_hi:[1,0]
	s_waitcnt lgkmcnt(1)
	v_pk_mul_f32 v[214:215], v[198:199], v[194:195]
	v_div_scale_f32 v193, s[26:27], v211, v211, v201
	v_rcp_f32_e32 v213, v193
	s_waitcnt lgkmcnt(0)
	v_mul_f32_e32 v198, 0xbfb8aa3b, v202
	v_mul_f32_e32 v199, 0xbfb8aa3b, v203
	v_exp_f32_e32 v198, v198
	v_fma_f32 v137, -v193, v213, 1.0
	v_fmac_f32_e32 v213, v137, v213
	v_div_scale_f32 v137, vcc, v201, v211, v201
	v_mul_f32_e32 v194, v137, v213
	v_fma_f32 v195, -v193, v194, v137
	v_fmac_f32_e32 v194, v195, v213
	v_fma_f32 v137, -v193, v194, v137
	v_div_scale_f32 v193, s[26:27], v210, v210, v200
	v_rcp_f32_e32 v216, v193
	v_div_fmas_f32 v137, v137, v213, v194
	v_div_fixup_f32 v195, v137, v211, v201
	v_exp_f32_e32 v199, v199
	v_fma_f32 v137, -v193, v216, 1.0
	v_fmac_f32_e32 v216, v137, v216
	v_div_scale_f32 v137, vcc, v200, v210, v200
	v_mul_f32_e32 v194, v137, v216
	v_fma_f32 v201, -v193, v194, v137
	v_fmac_f32_e32 v194, v201, v216
	v_pk_add_f32 v[198:199], v[198:199], 1.0 op_sel_hi:[1,0]
	v_fma_f32 v137, -v193, v194, v137
	v_div_scale_f32 v193, s[26:27], v199, v199, v203
	v_rcp_f32_e32 v201, v193
	v_div_fmas_f32 v137, v137, v216, v194
	v_div_fixup_f32 v194, v137, v210, v200
	v_pk_mul_f32 v[194:195], v[194:195], v[196:197]
	v_fma_f32 v137, -v193, v201, 1.0
	v_fmac_f32_e32 v201, v137, v201
	v_div_scale_f32 v137, vcc, v203, v199, v203
	v_mul_f32_e32 v196, v137, v201
	v_fma_f32 v197, -v193, v196, v137
	v_fmac_f32_e32 v196, v197, v201
	v_fma_f32 v137, -v193, v196, v137
	v_div_scale_f32 v193, s[26:27], v198, v198, v202
	v_rcp_f32_e32 v210, v193
	v_div_fmas_f32 v137, v137, v201, v196
	v_div_fixup_f32 v197, v137, v199, v203
	v_mul_f32_e32 v199, 0xbfb8aa3b, v204
	v_exp_f32_e32 v200, v199
	v_mul_f32_e32 v199, 0xbfb8aa3b, v205
	v_fma_f32 v137, -v193, v210, 1.0
	v_exp_f32_e32 v201, v199
	v_fmac_f32_e32 v210, v137, v210
	v_div_scale_f32 v137, vcc, v202, v198, v202
	v_mul_f32_e32 v196, v137, v210
	v_fma_f32 v199, -v193, v196, v137
	v_fmac_f32_e32 v196, v199, v210
	v_pk_add_f32 v[200:201], v[200:201], 1.0 op_sel_hi:[1,0]
	v_fma_f32 v137, -v193, v196, v137
	v_div_scale_f32 v193, s[26:27], v201, v201, v205
	v_rcp_f32_e32 v199, v193
	ds_read_b128 v[206:209], v138 offset:272
	v_div_fmas_f32 v137, v137, v210, v196
	v_div_fixup_f32 v196, v137, v198, v202
	v_fma_f32 v137, -v193, v199, 1.0
	v_fmac_f32_e32 v199, v137, v199
	v_div_scale_f32 v137, vcc, v205, v201, v205
	s_waitcnt lgkmcnt(0)
	v_pk_mul_f32 v[202:203], v[196:197], v[206:207]
	v_mul_f32_e32 v196, v137, v199
	v_fma_f32 v197, -v193, v196, v137
	v_fmac_f32_e32 v196, v197, v199
	v_fma_f32 v137, -v193, v196, v137
	v_div_scale_f32 v193, s[26:27], v200, v200, v204
	v_rcp_f32_e32 v198, v193
	v_div_fmas_f32 v137, v137, v199, v196
	v_div_fixup_f32 v197, v137, v201, v205
	v_cvt_pk_bf16_f32 v195, v194, v195
	v_fma_f32 v137, -v193, v198, 1.0
	v_fmac_f32_e32 v198, v137, v198
	v_div_scale_f32 v137, vcc, v204, v200, v204
	v_mul_f32_e32 v196, v137, v198
	v_fma_f32 v199, -v193, v196, v137
	v_fmac_f32_e32 v196, v199, v198
	v_fma_f32 v137, -v193, v196, v137
	v_div_fmas_f32 v137, v137, v198, v196
	v_div_fixup_f32 v196, v137, v200, v204
	ds_read_b128 v[198:201], v139 offset:33792
	v_pk_mul_f32 v[196:197], v[196:197], v[208:209]
	v_cvt_pk_bf16_f32 v194, v214, v215
	v_cvt_pk_bf16_f32 v197, v196, v197
	v_cvt_pk_bf16_f32 v196, v202, v203
	s_waitcnt lgkmcnt(0)
	v_mul_f32_e32 v137, 0xbfb8aa3b, v198
	v_exp_f32_e32 v206, v137
	v_mul_f32_e32 v137, 0xbfb8aa3b, v199
	v_exp_f32_e32 v207, v137
	v_ashrrev_i32_e32 v137, 31, v136
	v_lshlrev_b64 v[136:137], 11, v[136:137]
	v_lshl_add_u64 v[136:137], s[14:15], 0, v[136:137]
	v_pk_add_f32 v[206:207], v[206:207], 1.0 op_sel_hi:[1,0]
	v_lshl_add_u64 v[136:137], v[136:137], 0, v[128:129]
	v_div_scale_f32 v193, s[14:15], v207, v207, v199
	v_rcp_f32_e32 v208, v193
	global_store_dwordx4 v[136:137], v[194:197], off sc1
	ds_read_b128 v[194:197], v139 offset:34048
	ds_read_b128 v[202:205], v139 offset:33808
	v_fma_f32 v128, -v193, v208, 1.0
	v_fmac_f32_e32 v208, v128, v208
	v_div_scale_f32 v128, vcc, v199, v207, v199
	v_mul_f32_e32 v209, v128, v208
	v_fma_f32 v210, -v193, v209, v128
	v_fmac_f32_e32 v209, v210, v208
	v_fma_f32 v128, -v193, v209, v128
	v_div_scale_f32 v193, s[14:15], v206, v206, v198
	v_rcp_f32_e32 v210, v193
	v_div_fmas_f32 v128, v128, v208, v209
	v_div_fixup_f32 v199, v128, v207, v199
	v_mul_f32_e32 v209, 0xbfb8aa3b, v201
	v_fma_f32 v128, -v193, v210, 1.0
	v_fmac_f32_e32 v210, v128, v210
	v_div_scale_f32 v128, vcc, v198, v206, v198
	v_mul_f32_e32 v207, v128, v210
	v_fma_f32 v208, -v193, v207, v128
	v_fmac_f32_e32 v207, v208, v210
	v_mul_f32_e32 v208, 0xbfb8aa3b, v200
	v_exp_f32_e32 v208, v208
	v_exp_f32_e32 v209, v209
	v_fma_f32 v128, -v193, v207, v128
	v_div_fmas_f32 v128, v128, v210, v207
	v_div_fixup_f32 v198, v128, v206, v198
	v_pk_add_f32 v[210:211], v[208:209], 1.0 op_sel_hi:[1,0]
	s_waitcnt lgkmcnt(1)
	v_pk_mul_f32 v[198:199], v[198:199], v[194:195]
	v_div_scale_f32 v193, s[14:15], v211, v211, v201
	v_rcp_f32_e32 v213, v193
	ds_read_b128 v[206:209], v139 offset:34064
	v_cvt_pk_bf16_f32 v198, v198, v199
	v_fma_f32 v128, -v193, v213, 1.0
	v_fmac_f32_e32 v213, v128, v213
	v_div_scale_f32 v128, vcc, v201, v211, v201
	v_mul_f32_e32 v194, v128, v213
	v_fma_f32 v195, -v193, v194, v128
	v_fmac_f32_e32 v194, v195, v213
	v_fma_f32 v128, -v193, v194, v128
	v_div_scale_f32 v193, s[14:15], v210, v210, v200
	v_rcp_f32_e32 v216, v193
	v_div_fmas_f32 v128, v128, v213, v194
	v_div_fixup_f32 v195, v128, v211, v201
	s_waitcnt lgkmcnt(1)
	v_mul_f32_e32 v201, 0xbfb8aa3b, v202
	v_exp_f32_e32 v214, v201
	v_mul_f32_e32 v201, 0xbfb8aa3b, v203
	v_fma_f32 v128, -v193, v216, 1.0
	v_exp_f32_e32 v215, v201
	v_fmac_f32_e32 v216, v128, v216
	v_div_scale_f32 v128, vcc, v200, v210, v200
	v_mul_f32_e32 v194, v128, v216
	v_fma_f32 v201, -v193, v194, v128
	v_fmac_f32_e32 v194, v201, v216
	v_pk_add_f32 v[214:215], v[214:215], 1.0 op_sel_hi:[1,0]
	v_fma_f32 v128, -v193, v194, v128
	v_div_scale_f32 v193, s[14:15], v215, v215, v203
	v_rcp_f32_e32 v211, v193
	v_div_fmas_f32 v128, v128, v216, v194
	v_div_fixup_f32 v194, v128, v210, v200
	v_pk_mul_f32 v[200:201], v[194:195], v[196:197]
	v_fma_f32 v128, -v193, v211, 1.0
	v_fmac_f32_e32 v211, v128, v211
	v_div_scale_f32 v128, vcc, v203, v215, v203
	v_mul_f32_e32 v194, v128, v211
	v_fma_f32 v195, -v193, v194, v128
	v_fmac_f32_e32 v194, v195, v211
	v_fma_f32 v128, -v193, v194, v128
	v_div_scale_f32 v193, s[14:15], v214, v214, v202
	v_rcp_f32_e32 v213, v193
	v_div_fmas_f32 v128, v128, v211, v194
	v_mul_f32_e32 v196, 0xbfb8aa3b, v204
	v_mul_f32_e32 v197, 0xbfb8aa3b, v205
	v_div_fixup_f32 v195, v128, v215, v203
	v_fma_f32 v128, -v193, v213, 1.0
	v_exp_f32_e32 v196, v196
	v_exp_f32_e32 v197, v197
	v_fmac_f32_e32 v213, v128, v213
	v_div_scale_f32 v128, vcc, v202, v214, v202
	v_mul_f32_e32 v194, v128, v213
	v_fma_f32 v203, -v193, v194, v128
	v_fmac_f32_e32 v194, v203, v213
	v_pk_add_f32 v[210:211], v[196:197], 1.0 op_sel_hi:[1,0]
	v_fma_f32 v128, -v193, v194, v128
	v_div_scale_f32 v193, s[14:15], v211, v211, v205
	v_rcp_f32_e32 v196, v193
	v_div_fmas_f32 v128, v128, v213, v194
	v_div_fixup_f32 v194, v128, v214, v202
	s_waitcnt lgkmcnt(0)
	v_pk_mul_f32 v[206:207], v[194:195], v[206:207]
	v_fma_f32 v128, -v193, v196, 1.0
	v_fmac_f32_e32 v196, v128, v196
	v_div_scale_f32 v128, vcc, v205, v211, v205
	v_mul_f32_e32 v194, v128, v196
	v_fma_f32 v195, -v193, v194, v128
	v_fmac_f32_e32 v194, v195, v196
	v_fma_f32 v128, -v193, v194, v128
	v_div_scale_f32 v193, s[14:15], v210, v210, v204
	v_rcp_f32_e32 v195, v193
	v_div_fmas_f32 v128, v128, v196, v194
	v_div_fixup_f32 v203, v128, v211, v205
	v_cvt_pk_bf16_f32 v199, v200, v201
	v_fma_f32 v128, -v193, v195, 1.0
	v_fmac_f32_e32 v195, v128, v195
	v_div_scale_f32 v128, vcc, v204, v210, v204
	v_mul_f32_e32 v194, v128, v195
	v_fma_f32 v196, -v193, v194, v128
	v_fmac_f32_e32 v194, v196, v195
	v_fma_f32 v128, -v193, v194, v128
	v_div_fmas_f32 v128, v128, v195, v194
	ds_read_b128 v[194:197], v138 offset:33792
	v_div_fixup_f32 v202, v128, v210, v204
	v_cvt_pk_bf16_f32 v200, v206, v207
	v_pk_mul_f32 v[208:209], v[202:203], v[208:209]
	ds_read_b128 v[202:205], v138 offset:33808
	s_waitcnt lgkmcnt(1)
	v_mul_f32_e32 v128, 0xbfb8aa3b, v194
	v_exp_f32_e32 v210, v128
	v_mul_f32_e32 v128, 0xbfb8aa3b, v195
	v_exp_f32_e32 v211, v128
	v_cvt_pk_bf16_f32 v201, v208, v209
	v_add_co_u32_e32 v208, vcc, s23, v134
	v_pk_add_f32 v[206:207], v[210:211], 1.0 op_sel_hi:[1,0]
	s_nop 0
	v_addc_co_u32_e32 v209, vcc, 0, v135, vcc
	v_div_scale_f32 v128, s[14:15], v207, v207, v195
	v_rcp_f32_e32 v193, v128
	global_store_dwordx4 v[208:209], v[198:201], off sc1
	ds_read_b128 v[198:201], v138 offset:34048
	v_fma_f32 v208, -v128, v193, 1.0
	v_fmac_f32_e32 v193, v208, v193
	v_div_scale_f32 v208, vcc, v195, v207, v195
	v_mul_f32_e32 v209, v208, v193
	v_fma_f32 v210, -v128, v209, v208
	v_fmac_f32_e32 v209, v210, v193
	v_div_scale_f32 v210, s[14:15], v206, v206, v194
	v_rcp_f32_e32 v211, v210
	v_fma_f32 v128, -v128, v209, v208
	v_div_fmas_f32 v128, v128, v193, v209
	v_div_fixup_f32 v195, v128, v207, v195
	v_fma_f32 v128, -v210, v211, 1.0
	v_fmac_f32_e32 v211, v128, v211
	v_div_scale_f32 v128, vcc, v194, v206, v194
	v_mul_f32_e32 v193, v128, v211
	v_fma_f32 v207, -v210, v193, v128
	v_fmac_f32_e32 v193, v207, v211
	v_mul_f32_e32 v207, 0xbfb8aa3b, v196
	v_exp_f32_e32 v208, v207
	v_mul_f32_e32 v207, 0xbfb8aa3b, v197
	v_exp_f32_e32 v209, v207
	v_fma_f32 v128, -v210, v193, v128
	v_div_fmas_f32 v128, v128, v211, v193
	v_div_fixup_f32 v194, v128, v206, v194
	v_pk_add_f32 v[210:211], v[208:209], 1.0 op_sel_hi:[1,0]
	s_waitcnt lgkmcnt(0)
	v_pk_mul_f32 v[198:199], v[194:195], v[198:199]
	v_div_scale_f32 v193, s[14:15], v211, v211, v197
	v_rcp_f32_e32 v213, v193
	ds_read_b128 v[206:209], v138 offset:34064
	v_fma_f32 v128, -v193, v213, 1.0
	v_fmac_f32_e32 v213, v128, v213
	v_div_scale_f32 v128, vcc, v197, v211, v197
	v_mul_f32_e32 v194, v128, v213
	v_fma_f32 v195, -v193, v194, v128
	v_fmac_f32_e32 v194, v195, v213
	v_fma_f32 v128, -v193, v194, v128
	v_div_scale_f32 v193, s[14:15], v210, v210, v196
	v_rcp_f32_e32 v216, v193
	v_div_fmas_f32 v128, v128, v213, v194
	v_div_fixup_f32 v195, v128, v211, v197
	v_mul_f32_e32 v197, 0xbfb8aa3b, v202
	v_exp_f32_e32 v214, v197
	v_mul_f32_e32 v197, 0xbfb8aa3b, v203
	v_fma_f32 v128, -v193, v216, 1.0
	v_exp_f32_e32 v215, v197
	v_fmac_f32_e32 v216, v128, v216
	v_div_scale_f32 v128, vcc, v196, v210, v196
	v_mul_f32_e32 v194, v128, v216
	v_fma_f32 v197, -v193, v194, v128
	v_fmac_f32_e32 v194, v197, v216
	v_pk_add_f32 v[214:215], v[214:215], 1.0 op_sel_hi:[1,0]
	v_fma_f32 v128, -v193, v194, v128
	v_div_scale_f32 v193, s[14:15], v215, v215, v203
	v_rcp_f32_e32 v197, v193
	v_div_fmas_f32 v128, v128, v216, v194
	v_div_fixup_f32 v194, v128, v210, v196
	v_pk_mul_f32 v[194:195], v[194:195], v[200:201]
	v_fma_f32 v128, -v193, v197, 1.0
	v_fmac_f32_e32 v197, v128, v197
	v_div_scale_f32 v128, vcc, v203, v215, v203
	v_mul_f32_e32 v196, v128, v197
	v_fma_f32 v200, -v193, v196, v128
	v_fmac_f32_e32 v196, v200, v197
	v_fma_f32 v128, -v193, v196, v128
	v_div_scale_f32 v193, s[14:15], v214, v214, v202
	v_rcp_f32_e32 v210, v193
	v_div_fmas_f32 v128, v128, v197, v196
	v_mul_f32_e32 v200, 0xbfb8aa3b, v204
	v_mul_f32_e32 v201, 0xbfb8aa3b, v205
	v_div_fixup_f32 v197, v128, v215, v203
	v_fma_f32 v128, -v193, v210, 1.0
	v_exp_f32_e32 v200, v200
	v_exp_f32_e32 v201, v201
	v_fmac_f32_e32 v210, v128, v210
	v_div_scale_f32 v128, vcc, v202, v214, v202
	v_mul_f32_e32 v196, v128, v210
	v_fma_f32 v203, -v193, v196, v128
	v_fmac_f32_e32 v196, v203, v210
	v_pk_add_f32 v[200:201], v[200:201], 1.0 op_sel_hi:[1,0]
	v_fma_f32 v128, -v193, v196, v128
	v_div_scale_f32 v193, s[14:15], v201, v201, v205
	v_rcp_f32_e32 v211, v193
	v_div_fmas_f32 v128, v128, v210, v196
	v_div_fixup_f32 v196, v128, v214, v202
	s_waitcnt lgkmcnt(0)
	v_pk_mul_f32 v[202:203], v[196:197], v[206:207]
	v_fma_f32 v128, -v193, v211, 1.0
	v_fmac_f32_e32 v211, v128, v211
	v_div_scale_f32 v128, vcc, v205, v201, v205
	v_mul_f32_e32 v196, v128, v211
	v_fma_f32 v197, -v193, v196, v128
	v_fmac_f32_e32 v196, v197, v211
	v_fma_f32 v128, -v193, v196, v128
	v_div_scale_f32 v193, s[14:15], v200, v200, v204
	v_rcp_f32_e32 v206, v193
	v_div_fmas_f32 v128, v128, v211, v196
	v_div_fixup_f32 v197, v128, v201, v205
	v_cvt_pk_bf16_f32 v195, v194, v195
	v_fma_f32 v128, -v193, v206, 1.0
	v_fmac_f32_e32 v206, v128, v206
	v_div_scale_f32 v128, vcc, v204, v200, v204
	v_mul_f32_e32 v196, v128, v206
	v_fma_f32 v201, -v193, v196, v128
	v_fmac_f32_e32 v196, v201, v206
	v_fma_f32 v128, -v193, v196, v128
	v_div_fmas_f32 v128, v128, v206, v196
	v_div_fixup_f32 v196, v128, v200, v204
	v_pk_mul_f32 v[196:197], v[196:197], v[208:209]
	v_cvt_pk_bf16_f32 v194, v198, v199
	v_add_co_u32_e32 v198, vcc, 0x20000, v136
	v_cvt_pk_bf16_f32 v197, v196, v197
	v_cvt_pk_bf16_f32 v196, v202, v203
	v_addc_co_u32_e32 v199, vcc, 0, v137, vcc
	global_store_dwordx4 v[198:199], v[194:197], off sc1
	s_barrier
	s_and_saveexec_b64 s[14:15], s[8:9]
	s_cbranch_execz .LBB0_1669
	v_and_b32_e32 v254, 63, v180
	v_lshrrev_b32_e32 v253, 4, v254
	v_mul_u32_u24_e32 v253, 0x840, v253
	v_and_b32_e32 v254, 15, v254
	v_lshl_add_u32 v253, v254, 2, v253
	v_and_b32_e32 v254, 64, v180
	v_lshl_add_u32 v253, v254, 2, v253
	ds_write_b32 v253, v0 offset:0
	ds_write_b32 v253, v1 offset:528
	ds_write_b32 v253, v2 offset:1056
	ds_write_b32 v253, v3 offset:1584
	ds_write_b32 v253, v4 offset:64
	ds_write_b32 v253, v5 offset:592
	ds_write_b32 v253, v6 offset:1120
	ds_write_b32 v253, v7 offset:1648
	ds_write_b32 v253, v8 offset:128
	ds_write_b32 v253, v9 offset:656
	ds_write_b32 v253, v10 offset:1184
	ds_write_b32 v253, v11 offset:1712
	ds_write_b32 v253, v12 offset:192
	ds_write_b32 v253, v13 offset:720
	ds_write_b32 v253, v14 offset:1248
	ds_write_b32 v253, v15 offset:1776
	ds_write_b32 v253, v16 offset:8448
	ds_write_b32 v253, v17 offset:8976
	ds_write_b32 v253, v18 offset:9504
	ds_write_b32 v253, v19 offset:10032
	ds_write_b32 v253, v20 offset:8512
	ds_write_b32 v253, v21 offset:9040
	ds_write_b32 v253, v22 offset:9568
	ds_write_b32 v253, v23 offset:10096
	ds_write_b32 v253, v24 offset:8576
	ds_write_b32 v253, v25 offset:9104
	ds_write_b32 v253, v26 offset:9632
	ds_write_b32 v253, v27 offset:10160
	ds_write_b32 v253, v28 offset:8640
	ds_write_b32 v253, v29 offset:9168
	ds_write_b32 v253, v30 offset:9696
	ds_write_b32 v253, v31 offset:10224
	ds_write_b32 v253, v32 offset:16896
	ds_write_b32 v253, v33 offset:17424
	ds_write_b32 v253, v34 offset:17952
	ds_write_b32 v253, v35 offset:18480
	ds_write_b32 v253, v36 offset:16960
	ds_write_b32 v253, v37 offset:17488
	ds_write_b32 v253, v38 offset:18016
	ds_write_b32 v253, v39 offset:18544
	ds_write_b32 v253, v40 offset:17024
	ds_write_b32 v253, v41 offset:17552
	ds_write_b32 v253, v42 offset:18080
	ds_write_b32 v253, v43 offset:18608
	ds_write_b32 v253, v44 offset:17088
	ds_write_b32 v253, v45 offset:17616
	ds_write_b32 v253, v46 offset:18144
	ds_write_b32 v253, v47 offset:18672
	ds_write_b32 v253, v48 offset:25344
	ds_write_b32 v253, v49 offset:25872
	ds_write_b32 v253, v50 offset:26400
	ds_write_b32 v253, v51 offset:26928
	ds_write_b32 v253, v52 offset:25408
	ds_write_b32 v253, v53 offset:25936
	ds_write_b32 v253, v54 offset:26464
	ds_write_b32 v253, v55 offset:26992
	ds_write_b32 v253, v56 offset:25472
	ds_write_b32 v253, v57 offset:26000
	ds_write_b32 v253, v58 offset:26528
	ds_write_b32 v253, v59 offset:27056
	ds_write_b32 v253, v60 offset:25536
	ds_write_b32 v253, v61 offset:26064
	ds_write_b32 v253, v62 offset:26592
	ds_write_b32 v253, v63 offset:27120
	ds_write_b32 v253, v64 offset:33792
	ds_write_b32 v253, v65 offset:34320
	ds_write_b32 v253, v66 offset:34848
	ds_write_b32 v253, v67 offset:35376
	ds_write_b32 v253, v68 offset:33856
	ds_write_b32 v253, v69 offset:34384
	ds_write_b32 v253, v70 offset:34912
	ds_write_b32 v253, v71 offset:35440
	ds_write_b32 v253, v72 offset:33920
	ds_write_b32 v253, v73 offset:34448
	ds_write_b32 v253, v74 offset:34976
	ds_write_b32 v253, v75 offset:35504
	ds_write_b32 v253, v76 offset:33984
	ds_write_b32 v253, v77 offset:34512
	ds_write_b32 v253, v78 offset:35040
	ds_write_b32 v253, v79 offset:35568
	ds_write_b32 v253, v80 offset:42240
	ds_write_b32 v253, v81 offset:42768
	ds_write_b32 v253, v82 offset:43296
	ds_write_b32 v253, v83 offset:43824
	ds_write_b32 v253, v84 offset:42304
	ds_write_b32 v253, v85 offset:42832
	ds_write_b32 v253, v86 offset:43360
	ds_write_b32 v253, v87 offset:43888
	ds_write_b32 v253, v88 offset:42368
	ds_write_b32 v253, v89 offset:42896
	ds_write_b32 v253, v90 offset:43424
	ds_write_b32 v253, v91 offset:43952
	ds_write_b32 v253, v92 offset:42432
	ds_write_b32 v253, v93 offset:42960
	ds_write_b32 v253, v94 offset:43488
	ds_write_b32 v253, v95 offset:44016
	ds_write_b32 v253, v96 offset:50688
	ds_write_b32 v253, v97 offset:51216
	ds_write_b32 v253, v98 offset:51744
	ds_write_b32 v253, v99 offset:52272
	ds_write_b32 v253, v100 offset:50752
	ds_write_b32 v253, v101 offset:51280
	ds_write_b32 v253, v102 offset:51808
	ds_write_b32 v253, v103 offset:52336
	ds_write_b32 v253, v104 offset:50816
	ds_write_b32 v253, v105 offset:51344
	ds_write_b32 v253, v106 offset:51872
	ds_write_b32 v253, v107 offset:52400
	ds_write_b32 v253, v108 offset:50880
	ds_write_b32 v253, v109 offset:51408
	ds_write_b32 v253, v110 offset:51936
	ds_write_b32 v253, v111 offset:52464
	ds_write_b32 v253, v112 offset:59136
	ds_write_b32 v253, v113 offset:59664
	ds_write_b32 v253, v114 offset:60192
	ds_write_b32 v253, v115 offset:60720
	ds_write_b32 v253, v116 offset:59200
	ds_write_b32 v253, v117 offset:59728
	ds_write_b32 v253, v118 offset:60256
	ds_write_b32 v253, v119 offset:60784
	ds_write_b32 v253, v120 offset:59264
	ds_write_b32 v253, v121 offset:59792
	ds_write_b32 v253, v122 offset:60320
	ds_write_b32 v253, v123 offset:60848
	ds_write_b32 v253, v124 offset:59328
	ds_write_b32 v253, v125 offset:59856
	ds_write_b32 v253, v126 offset:60384
	ds_write_b32 v253, v127 offset:60912
	s_branch .LBB0_1669

.LBB0_1735:
	s_or_b64 exec, exec, s[20:21]
	s_waitcnt lgkmcnt(0)
	s_barrier
	global_load_dword v8, v[136:137], off offset:512
	ds_read_b128 v[0:3], v173
	ds_read_b128 v[4:7], v173 offset:16
	v_add_co_u32_e32 v10, vcc, s35, v140
	s_add_i32 s30, s30, s29
	s_nop 0
	v_addc_co_u32_e32 v11, vcc, 0, v141, vcc
	s_cmpk_lt_u32 s30, 0x80
	s_waitcnt vmcnt(0) lgkmcnt(1)
	v_pk_mul_f32 v[0:1], v[0:1], v[8:9] op_sel_hi:[1,0]
	v_pk_mul_f32 v[2:3], v[2:3], v[8:9] op_sel_hi:[1,0]
	s_waitcnt lgkmcnt(0)
	v_pk_mul_f32 v[4:5], v[4:5], v[8:9] op_sel_hi:[1,0]
	v_pk_mul_f32 v[6:7], v[6:7], v[8:9] op_sel_hi:[1,0]
	v_cvt_pk_bf16_f32 v0, v0, v1
	v_cvt_pk_bf16_f32 v1, v2, v3
	v_cvt_pk_bf16_f32 v2, v4, v5
	v_cvt_pk_bf16_f32 v3, v6, v7
	global_store_dwordx4 v[10:11], v[0:3], off sc1
	global_load_dword v8, v[138:139], off offset:512
	ds_read_b128 v[0:3], v179
	ds_read_b128 v[4:7], v179 offset:16
	v_add_co_u32_e32 v10, vcc, s35, v144
	s_waitcnt vmcnt(0) lgkmcnt(1)
	v_pk_mul_f32 v[0:1], v[0:1], v[8:9] op_sel_hi:[1,0]
	v_pk_mul_f32 v[2:3], v[2:3], v[8:9] op_sel_hi:[1,0]
	s_waitcnt lgkmcnt(0)
	v_pk_mul_f32 v[4:5], v[4:5], v[8:9] op_sel_hi:[1,0]
	v_pk_mul_f32 v[6:7], v[6:7], v[8:9] op_sel_hi:[1,0]
	v_addc_co_u32_e32 v11, vcc, 0, v145, vcc
	v_cvt_pk_bf16_f32 v0, v0, v1
	v_cvt_pk_bf16_f32 v1, v2, v3
	v_cvt_pk_bf16_f32 v2, v4, v5
	v_cvt_pk_bf16_f32 v3, v6, v7
	global_store_dwordx4 v[10:11], v[0:3], off sc1
	global_load_dword v8, v[142:143], off offset:512
	ds_read_b128 v[0:3], v209
	ds_read_b128 v[4:7], v209 offset:16
	v_add_co_u32_e32 v10, vcc, s35, v150
	s_waitcnt vmcnt(0) lgkmcnt(1)
	v_pk_mul_f32 v[0:1], v[0:1], v[8:9] op_sel_hi:[1,0]
	v_pk_mul_f32 v[2:3], v[2:3], v[8:9] op_sel_hi:[1,0]
	s_waitcnt lgkmcnt(0)
	v_pk_mul_f32 v[4:5], v[4:5], v[8:9] op_sel_hi:[1,0]
	v_pk_mul_f32 v[6:7], v[6:7], v[8:9] op_sel_hi:[1,0]
	v_addc_co_u32_e32 v11, vcc, 0, v151, vcc
	v_cvt_pk_bf16_f32 v0, v0, v1
	v_cvt_pk_bf16_f32 v1, v2, v3
	v_cvt_pk_bf16_f32 v2, v4, v5
	v_cvt_pk_bf16_f32 v3, v6, v7
	global_store_dwordx4 v[10:11], v[0:3], off sc1
	global_load_dword v8, v[148:149], off offset:512
	ds_read_b128 v[0:3], v182
	ds_read_b128 v[4:7], v182 offset:16
	v_add_co_u32_e32 v10, vcc, s35, v146
	s_waitcnt vmcnt(0) lgkmcnt(1)
	v_pk_mul_f32 v[12:13], v[0:1], v[8:9] op_sel_hi:[1,0]
	v_pk_mul_f32 v[0:1], v[2:3], v[8:9] op_sel_hi:[1,0]
	s_waitcnt lgkmcnt(0)
	v_pk_mul_f32 v[4:5], v[4:5], v[8:9] op_sel_hi:[1,0]
	v_pk_mul_f32 v[2:3], v[6:7], v[8:9] op_sel_hi:[1,0]
	v_addc_co_u32_e32 v11, vcc, 0, v147, vcc
	v_cvt_pk_bf16_f32 v3, v2, v3
	v_cvt_pk_bf16_f32 v2, v4, v5
	v_cvt_pk_bf16_f32 v1, v0, v1
	v_cvt_pk_bf16_f32 v0, v12, v13
	global_store_dwordx4 v[10:11], v[0:3], off sc1
	global_load_dword v8, v[136:137], off offset:768
	ds_read_b128 v[0:3], v173 offset:33792
	ds_read_b128 v[4:7], v173 offset:33808
	v_add_co_u32_e32 v10, vcc, s36, v140
	s_waitcnt vmcnt(0) lgkmcnt(1)
	v_pk_mul_f32 v[0:1], v[0:1], v[8:9] op_sel_hi:[1,0]
	v_pk_mul_f32 v[2:3], v[2:3], v[8:9] op_sel_hi:[1,0]
	s_waitcnt lgkmcnt(0)
	v_pk_mul_f32 v[4:5], v[4:5], v[8:9] op_sel_hi:[1,0]
	v_pk_mul_f32 v[6:7], v[6:7], v[8:9] op_sel_hi:[1,0]
	v_addc_co_u32_e32 v11, vcc, 0, v141, vcc
	v_cvt_pk_bf16_f32 v0, v0, v1
	v_cvt_pk_bf16_f32 v1, v2, v3
	v_cvt_pk_bf16_f32 v2, v4, v5
	v_cvt_pk_bf16_f32 v3, v6, v7
	global_store_dwordx4 v[10:11], v[0:3], off sc1
	global_load_dword v8, v[138:139], off offset:768
	ds_read_b128 v[0:3], v179 offset:33792
	ds_read_b128 v[4:7], v179 offset:33808
	v_add_co_u32_e32 v10, vcc, s36, v144
	s_waitcnt vmcnt(0) lgkmcnt(1)
	v_pk_mul_f32 v[0:1], v[0:1], v[8:9] op_sel_hi:[1,0]
	v_pk_mul_f32 v[2:3], v[2:3], v[8:9] op_sel_hi:[1,0]
	s_waitcnt lgkmcnt(0)
	v_pk_mul_f32 v[4:5], v[4:5], v[8:9] op_sel_hi:[1,0]
	v_pk_mul_f32 v[6:7], v[6:7], v[8:9] op_sel_hi:[1,0]
	v_addc_co_u32_e32 v11, vcc, 0, v145, vcc
	v_cvt_pk_bf16_f32 v0, v0, v1
	v_cvt_pk_bf16_f32 v1, v2, v3
	v_cvt_pk_bf16_f32 v2, v4, v5
	v_cvt_pk_bf16_f32 v3, v6, v7
	global_store_dwordx4 v[10:11], v[0:3], off sc1
	global_load_dword v8, v[142:143], off offset:768
	ds_read_b128 v[0:3], v209 offset:33792
	ds_read_b128 v[4:7], v209 offset:33808
	v_add_co_u32_e32 v10, vcc, s36, v150
	s_waitcnt vmcnt(0) lgkmcnt(1)
	v_pk_mul_f32 v[0:1], v[0:1], v[8:9] op_sel_hi:[1,0]
	v_pk_mul_f32 v[2:3], v[2:3], v[8:9] op_sel_hi:[1,0]
	s_waitcnt lgkmcnt(0)
	v_pk_mul_f32 v[4:5], v[4:5], v[8:9] op_sel_hi:[1,0]
	v_pk_mul_f32 v[6:7], v[6:7], v[8:9] op_sel_hi:[1,0]
	v_addc_co_u32_e32 v11, vcc, 0, v151, vcc
	v_cvt_pk_bf16_f32 v0, v0, v1
	v_cvt_pk_bf16_f32 v1, v2, v3
	v_cvt_pk_bf16_f32 v2, v4, v5
	v_cvt_pk_bf16_f32 v3, v6, v7
	global_store_dwordx4 v[10:11], v[0:3], off sc1
	global_load_dword v8, v[148:149], off offset:768
	ds_read_b128 v[0:3], v182 offset:33792
	ds_read_b128 v[4:7], v182 offset:33808
	v_add_co_u32_e32 v10, vcc, 0x60000, v146
	s_waitcnt vmcnt(0) lgkmcnt(1)
	v_pk_mul_f32 v[12:13], v[0:1], v[8:9] op_sel_hi:[1,0]
	v_pk_mul_f32 v[0:1], v[2:3], v[8:9] op_sel_hi:[1,0]
	s_waitcnt lgkmcnt(0)
	v_pk_mul_f32 v[4:5], v[4:5], v[8:9] op_sel_hi:[1,0]
	v_pk_mul_f32 v[2:3], v[6:7], v[8:9] op_sel_hi:[1,0]
	v_addc_co_u32_e32 v11, vcc, 0, v147, vcc
	v_cvt_pk_bf16_f32 v3, v2, v3
	v_cvt_pk_bf16_f32 v2, v4, v5
	v_cvt_pk_bf16_f32 v1, v0, v1
	v_cvt_pk_bf16_f32 v0, v12, v13
	global_store_dwordx4 v[10:11], v[0:3], off sc1
	s_barrier
	s_cbranch_scc0 .LBB0_1742

.LBB0_1740:
	s_or_b64 exec, exec, s[20:21]
	s_lshl_b32 s4, s37, 19
	s_lshl_b32 s20, s38, 20
	s_or_b32 s4, s20, s4
	s_add_u32 s4, s24, s4
	s_addc_u32 s21, s25, 0
	s_lshl_b32 s20, s23, 2
	s_add_u32 s23, s26, s20
	s_addc_u32 s37, s27, 0
	s_lshl_b32 s20, s39, 1
	s_add_u32 s20, s4, s20
	s_addc_u32 s21, s21, 0
	s_lshl_b32 s4, s22, 2
	s_add_u32 s22, s23, s4
	v_ashrrev_i32_e32 v138, 4, v146
	s_addc_u32 s23, s37, 0
	v_ashrrev_i32_e32 v139, 31, v138
	v_lshl_add_u64 v[136:137], v[138:139], 2, s[22:23]
	s_waitcnt lgkmcnt(0)
	s_barrier
	global_load_dword v182, v[136:137], off
	v_lshlrev_b32_e32 v130, 3, v146
	v_and_b32_e32 v130, 0x78, v130
	v_mul_lo_u32 v141, v138, s31
	v_lshl_add_u32 v213, v130, 2, 0
	v_add_u32_e32 v173, v213, v141
	ds_read_b128 v[142:145], v173
	ds_read_b128 v[148:151], v173 offset:16
	v_add_u32_e32 v140, 0x100, v146
	v_lshlrev_b64 v[138:139], 11, v[138:139]
	v_ashrrev_i32_e32 v210, 4, v140
	v_lshlrev_b32_e32 v130, 1, v130
	v_lshl_add_u64 v[138:139], s[20:21], 0, v[138:139]
	v_ashrrev_i32_e32 v211, 31, v210
	v_lshl_add_u64 v[140:141], v[138:139], 0, v[130:131]
	v_lshl_add_u64 v[138:139], v[210:211], 2, s[22:23]
	s_waitcnt vmcnt(0) lgkmcnt(1)
	v_pk_mul_f32 v[142:143], v[142:143], v[182:183] op_sel_hi:[1,0]
	v_pk_mul_f32 v[144:145], v[144:145], v[182:183] op_sel_hi:[1,0]
	s_waitcnt lgkmcnt(0)
	v_pk_mul_f32 v[148:149], v[148:149], v[182:183] op_sel_hi:[1,0]
	v_pk_mul_f32 v[150:151], v[150:151], v[182:183] op_sel_hi:[1,0]
	v_cvt_pk_bf16_f32 v142, v142, v143
	v_cvt_pk_bf16_f32 v143, v144, v145
	v_cvt_pk_bf16_f32 v144, v148, v149
	v_cvt_pk_bf16_f32 v145, v150, v151
	global_store_dwordx4 v[140:141], v[142:145], off sc1
	global_load_dword v182, v[138:139], off
	s_nop 0
	v_add_u32_e32 v142, 0x200, v146
	v_ashrrev_i32_e32 v218, 4, v142
	v_mul_lo_u32 v142, v210, s31
	v_add_u32_e32 v179, v213, v142
	ds_read_b128 v[148:151], v179
	ds_read_b128 v[214:217], v179 offset:16
	v_lshlrev_b64 v[142:143], 11, v[210:211]
	v_lshl_add_u64 v[142:143], s[20:21], 0, v[142:143]
	v_ashrrev_i32_e32 v219, 31, v218
	v_lshl_add_u64 v[144:145], v[142:143], 0, v[130:131]
	v_lshl_add_u64 v[142:143], v[218:219], 2, s[22:23]
	v_add_u32_e32 v146, 0x300, v146
	v_ashrrev_i32_e32 v146, 4, v146
	v_ashrrev_i32_e32 v147, 31, v146
	s_waitcnt vmcnt(0) lgkmcnt(1)
	v_pk_mul_f32 v[148:149], v[148:149], v[182:183] op_sel_hi:[1,0]
	v_pk_mul_f32 v[150:151], v[150:151], v[182:183] op_sel_hi:[1,0]
	s_waitcnt lgkmcnt(0)
	v_pk_mul_f32 v[210:211], v[214:215], v[182:183] op_sel_hi:[1,0]
	v_pk_mul_f32 v[214:215], v[216:217], v[182:183] op_sel_hi:[1,0]
	v_cvt_pk_bf16_f32 v148, v148, v149
	v_cvt_pk_bf16_f32 v149, v150, v151
	v_cvt_pk_bf16_f32 v150, v210, v211
	v_cvt_pk_bf16_f32 v151, v214, v215
	global_store_dwordx4 v[144:145], v[148:151], off sc1
	global_load_dword v182, v[142:143], off
	s_nop 0
	v_mul_lo_u32 v148, v218, s31
	v_add_u32_e32 v209, v213, v148
	v_lshlrev_b64 v[148:149], 11, v[218:219]
	ds_read_b128 v[214:217], v209
	ds_read_b128 v[218:221], v209 offset:16
	v_lshl_add_u64 v[148:149], s[20:21], 0, v[148:149]
	v_lshl_add_u64 v[150:151], v[148:149], 0, v[130:131]
	v_lshl_add_u64 v[148:149], v[146:147], 2, s[22:23]
	s_waitcnt vmcnt(0) lgkmcnt(1)
	v_pk_mul_f32 v[210:211], v[214:215], v[182:183] op_sel_hi:[1,0]
	v_pk_mul_f32 v[216:217], v[216:217], v[182:183] op_sel_hi:[1,0]
	s_waitcnt lgkmcnt(0)
	v_pk_mul_f32 v[218:219], v[218:219], v[182:183] op_sel_hi:[1,0]
	v_pk_mul_f32 v[220:221], v[220:221], v[182:183] op_sel_hi:[1,0]
	v_cvt_pk_bf16_f32 v214, v210, v211
	v_cvt_pk_bf16_f32 v215, v216, v217
	v_cvt_pk_bf16_f32 v216, v218, v219
	v_cvt_pk_bf16_f32 v217, v220, v221
	global_store_dwordx4 v[150:151], v[214:217], off sc1
	global_load_dword v210, v[148:149], off
	v_mul_lo_u32 v182, v146, s31
	v_add_u32_e32 v182, v213, v182
	ds_read_b128 v[214:217], v182
	ds_read_b128 v[218:221], v182 offset:16
	v_lshlrev_b64 v[146:147], 11, v[146:147]
	v_lshl_add_u64 v[146:147], s[20:21], 0, v[146:147]
	v_lshl_add_u64 v[146:147], v[146:147], 0, v[130:131]
	s_waitcnt vmcnt(0) lgkmcnt(1)
	v_pk_mul_f32 v[222:223], v[214:215], v[210:211] op_sel_hi:[1,0]
	v_pk_mul_f32 v[214:215], v[216:217], v[210:211] op_sel_hi:[1,0]
	s_waitcnt lgkmcnt(0)
	v_pk_mul_f32 v[218:219], v[218:219], v[210:211] op_sel_hi:[1,0]
	v_pk_mul_f32 v[210:211], v[220:221], v[210:211] op_sel_hi:[1,0]
	v_cvt_pk_bf16_f32 v216, v218, v219
	v_cvt_pk_bf16_f32 v217, v210, v211
	v_cvt_pk_bf16_f32 v215, v214, v215
	v_cvt_pk_bf16_f32 v214, v222, v223
	global_store_dwordx4 v[146:147], v[214:217], off sc1
	global_load_dword v130, v[136:137], off offset:256
	ds_read_b128 v[214:217], v173 offset:33792
	ds_read_b128 v[218:221], v173 offset:33808
	v_add_co_u32_e32 v210, vcc, s34, v140
	s_waitcnt vmcnt(0) lgkmcnt(1)
	v_pk_mul_f32 v[214:215], v[214:215], v[130:131] op_sel_hi:[1,0]
	v_pk_mul_f32 v[216:217], v[216:217], v[130:131] op_sel_hi:[1,0]
	s_waitcnt lgkmcnt(0)
	v_pk_mul_f32 v[218:219], v[218:219], v[130:131] op_sel_hi:[1,0]
	v_pk_mul_f32 v[220:221], v[220:221], v[130:131] op_sel_hi:[1,0]
	v_addc_co_u32_e32 v211, vcc, 0, v141, vcc
	v_cvt_pk_bf16_f32 v214, v214, v215
	v_cvt_pk_bf16_f32 v215, v216, v217
	v_cvt_pk_bf16_f32 v216, v218, v219
	v_cvt_pk_bf16_f32 v217, v220, v221
	global_store_dwordx4 v[210:211], v[214:217], off sc1
	global_load_dword v130, v[138:139], off offset:256
	ds_read_b128 v[214:217], v179 offset:33792
	ds_read_b128 v[218:221], v179 offset:33808
	v_add_co_u32_e32 v210, vcc, s34, v144
	s_waitcnt vmcnt(0) lgkmcnt(1)
	v_pk_mul_f32 v[214:215], v[214:215], v[130:131] op_sel_hi:[1,0]
	v_pk_mul_f32 v[216:217], v[216:217], v[130:131] op_sel_hi:[1,0]
	s_waitcnt lgkmcnt(0)
	v_pk_mul_f32 v[218:219], v[218:219], v[130:131] op_sel_hi:[1,0]
	v_pk_mul_f32 v[220:221], v[220:221], v[130:131] op_sel_hi:[1,0]
	v_addc_co_u32_e32 v211, vcc, 0, v145, vcc
	v_cvt_pk_bf16_f32 v214, v214, v215
	v_cvt_pk_bf16_f32 v215, v216, v217
	v_cvt_pk_bf16_f32 v216, v218, v219
	v_cvt_pk_bf16_f32 v217, v220, v221
	global_store_dwordx4 v[210:211], v[214:217], off sc1
	global_load_dword v130, v[142:143], off offset:256
	ds_read_b128 v[214:217], v209 offset:33792
	ds_read_b128 v[218:221], v209 offset:33808
	v_add_co_u32_e32 v210, vcc, s34, v150
	s_waitcnt vmcnt(0) lgkmcnt(1)
	v_pk_mul_f32 v[214:215], v[214:215], v[130:131] op_sel_hi:[1,0]
	v_pk_mul_f32 v[216:217], v[216:217], v[130:131] op_sel_hi:[1,0]
	s_waitcnt lgkmcnt(0)
	v_pk_mul_f32 v[218:219], v[218:219], v[130:131] op_sel_hi:[1,0]
	v_pk_mul_f32 v[220:221], v[220:221], v[130:131] op_sel_hi:[1,0]
	v_addc_co_u32_e32 v211, vcc, 0, v151, vcc
	v_cvt_pk_bf16_f32 v214, v214, v215
	v_cvt_pk_bf16_f32 v215, v216, v217
	v_cvt_pk_bf16_f32 v216, v218, v219
	v_cvt_pk_bf16_f32 v217, v220, v221
	global_store_dwordx4 v[210:211], v[214:217], off sc1
	global_load_dword v130, v[148:149], off offset:256
	ds_read_b128 v[214:217], v182 offset:33792
	ds_read_b128 v[218:221], v182 offset:33808
	v_add_co_u32_e32 v210, vcc, 0x20000, v146
	s_waitcnt vmcnt(0) lgkmcnt(1)
	v_pk_mul_f32 v[222:223], v[214:215], v[130:131] op_sel_hi:[1,0]
	v_pk_mul_f32 v[214:215], v[216:217], v[130:131] op_sel_hi:[1,0]
	s_waitcnt lgkmcnt(0)
	v_pk_mul_f32 v[218:219], v[218:219], v[130:131] op_sel_hi:[1,0]
	v_pk_mul_f32 v[216:217], v[220:221], v[130:131] op_sel_hi:[1,0]
	v_addc_co_u32_e32 v211, vcc, 0, v147, vcc
	v_cvt_pk_bf16_f32 v217, v216, v217
	v_cvt_pk_bf16_f32 v216, v218, v219
	v_cvt_pk_bf16_f32 v215, v214, v215
	v_cvt_pk_bf16_f32 v214, v222, v223
	global_store_dwordx4 v[210:211], v[214:217], off sc1
	s_barrier
	s_and_saveexec_b64 s[20:21], s[8:9]
	s_cbranch_execz .LBB0_1735
	v_and_b32_e32 v254, 63, v180
	v_lshrrev_b32_e32 v253, 4, v254
	v_mul_u32_u24_e32 v253, 0x840, v253
	v_and_b32_e32 v254, 15, v254
	v_lshl_add_u32 v253, v254, 2, v253
	v_and_b32_e32 v254, 64, v180
	v_lshl_add_u32 v253, v254, 2, v253
	ds_write_b32 v253, v0 offset:0
	ds_write_b32 v253, v1 offset:528
	ds_write_b32 v253, v2 offset:1056
	ds_write_b32 v253, v3 offset:1584
	ds_write_b32 v253, v4 offset:64
	ds_write_b32 v253, v5 offset:592
	ds_write_b32 v253, v6 offset:1120
	ds_write_b32 v253, v7 offset:1648
	ds_write_b32 v253, v8 offset:128
	ds_write_b32 v253, v9 offset:656
	ds_write_b32 v253, v10 offset:1184
	ds_write_b32 v253, v11 offset:1712
	ds_write_b32 v253, v12 offset:192
	ds_write_b32 v253, v13 offset:720
	ds_write_b32 v253, v14 offset:1248
	ds_write_b32 v253, v15 offset:1776
	ds_write_b32 v253, v16 offset:8448
	ds_write_b32 v253, v17 offset:8976
	ds_write_b32 v253, v18 offset:9504
	ds_write_b32 v253, v19 offset:10032
	ds_write_b32 v253, v20 offset:8512
	ds_write_b32 v253, v21 offset:9040
	ds_write_b32 v253, v22 offset:9568
	ds_write_b32 v253, v23 offset:10096
	ds_write_b32 v253, v24 offset:8576
	ds_write_b32 v253, v25 offset:9104
	ds_write_b32 v253, v26 offset:9632
	ds_write_b32 v253, v27 offset:10160
	ds_write_b32 v253, v28 offset:8640
	ds_write_b32 v253, v29 offset:9168
	ds_write_b32 v253, v30 offset:9696
	ds_write_b32 v253, v31 offset:10224
	ds_write_b32 v253, v32 offset:16896
	ds_write_b32 v253, v33 offset:17424
	ds_write_b32 v253, v34 offset:17952
	ds_write_b32 v253, v35 offset:18480
	ds_write_b32 v253, v36 offset:16960
	ds_write_b32 v253, v37 offset:17488
	ds_write_b32 v253, v38 offset:18016
	ds_write_b32 v253, v39 offset:18544
	ds_write_b32 v253, v40 offset:17024
	ds_write_b32 v253, v41 offset:17552
	ds_write_b32 v253, v42 offset:18080
	ds_write_b32 v253, v43 offset:18608
	ds_write_b32 v253, v44 offset:17088
	ds_write_b32 v253, v45 offset:17616
	ds_write_b32 v253, v46 offset:18144
	ds_write_b32 v253, v47 offset:18672
	ds_write_b32 v253, v48 offset:25344
	ds_write_b32 v253, v49 offset:25872
	ds_write_b32 v253, v50 offset:26400
	ds_write_b32 v253, v51 offset:26928
	ds_write_b32 v253, v52 offset:25408
	ds_write_b32 v253, v53 offset:25936
	ds_write_b32 v253, v54 offset:26464
	ds_write_b32 v253, v55 offset:26992
	ds_write_b32 v253, v56 offset:25472
	ds_write_b32 v253, v57 offset:26000
	ds_write_b32 v253, v58 offset:26528
	ds_write_b32 v253, v59 offset:27056
	ds_write_b32 v253, v60 offset:25536
	ds_write_b32 v253, v61 offset:26064
	ds_write_b32 v253, v62 offset:26592
	ds_write_b32 v253, v63 offset:27120
	ds_write_b32 v253, v64 offset:33792
	ds_write_b32 v253, v65 offset:34320
	ds_write_b32 v253, v66 offset:34848
	ds_write_b32 v253, v67 offset:35376
	ds_write_b32 v253, v68 offset:33856
	ds_write_b32 v253, v69 offset:34384
	ds_write_b32 v253, v70 offset:34912
	ds_write_b32 v253, v71 offset:35440
	ds_write_b32 v253, v72 offset:33920
	ds_write_b32 v253, v73 offset:34448
	ds_write_b32 v253, v74 offset:34976
	ds_write_b32 v253, v75 offset:35504
	ds_write_b32 v253, v76 offset:33984
	ds_write_b32 v253, v77 offset:34512
	ds_write_b32 v253, v78 offset:35040
	ds_write_b32 v253, v79 offset:35568
	ds_write_b32 v253, v80 offset:42240
	ds_write_b32 v253, v81 offset:42768
	ds_write_b32 v253, v82 offset:43296
	ds_write_b32 v253, v83 offset:43824
	ds_write_b32 v253, v84 offset:42304
	ds_write_b32 v253, v85 offset:42832
	ds_write_b32 v253, v86 offset:43360
	ds_write_b32 v253, v87 offset:43888
	ds_write_b32 v253, v88 offset:42368
	ds_write_b32 v253, v89 offset:42896
	ds_write_b32 v253, v90 offset:43424
	ds_write_b32 v253, v91 offset:43952
	ds_write_b32 v253, v92 offset:42432
	ds_write_b32 v253, v93 offset:42960
	ds_write_b32 v253, v94 offset:43488
	ds_write_b32 v253, v95 offset:44016
	ds_write_b32 v253, v96 offset:50688
	ds_write_b32 v253, v97 offset:51216
	ds_write_b32 v253, v98 offset:51744
	ds_write_b32 v253, v99 offset:52272
	ds_write_b32 v253, v100 offset:50752
	ds_write_b32 v253, v101 offset:51280
	ds_write_b32 v253, v102 offset:51808
	ds_write_b32 v253, v103 offset:52336
	ds_write_b32 v253, v104 offset:50816
	ds_write_b32 v253, v105 offset:51344
	ds_write_b32 v253, v106 offset:51872
	ds_write_b32 v253, v107 offset:52400
	ds_write_b32 v253, v108 offset:50880
	ds_write_b32 v253, v109 offset:51408
	ds_write_b32 v253, v110 offset:51936
	ds_write_b32 v253, v111 offset:52464
	ds_write_b32 v253, v112 offset:59136
	ds_write_b32 v253, v113 offset:59664
	ds_write_b32 v253, v114 offset:60192
	ds_write_b32 v253, v115 offset:60720
	ds_write_b32 v253, v116 offset:59200
	ds_write_b32 v253, v117 offset:59728
	ds_write_b32 v253, v118 offset:60256
	ds_write_b32 v253, v119 offset:60784
	ds_write_b32 v253, v120 offset:59264
	ds_write_b32 v253, v121 offset:59792
	ds_write_b32 v253, v122 offset:60320
	ds_write_b32 v253, v123 offset:60848
	ds_write_b32 v253, v124 offset:59328
	ds_write_b32 v253, v125 offset:59856
	ds_write_b32 v253, v126 offset:60384
	ds_write_b32 v253, v127 offset:60912
	s_branch .LBB0_1735

.LBB0_1810:
	s_waitcnt vmcnt(2)
	v_pk_mul_f32 v[114:115], v[36:37], v[114:115]
	v_pk_mul_f32 v[112:113], v[38:39], v[112:113]
	v_pk_fma_f32 v[60:61], v[60:61], s[12:13], v[114:115] op_sel_hi:[1,0,1]
	v_pk_mul_f32 v[108:109], v[32:33], v[108:109]
	v_pk_fma_f32 v[62:63], v[62:63], s[12:13], v[112:113] op_sel_hi:[1,0,1]
	v_add_f32_e32 v55, v60, v61
	v_pk_fma_f32 v[48:49], v[48:49], s[12:13], v[108:109] op_sel_hi:[1,0,1]
	v_pk_mul_f32 v[106:107], v[34:35], v[106:107]
	v_add_f32_e32 v72, v62, v55
	v_mov_b32_e32 v55, v110
	v_mul_f32_e32 v110, 0x3fb504f3, v53
	s_waitcnt vmcnt(0)
	v_mul_f32_e32 v114, v45, v105
	v_pk_fma_f32 v[50:51], v[50:51], s[12:13], v[106:107] op_sel_hi:[1,0,1]
	v_add_f32_e32 v53, v48, v49
	v_mov_b32_e32 v108, v44
	v_mov_b32_e32 v109, v42
	v_mov_b32_e32 v105, v102
	v_pk_add_f32 v[112:113], v[62:63], v[72:73] op_sel_hi:[1,0]
	v_add_f32_e32 v72, v50, v53
	v_pk_mul_f32 v[104:105], v[108:109], v[104:105]
	v_mov_b32_e32 v57, v40
	v_mul_f32_e32 v112, v47, v79
	v_pk_add_f32 v[106:107], v[50:51], v[72:73] op_sel_hi:[1,0]
	v_pk_fma_f32 v[98:99], v[98:99], s[12:13], v[104:105] op_sel_hi:[1,0,1]
	v_mov_b32_e32 v104, v46
	v_mov_b32_e32 v105, v43
	v_mov_b32_e32 v79, v103
	v_pk_mul_f32 v[56:57], v[56:57], v[54:55]
	v_mov_b32_e32 v101, v41
	v_mov_b32_e32 v55, v111
	v_pk_mul_f32 v[78:79], v[104:105], v[78:79]
	v_mov_b32_e32 v53, v107
	v_pk_mul_f32 v[100:101], v[100:101], v[54:55]
	v_pk_fma_f32 v[78:79], v[96:97], s[12:13], v[78:79] op_sel_hi:[1,0,1]
	v_pk_mul_f32 v[52:53], v[52:53], s[12:13]
	v_pk_add_f32 v[96:97], v[106:107], s[10:11]
	v_ashrrev_i32_e32 v81, 31, v80
	v_mov_b32_e32 v53, v97
	v_mov_b32_e32 v96, v56
	v_mov_b32_e32 v97, v100
	v_mov_b32_e32 v100, v57
	v_pk_add_f32 v[56:57], v[96:97], v[100:101]
	v_pk_add_f32 v[52:53], v[52:53], v[112:113]
	v_mov_b32_e32 v111, v56
	v_mov_b32_e32 v115, v57
	v_pk_add_f32 v[96:97], v[110:111], v[114:115]
	v_mov_b32_e32 v110, v99
	v_pk_add_f32 v[100:101], v[98:99], v[96:97]
	v_mov_b32_e32 v111, v79
	v_pk_add_f32 v[100:101], v[78:79], v[100:101]
	v_mov_b32_e32 v99, v96
	v_pk_add_f32 v[100:101], v[100:101], v[52:53]
	v_mov_b32_e32 v79, v52
	v_add_f32_e32 v53, v100, v101
	ds_bpermute_b32 v55, v154, v53
	s_and_b64 s[6:7], exec, s[6:7]
	s_or_b64 s[4:5], s[6:7], s[4:5]
	s_waitcnt lgkmcnt(0)
	v_add_f32_e32 v53, v53, v55
	ds_bpermute_b32 v55, v155, v53
	s_waitcnt lgkmcnt(0)
	v_add_f32_e32 v53, v53, v55
	ds_bpermute_b32 v55, v156, v53
	s_waitcnt lgkmcnt(0)
	v_add_f32_e32 v53, v53, v55
	ds_bpermute_b32 v55, v157, v53
	s_waitcnt lgkmcnt(0)
	v_add_f32_e32 v53, v53, v55
	ds_bpermute_b32 v55, v158, v53
	s_waitcnt lgkmcnt(0)
	v_add_f32_e32 v53, v53, v55
	ds_bpermute_b32 v55, v159, v53
	s_waitcnt lgkmcnt(0)
	v_add_f32_e32 v53, v53, v55
	v_mul_f32_e32 v72, 0x3a800000, v53
	v_pk_add_f32 v[48:49], v[48:49], v[72:73] op_sel_hi:[1,0] neg_lo:[0,1] neg_hi:[0,1]
	v_pk_add_f32 v[50:51], v[50:51], v[72:73] op_sel_hi:[1,0] neg_lo:[0,1] neg_hi:[0,1]
	v_pk_mul_f32 v[100:101], v[48:49], v[48:49]
	v_pk_mul_f32 v[102:103], v[50:51], v[50:51]
	v_add_f32_e32 v55, v100, v101
	v_pk_add_f32 v[60:61], v[60:61], v[72:73] op_sel_hi:[1,0] neg_lo:[0,1] neg_hi:[0,1]
	v_add_f32_e32 v55, v102, v55
	v_pk_mul_f32 v[106:107], v[60:61], v[60:61]
	v_add_f32_e32 v55, v103, v55
	v_pk_add_f32 v[62:63], v[62:63], v[72:73] op_sel_hi:[1,0] neg_lo:[0,1] neg_hi:[0,1]
	v_add_f32_e32 v55, v106, v55
	v_pk_mul_f32 v[108:109], v[62:63], v[62:63]
	v_add_f32_e32 v55, v107, v55
	v_pk_add_f32 v[56:57], v[56:57], v[72:73] op_sel_hi:[1,0] neg_lo:[0,1] neg_hi:[0,1]
	v_add_f32_e32 v55, v108, v55
	v_pk_mul_f32 v[104:105], v[56:57], v[56:57]
	v_add_f32_e32 v55, v109, v55
	v_pk_add_f32 v[110:111], v[110:111], v[72:73] op_sel_hi:[1,0] neg_lo:[0,1] neg_hi:[0,1]
	v_add_f32_e32 v55, v104, v55
	v_pk_mul_f32 v[112:113], v[110:111], v[110:111]
	v_add_f32_e32 v55, v105, v55
	v_pk_add_f32 v[96:97], v[98:99], v[72:73] op_sel_hi:[1,0] neg_lo:[0,1] neg_hi:[0,1]
	v_add_f32_e32 v55, v112, v55
	v_pk_mul_f32 v[98:99], v[96:97], v[96:97]
	v_add_f32_e32 v55, v113, v55
	v_pk_add_f32 v[52:53], v[78:79], v[72:73] op_sel_hi:[1,0] neg_lo:[0,1] neg_hi:[0,1]
	v_add_f32_e32 v55, v98, v55
	v_pk_mul_f32 v[78:79], v[52:53], v[52:53]
	v_add_f32_e32 v55, v99, v55
	v_add_f32_e32 v55, v78, v55
	v_add_f32_e32 v55, v79, v55
	ds_bpermute_b32 v59, v154, v55
	v_lshlrev_b64 v[78:79], 12, v[80:81]
	v_lshl_add_u64 v[78:79], v[90:91], 0, v[78:79]
	v_mov_b32_e32 v101, v161
	v_mov_b32_e32 v80, v58
	s_waitcnt lgkmcnt(0)
	v_add_f32_e32 v55, v55, v59
	ds_bpermute_b32 v59, v155, v55
	v_mov_b32_e32 v100, v77
	v_mov_b64_e32 v[98:99], v[94:95]
	s_waitcnt lgkmcnt(0)
	v_add_f32_e32 v55, v55, v59
	ds_bpermute_b32 v59, v156, v55
	s_waitcnt lgkmcnt(0)
	v_add_f32_e32 v55, v55, v59
	ds_bpermute_b32 v59, v157, v55
	s_waitcnt lgkmcnt(0)
	v_add_f32_e32 v55, v55, v59
	ds_bpermute_b32 v59, v158, v55
	s_waitcnt lgkmcnt(0)
	v_add_f32_e32 v55, v55, v59
	ds_bpermute_b32 v59, v159, v55
	s_waitcnt lgkmcnt(0)
	v_add_f32_e32 v55, v55, v59
	v_fmamk_f32 v55, v55, 0x3a800000, v160
	v_mul_f32_e32 v59, 0x4b800000, v55
	v_cmp_gt_f32_e32 vcc, s1, v55
	s_nop 1
	v_cndmask_b32_e32 v55, v55, v59, vcc
	v_rsq_f32_e32 v55, v55
	s_nop 0
	v_mul_f32_e32 v59, 0x45800000, v55
	v_cndmask_b32_e32 v72, v55, v59, vcc
	v_pk_mul_f32 v[48:49], v[48:49], v[72:73] op_sel_hi:[1,0]
	v_pk_mul_f32 v[50:51], v[50:51], v[72:73] op_sel_hi:[1,0]
	v_pk_fma_f32 v[48:49], v[0:1], v[48:49], v[4:5]
	v_pk_fma_f32 v[50:51], v[2:3], v[50:51], v[6:7]
	global_store_dwordx4 v[78:79], v[48:51], off sc1 nt
	s_nop 1
	v_pk_mul_f32 v[48:49], v[60:61], v[72:73] op_sel_hi:[1,0]
	v_pk_mul_f32 v[50:51], v[62:63], v[72:73] op_sel_hi:[1,0]
	v_pk_fma_f32 v[48:49], v[8:9], v[48:49], v[16:17]
	v_pk_fma_f32 v[50:51], v[10:11], v[50:51], v[18:19]
	global_store_dwordx4 v[78:79], v[48:51], off offset:1024 sc1 nt
	v_mov_b32_e32 v62, v70
	v_mov_b32_e32 v63, v71
	v_pk_mul_f32 v[48:49], v[56:57], v[72:73] op_sel_hi:[1,0]
	v_pk_mul_f32 v[50:51], v[110:111], v[72:73] op_sel_hi:[1,0]
	v_pk_fma_f32 v[48:49], v[12:13], v[48:49], v[20:21]
	v_pk_fma_f32 v[50:51], v[14:15], v[50:51], v[22:23]
	global_store_dwordx4 v[78:79], v[48:51], off offset:2048 sc1 nt
	v_mov_b32_e32 v56, v76
	v_mov_b32_e32 v60, v68
	v_pk_mul_f32 v[48:49], v[96:97], v[72:73] op_sel_hi:[1,0]
	v_pk_mul_f32 v[50:51], v[52:53], v[72:73] op_sel_hi:[1,0]
	v_pk_fma_f32 v[48:49], v[24:25], v[48:49], v[28:29]
	v_pk_fma_f32 v[50:51], v[26:27], v[50:51], v[30:31]
	global_store_dwordx4 v[78:79], v[48:51], off offset:3072 sc1 nt
	v_mov_b32_e32 v52, v75
	v_mov_b32_e32 v53, v73
	v_mov_b64_e32 v[96:97], v[92:93]
	v_mov_b32_e32 v48, v64
	v_mov_b32_e32 v49, v65
	v_mov_b32_e32 v50, v66
	v_mov_b32_e32 v51, v67
	v_mov_b32_e32 v61, v69
	s_andn2_b64 exec, exec, s[4:5]
	s_cbranch_execz .LBB0_1826
